# GEMM k-loop head labels aligned to 64 bytes (code placement)
# speedup vs baseline: 1.0136x; 1.0051x over previous
; DEVI int otid() { int t = threadIdx.x; asm volatile("" : "+v"(t)); return t; }
; #define RAW_BARRIER() do { asm volatile("s_waitcnt lgkmcnt(0)" ::: "memory"); __builtin_amdgcn_s_barrier(); } while (0)
; template <int EPI, int NB>
; DEVI void gemm_tile(const GemmJob& J, int m0, int n0, unsigned char* smem) {
;     ...
;   const int tid = otid(), lane = tid & 63, wid = tid >> 6, wm = wid >> 1, wn = wid & 1;
;   const int l16 = lane & 15, g = lane >> 4;
;   f32x4 acc[4][NB];
; #pragma unroll
;   for (int i = 0; i < 4; ++i)
; #pragma unroll
;     for (int j = 0; j < NB; ++j) acc[i][j] = (f32x4){0.f, 0.f, 0.f, 0.f};
;   const int srow = tid >> 2, sch = tid & 3;
;   const int gch = sch ^ ((0 - (tid >> 4)) & 3);
;   const bf16_t* Ag = J.A + (size_t)(m0 + srow) * (J.ablk ? 32 : J.lda) + gch * 8;
;   const bf16_t* Bg = J.Bt + (size_t)(n0 + srow) * 32 + gch * 8;
;   const size_t Astep = (size_t)64 * (J.ablk ? 32 : J.lda), Ak = J.ablk ? (size_t)MROWS * 32 : (size_t)32, Bstep = (size_t)64 * 32, Bk = (size_t)J.NR * 32;
;   const int nk = J.K >> 5;
;   unsigned char* lds_t = smem + tid * 16;
;   const unsigned lbase = (unsigned)(uintptr_t)(__attribute__((address_space(3))) unsigned char*)smem;
;     ...
;   asm volatile("s_waitcnt vmcnt(0)" ::: "memory");
;   RAW_BARRIER();
; #pragma unroll
;   for (int st = 0; st < S - 1; ++st) GEMM_ISSUE(st, st);
;   const int fsl = (g ^ ((0 - (l16 >> 2)) & 3)) << 4;
;   const int aofs = (wm * 64 + l16) * 64 + fsl;
;   const int bofs = A_BYTES + (wn * NB * 16 + l16) * 64 + fsl;
;   int cs = 0, is = S - 1;
; template <int EPI, int NB>
; DEVI void gemm_run(const GemmJob& J, unsigned char* smem, int rot) {
;     ...
;     for (int t = b; t < ntiles; t += G) {
;       const int mt = t / J.ntn, nt = J.nt0 + (t - mt * J.ntn);
;       gemm_tile<EPI, NB>(J, mt * 128, nt * BN, smem);
.LBB0_152:
	s_mul_hi_i32 s0, s3, 0x2e8ba2e9
	s_lshr_b32 s1, s0, 31
	s_ashr_i32 s0, s0, 2
	s_add_i32 s0, s0, s1
	s_mul_i32 s1, s0, 0xffffffea
	s_add_i32 s1, s1, s3
	v_mov_b32_e32 v186, v177
	s_lshl_b32 s8, s0, 7
	s_lshl_b32 s9, s1, 8
	s_nop 0
	s_mov_b64 s[28:29], 0x1000
	v_ashrrev_i32_e32 v10, 2, v186
	v_lshrrev_b32_e32 v0, 4, v186
	v_sub_u32_e32 v11, 0, v0
	v_add_u32_e32 v2, s8, v10
	v_add_u32_e32 v6, s9, v10
	v_xor_b32_e32 v0, v186, v11
	v_ashrrev_i32_e32 v3, 31, v2
	v_ashrrev_i32_e32 v7, 31, v6
	v_lshlrev_b64 v[2:3], 6, v[2:3]
	v_lshlrev_b32_e32 v0, 4, v0
	v_lshlrev_b64 v[6:7], 6, v[6:7]
	v_lshl_add_u64 v[4:5], v[146:147], 0, v[2:3]
	v_and_b32_e32 v0, 48, v0
	v_lshl_add_u64 v[6:7], v[178:179], 0, v[6:7]
	v_lshlrev_b32_e32 v187, 4, v186
	v_lshl_add_u64 v[4:5], v[4:5], 0, v[0:1]
	v_lshl_add_u64 v[6:7], v[6:7], 0, v[0:1]
	v_readfirstlane_b32 s1, v187
	v_add_u32_e32 v0, 0x1000, v187
	s_mov_b32 m0, s1
	v_readfirstlane_b32 s1, v0
	v_add_u32_e32 v0, 0x2000, v187
	s_waitcnt lgkmcnt(0)
	s_barrier
	global_load_lds_dwordx4 v[4:5], off
	v_lshl_add_u64 v[8:9], v[4:5], 0, s[28:29]
	s_mov_b32 m0, s1
	v_readfirstlane_b32 s1, v0
	v_add_u32_e32 v0, 0x3000, v187
	global_load_lds_dwordx4 v[8:9], off
	s_mov_b32 m0, s1
	v_readfirstlane_b32 s1, v0
	v_add_u32_e32 v0, 0x4000, v187
	global_load_lds_dwordx4 v[6:7], off
	v_lshl_add_u64 v[8:9], v[6:7], 0, s[28:29]
	s_mov_b32 m0, s1
	s_mov_b64 s[28:29], 0x2000
	v_readfirstlane_b32 s1, v0
	v_add_u32_e32 v0, 0x5000, v187
	global_load_lds_dwordx4 v[8:9], off
	v_lshl_add_u64 v[8:9], v[6:7], 0, s[28:29]
	s_mov_b32 m0, s1
	s_mov_b64 s[28:29], 0x3000
	v_readfirstlane_b32 s1, v0
	v_add_u32_e32 v0, 0x6000, v187
	global_load_lds_dwordx4 v[8:9], off
	v_lshl_add_u64 v[8:9], v[6:7], 0, s[28:29]
	s_mov_b32 m0, s1
	v_readfirstlane_b32 s1, v0
	v_add_u32_e32 v0, 0x7000, v187
	global_load_lds_dwordx4 v[8:9], off
	v_lshl_add_u64 v[8:9], v[4:5], 0, s[94:95]
	s_mov_b32 m0, s1
	s_mov_b64 s[28:29], 0x30b000
	v_readfirstlane_b32 s1, v0
	v_add_u32_e32 v0, 0x8000, v187
	global_load_lds_dwordx4 v[8:9], off
	v_lshl_add_u64 v[4:5], v[4:5], 0, s[28:29]
	s_mov_b32 m0, s1
	v_readfirstlane_b32 s1, v0
	v_add_u32_e32 v0, 0x9000, v187
	global_load_lds_dwordx4 v[4:5], off
	v_lshl_add_u64 v[4:5], v[6:7], 0, s[50:51]
	s_mov_b32 m0, s1
	s_mov_b64 s[28:29], 0x59000
	v_readfirstlane_b32 s1, v0
	v_add_u32_e32 v0, 0xa000, v187
	global_load_lds_dwordx4 v[4:5], off
	v_lshl_add_u64 v[4:5], v[6:7], 0, s[28:29]
	s_mov_b32 m0, s1
	s_mov_b64 s[28:29], 0x5a000
	v_readfirstlane_b32 s1, v0
	v_add_u32_e32 v0, 0xb000, v187
	global_load_lds_dwordx4 v[4:5], off
	v_lshl_add_u64 v[4:5], v[6:7], 0, s[28:29]
	s_mov_b32 m0, s1
	s_mov_b64 s[28:29], 0x5b000
	v_readfirstlane_b32 s1, v0
	global_load_lds_dwordx4 v[4:5], off
	v_lshl_add_u64 v[4:5], v[6:7], 0, s[28:29]
	s_mov_b32 m0, s1
	v_lshlrev_b32_e32 v0, 2, v186
	global_load_lds_dwordx4 v[4:5], off
	v_and_b32_e32 v0, 48, v0
	v_ashrrev_i32_e32 v4, 1, v186
	v_and_b32_e32 v208, 15, v186
	v_sub_u32_e32 v0, 0, v0
	v_and_b32_e32 v209, 0xffffffc0, v4
	v_bitop3_b32 v0, v186, 48, v0 bitop3:0x48
	v_or_b32_e32 v4, v209, v208
	v_lshl_or_b32 v210, v4, 6, v0
	v_lshlrev_b32_e32 v4, 1, v186
	v_and_b32_e32 v211, 0x80, v4
	v_or_b32_e32 v4, v211, v208
	v_lshl_or_b32 v0, v4, 6, v0
	v_add_u32_e32 v4, s2, v10
	s_mulk_i32 s0, 0x1600
	v_subrev_u32_e32 v4, s0, v4
	v_ashrrev_i32_e32 v5, 31, v4
	v_add_u32_e32 v212, 0x2000, v0
	v_bitop3_b32 v0, v186, 3, v11 bitop3:0x48
	v_lshlrev_b64 v[4:5], 6, v[4:5]
	v_mov_b32_e32 v6, 0
	s_mov_b32 s42, 2
	s_mov_b32 s20, 0
	s_mov_b64 s[30:31], 0x1000
	v_lshlrev_b32_e32 v0, 4, v0
	v_lshl_add_u64 v[182:183], v[180:181], 0, v[4:5]
	v_lshl_add_u64 v[184:185], v[130:131], 0, v[2:3]
	s_mov_b32 s43, 0
	v_mov_b32_e32 v7, v6
	v_mov_b32_e32 v8, v6
	v_mov_b32_e32 v9, v6
	v_mov_b32_e32 v14, v6
	v_mov_b32_e32 v15, v6
	v_mov_b32_e32 v16, v6
	v_mov_b32_e32 v17, v6
	v_mov_b32_e32 v2, v6
	v_mov_b32_e32 v3, v6
	v_mov_b32_e32 v4, v6
	v_mov_b32_e32 v5, v6
	v_mov_b32_e32 v10, v6
	v_mov_b32_e32 v11, v6
	v_mov_b32_e32 v12, v6
	v_mov_b32_e32 v13, v6
	v_mov_b32_e32 v22, v6
	v_mov_b32_e32 v23, v6
	v_mov_b32_e32 v24, v6
	v_mov_b32_e32 v25, v6
	v_mov_b32_e32 v30, v6
; #define RAW_BARRIER() do { asm volatile("s_waitcnt lgkmcnt(0)" ::: "memory"); __builtin_amdgcn_s_barrier(); } while (0)
; template <int EPI, int NB>
; DEVI void gemm_tile(const GemmJob& J, int m0, int n0, unsigned char* smem) {
;     ...
;   f32x4 acc[4][NB];
; #pragma unroll
;   for (int i = 0; i < 4; ++i)
; #pragma unroll
;     for (int j = 0; j < NB; ++j) acc[i][j] = (f32x4){0.f, 0.f, 0.f, 0.f};
;   const int srow = tid >> 2, sch = tid & 3;
;   const int gch = sch ^ ((0 - (tid >> 4)) & 3);
;   const bf16_t* Ag = J.A + (size_t)(m0 + srow) * (J.ablk ? 32 : J.lda) + gch * 8;
;   const bf16_t* Bg = J.Bt + (size_t)(n0 + srow) * 32 + gch * 8;
;   const size_t Astep = (size_t)64 * (J.ablk ? 32 : J.lda), Ak = J.ablk ? (size_t)MROWS * 32 : (size_t)32, Bstep = (size_t)64 * 32, Bk = (size_t)J.NR * 32;
;   const int nk = J.K >> 5;
;   unsigned char* lds_t = smem + tid * 16;
;   const unsigned lbase = (unsigned)(uintptr_t)(__attribute__((address_space(3))) unsigned char*)smem;
;     ...
;   asm volatile("s_waitcnt vmcnt(0)" ::: "memory");
;   RAW_BARRIER();
; #pragma unroll
;   for (int st = 0; st < S - 1; ++st) GEMM_ISSUE(st, st);
;   const int fsl = (g ^ ((0 - (l16 >> 2)) & 3)) << 4;
;   const int aofs = (wm * 64 + l16) * 64 + fsl;
;   const int bofs = A_BYTES + (wn * NB * 16 + l16) * 64 + fsl;
;   int cs = 0, is = S - 1;
; #pragma clang loop unroll(disable)
;   for (int kt = 0; kt < nk; ++kt) {
;     if (nk - 1 - kt >= S - 2) {
;       if constexpr (NB == 8) asm volatile("s_waitcnt vmcnt(6)" ::: "memory");
;       else                   asm volatile("s_waitcnt vmcnt(8)" ::: "memory");
;     } else {
;       asm volatile("s_waitcnt vmcnt(0)" ::: "memory");
;     }
;     RAW_BARRIER();
;     if (kt + S - 1 < nk) GEMM_ISSUE(kt + S - 1, is);
;     is = (is + 1 == S) ? 0 : is + 1;
;     const unsigned cur = lbase + cs * STG;
;     cs = (cs + 1 == S) ? 0 : cs + 1;
;     bf16x8 af[4], bfr[NB];
;     const unsigned aa = cur + aofs, ba = cur + bofs;
	v_mov_b32_e32 v31, v6
	v_mov_b32_e32 v32, v6
	v_mov_b32_e32 v33, v6
	v_mov_b32_e32 v18, v6
	v_mov_b32_e32 v19, v6
	v_mov_b32_e32 v20, v6
	v_mov_b32_e32 v21, v6
	v_mov_b32_e32 v26, v6
	v_mov_b32_e32 v27, v6
	v_mov_b32_e32 v28, v6
	v_mov_b32_e32 v29, v6
	v_mov_b32_e32 v38, v6
	v_mov_b32_e32 v39, v6
	v_mov_b32_e32 v40, v6
	v_mov_b32_e32 v41, v6
	v_mov_b32_e32 v46, v6
	v_mov_b32_e32 v47, v6
	v_mov_b32_e32 v48, v6
	v_mov_b32_e32 v49, v6
	v_mov_b32_e32 v34, v6
	v_mov_b32_e32 v35, v6
	v_mov_b32_e32 v36, v6
	v_mov_b32_e32 v37, v6
	v_mov_b32_e32 v42, v6
	v_mov_b32_e32 v43, v6
	v_mov_b32_e32 v44, v6
	v_mov_b32_e32 v45, v6
	v_mov_b32_e32 v54, v6
	v_mov_b32_e32 v55, v6
	v_mov_b32_e32 v56, v6
	v_mov_b32_e32 v57, v6
	v_mov_b32_e32 v62, v6
	v_mov_b32_e32 v63, v6
	v_mov_b32_e32 v64, v6
	v_mov_b32_e32 v65, v6
	v_mov_b32_e32 v50, v6
	v_mov_b32_e32 v51, v6
	v_mov_b32_e32 v52, v6
	v_mov_b32_e32 v53, v6
	v_mov_b32_e32 v58, v6
	v_mov_b32_e32 v59, v6
	v_mov_b32_e32 v60, v6
	v_mov_b32_e32 v61, v6
	v_mov_b32_e32 v70, v6
	v_mov_b32_e32 v71, v6
	v_mov_b32_e32 v72, v6
	v_mov_b32_e32 v73, v6
	v_mov_b32_e32 v78, v6
	v_mov_b32_e32 v79, v6
	v_mov_b32_e32 v80, v6
	v_mov_b32_e32 v81, v6
	v_mov_b32_e32 v66, v6
	v_mov_b32_e32 v67, v6
	v_mov_b32_e32 v68, v6
	v_mov_b32_e32 v69, v6
	v_mov_b32_e32 v74, v6
	v_mov_b32_e32 v75, v6
	v_mov_b32_e32 v76, v6
	v_mov_b32_e32 v77, v6
	v_mov_b32_e32 v86, v6
	v_mov_b32_e32 v87, v6
	v_mov_b32_e32 v88, v6
	v_mov_b32_e32 v89, v6
	v_mov_b32_e32 v94, v6
	v_mov_b32_e32 v95, v6
	v_mov_b32_e32 v96, v6
	v_mov_b32_e32 v97, v6
	v_mov_b32_e32 v82, v6
	v_mov_b32_e32 v83, v6
	v_mov_b32_e32 v84, v6
	v_mov_b32_e32 v85, v6
	v_mov_b32_e32 v90, v6
	v_mov_b32_e32 v91, v6
	v_mov_b32_e32 v92, v6
	v_mov_b32_e32 v93, v6
	v_mov_b32_e32 v102, v6
	v_mov_b32_e32 v103, v6
	v_mov_b32_e32 v104, v6
	v_mov_b32_e32 v105, v6
	v_mov_b32_e32 v110, v6
	v_mov_b32_e32 v111, v6
	v_mov_b32_e32 v112, v6
	v_mov_b32_e32 v113, v6
	v_mov_b32_e32 v98, v6
	v_mov_b32_e32 v99, v6
	v_mov_b32_e32 v100, v6
	v_mov_b32_e32 v101, v6
	v_mov_b32_e32 v106, v6
	v_mov_b32_e32 v107, v6
	v_mov_b32_e32 v108, v6
	v_mov_b32_e32 v109, v6
	v_mov_b32_e32 v118, v6
	v_mov_b32_e32 v119, v6
	v_mov_b32_e32 v120, v6
	v_mov_b32_e32 v121, v6
	v_mov_b32_e32 v126, v6
	v_mov_b32_e32 v127, v6
	v_mov_b32_e32 v128, v6
	v_mov_b32_e32 v129, v6
	v_mov_b32_e32 v114, v6
	v_mov_b32_e32 v115, v6
	v_mov_b32_e32 v116, v6
	v_mov_b32_e32 v117, v6
	v_mov_b32_e32 v122, v6
	v_mov_b32_e32 v123, v6
	v_mov_b32_e32 v124, v6
	v_mov_b32_e32 v125, v6
	s_mul_i32 s0, s42, 0x6000
	v_add_u32_e32 v213, s0, v187
	v_lshl_add_u64 v[214:215], v[184:185], 0, v[0:1]
	v_readfirstlane_b32 s0, v213
	v_lshl_add_u64 v[216:217], v[214:215], 0, s[84:85]
	s_mov_b32 m0, s0
	v_lshl_add_u64 v[214:215], v[214:215], 0, s[12:13]
	s_nop 0
	v_readfirstlane_b32 s100, v216
	v_readfirstlane_b32 s101, v217
	s_nop 1
	v_subrev_u32_e32 v230, s100, v216
	v_add_u32_e32 v216, 0x1000, v213
	v_add_u32_e32 v218, 0x2000, v213
	v_readfirstlane_b32 s0, v216
	s_mov_b32 m0, s0
	s_mov_b64 s[0:1], 0x256000
	v_subrev_u32_e32 v231, s100, v214
	v_lshl_add_u64 v[214:215], v[182:183], 0, v[0:1]
	v_lshl_add_u64 v[216:217], v[214:215], 0, s[0:1]
	v_readfirstlane_b32 s0, v218
	s_mov_b32 m0, s0
	s_mov_b64 s[0:1], 0x257000
	v_add_u32_e32 v218, 0x3000, v213
	s_nop 0
	v_readfirstlane_b32 vcc_lo, v216
	v_readfirstlane_b32 vcc_hi, v217
	s_nop 1
	v_subrev_u32_e32 v232, vcc_lo, v216
	v_lshl_add_u64 v[216:217], v[214:215], 0, s[0:1]
	v_readfirstlane_b32 s0, v218
	s_mov_b32 m0, s0
	s_mov_b64 s[0:1], 0x258000
	v_add_u32_e32 v218, 0x4000, v213
	v_subrev_u32_e32 v233, vcc_lo, v216
	v_lshl_add_u64 v[216:217], v[214:215], 0, s[0:1]
	v_readfirstlane_b32 s0, v218
	s_mov_b32 m0, s0
	s_mov_b64 s[0:1], 0x259000
	v_add_u32_e32 v213, 0x5000, v213
	v_lshl_add_u64 v[214:215], v[214:215], 0, s[0:1]
	v_readfirstlane_b32 s0, v213
	v_subrev_u32_e32 v234, vcc_lo, v216
	s_mov_b32 m0, s0
	s_nop 0
	v_subrev_u32_e32 v235, vcc_lo, v214
	v_mov_b32_e32 v184, v230
	v_mov_b32_e32 v185, v231
	v_mov_b32_e32 v182, v232
	v_mov_b32_e32 v183, v233
	v_mov_b32_e32 v253, v234
	v_mov_b32_e32 v254, v235
	v_readfirstlane_b32 s0, v187
	s_branch .LBB0_154
	.p2align	6

; DEVI int otid() { int t = threadIdx.x; asm volatile("" : "+v"(t)); return t; }
; #define RAW_BARRIER() do { asm volatile("s_waitcnt lgkmcnt(0)" ::: "memory"); __builtin_amdgcn_s_barrier(); } while (0)
; template <int EPI, int NB>
; DEVI void gemm_tile(const GemmJob& J, int m0, int n0, unsigned char* smem) {
;     ...
;   const int tid = otid(), lane = tid & 63, wid = tid >> 6, wm = wid >> 1, wn = wid & 1;
;   const int l16 = lane & 15, g = lane >> 4;
;   f32x4 acc[4][NB];
; #pragma unroll
;   for (int i = 0; i < 4; ++i)
; #pragma unroll
;     for (int j = 0; j < NB; ++j) acc[i][j] = (f32x4){0.f, 0.f, 0.f, 0.f};
;   const int srow = tid >> 2, sch = tid & 3;
;   const int gch = sch ^ ((0 - (tid >> 4)) & 3);
;   const bf16_t* Ag = J.A + (size_t)(m0 + srow) * (J.ablk ? 32 : J.lda) + gch * 8;
;   const bf16_t* Bg = J.Bt + (size_t)(n0 + srow) * 32 + gch * 8;
;   const size_t Astep = (size_t)64 * (J.ablk ? 32 : J.lda), Ak = J.ablk ? (size_t)MROWS * 32 : (size_t)32, Bstep = (size_t)64 * 32, Bk = (size_t)J.NR * 32;
;   const int nk = J.K >> 5;
;   unsigned char* lds_t = smem + tid * 16;
;   const unsigned lbase = (unsigned)(uintptr_t)(__attribute__((address_space(3))) unsigned char*)smem;
;     ...
;   asm volatile("s_waitcnt vmcnt(0)" ::: "memory");
;   RAW_BARRIER();
; #pragma unroll
;   for (int st = 0; st < S - 1; ++st) GEMM_ISSUE(st, st);
;   const int fsl = (g ^ ((0 - (l16 >> 2)) & 3)) << 4;
;   const int aofs = (wm * 64 + l16) * 64 + fsl;
;   const int bofs = A_BYTES + (wn * NB * 16 + l16) * 64 + fsl;
;   int cs = 0, is = S - 1;
; template <int EPI, int NB>
; DEVI void gemm_run(const GemmJob& J, unsigned char* smem, int rot) {
;     ...
;     const int x = b & 7, lb = b >> 3, nlb = G >> 3;
;     const int mlo = x * 49;
;     const int mcnt = min(49, MT128 - mlo);
;     const int ntot = mcnt * J.ntn, gsz = 8 * J.ntn;
;     const int ngrp = (mcnt + 7) >> 3;
;     for (int q0 = lb; q0 < ntot; q0 += nlb) {
;       const int q = J.rev ? ntot - 1 - q0 : q0;
;       int grp = q / gsz; const int qq = q - grp * gsz;
;       const int mg = min(8, mcnt - grp * 8);
;       const int nt = qq / mg, mi = qq - nt * mg;
;       gemm_tile<EPI, NB>(J, (mlo + grp * 8 + mi) * 128, (J.nt0 + nt) * BN, smem);
.LBB0_165:
	s_mul_hi_i32 s0, s3, 0x2e8ba2e9
	s_lshr_b32 s1, s0, 31
	s_ashr_i32 s0, s0, 5
	s_add_i32 s0, s0, s1
	s_lshl_b32 s1, s0, 3
	v_readlane_b32 s8, v251, 48
	s_sub_i32 s8, s8, s1
	s_min_i32 s9, s8, 8
	s_abs_i32 s20, s9
	v_cvt_f32_u32_e32 v0, s20
	s_sub_i32 s43, 0, s20
	s_mul_i32 s40, s0, 0xffffff50
	s_add_i32 s40, s40, s3
	v_rcp_iflag_f32_e32 v0, v0
	s_abs_i32 s41, s40
	s_xor_b32 s42, s40, s9
	s_ashr_i32 s42, s42, 31
	v_mul_f32_e32 v0, 0x4f7ffffe, v0
	v_cvt_u32_f32_e32 v0, v0
	v_mov_b32_e32 v186, v177
	s_nop 0
	v_readfirstlane_b32 s44, v0
	s_mul_i32 s43, s43, s44
	s_mul_hi_u32 s43, s44, s43
	s_add_i32 s44, s44, s43
	s_mul_hi_u32 s43, s41, s44
	s_mul_i32 s44, s43, s20
	s_sub_i32 s41, s41, s44
	s_add_i32 s45, s43, 1
	s_sub_i32 s44, s41, s20
	s_cmp_ge_u32 s41, s20
	s_cselect_b32 s43, s45, s43
	s_cselect_b32 s41, s44, s41
	s_add_i32 s44, s43, 1
	s_cmp_ge_u32 s41, s20
	s_cselect_b32 s20, s44, s43
	s_xor_b32 s20, s20, s42
	s_sub_i32 s20, s20, s42
	s_mul_i32 s41, s9, s20
	v_readlane_b32 s9, v250, 37
	s_add_i32 s1, s1, s9
	s_add_i32 s1, s1, s40
	s_sub_i32 s1, s1, s41
	s_lshl_b32 s9, s1, 7
	s_lshl_b32 s20, s20, 8
	v_ashrrev_i32_e32 v10, 2, v186
	v_lshrrev_b32_e32 v0, 4, v186
	v_sub_u32_e32 v11, 0, v0
	v_add_u32_e32 v2, s9, v10
	v_add_u32_e32 v4, s20, v10
	v_xor_b32_e32 v0, v186, v11
	v_ashrrev_i32_e32 v3, 31, v2
	v_ashrrev_i32_e32 v5, 31, v4
	v_lshlrev_b64 v[2:3], 6, v[2:3]
	v_lshlrev_b32_e32 v0, 4, v0
	v_lshlrev_b64 v[4:5], 6, v[4:5]
	v_lshl_add_u64 v[2:3], v[146:147], 0, v[2:3]
	v_and_b32_e32 v0, 48, v0
	v_lshl_add_u64 v[6:7], v[178:179], 0, v[4:5]
	v_lshlrev_b32_e32 v187, 4, v186
	v_lshl_add_u64 v[2:3], v[2:3], 0, v[0:1]
	v_lshl_add_u64 v[6:7], v[6:7], 0, v[0:1]
	v_readfirstlane_b32 s1, v187
	v_add_u32_e32 v0, 0x1000, v187
	s_mov_b32 m0, s1
	s_mov_b64 s[28:29], 0x1000
	v_readfirstlane_b32 s1, v0
	v_add_u32_e32 v0, 0x2000, v187
	s_waitcnt lgkmcnt(0)
	s_barrier
	global_load_lds_dwordx4 v[2:3], off
	v_lshl_add_u64 v[8:9], v[2:3], 0, s[28:29]
	s_mov_b32 m0, s1
	v_readfirstlane_b32 s1, v0
	v_add_u32_e32 v0, 0x3000, v187
	global_load_lds_dwordx4 v[8:9], off
	s_mov_b32 m0, s1
	v_readfirstlane_b32 s1, v0
	v_add_u32_e32 v0, 0x4000, v187
	global_load_lds_dwordx4 v[6:7], off
	v_lshl_add_u64 v[8:9], v[6:7], 0, s[28:29]
	s_mov_b32 m0, s1
	s_mov_b64 s[28:29], 0x2000
	v_readfirstlane_b32 s1, v0
	v_add_u32_e32 v0, 0x5000, v187
	global_load_lds_dwordx4 v[8:9], off
	v_lshl_add_u64 v[8:9], v[6:7], 0, s[28:29]
	s_mov_b32 m0, s1
	s_mov_b64 s[28:29], 0x3000
	v_readfirstlane_b32 s1, v0
	v_add_u32_e32 v0, 0x6000, v187
	global_load_lds_dwordx4 v[8:9], off
	v_lshl_add_u64 v[8:9], v[6:7], 0, s[28:29]
	s_mov_b32 m0, s1
	v_readfirstlane_b32 s1, v0
	v_add_u32_e32 v0, 0x7000, v187
	global_load_lds_dwordx4 v[8:9], off
	v_lshl_add_u64 v[8:9], v[2:3], 0, s[94:95]
	s_mov_b32 m0, s1
	s_mov_b64 s[28:29], 0x30b000
	v_readfirstlane_b32 s1, v0
	v_add_u32_e32 v0, 0x8000, v187
	global_load_lds_dwordx4 v[8:9], off
	v_lshl_add_u64 v[2:3], v[2:3], 0, s[28:29]
	s_mov_b32 m0, s1
	v_readfirstlane_b32 s1, v0
	v_add_u32_e32 v0, 0x9000, v187
	global_load_lds_dwordx4 v[2:3], off
	v_lshl_add_u64 v[2:3], v[6:7], 0, s[50:51]
	s_mov_b32 m0, s1
	s_mov_b64 s[28:29], 0x59000
	v_readfirstlane_b32 s1, v0
	v_add_u32_e32 v0, 0xa000, v187
	global_load_lds_dwordx4 v[2:3], off
	v_lshl_add_u64 v[2:3], v[6:7], 0, s[28:29]
	s_mov_b32 m0, s1
	s_mov_b64 s[28:29], 0x5a000
	v_readfirstlane_b32 s1, v0
	v_add_u32_e32 v0, 0xb000, v187
	global_load_lds_dwordx4 v[2:3], off
	v_lshl_add_u64 v[2:3], v[6:7], 0, s[28:29]
	s_mov_b32 m0, s1
	s_mov_b64 s[28:29], 0x5b000
	v_readfirstlane_b32 s1, v0
	global_load_lds_dwordx4 v[2:3], off
	v_lshl_add_u64 v[2:3], v[6:7], 0, s[28:29]
	s_mov_b32 m0, s1
	v_lshlrev_b32_e32 v0, 2, v186
	global_load_lds_dwordx4 v[2:3], off
	v_and_b32_e32 v0, 48, v0
	v_ashrrev_i32_e32 v2, 1, v186
	v_and_b32_e32 v208, 15, v186
	v_sub_u32_e32 v0, 0, v0
	v_and_b32_e32 v209, 0xffffffc0, v2
	v_bitop3_b32 v0, v186, 48, v0 bitop3:0x48
	v_or_b32_e32 v2, v209, v208
	v_lshl_or_b32 v210, v2, 6, v0
	v_lshlrev_b32_e32 v2, 1, v186
	v_and_b32_e32 v211, 0x80, v2
	s_sub_i32 s1, s2, s41
	s_mulk_i32 s0, 0xa8
	v_or_b32_e32 v2, v211, v208
	s_sub_i32 s0, s1, s0
	v_lshl_or_b32 v0, v2, 6, v0
	v_lshl_add_u32 v2, s0, 7, v10
	v_ashrrev_i32_e32 v3, 31, v2
	v_add_u32_e32 v212, 0x2000, v0
	v_bitop3_b32 v0, v186, 3, v11 bitop3:0x48
	v_lshlrev_b64 v[2:3], 6, v[2:3]
	v_mov_b32_e32 v6, 0
	s_mov_b32 s8, 0
	s_mov_b32 s42, 2
	s_mov_b64 s[30:31], 0x1000
	v_lshlrev_b32_e32 v0, 4, v0
	v_lshl_add_u64 v[182:183], v[180:181], 0, v[4:5]
	v_lshl_add_u64 v[184:185], v[130:131], 0, v[2:3]
	s_mov_b32 s43, 0
; #define RAW_BARRIER() do { asm volatile("s_waitcnt lgkmcnt(0)" ::: "memory"); __builtin_amdgcn_s_barrier(); } while (0)
; template <int EPI, int NB>
; DEVI void gemm_tile(const GemmJob& J, int m0, int n0, unsigned char* smem) {
;     ...
;   f32x4 acc[4][NB];
; #pragma unroll
;   for (int i = 0; i < 4; ++i)
; #pragma unroll
;     for (int j = 0; j < NB; ++j) acc[i][j] = (f32x4){0.f, 0.f, 0.f, 0.f};
;   const int srow = tid >> 2, sch = tid & 3;
;   const int gch = sch ^ ((0 - (tid >> 4)) & 3);
;   const bf16_t* Ag = J.A + (size_t)(m0 + srow) * (J.ablk ? 32 : J.lda) + gch * 8;
;   const bf16_t* Bg = J.Bt + (size_t)(n0 + srow) * 32 + gch * 8;
;   const size_t Astep = (size_t)64 * (J.ablk ? 32 : J.lda), Ak = J.ablk ? (size_t)MROWS * 32 : (size_t)32, Bstep = (size_t)64 * 32, Bk = (size_t)J.NR * 32;
;   const int nk = J.K >> 5;
;   unsigned char* lds_t = smem + tid * 16;
;   const unsigned lbase = (unsigned)(uintptr_t)(__attribute__((address_space(3))) unsigned char*)smem;
;     ...
;   asm volatile("s_waitcnt vmcnt(0)" ::: "memory");
;   RAW_BARRIER();
; #pragma unroll
;   for (int st = 0; st < S - 1; ++st) GEMM_ISSUE(st, st);
;   const int fsl = (g ^ ((0 - (l16 >> 2)) & 3)) << 4;
;   const int aofs = (wm * 64 + l16) * 64 + fsl;
;   const int bofs = A_BYTES + (wn * NB * 16 + l16) * 64 + fsl;
;   int cs = 0, is = S - 1;
; #pragma clang loop unroll(disable)
;   for (int kt = 0; kt < nk; ++kt) {
;     if (nk - 1 - kt >= S - 2) {
;       if constexpr (NB == 8) asm volatile("s_waitcnt vmcnt(6)" ::: "memory");
;       else                   asm volatile("s_waitcnt vmcnt(8)" ::: "memory");
;     } else {
;       asm volatile("s_waitcnt vmcnt(0)" ::: "memory");
;     }
;     RAW_BARRIER();
;     if (kt + S - 1 < nk) GEMM_ISSUE(kt + S - 1, is);
;     is = (is + 1 == S) ? 0 : is + 1;
;     const unsigned cur = lbase + cs * STG;
;     cs = (cs + 1 == S) ? 0 : cs + 1;
;     bf16x8 af[4], bfr[NB];
;     const unsigned aa = cur + aofs, ba = cur + bofs;
	v_mov_b32_e32 v7, v6
	v_mov_b32_e32 v8, v6
	v_mov_b32_e32 v9, v6
	v_mov_b32_e32 v14, v6
	v_mov_b32_e32 v15, v6
	v_mov_b32_e32 v16, v6
	v_mov_b32_e32 v17, v6
	v_mov_b32_e32 v2, v6
	v_mov_b32_e32 v3, v6
	v_mov_b32_e32 v4, v6
	v_mov_b32_e32 v5, v6
	v_mov_b32_e32 v10, v6
	v_mov_b32_e32 v11, v6
	v_mov_b32_e32 v12, v6
	v_mov_b32_e32 v13, v6
	v_mov_b32_e32 v22, v6
	v_mov_b32_e32 v23, v6
	v_mov_b32_e32 v24, v6
	v_mov_b32_e32 v25, v6
	v_mov_b32_e32 v30, v6
	v_mov_b32_e32 v31, v6
	v_mov_b32_e32 v32, v6
	v_mov_b32_e32 v33, v6
	v_mov_b32_e32 v18, v6
	v_mov_b32_e32 v19, v6
	v_mov_b32_e32 v20, v6
	v_mov_b32_e32 v21, v6
	v_mov_b32_e32 v26, v6
	v_mov_b32_e32 v27, v6
	v_mov_b32_e32 v28, v6
	v_mov_b32_e32 v29, v6
	v_mov_b32_e32 v38, v6
	v_mov_b32_e32 v39, v6
	v_mov_b32_e32 v40, v6
	v_mov_b32_e32 v41, v6
	v_mov_b32_e32 v46, v6
	v_mov_b32_e32 v47, v6
	v_mov_b32_e32 v48, v6
	v_mov_b32_e32 v49, v6
	v_mov_b32_e32 v34, v6
	v_mov_b32_e32 v35, v6
	v_mov_b32_e32 v36, v6
	v_mov_b32_e32 v37, v6
	v_mov_b32_e32 v42, v6
	v_mov_b32_e32 v43, v6
	v_mov_b32_e32 v44, v6
	v_mov_b32_e32 v45, v6
	v_mov_b32_e32 v54, v6
	v_mov_b32_e32 v55, v6
	v_mov_b32_e32 v56, v6
	v_mov_b32_e32 v57, v6
	v_mov_b32_e32 v62, v6
	v_mov_b32_e32 v63, v6
	v_mov_b32_e32 v64, v6
	v_mov_b32_e32 v65, v6
	v_mov_b32_e32 v50, v6
	v_mov_b32_e32 v51, v6
	v_mov_b32_e32 v52, v6
	v_mov_b32_e32 v53, v6
	v_mov_b32_e32 v58, v6
	v_mov_b32_e32 v59, v6
	v_mov_b32_e32 v60, v6
	v_mov_b32_e32 v61, v6
	v_mov_b32_e32 v70, v6
	v_mov_b32_e32 v71, v6
	v_mov_b32_e32 v72, v6
	v_mov_b32_e32 v73, v6
	v_mov_b32_e32 v78, v6
	v_mov_b32_e32 v79, v6
	v_mov_b32_e32 v80, v6
	v_mov_b32_e32 v81, v6
	v_mov_b32_e32 v66, v6
	v_mov_b32_e32 v67, v6
	v_mov_b32_e32 v68, v6
	v_mov_b32_e32 v69, v6
	v_mov_b32_e32 v74, v6
	v_mov_b32_e32 v75, v6
	v_mov_b32_e32 v76, v6
	v_mov_b32_e32 v77, v6
	v_mov_b32_e32 v86, v6
	v_mov_b32_e32 v87, v6
	v_mov_b32_e32 v88, v6
	v_mov_b32_e32 v89, v6
	v_mov_b32_e32 v94, v6
	v_mov_b32_e32 v95, v6
	v_mov_b32_e32 v96, v6
	v_mov_b32_e32 v97, v6
	v_mov_b32_e32 v82, v6
	v_mov_b32_e32 v83, v6
	v_mov_b32_e32 v84, v6
	v_mov_b32_e32 v85, v6
	v_mov_b32_e32 v90, v6
	v_mov_b32_e32 v91, v6
	v_mov_b32_e32 v92, v6
	v_mov_b32_e32 v93, v6
	v_mov_b32_e32 v102, v6
	v_mov_b32_e32 v103, v6
	v_mov_b32_e32 v104, v6
	v_mov_b32_e32 v105, v6
	v_mov_b32_e32 v110, v6
	v_mov_b32_e32 v111, v6
	v_mov_b32_e32 v112, v6
	v_mov_b32_e32 v113, v6
	v_mov_b32_e32 v98, v6
	v_mov_b32_e32 v99, v6
	v_mov_b32_e32 v100, v6
	v_mov_b32_e32 v101, v6
	v_mov_b32_e32 v106, v6
	v_mov_b32_e32 v107, v6
	v_mov_b32_e32 v108, v6
	v_mov_b32_e32 v109, v6
	v_mov_b32_e32 v118, v6
	v_mov_b32_e32 v119, v6
	v_mov_b32_e32 v120, v6
	v_mov_b32_e32 v121, v6
	v_mov_b32_e32 v126, v6
	v_mov_b32_e32 v127, v6
	v_mov_b32_e32 v128, v6
	v_mov_b32_e32 v129, v6
	v_mov_b32_e32 v114, v6
	v_mov_b32_e32 v115, v6
	v_mov_b32_e32 v116, v6
	v_mov_b32_e32 v117, v6
	v_mov_b32_e32 v122, v6
	v_mov_b32_e32 v123, v6
	v_mov_b32_e32 v124, v6
	v_mov_b32_e32 v125, v6
	s_mul_i32 s0, s42, 0x6000
	v_add_u32_e32 v213, s0, v187
	v_lshl_add_u64 v[214:215], v[184:185], 0, v[0:1]
	v_readfirstlane_b32 s0, v213
	v_lshl_add_u64 v[216:217], v[214:215], 0, s[84:85]
	s_mov_b32 m0, s0
	v_lshl_add_u64 v[214:215], v[214:215], 0, s[12:13]
	s_nop 0
	v_readfirstlane_b32 s100, v216
	v_readfirstlane_b32 s101, v217
	s_nop 1
	v_subrev_u32_e32 v230, s100, v216
	v_add_u32_e32 v216, 0x1000, v213
	v_add_u32_e32 v218, 0x2000, v213
	v_readfirstlane_b32 s0, v216
	s_mov_b32 m0, s0
	s_mov_b64 s[0:1], 0x256000
	v_subrev_u32_e32 v231, s100, v214
	v_lshl_add_u64 v[214:215], v[182:183], 0, v[0:1]
	v_lshl_add_u64 v[216:217], v[214:215], 0, s[0:1]
	v_readfirstlane_b32 s0, v218
	s_mov_b32 m0, s0
	s_mov_b64 s[0:1], 0x257000
	v_add_u32_e32 v218, 0x3000, v213
	s_nop 0
	v_readfirstlane_b32 vcc_lo, v216
	v_readfirstlane_b32 vcc_hi, v217
	s_nop 1
	v_subrev_u32_e32 v232, vcc_lo, v216
	v_lshl_add_u64 v[216:217], v[214:215], 0, s[0:1]
	v_readfirstlane_b32 s0, v218
	s_mov_b32 m0, s0
	s_mov_b64 s[0:1], 0x258000
	v_add_u32_e32 v218, 0x4000, v213
	v_subrev_u32_e32 v233, vcc_lo, v216
	v_lshl_add_u64 v[216:217], v[214:215], 0, s[0:1]
	v_readfirstlane_b32 s0, v218
	s_mov_b32 m0, s0
	s_mov_b64 s[0:1], 0x259000
	v_add_u32_e32 v213, 0x5000, v213
	v_lshl_add_u64 v[214:215], v[214:215], 0, s[0:1]
	v_readfirstlane_b32 s0, v213
	v_subrev_u32_e32 v234, vcc_lo, v216
	s_mov_b32 m0, s0
	s_nop 0
	v_subrev_u32_e32 v235, vcc_lo, v214
	v_mov_b32_e32 v184, v230
	v_mov_b32_e32 v185, v231
	v_mov_b32_e32 v182, v232
	v_mov_b32_e32 v183, v233
	v_mov_b32_e32 v253, v234
	v_mov_b32_e32 v254, v235
	v_readfirstlane_b32 s0, v187
	s_branch .LBB0_167
	.p2align	6

; DEVI int otid() { int t = threadIdx.x; asm volatile("" : "+v"(t)); return t; }
; #define RAW_BARRIER() do { asm volatile("s_waitcnt lgkmcnt(0)" ::: "memory"); __builtin_amdgcn_s_barrier(); } while (0)
; template <int EPI, int NB>
; DEVI void gemm_tile(const GemmJob& J, int m0, int n0, unsigned char* smem) {
;     ...
;   const int tid = otid(), lane = tid & 63, wid = tid >> 6, wm = wid >> 1, wn = wid & 1;
;   const int l16 = lane & 15, g = lane >> 4;
;   f32x4 acc[4][NB];
; #pragma unroll
;   for (int i = 0; i < 4; ++i)
; #pragma unroll
;     for (int j = 0; j < NB; ++j) acc[i][j] = (f32x4){0.f, 0.f, 0.f, 0.f};
;   const int srow = tid >> 2, sch = tid & 3;
;   const int gch = sch ^ ((0 - (tid >> 4)) & 3);
;   const bf16_t* Ag = J.A + (size_t)(m0 + srow) * (J.ablk ? 32 : J.lda) + gch * 8;
;   const bf16_t* Bg = J.Bt + (size_t)(n0 + srow) * 32 + gch * 8;
;   const size_t Astep = (size_t)64 * (J.ablk ? 32 : J.lda), Ak = J.ablk ? (size_t)MROWS * 32 : (size_t)32, Bstep = (size_t)64 * 32, Bk = (size_t)J.NR * 32;
;   const int nk = J.K >> 5;
;   unsigned char* lds_t = smem + tid * 16;
;   const unsigned lbase = (unsigned)(uintptr_t)(__attribute__((address_space(3))) unsigned char*)smem;
;     ...
;   asm volatile("s_waitcnt vmcnt(0)" ::: "memory");
;   RAW_BARRIER();
; #pragma unroll
;   for (int st = 0; st < S - 1; ++st) GEMM_ISSUE(st, st);
;   const int fsl = (g ^ ((0 - (l16 >> 2)) & 3)) << 4;
;   const int aofs = (wm * 64 + l16) * 64 + fsl;
;   const int bofs = A_BYTES + (wn * NB * 16 + l16) * 64 + fsl;
;   int cs = 0, is = S - 1;
; template <int EPI, int NB>
; DEVI void gemm_run(const GemmJob& J, unsigned char* smem, int rot) {
;     ...
;     for (int t = b; t < ntiles; t += G) {
;       const int mt = t / J.ntn, nt = J.nt0 + (t - mt * J.ntn);
;       gemm_tile<EPI, NB>(J, mt * 128, nt * BN, smem);
.LBB0_229:
	s_ashr_i32 s0, s9, 31
	s_lshr_b32 s0, s0, 30
	s_add_i32 s0, s9, s0
	s_ashr_i32 s0, s0, 2
	s_lshl_b32 s3, s0, 7
	s_lshl_b32 s0, s0, 10
	s_lshl_b32 s1, s9, 8
	v_mov_b32_e32 v208, v177
	s_sub_i32 s2, s1, s0
	s_nop 0
	s_mov_b64 s[28:29], 0x1000
	v_ashrrev_i32_e32 v10, 2, v208
	v_lshrrev_b32_e32 v0, 4, v208
	v_sub_u32_e32 v11, 0, v0
	v_add_u32_e32 v2, s3, v10
	v_add_u32_e32 v6, s2, v10
	v_xor_b32_e32 v0, v208, v11
	v_ashrrev_i32_e32 v3, 31, v2
	v_ashrrev_i32_e32 v7, 31, v6
	v_lshlrev_b64 v[2:3], 6, v[2:3]
	v_lshlrev_b32_e32 v0, 4, v0
	v_lshlrev_b64 v[6:7], 6, v[6:7]
	v_lshl_add_u64 v[4:5], v[152:153], 0, v[2:3]
	v_and_b32_e32 v0, 48, v0
	v_lshl_add_u64 v[6:7], v[180:181], 0, v[6:7]
	v_lshlrev_b32_e32 v209, 4, v208
	v_lshl_add_u64 v[4:5], v[4:5], 0, v[0:1]
	v_lshl_add_u64 v[6:7], v[6:7], 0, v[0:1]
	v_readfirstlane_b32 s1, v209
	v_add_u32_e32 v0, 0x1000, v209
	s_mov_b32 m0, s1
	v_readfirstlane_b32 s1, v0
	v_add_u32_e32 v0, 0x2000, v209
	s_waitcnt lgkmcnt(0)
	s_barrier
	global_load_lds_dwordx4 v[4:5], off
	v_lshl_add_u64 v[8:9], v[4:5], 0, s[28:29]
	s_mov_b32 m0, s1
	v_readfirstlane_b32 s1, v0
	v_add_u32_e32 v0, 0x3000, v209
	global_load_lds_dwordx4 v[8:9], off
	s_mov_b32 m0, s1
	v_readfirstlane_b32 s1, v0
	v_add_u32_e32 v0, 0x4000, v209
	global_load_lds_dwordx4 v[6:7], off
	v_lshl_add_u64 v[8:9], v[6:7], 0, s[28:29]
	s_mov_b32 m0, s1
	s_mov_b64 s[28:29], 0x2000
	v_readfirstlane_b32 s1, v0
	v_add_u32_e32 v0, 0x5000, v209
	global_load_lds_dwordx4 v[8:9], off
	v_lshl_add_u64 v[8:9], v[6:7], 0, s[28:29]
	s_mov_b32 m0, s1
	s_mov_b64 s[28:29], 0x3000
	v_readfirstlane_b32 s1, v0
	v_add_u32_e32 v0, 0x6000, v209
	global_load_lds_dwordx4 v[8:9], off
	v_lshl_add_u64 v[8:9], v[6:7], 0, s[28:29]
	s_mov_b32 m0, s1
	v_readfirstlane_b32 s1, v0
	v_add_u32_e32 v0, 0x7000, v209
	global_load_lds_dwordx4 v[8:9], off
	v_lshl_add_u64 v[8:9], v[4:5], 0, s[94:95]
	s_mov_b32 m0, s1
	s_mov_b64 s[28:29], 0x30b000
	v_readfirstlane_b32 s1, v0
	v_add_u32_e32 v0, 0x8000, v209
	global_load_lds_dwordx4 v[8:9], off
	v_lshl_add_u64 v[4:5], v[4:5], 0, s[28:29]
	s_mov_b32 m0, s1
	v_readfirstlane_b32 s1, v0
	v_add_u32_e32 v0, 0x9000, v209
	global_load_lds_dwordx4 v[4:5], off
	v_lshl_add_u64 v[4:5], v[6:7], 0, s[22:23]
	s_mov_b32 m0, s1
	s_mov_b64 s[28:29], 0x11000
	v_readfirstlane_b32 s1, v0
	v_add_u32_e32 v0, 0xa000, v209
	global_load_lds_dwordx4 v[4:5], off
	v_lshl_add_u64 v[4:5], v[6:7], 0, s[28:29]
	s_mov_b32 m0, s1
	s_mov_b64 s[28:29], 0x12000
	v_readfirstlane_b32 s1, v0
	v_add_u32_e32 v0, 0xb000, v209
	global_load_lds_dwordx4 v[4:5], off
	v_lshl_add_u64 v[4:5], v[6:7], 0, s[28:29]
	s_mov_b32 m0, s1
	s_mov_b64 s[28:29], 0x13000
	v_readfirstlane_b32 s1, v0
	global_load_lds_dwordx4 v[4:5], off
	v_lshl_add_u64 v[4:5], v[6:7], 0, s[28:29]
	s_mov_b32 m0, s1
	v_lshlrev_b32_e32 v0, 2, v208
	global_load_lds_dwordx4 v[4:5], off
	v_and_b32_e32 v0, 48, v0
	v_ashrrev_i32_e32 v4, 1, v208
	v_and_b32_e32 v210, 15, v208
	v_sub_u32_e32 v0, 0, v0
	v_and_b32_e32 v211, 0xffffffc0, v4
	v_bitop3_b32 v0, v208, 48, v0 bitop3:0x48
	v_or_b32_e32 v4, v211, v210
	v_lshl_or_b32 v213, v4, 6, v0
	v_lshlrev_b32_e32 v4, 1, v208
	v_and_b32_e32 v212, 0x80, v4
	v_or_b32_e32 v4, v212, v210
	v_lshl_or_b32 v0, v4, 6, v0
	v_add_u32_e32 v4, s8, v10
	v_subrev_u32_e32 v4, s0, v4
	v_ashrrev_i32_e32 v5, 31, v4
	v_add_u32_e32 v214, 0x2000, v0
	v_bitop3_b32 v0, v208, 3, v11 bitop3:0x48
	v_lshlrev_b64 v[4:5], 6, v[4:5]
	v_lshl_add_u64 v[186:187], v[130:131], 0, v[2:3]
	v_mov_b32_e32 v2, 0
	s_mov_b32 s42, 2
	s_mov_b32 s20, 0
	s_mov_b64 s[30:31], 0x1000
	v_lshlrev_b32_e32 v0, 4, v0
	v_lshl_add_u64 v[184:185], v[182:183], 0, v[4:5]
	s_mov_b32 s43, 0
	v_mov_b32_e32 v3, v2
	v_mov_b32_e32 v4, v2
	v_mov_b32_e32 v5, v2
	v_mov_b32_e32 v6, v2
	v_mov_b32_e32 v7, v2
	v_mov_b32_e32 v8, v2
	v_mov_b32_e32 v9, v2
	v_mov_b32_e32 v10, v2
	v_mov_b32_e32 v11, v2
	v_mov_b32_e32 v12, v2
	v_mov_b32_e32 v13, v2
	v_mov_b32_e32 v14, v2
	v_mov_b32_e32 v15, v2
	v_mov_b32_e32 v16, v2
	v_mov_b32_e32 v17, v2
	v_mov_b32_e32 v18, v2
	v_mov_b32_e32 v19, v2
	v_mov_b32_e32 v20, v2
	v_mov_b32_e32 v21, v2
	v_mov_b32_e32 v22, v2
	v_mov_b32_e32 v23, v2
; #define RAW_BARRIER() do { asm volatile("s_waitcnt lgkmcnt(0)" ::: "memory"); __builtin_amdgcn_s_barrier(); } while (0)
; template <int EPI, int NB>
; DEVI void gemm_tile(const GemmJob& J, int m0, int n0, unsigned char* smem) {
;     ...
;   f32x4 acc[4][NB];
; #pragma unroll
;   for (int i = 0; i < 4; ++i)
; #pragma unroll
;     for (int j = 0; j < NB; ++j) acc[i][j] = (f32x4){0.f, 0.f, 0.f, 0.f};
;   const int srow = tid >> 2, sch = tid & 3;
;   const int gch = sch ^ ((0 - (tid >> 4)) & 3);
;   const bf16_t* Ag = J.A + (size_t)(m0 + srow) * (J.ablk ? 32 : J.lda) + gch * 8;
;   const bf16_t* Bg = J.Bt + (size_t)(n0 + srow) * 32 + gch * 8;
;   const size_t Astep = (size_t)64 * (J.ablk ? 32 : J.lda), Ak = J.ablk ? (size_t)MROWS * 32 : (size_t)32, Bstep = (size_t)64 * 32, Bk = (size_t)J.NR * 32;
;   const int nk = J.K >> 5;
;   unsigned char* lds_t = smem + tid * 16;
;   const unsigned lbase = (unsigned)(uintptr_t)(__attribute__((address_space(3))) unsigned char*)smem;
;     ...
;   asm volatile("s_waitcnt vmcnt(0)" ::: "memory");
;   RAW_BARRIER();
; #pragma unroll
;   for (int st = 0; st < S - 1; ++st) GEMM_ISSUE(st, st);
;   const int fsl = (g ^ ((0 - (l16 >> 2)) & 3)) << 4;
;   const int aofs = (wm * 64 + l16) * 64 + fsl;
;   const int bofs = A_BYTES + (wn * NB * 16 + l16) * 64 + fsl;
;   int cs = 0, is = S - 1;
; #pragma clang loop unroll(disable)
;   for (int kt = 0; kt < nk; ++kt) {
;     if (nk - 1 - kt >= S - 2) {
;       if constexpr (NB == 8) asm volatile("s_waitcnt vmcnt(6)" ::: "memory");
;       else                   asm volatile("s_waitcnt vmcnt(8)" ::: "memory");
;     } else {
;       asm volatile("s_waitcnt vmcnt(0)" ::: "memory");
;     }
;     RAW_BARRIER();
;     if (kt + S - 1 < nk) GEMM_ISSUE(kt + S - 1, is);
;     is = (is + 1 == S) ? 0 : is + 1;
;     const unsigned cur = lbase + cs * STG;
;     cs = (cs + 1 == S) ? 0 : cs + 1;
;     bf16x8 af[4], bfr[NB];
;     const unsigned aa = cur + aofs, ba = cur + bofs;
	v_mov_b32_e32 v24, v2
	v_mov_b32_e32 v25, v2
	v_mov_b32_e32 v26, v2
	v_mov_b32_e32 v27, v2
	v_mov_b32_e32 v28, v2
	v_mov_b32_e32 v29, v2
	v_mov_b32_e32 v30, v2
	v_mov_b32_e32 v31, v2
	v_mov_b32_e32 v32, v2
	v_mov_b32_e32 v33, v2
	v_mov_b32_e32 v34, v2
	v_mov_b32_e32 v35, v2
	v_mov_b32_e32 v36, v2
	v_mov_b32_e32 v37, v2
	v_mov_b32_e32 v38, v2
	v_mov_b32_e32 v39, v2
	v_mov_b32_e32 v40, v2
	v_mov_b32_e32 v41, v2
	v_mov_b32_e32 v42, v2
	v_mov_b32_e32 v43, v2
	v_mov_b32_e32 v44, v2
	v_mov_b32_e32 v45, v2
	v_mov_b32_e32 v46, v2
	v_mov_b32_e32 v47, v2
	v_mov_b32_e32 v48, v2
	v_mov_b32_e32 v49, v2
	v_mov_b32_e32 v50, v2
	v_mov_b32_e32 v51, v2
	v_mov_b32_e32 v52, v2
	v_mov_b32_e32 v53, v2
	v_mov_b32_e32 v54, v2
	v_mov_b32_e32 v55, v2
	v_mov_b32_e32 v56, v2
	v_mov_b32_e32 v57, v2
	v_mov_b32_e32 v58, v2
	v_mov_b32_e32 v59, v2
	v_mov_b32_e32 v60, v2
	v_mov_b32_e32 v61, v2
	v_mov_b32_e32 v62, v2
	v_mov_b32_e32 v63, v2
	v_mov_b32_e32 v64, v2
	v_mov_b32_e32 v65, v2
	v_mov_b32_e32 v66, v2
	v_mov_b32_e32 v67, v2
	v_mov_b32_e32 v68, v2
	v_mov_b32_e32 v69, v2
	v_mov_b32_e32 v70, v2
	v_mov_b32_e32 v71, v2
	v_mov_b32_e32 v72, v2
	v_mov_b32_e32 v73, v2
	v_mov_b32_e32 v74, v2
	v_mov_b32_e32 v75, v2
	v_mov_b32_e32 v76, v2
	v_mov_b32_e32 v77, v2
	v_mov_b32_e32 v78, v2
	v_mov_b32_e32 v79, v2
	v_mov_b32_e32 v80, v2
	v_mov_b32_e32 v81, v2
	v_mov_b32_e32 v82, v2
	v_mov_b32_e32 v83, v2
	v_mov_b32_e32 v84, v2
	v_mov_b32_e32 v85, v2
	v_mov_b32_e32 v86, v2
	v_mov_b32_e32 v87, v2
	v_mov_b32_e32 v88, v2
	v_mov_b32_e32 v89, v2
	v_mov_b32_e32 v90, v2
	v_mov_b32_e32 v91, v2
	v_mov_b32_e32 v92, v2
	v_mov_b32_e32 v93, v2
	v_mov_b32_e32 v94, v2
	v_mov_b32_e32 v95, v2
	v_mov_b32_e32 v96, v2
	v_mov_b32_e32 v97, v2
	v_mov_b32_e32 v98, v2
	v_mov_b32_e32 v99, v2
	v_mov_b32_e32 v100, v2
	v_mov_b32_e32 v101, v2
	v_mov_b32_e32 v102, v2
	v_mov_b32_e32 v103, v2
	v_mov_b32_e32 v104, v2
	v_mov_b32_e32 v105, v2
	v_mov_b32_e32 v106, v2
	v_mov_b32_e32 v107, v2
	v_mov_b32_e32 v108, v2
	v_mov_b32_e32 v109, v2
	v_mov_b32_e32 v110, v2
	v_mov_b32_e32 v111, v2
	v_mov_b32_e32 v112, v2
	v_mov_b32_e32 v113, v2
	v_mov_b32_e32 v114, v2
	v_mov_b32_e32 v115, v2
	v_mov_b32_e32 v116, v2
	v_mov_b32_e32 v117, v2
	v_mov_b32_e32 v118, v2
	v_mov_b32_e32 v119, v2
	v_mov_b32_e32 v120, v2
	v_mov_b32_e32 v121, v2
	v_mov_b32_e32 v122, v2
	v_mov_b32_e32 v123, v2
	v_mov_b32_e32 v124, v2
	v_mov_b32_e32 v125, v2
	v_mov_b32_e32 v126, v2
	v_mov_b32_e32 v127, v2
	v_mov_b32_e32 v128, v2
	v_mov_b32_e32 v129, v2
	s_mul_i32 s0, s42, 0x6000
	v_add_u32_e32 v215, s0, v209
	v_lshl_add_u64 v[216:217], v[186:187], 0, v[0:1]
	v_readfirstlane_b32 s0, v215
	v_lshl_add_u64 v[218:219], v[216:217], 0, s[24:25]
	s_mov_b32 m0, s0
	v_lshl_add_u64 v[216:217], v[216:217], 0, s[26:27]
	s_nop 0
	v_readfirstlane_b32 s100, v218
	v_readfirstlane_b32 s101, v219
	s_nop 1
	v_subrev_u32_e32 v232, s100, v218
	v_add_u32_e32 v218, 0x1000, v215
	v_add_u32_e32 v220, 0x2000, v215
	v_readfirstlane_b32 s0, v218
	s_mov_b32 m0, s0
	s_mov_b64 s[0:1], 0xcc6000
	v_subrev_u32_e32 v233, s100, v216
	v_lshl_add_u64 v[216:217], v[184:185], 0, v[0:1]
	v_lshl_add_u64 v[218:219], v[216:217], 0, s[0:1]
	v_readfirstlane_b32 s0, v220
	s_mov_b32 m0, s0
	s_mov_b64 s[0:1], 0xcc7000
	v_add_u32_e32 v220, 0x3000, v215
	s_nop 0
	v_readfirstlane_b32 vcc_lo, v218
	v_readfirstlane_b32 vcc_hi, v219
	s_nop 1
	v_subrev_u32_e32 v234, vcc_lo, v218
	v_lshl_add_u64 v[218:219], v[216:217], 0, s[0:1]
	v_readfirstlane_b32 s0, v220
	s_mov_b32 m0, s0
	s_mov_b64 s[0:1], 0xcc8000
	v_add_u32_e32 v220, 0x4000, v215
	v_subrev_u32_e32 v235, vcc_lo, v218
	v_lshl_add_u64 v[218:219], v[216:217], 0, s[0:1]
	v_readfirstlane_b32 s0, v220
	s_mov_b32 m0, s0
	s_mov_b64 s[0:1], 0xcc9000
	v_add_u32_e32 v215, 0x5000, v215
	v_lshl_add_u64 v[216:217], v[216:217], 0, s[0:1]
	v_readfirstlane_b32 s0, v215
	v_subrev_u32_e32 v236, vcc_lo, v218
	s_mov_b32 m0, s0
	s_nop 0
	v_subrev_u32_e32 v237, vcc_lo, v216
	v_mov_b32_e32 v186, v232
	v_mov_b32_e32 v187, v233
	v_mov_b32_e32 v184, v234
	v_mov_b32_e32 v185, v235
	v_mov_b32_e32 v253, v236
	v_mov_b32_e32 v254, v237
	v_readfirstlane_b32 s0, v209
	s_branch .LBB0_231
	.p2align	6

; DEVI int otid() { int t = threadIdx.x; asm volatile("" : "+v"(t)); return t; }
; #define RAW_BARRIER() do { asm volatile("s_waitcnt lgkmcnt(0)" ::: "memory"); __builtin_amdgcn_s_barrier(); } while (0)
; template <int EPI, int NB>
; DEVI void gemm_tile(const GemmJob& J, int m0, int n0, unsigned char* smem) {
;     ...
;   const int tid = otid(), lane = tid & 63, wid = tid >> 6, wm = wid >> 1, wn = wid & 1;
;   const int l16 = lane & 15, g = lane >> 4;
;   f32x4 acc[4][NB];
; #pragma unroll
;   for (int i = 0; i < 4; ++i)
; #pragma unroll
;     for (int j = 0; j < NB; ++j) acc[i][j] = (f32x4){0.f, 0.f, 0.f, 0.f};
;   const int srow = tid >> 2, sch = tid & 3;
;   const int gch = sch ^ ((0 - (tid >> 4)) & 3);
;   const bf16_t* Ag = J.A + (size_t)(m0 + srow) * (J.ablk ? 32 : J.lda) + gch * 8;
;   const bf16_t* Bg = J.Bt + (size_t)(n0 + srow) * 32 + gch * 8;
;   const size_t Astep = (size_t)64 * (J.ablk ? 32 : J.lda), Ak = J.ablk ? (size_t)MROWS * 32 : (size_t)32, Bstep = (size_t)64 * 32, Bk = (size_t)J.NR * 32;
;   const int nk = J.K >> 5;
;   unsigned char* lds_t = smem + tid * 16;
;   const unsigned lbase = (unsigned)(uintptr_t)(__attribute__((address_space(3))) unsigned char*)smem;
;     ...
;   asm volatile("s_waitcnt vmcnt(0)" ::: "memory");
;   RAW_BARRIER();
; #pragma unroll
;   for (int st = 0; st < S - 1; ++st) GEMM_ISSUE(st, st);
;   const int fsl = (g ^ ((0 - (l16 >> 2)) & 3)) << 4;
;   const int aofs = (wm * 64 + l16) * 64 + fsl;
;   const int bofs = A_BYTES + (wn * NB * 16 + l16) * 64 + fsl;
;   int cs = 0, is = S - 1;
; template <int EPI, int NB>
; DEVI void gemm_run(const GemmJob& J, unsigned char* smem, int rot) {
;     ...
;     const int x = b & 7, lb = b >> 3, nlb = G >> 3;
;     const int mlo = x * 49;
;     const int mcnt = min(49, MT128 - mlo);
;     const int ntot = mcnt * J.ntn, gsz = 8 * J.ntn;
;     const int ngrp = (mcnt + 7) >> 3;
;     for (int q0 = lb; q0 < ntot; q0 += nlb) {
;       const int q = J.rev ? ntot - 1 - q0 : q0;
;       int grp = q / gsz; const int qq = q - grp * gsz;
;       const int mg = min(8, mcnt - grp * 8);
;       const int nt = qq / mg, mi = qq - nt * mg;
;       gemm_tile<EPI, NB>(J, (mlo + grp * 8 + mi) * 128, (J.nt0 + nt) * BN, smem);
.LBB0_307:
	s_not_b32 s0, s9
	s_add_i32 s0, s1, s0
	s_ashr_i32 s1, s0, 31
	s_lshr_b32 s1, s1, 27
	s_add_i32 s1, s0, s1
	s_ashr_i32 s40, s1, 5
	s_lshl_b32 s3, s40, 3
	v_readlane_b32 s2, v251, 48
	s_sub_i32 s2, s2, s3
	s_min_i32 s20, s2, 8
	s_abs_i32 s41, s20
	v_cvt_f32_u32_e32 v0, s41
	s_sub_i32 s43, 0, s41
	s_andn2_b32 s1, s1, 31
	s_sub_i32 s0, s0, s1
	v_rcp_iflag_f32_e32 v0, v0
	s_abs_i32 s1, s0
	s_xor_b32 s42, s0, s20
	s_ashr_i32 s42, s42, 31
	v_mul_f32_e32 v0, 0x4f7ffffe, v0
	v_cvt_u32_f32_e32 v0, v0
	v_mov_b32_e32 v208, v177
	s_nop 0
	v_readfirstlane_b32 s44, v0
	s_mul_i32 s43, s43, s44
	s_mul_hi_u32 s43, s44, s43
	s_add_i32 s44, s44, s43
	s_mul_hi_u32 s43, s1, s44
	s_mul_i32 s44, s43, s41
	s_sub_i32 s1, s1, s44
	s_add_i32 s45, s43, 1
	s_sub_i32 s44, s1, s41
	s_cmp_ge_u32 s1, s41
	s_cselect_b32 s43, s45, s43
	s_cselect_b32 s1, s44, s1
	s_add_i32 s44, s43, 1
	s_cmp_ge_u32 s1, s41
	s_cselect_b32 s1, s44, s43
	s_xor_b32 s1, s1, s42
	s_sub_i32 s1, s1, s42
	s_mul_i32 s41, s20, s1
	v_readlane_b32 s20, v250, 37
	s_add_i32 s3, s3, s20
	s_add_i32 s3, s3, s0
	s_sub_i32 s0, s3, s41
	s_lshl_b32 s20, s0, 7
	s_lshl_b32 s3, s1, 8
	v_ashrrev_i32_e32 v10, 2, v208
	v_lshrrev_b32_e32 v0, 4, v208
	v_sub_u32_e32 v11, 0, v0
	v_add_u32_e32 v2, s20, v10
	v_add_u32_e32 v4, s3, v10
	v_xor_b32_e32 v0, v208, v11
	v_ashrrev_i32_e32 v3, 31, v2
	v_ashrrev_i32_e32 v5, 31, v4
	v_lshlrev_b64 v[2:3], 6, v[2:3]
	v_lshlrev_b32_e32 v0, 4, v0
	v_lshlrev_b64 v[4:5], 6, v[4:5]
	v_lshl_add_u64 v[2:3], v[152:153], 0, v[2:3]
	v_and_b32_e32 v0, 48, v0
	v_lshl_add_u64 v[6:7], v[180:181], 0, v[4:5]
	v_lshlrev_b32_e32 v209, 4, v208
	v_lshl_add_u64 v[2:3], v[2:3], 0, v[0:1]
	v_lshl_add_u64 v[6:7], v[6:7], 0, v[0:1]
	v_readfirstlane_b32 s0, v209
	v_add_u32_e32 v0, 0x1000, v209
	s_mov_b32 m0, s0
	s_mov_b64 s[28:29], 0x1000
	v_readfirstlane_b32 s0, v0
	v_add_u32_e32 v0, 0x2000, v209
	s_waitcnt lgkmcnt(0)
	s_barrier
	global_load_lds_dwordx4 v[2:3], off
	v_lshl_add_u64 v[8:9], v[2:3], 0, s[28:29]
	s_mov_b32 m0, s0
	v_readfirstlane_b32 s0, v0
	v_add_u32_e32 v0, 0x3000, v209
	global_load_lds_dwordx4 v[8:9], off
	s_mov_b32 m0, s0
	v_readfirstlane_b32 s0, v0
	global_load_lds_dwordx4 v[6:7], off
	v_lshl_add_u64 v[8:9], v[6:7], 0, s[28:29]
	s_mov_b32 m0, s0
	s_mov_b64 s[0:1], 0x2000
	v_add_u32_e32 v0, 0x4000, v209
	global_load_lds_dwordx4 v[8:9], off
	v_lshl_add_u64 v[8:9], v[6:7], 0, s[0:1]
	v_readfirstlane_b32 s0, v0
	s_mov_b32 m0, s0
	s_mov_b64 s[0:1], 0x3000
	v_add_u32_e32 v0, 0x5000, v209
	global_load_lds_dwordx4 v[8:9], off
	v_lshl_add_u64 v[8:9], v[6:7], 0, s[0:1]
	v_readfirstlane_b32 s0, v0
	v_add_u32_e32 v0, 0x6000, v209
	s_mov_b32 m0, s0
	v_readfirstlane_b32 s0, v0
	global_load_lds_dwordx4 v[8:9], off
	s_mov_b32 m0, s0
	s_mov_b64 s[0:1], 0x30b000
	v_add_u32_e32 v0, 0x7000, v209
	v_lshl_add_u64 v[8:9], v[2:3], 0, s[94:95]
	v_lshl_add_u64 v[2:3], v[2:3], 0, s[0:1]
	v_readfirstlane_b32 s0, v0
	v_add_u32_e32 v0, 0x8000, v209
	global_load_lds_dwordx4 v[8:9], off
	s_mov_b32 m0, s0
	v_readfirstlane_b32 s0, v0
	global_load_lds_dwordx4 v[2:3], off
	v_lshl_add_u64 v[2:3], v[6:7], 0, s[22:23]
	s_mov_b32 m0, s0
	s_mov_b64 s[0:1], 0x11000
	v_add_u32_e32 v0, 0x9000, v209
	global_load_lds_dwordx4 v[2:3], off
	v_lshl_add_u64 v[2:3], v[6:7], 0, s[0:1]
	v_readfirstlane_b32 s0, v0
	s_mov_b32 m0, s0
	s_mov_b64 s[0:1], 0x12000
	v_add_u32_e32 v0, 0xa000, v209
	global_load_lds_dwordx4 v[2:3], off
	v_lshl_add_u64 v[2:3], v[6:7], 0, s[0:1]
	v_readfirstlane_b32 s0, v0
	s_mov_b32 m0, s0
	s_mov_b64 s[0:1], 0x13000
	v_add_u32_e32 v0, 0xb000, v209
	global_load_lds_dwordx4 v[2:3], off
	v_lshl_add_u64 v[2:3], v[6:7], 0, s[0:1]
	v_readfirstlane_b32 s0, v0
	s_mov_b32 m0, s0
	v_lshlrev_b32_e32 v0, 2, v208
	global_load_lds_dwordx4 v[2:3], off
	v_and_b32_e32 v0, 48, v0
	v_ashrrev_i32_e32 v2, 1, v208
	v_and_b32_e32 v210, 15, v208
	v_sub_u32_e32 v0, 0, v0
	v_and_b32_e32 v211, 0xffffffc0, v2
	v_bitop3_b32 v0, v208, 48, v0 bitop3:0x48
	v_or_b32_e32 v2, v211, v210
	v_lshl_or_b32 v213, v2, 6, v0
	v_lshlrev_b32_e32 v2, 1, v208
	v_and_b32_e32 v212, 0x80, v2
	s_sub_i32 s0, s8, s41
	s_mul_i32 s40, s40, 24
	v_or_b32_e32 v2, v212, v210
	s_sub_i32 s0, s0, s40
	v_lshl_or_b32 v0, v2, 6, v0
	v_lshl_add_u32 v2, s0, 7, v10
	v_ashrrev_i32_e32 v3, 31, v2
	v_lshlrev_b64 v[2:3], 6, v[2:3]
	v_add_u32_e32 v214, 0x2000, v0
	v_bitop3_b32 v0, v208, 3, v11 bitop3:0x48
	v_lshl_add_u64 v[186:187], v[130:131], 0, v[2:3]
	v_mov_b32_e32 v2, 0
	s_mov_b32 s2, 0
	s_mov_b32 s42, 2
	s_mov_b64 s[30:31], 0x1000
	v_lshlrev_b32_e32 v0, 4, v0
	v_lshl_add_u64 v[184:185], v[182:183], 0, v[4:5]
	s_mov_b32 s43, 0
; #define RAW_BARRIER() do { asm volatile("s_waitcnt lgkmcnt(0)" ::: "memory"); __builtin_amdgcn_s_barrier(); } while (0)
; template <int EPI, int NB>
; DEVI void gemm_tile(const GemmJob& J, int m0, int n0, unsigned char* smem) {
;     ...
;   f32x4 acc[4][NB];
; #pragma unroll
;   for (int i = 0; i < 4; ++i)
; #pragma unroll
;     for (int j = 0; j < NB; ++j) acc[i][j] = (f32x4){0.f, 0.f, 0.f, 0.f};
;   const int srow = tid >> 2, sch = tid & 3;
;   const int gch = sch ^ ((0 - (tid >> 4)) & 3);
;   const bf16_t* Ag = J.A + (size_t)(m0 + srow) * (J.ablk ? 32 : J.lda) + gch * 8;
;   const bf16_t* Bg = J.Bt + (size_t)(n0 + srow) * 32 + gch * 8;
;   const size_t Astep = (size_t)64 * (J.ablk ? 32 : J.lda), Ak = J.ablk ? (size_t)MROWS * 32 : (size_t)32, Bstep = (size_t)64 * 32, Bk = (size_t)J.NR * 32;
;   const int nk = J.K >> 5;
;   unsigned char* lds_t = smem + tid * 16;
;   const unsigned lbase = (unsigned)(uintptr_t)(__attribute__((address_space(3))) unsigned char*)smem;
;     ...
;   asm volatile("s_waitcnt vmcnt(0)" ::: "memory");
;   RAW_BARRIER();
; #pragma unroll
;   for (int st = 0; st < S - 1; ++st) GEMM_ISSUE(st, st);
;   const int fsl = (g ^ ((0 - (l16 >> 2)) & 3)) << 4;
;   const int aofs = (wm * 64 + l16) * 64 + fsl;
;   const int bofs = A_BYTES + (wn * NB * 16 + l16) * 64 + fsl;
;   int cs = 0, is = S - 1;
; #pragma clang loop unroll(disable)
;   for (int kt = 0; kt < nk; ++kt) {
;     if (nk - 1 - kt >= S - 2) {
;       if constexpr (NB == 8) asm volatile("s_waitcnt vmcnt(6)" ::: "memory");
;       else                   asm volatile("s_waitcnt vmcnt(8)" ::: "memory");
;     } else {
;       asm volatile("s_waitcnt vmcnt(0)" ::: "memory");
;     }
;     RAW_BARRIER();
;     if (kt + S - 1 < nk) GEMM_ISSUE(kt + S - 1, is);
;     is = (is + 1 == S) ? 0 : is + 1;
;     const unsigned cur = lbase + cs * STG;
;     cs = (cs + 1 == S) ? 0 : cs + 1;
;     bf16x8 af[4], bfr[NB];
;     const unsigned aa = cur + aofs, ba = cur + bofs;
	v_mov_b32_e32 v3, v2
	v_mov_b32_e32 v4, v2
	v_mov_b32_e32 v5, v2
	v_mov_b32_e32 v6, v2
	v_mov_b32_e32 v7, v2
	v_mov_b32_e32 v8, v2
	v_mov_b32_e32 v9, v2
	v_mov_b32_e32 v10, v2
	v_mov_b32_e32 v11, v2
	v_mov_b32_e32 v12, v2
	v_mov_b32_e32 v13, v2
	v_mov_b32_e32 v14, v2
	v_mov_b32_e32 v15, v2
	v_mov_b32_e32 v16, v2
	v_mov_b32_e32 v17, v2
	v_mov_b32_e32 v18, v2
	v_mov_b32_e32 v19, v2
	v_mov_b32_e32 v20, v2
	v_mov_b32_e32 v21, v2
	v_mov_b32_e32 v22, v2
	v_mov_b32_e32 v23, v2
	v_mov_b32_e32 v24, v2
	v_mov_b32_e32 v25, v2
	v_mov_b32_e32 v26, v2
	v_mov_b32_e32 v27, v2
	v_mov_b32_e32 v28, v2
	v_mov_b32_e32 v29, v2
	v_mov_b32_e32 v30, v2
	v_mov_b32_e32 v31, v2
	v_mov_b32_e32 v32, v2
	v_mov_b32_e32 v33, v2
	v_mov_b32_e32 v34, v2
	v_mov_b32_e32 v35, v2
	v_mov_b32_e32 v36, v2
	v_mov_b32_e32 v37, v2
	v_mov_b32_e32 v38, v2
	v_mov_b32_e32 v39, v2
	v_mov_b32_e32 v40, v2
	v_mov_b32_e32 v41, v2
	v_mov_b32_e32 v42, v2
	v_mov_b32_e32 v43, v2
	v_mov_b32_e32 v44, v2
	v_mov_b32_e32 v45, v2
	v_mov_b32_e32 v46, v2
	v_mov_b32_e32 v47, v2
	v_mov_b32_e32 v48, v2
	v_mov_b32_e32 v49, v2
	v_mov_b32_e32 v50, v2
	v_mov_b32_e32 v51, v2
	v_mov_b32_e32 v52, v2
	v_mov_b32_e32 v53, v2
	v_mov_b32_e32 v54, v2
	v_mov_b32_e32 v55, v2
	v_mov_b32_e32 v56, v2
	v_mov_b32_e32 v57, v2
	v_mov_b32_e32 v58, v2
	v_mov_b32_e32 v59, v2
	v_mov_b32_e32 v60, v2
	v_mov_b32_e32 v61, v2
	v_mov_b32_e32 v62, v2
	v_mov_b32_e32 v63, v2
	v_mov_b32_e32 v64, v2
	v_mov_b32_e32 v65, v2
	v_mov_b32_e32 v66, v2
	v_mov_b32_e32 v67, v2
	v_mov_b32_e32 v68, v2
	v_mov_b32_e32 v69, v2
	v_mov_b32_e32 v70, v2
	v_mov_b32_e32 v71, v2
	v_mov_b32_e32 v72, v2
	v_mov_b32_e32 v73, v2
	v_mov_b32_e32 v74, v2
	v_mov_b32_e32 v75, v2
	v_mov_b32_e32 v76, v2
	v_mov_b32_e32 v77, v2
	v_mov_b32_e32 v78, v2
	v_mov_b32_e32 v79, v2
	v_mov_b32_e32 v80, v2
	v_mov_b32_e32 v81, v2
	v_mov_b32_e32 v82, v2
	v_mov_b32_e32 v83, v2
	v_mov_b32_e32 v84, v2
	v_mov_b32_e32 v85, v2
	v_mov_b32_e32 v86, v2
	v_mov_b32_e32 v87, v2
	v_mov_b32_e32 v88, v2
	v_mov_b32_e32 v89, v2
	v_mov_b32_e32 v90, v2
	v_mov_b32_e32 v91, v2
	v_mov_b32_e32 v92, v2
	v_mov_b32_e32 v93, v2
	v_mov_b32_e32 v94, v2
	v_mov_b32_e32 v95, v2
	v_mov_b32_e32 v96, v2
	v_mov_b32_e32 v97, v2
	v_mov_b32_e32 v98, v2
	v_mov_b32_e32 v99, v2
	v_mov_b32_e32 v100, v2
	v_mov_b32_e32 v101, v2
	v_mov_b32_e32 v102, v2
	v_mov_b32_e32 v103, v2
	v_mov_b32_e32 v104, v2
	v_mov_b32_e32 v105, v2
	v_mov_b32_e32 v106, v2
	v_mov_b32_e32 v107, v2
	v_mov_b32_e32 v108, v2
	v_mov_b32_e32 v109, v2
	v_mov_b32_e32 v110, v2
	v_mov_b32_e32 v111, v2
	v_mov_b32_e32 v112, v2
	v_mov_b32_e32 v113, v2
	v_mov_b32_e32 v114, v2
	v_mov_b32_e32 v115, v2
	v_mov_b32_e32 v116, v2
	v_mov_b32_e32 v117, v2
	v_mov_b32_e32 v118, v2
	v_mov_b32_e32 v119, v2
	v_mov_b32_e32 v120, v2
	v_mov_b32_e32 v121, v2
	v_mov_b32_e32 v122, v2
	v_mov_b32_e32 v123, v2
	v_mov_b32_e32 v124, v2
	v_mov_b32_e32 v125, v2
	v_mov_b32_e32 v126, v2
	v_mov_b32_e32 v127, v2
	v_mov_b32_e32 v128, v2
	v_mov_b32_e32 v129, v2
	s_mul_i32 s0, s42, 0x6000
	v_add_u32_e32 v215, s0, v209
	v_lshl_add_u64 v[216:217], v[186:187], 0, v[0:1]
	v_readfirstlane_b32 s0, v215
	v_lshl_add_u64 v[218:219], v[216:217], 0, s[24:25]
	s_mov_b32 m0, s0
	v_lshl_add_u64 v[216:217], v[216:217], 0, s[26:27]
	s_nop 0
	v_readfirstlane_b32 s100, v218
	v_readfirstlane_b32 s101, v219
	s_nop 1
	v_subrev_u32_e32 v232, s100, v218
	v_add_u32_e32 v218, 0x1000, v215
	v_add_u32_e32 v220, 0x2000, v215
	v_readfirstlane_b32 s0, v218
	s_mov_b32 m0, s0
	s_mov_b64 s[0:1], 0xcc6000
	v_subrev_u32_e32 v233, s100, v216
	v_lshl_add_u64 v[216:217], v[184:185], 0, v[0:1]
	v_lshl_add_u64 v[218:219], v[216:217], 0, s[0:1]
	v_readfirstlane_b32 s0, v220
	s_mov_b32 m0, s0
	s_mov_b64 s[0:1], 0xcc7000
	v_add_u32_e32 v220, 0x3000, v215
	s_nop 0
	v_readfirstlane_b32 vcc_lo, v218
	v_readfirstlane_b32 vcc_hi, v219
	s_nop 1
	v_subrev_u32_e32 v234, vcc_lo, v218
	v_lshl_add_u64 v[218:219], v[216:217], 0, s[0:1]
	v_readfirstlane_b32 s0, v220
	s_mov_b32 m0, s0
	s_mov_b64 s[0:1], 0xcc8000
	v_add_u32_e32 v220, 0x4000, v215
	v_subrev_u32_e32 v235, vcc_lo, v218
	v_lshl_add_u64 v[218:219], v[216:217], 0, s[0:1]
	v_readfirstlane_b32 s0, v220
	s_mov_b32 m0, s0
	s_mov_b64 s[0:1], 0xcc9000
	v_add_u32_e32 v215, 0x5000, v215
	v_lshl_add_u64 v[216:217], v[216:217], 0, s[0:1]
	v_readfirstlane_b32 s0, v215
	v_subrev_u32_e32 v236, vcc_lo, v218
	s_mov_b32 m0, s0
	s_nop 0
	v_subrev_u32_e32 v237, vcc_lo, v216
	v_mov_b32_e32 v186, v232
	v_mov_b32_e32 v187, v233
	v_mov_b32_e32 v184, v234
	v_mov_b32_e32 v185, v235
	v_mov_b32_e32 v253, v236
	v_mov_b32_e32 v254, v237
	v_readfirstlane_b32 s0, v209
	s_branch .LBB0_309
	.p2align	6

; DEVI int otid() { int t = threadIdx.x; asm volatile("" : "+v"(t)); return t; }
; #define RAW_BARRIER() do { asm volatile("s_waitcnt lgkmcnt(0)" ::: "memory"); __builtin_amdgcn_s_barrier(); } while (0)
; template <int EPI, int NB>
; DEVI void gemm_tile(const GemmJob& J, int m0, int n0, unsigned char* smem) {
;     ...
;   const int tid = otid(), lane = tid & 63, wid = tid >> 6, wm = wid >> 1, wn = wid & 1;
;   const int l16 = lane & 15, g = lane >> 4;
;   f32x4 acc[4][NB];
; #pragma unroll
;   for (int i = 0; i < 4; ++i)
; #pragma unroll
;     for (int j = 0; j < NB; ++j) acc[i][j] = (f32x4){0.f, 0.f, 0.f, 0.f};
;   const int srow = tid >> 2, sch = tid & 3;
;   const int gch = sch ^ ((0 - (tid >> 4)) & 3);
;   const bf16_t* Ag = J.A + (size_t)(m0 + srow) * (J.ablk ? 32 : J.lda) + gch * 8;
;   const bf16_t* Bg = J.Bt + (size_t)(n0 + srow) * 32 + gch * 8;
;   const size_t Astep = (size_t)64 * (J.ablk ? 32 : J.lda), Ak = J.ablk ? (size_t)MROWS * 32 : (size_t)32, Bstep = (size_t)64 * 32, Bk = (size_t)J.NR * 32;
;   const int nk = J.K >> 5;
;   unsigned char* lds_t = smem + tid * 16;
;   const unsigned lbase = (unsigned)(uintptr_t)(__attribute__((address_space(3))) unsigned char*)smem;
;     ...
;   asm volatile("s_waitcnt vmcnt(0)" ::: "memory");
;   RAW_BARRIER();
; #pragma unroll
;   for (int st = 0; st < S - 1; ++st) GEMM_ISSUE(st, st);
;   const int fsl = (g ^ ((0 - (l16 >> 2)) & 3)) << 4;
;   const int aofs = (wm * 64 + l16) * 64 + fsl;
;   const int bofs = A_BYTES + (wn * NB * 16 + l16) * 64 + fsl;
;   int cs = 0, is = S - 1;
; template <int EPI, int NB>
; DEVI void gemm_run(const GemmJob& J, unsigned char* smem, int rot) {
;     ...
;     for (int t = b; t < ntiles; t += G) {
;       const int mt = t / J.ntn, nt = J.nt0 + (t - mt * J.ntn);
;       gemm_tile<EPI, NB>(J, mt * 128, nt * BN, smem);
.LBB0_527:
	s_ashr_i32 s0, s9, 31
	s_lshr_b32 s0, s0, 29
	s_add_i32 s0, s9, s0
	s_ashr_i32 s0, s0, 3
	s_lshl_b32 s3, s0, 7
	s_lshl_b32 s0, s0, 11
	s_lshl_b32 s1, s9, 8
	v_mov_b32_e32 v184, v177
	s_sub_i32 s2, s1, s0
	s_nop 0
	s_mov_b64 s[28:29], 0x1000
	v_ashrrev_i32_e32 v10, 2, v184
	v_lshrrev_b32_e32 v0, 4, v184
	v_sub_u32_e32 v11, 0, v0
	v_add_u32_e32 v2, s3, v10
	v_add_u32_e32 v6, s2, v10
	v_xor_b32_e32 v0, v184, v11
	v_ashrrev_i32_e32 v3, 31, v2
	v_ashrrev_i32_e32 v7, 31, v6
	v_lshlrev_b64 v[2:3], 6, v[2:3]
	v_lshlrev_b32_e32 v0, 4, v0
	v_lshlrev_b64 v[6:7], 6, v[6:7]
	v_lshl_add_u64 v[4:5], v[146:147], 0, v[2:3]
	v_and_b32_e32 v0, 48, v0
	v_lshl_add_u64 v[6:7], v[142:143], 0, v[6:7]
	v_lshlrev_b32_e32 v185, 4, v184
	v_lshl_add_u64 v[4:5], v[4:5], 0, v[0:1]
	v_lshl_add_u64 v[6:7], v[6:7], 0, v[0:1]
	v_readfirstlane_b32 s1, v185
	v_add_u32_e32 v0, 0x1000, v185
	s_mov_b32 m0, s1
	v_readfirstlane_b32 s1, v0
	v_add_u32_e32 v0, 0x2000, v185
	s_waitcnt lgkmcnt(0)
	s_barrier
	global_load_lds_dwordx4 v[4:5], off
	v_lshl_add_u64 v[8:9], v[4:5], 0, s[28:29]
	s_mov_b32 m0, s1
	v_readfirstlane_b32 s1, v0
	v_add_u32_e32 v0, 0x3000, v185
	global_load_lds_dwordx4 v[8:9], off
	s_mov_b32 m0, s1
	v_readfirstlane_b32 s1, v0
	v_add_u32_e32 v0, 0x4000, v185
	global_load_lds_dwordx4 v[6:7], off
	v_lshl_add_u64 v[8:9], v[6:7], 0, s[28:29]
	s_mov_b32 m0, s1
	s_mov_b64 s[28:29], 0x2000
	v_readfirstlane_b32 s1, v0
	v_add_u32_e32 v0, 0x5000, v185
	global_load_lds_dwordx4 v[8:9], off
	v_lshl_add_u64 v[8:9], v[6:7], 0, s[28:29]
	s_mov_b32 m0, s1
	s_mov_b64 s[28:29], 0x3000
	v_readfirstlane_b32 s1, v0
	v_add_u32_e32 v0, 0x6000, v185
	global_load_lds_dwordx4 v[8:9], off
	v_lshl_add_u64 v[8:9], v[6:7], 0, s[28:29]
	s_mov_b32 m0, s1
	v_readfirstlane_b32 s1, v0
	v_add_u32_e32 v0, 0x7000, v185
	global_load_lds_dwordx4 v[8:9], off
	v_lshl_add_u64 v[8:9], v[4:5], 0, s[94:95]
	s_mov_b32 m0, s1
	s_mov_b64 s[28:29], 0x30b000
	v_readfirstlane_b32 s1, v0
	v_add_u32_e32 v0, 0x8000, v185
	global_load_lds_dwordx4 v[8:9], off
	v_lshl_add_u64 v[4:5], v[4:5], 0, s[28:29]
	s_mov_b32 m0, s1
	v_readfirstlane_b32 s1, v0
	v_add_u32_e32 v0, 0x9000, v185
	global_load_lds_dwordx4 v[4:5], off
	v_lshl_add_u64 v[4:5], v[6:7], 0, s[4:5]
	s_mov_b32 m0, s1
	s_mov_b64 s[28:29], 0x31000
	v_readfirstlane_b32 s1, v0
	v_add_u32_e32 v0, 0xa000, v185
	global_load_lds_dwordx4 v[4:5], off
	v_lshl_add_u64 v[4:5], v[6:7], 0, s[28:29]
	s_mov_b32 m0, s1
	s_mov_b64 s[28:29], 0x32000
	v_readfirstlane_b32 s1, v0
	v_add_u32_e32 v0, 0xb000, v185
	global_load_lds_dwordx4 v[4:5], off
	v_lshl_add_u64 v[4:5], v[6:7], 0, s[28:29]
	s_mov_b32 m0, s1
	s_mov_b64 s[28:29], 0x33000
	v_readfirstlane_b32 s1, v0
	global_load_lds_dwordx4 v[4:5], off
	v_lshl_add_u64 v[4:5], v[6:7], 0, s[28:29]
	s_mov_b32 m0, s1
	v_lshlrev_b32_e32 v0, 2, v184
	global_load_lds_dwordx4 v[4:5], off
	v_and_b32_e32 v0, 48, v0
	v_ashrrev_i32_e32 v4, 1, v184
	v_and_b32_e32 v186, 15, v184
	v_sub_u32_e32 v0, 0, v0
	v_and_b32_e32 v187, 0xffffffc0, v4
	v_bitop3_b32 v0, v184, 48, v0 bitop3:0x48
	v_or_b32_e32 v4, v187, v186
	v_lshl_or_b32 v209, v4, 6, v0
	v_lshlrev_b32_e32 v4, 1, v184
	v_and_b32_e32 v208, 0x80, v4
	v_or_b32_e32 v4, v208, v186
	v_lshl_or_b32 v0, v4, 6, v0
	v_add_u32_e32 v4, s8, v10
	v_subrev_u32_e32 v4, s0, v4
	v_ashrrev_i32_e32 v5, 31, v4
	v_add_u32_e32 v210, 0x2000, v0
	v_bitop3_b32 v0, v184, 3, v11 bitop3:0x48
	v_lshlrev_b64 v[4:5], 6, v[4:5]
	v_lshl_add_u64 v[182:183], v[130:131], 0, v[2:3]
	v_mov_b32_e32 v2, 0
	s_mov_b32 s42, 2
	s_mov_b32 s20, 0
	s_mov_b64 s[30:31], 0x1000
	v_lshlrev_b32_e32 v0, 4, v0
	v_lshl_add_u64 v[180:181], v[130:131], 0, v[4:5]
	s_mov_b32 s43, 0
	v_mov_b32_e32 v3, v2
	v_mov_b32_e32 v4, v2
	v_mov_b32_e32 v5, v2
	v_mov_b32_e32 v6, v2
	v_mov_b32_e32 v7, v2
	v_mov_b32_e32 v8, v2
	v_mov_b32_e32 v9, v2
	v_mov_b32_e32 v10, v2
	v_mov_b32_e32 v11, v2
	v_mov_b32_e32 v12, v2
	v_mov_b32_e32 v13, v2
	v_mov_b32_e32 v14, v2
	v_mov_b32_e32 v15, v2
	v_mov_b32_e32 v16, v2
	v_mov_b32_e32 v17, v2
	v_mov_b32_e32 v18, v2
	v_mov_b32_e32 v19, v2
	v_mov_b32_e32 v20, v2
	v_mov_b32_e32 v21, v2
	v_mov_b32_e32 v22, v2
	v_mov_b32_e32 v23, v2
; #define RAW_BARRIER() do { asm volatile("s_waitcnt lgkmcnt(0)" ::: "memory"); __builtin_amdgcn_s_barrier(); } while (0)
; template <int EPI, int NB>
; DEVI void gemm_tile(const GemmJob& J, int m0, int n0, unsigned char* smem) {
;     ...
;   f32x4 acc[4][NB];
; #pragma unroll
;   for (int i = 0; i < 4; ++i)
; #pragma unroll
;     for (int j = 0; j < NB; ++j) acc[i][j] = (f32x4){0.f, 0.f, 0.f, 0.f};
;   const int srow = tid >> 2, sch = tid & 3;
;   const int gch = sch ^ ((0 - (tid >> 4)) & 3);
;   const bf16_t* Ag = J.A + (size_t)(m0 + srow) * (J.ablk ? 32 : J.lda) + gch * 8;
;   const bf16_t* Bg = J.Bt + (size_t)(n0 + srow) * 32 + gch * 8;
;   const size_t Astep = (size_t)64 * (J.ablk ? 32 : J.lda), Ak = J.ablk ? (size_t)MROWS * 32 : (size_t)32, Bstep = (size_t)64 * 32, Bk = (size_t)J.NR * 32;
;   const int nk = J.K >> 5;
;   unsigned char* lds_t = smem + tid * 16;
;   const unsigned lbase = (unsigned)(uintptr_t)(__attribute__((address_space(3))) unsigned char*)smem;
;     ...
;   asm volatile("s_waitcnt vmcnt(0)" ::: "memory");
;   RAW_BARRIER();
; #pragma unroll
;   for (int st = 0; st < S - 1; ++st) GEMM_ISSUE(st, st);
;   const int fsl = (g ^ ((0 - (l16 >> 2)) & 3)) << 4;
;   const int aofs = (wm * 64 + l16) * 64 + fsl;
;   const int bofs = A_BYTES + (wn * NB * 16 + l16) * 64 + fsl;
;   int cs = 0, is = S - 1;
; #pragma clang loop unroll(disable)
;   for (int kt = 0; kt < nk; ++kt) {
;     if (nk - 1 - kt >= S - 2) {
;       if constexpr (NB == 8) asm volatile("s_waitcnt vmcnt(6)" ::: "memory");
;       else                   asm volatile("s_waitcnt vmcnt(8)" ::: "memory");
;     } else {
;       asm volatile("s_waitcnt vmcnt(0)" ::: "memory");
;     }
;     RAW_BARRIER();
;     if (kt + S - 1 < nk) GEMM_ISSUE(kt + S - 1, is);
;     is = (is + 1 == S) ? 0 : is + 1;
;     const unsigned cur = lbase + cs * STG;
;     cs = (cs + 1 == S) ? 0 : cs + 1;
;     bf16x8 af[4], bfr[NB];
;     const unsigned aa = cur + aofs, ba = cur + bofs;
	v_mov_b32_e32 v24, v2
	v_mov_b32_e32 v25, v2
	v_mov_b32_e32 v26, v2
	v_mov_b32_e32 v27, v2
	v_mov_b32_e32 v28, v2
	v_mov_b32_e32 v29, v2
	v_mov_b32_e32 v30, v2
	v_mov_b32_e32 v31, v2
	v_mov_b32_e32 v32, v2
	v_mov_b32_e32 v33, v2
	v_mov_b32_e32 v34, v2
	v_mov_b32_e32 v35, v2
	v_mov_b32_e32 v36, v2
	v_mov_b32_e32 v37, v2
	v_mov_b32_e32 v38, v2
	v_mov_b32_e32 v39, v2
	v_mov_b32_e32 v40, v2
	v_mov_b32_e32 v41, v2
	v_mov_b32_e32 v42, v2
	v_mov_b32_e32 v43, v2
	v_mov_b32_e32 v44, v2
	v_mov_b32_e32 v45, v2
	v_mov_b32_e32 v46, v2
	v_mov_b32_e32 v47, v2
	v_mov_b32_e32 v48, v2
	v_mov_b32_e32 v49, v2
	v_mov_b32_e32 v50, v2
	v_mov_b32_e32 v51, v2
	v_mov_b32_e32 v52, v2
	v_mov_b32_e32 v53, v2
	v_mov_b32_e32 v54, v2
	v_mov_b32_e32 v55, v2
	v_mov_b32_e32 v56, v2
	v_mov_b32_e32 v57, v2
	v_mov_b32_e32 v58, v2
	v_mov_b32_e32 v59, v2
	v_mov_b32_e32 v60, v2
	v_mov_b32_e32 v61, v2
	v_mov_b32_e32 v62, v2
	v_mov_b32_e32 v63, v2
	v_mov_b32_e32 v64, v2
	v_mov_b32_e32 v65, v2
	v_mov_b32_e32 v66, v2
	v_mov_b32_e32 v67, v2
	v_mov_b32_e32 v68, v2
	v_mov_b32_e32 v69, v2
	v_mov_b32_e32 v70, v2
	v_mov_b32_e32 v71, v2
	v_mov_b32_e32 v72, v2
	v_mov_b32_e32 v73, v2
	v_mov_b32_e32 v74, v2
	v_mov_b32_e32 v75, v2
	v_mov_b32_e32 v76, v2
	v_mov_b32_e32 v77, v2
	v_mov_b32_e32 v78, v2
	v_mov_b32_e32 v79, v2
	v_mov_b32_e32 v80, v2
	v_mov_b32_e32 v81, v2
	v_mov_b32_e32 v82, v2
	v_mov_b32_e32 v83, v2
	v_mov_b32_e32 v84, v2
	v_mov_b32_e32 v85, v2
	v_mov_b32_e32 v86, v2
	v_mov_b32_e32 v87, v2
	v_mov_b32_e32 v88, v2
	v_mov_b32_e32 v89, v2
	v_mov_b32_e32 v90, v2
	v_mov_b32_e32 v91, v2
	v_mov_b32_e32 v92, v2
	v_mov_b32_e32 v93, v2
	v_mov_b32_e32 v94, v2
	v_mov_b32_e32 v95, v2
	v_mov_b32_e32 v96, v2
	v_mov_b32_e32 v97, v2
	v_mov_b32_e32 v98, v2
	v_mov_b32_e32 v99, v2
	v_mov_b32_e32 v100, v2
	v_mov_b32_e32 v101, v2
	v_mov_b32_e32 v102, v2
	v_mov_b32_e32 v103, v2
	v_mov_b32_e32 v104, v2
	v_mov_b32_e32 v105, v2
	v_mov_b32_e32 v106, v2
	v_mov_b32_e32 v107, v2
	v_mov_b32_e32 v108, v2
	v_mov_b32_e32 v109, v2
	v_mov_b32_e32 v110, v2
	v_mov_b32_e32 v111, v2
	v_mov_b32_e32 v112, v2
	v_mov_b32_e32 v113, v2
	v_mov_b32_e32 v114, v2
	v_mov_b32_e32 v115, v2
	v_mov_b32_e32 v116, v2
	v_mov_b32_e32 v117, v2
	v_mov_b32_e32 v118, v2
	v_mov_b32_e32 v119, v2
	v_mov_b32_e32 v120, v2
	v_mov_b32_e32 v121, v2
	v_mov_b32_e32 v122, v2
	v_mov_b32_e32 v123, v2
	v_mov_b32_e32 v124, v2
	v_mov_b32_e32 v125, v2
	v_mov_b32_e32 v126, v2
	v_mov_b32_e32 v127, v2
	v_mov_b32_e32 v128, v2
	v_mov_b32_e32 v129, v2
	s_mul_i32 s0, s42, 0x6000
	v_add_u32_e32 v211, s0, v185
	v_lshl_add_u64 v[212:213], v[182:183], 0, v[0:1]
	v_readfirstlane_b32 s0, v211
	v_lshl_add_u64 v[214:215], v[212:213], 0, s[84:85]
	s_mov_b32 m0, s0
	v_lshl_add_u64 v[212:213], v[212:213], 0, s[12:13]
	s_nop 0
	v_readfirstlane_b32 s100, v214
	v_readfirstlane_b32 s101, v215
	s_nop 1
	v_subrev_u32_e32 v228, s100, v214
	v_add_u32_e32 v214, 0x1000, v211
	v_add_u32_e32 v216, 0x2000, v211
	v_readfirstlane_b32 s0, v214
	s_mov_b32 m0, s0
	s_mov_b64 s[0:1], 0x49a6000
	v_subrev_u32_e32 v229, s100, v212
	v_lshl_add_u64 v[212:213], v[180:181], 0, v[0:1]
	v_lshl_add_u64 v[214:215], v[212:213], 0, s[0:1]
	v_readfirstlane_b32 s0, v216
	s_mov_b32 m0, s0
	s_mov_b64 s[0:1], 0x49a7000
	v_add_u32_e32 v216, 0x3000, v211
	s_nop 0
	v_readfirstlane_b32 vcc_lo, v214
	v_readfirstlane_b32 vcc_hi, v215
	s_nop 1
	v_subrev_u32_e32 v230, vcc_lo, v214
	v_lshl_add_u64 v[214:215], v[212:213], 0, s[0:1]
	v_readfirstlane_b32 s0, v216
	s_mov_b32 m0, s0
	s_mov_b64 s[0:1], 0x49a8000
	v_add_u32_e32 v216, 0x4000, v211
	v_subrev_u32_e32 v231, vcc_lo, v214
	v_lshl_add_u64 v[214:215], v[212:213], 0, s[0:1]
	v_readfirstlane_b32 s0, v216
	s_mov_b32 m0, s0
	s_mov_b64 s[0:1], 0x49a9000
	v_add_u32_e32 v211, 0x5000, v211
	v_lshl_add_u64 v[212:213], v[212:213], 0, s[0:1]
	v_readfirstlane_b32 s0, v211
	v_subrev_u32_e32 v232, vcc_lo, v214
	s_mov_b32 m0, s0
	s_nop 0
	v_subrev_u32_e32 v233, vcc_lo, v212
	v_mov_b32_e32 v182, v228
	v_mov_b32_e32 v183, v229
	v_mov_b32_e32 v180, v230
	v_mov_b32_e32 v181, v231
	v_mov_b32_e32 v253, v232
	v_mov_b32_e32 v254, v233
	v_readfirstlane_b32 s0, v185
	s_branch .LBB0_529
	.p2align	6

; DEVI int otid() { int t = threadIdx.x; asm volatile("" : "+v"(t)); return t; }
; #define RAW_BARRIER() do { asm volatile("s_waitcnt lgkmcnt(0)" ::: "memory"); __builtin_amdgcn_s_barrier(); } while (0)
; template <int EPI, int NB>
; DEVI void gemm_tile(const GemmJob& J, int m0, int n0, unsigned char* smem) {
;     ...
;   const int tid = otid(), lane = tid & 63, wid = tid >> 6, wm = wid >> 1, wn = wid & 1;
;   const int l16 = lane & 15, g = lane >> 4;
;   f32x4 acc[4][NB];
; #pragma unroll
;   for (int i = 0; i < 4; ++i)
; #pragma unroll
;     for (int j = 0; j < NB; ++j) acc[i][j] = (f32x4){0.f, 0.f, 0.f, 0.f};
;   const int srow = tid >> 2, sch = tid & 3;
;   const int gch = sch ^ ((0 - (tid >> 4)) & 3);
;   const bf16_t* Ag = J.A + (size_t)(m0 + srow) * (J.ablk ? 32 : J.lda) + gch * 8;
;   const bf16_t* Bg = J.Bt + (size_t)(n0 + srow) * 32 + gch * 8;
;   const size_t Astep = (size_t)64 * (J.ablk ? 32 : J.lda), Ak = J.ablk ? (size_t)MROWS * 32 : (size_t)32, Bstep = (size_t)64 * 32, Bk = (size_t)J.NR * 32;
;   const int nk = J.K >> 5;
;   unsigned char* lds_t = smem + tid * 16;
;   const unsigned lbase = (unsigned)(uintptr_t)(__attribute__((address_space(3))) unsigned char*)smem;
;     ...
;   asm volatile("s_waitcnt vmcnt(0)" ::: "memory");
;   RAW_BARRIER();
; #pragma unroll
;   for (int st = 0; st < S - 1; ++st) GEMM_ISSUE(st, st);
;   const int fsl = (g ^ ((0 - (l16 >> 2)) & 3)) << 4;
;   const int aofs = (wm * 64 + l16) * 64 + fsl;
;   const int bofs = A_BYTES + (wn * NB * 16 + l16) * 64 + fsl;
;   int cs = 0, is = S - 1;
; template <int EPI, int NB>
; DEVI void gemm_run(const GemmJob& J, unsigned char* smem, int rot) {
;     ...
;     for (int t = b; t < ntiles; t += G) {
;       const int mt = t / J.ntn, nt = J.nt0 + (t - mt * J.ntn);
;       gemm_tile<EPI, NB>(J, mt * 128, nt * BN, smem);
.LBB0_605:
	s_ashr_i32 s0, s9, 31
	s_lshr_b32 s0, s0, 30
	s_add_i32 s0, s9, s0
	s_ashr_i32 s0, s0, 2
	s_lshl_b32 s3, s0, 7
	s_lshl_b32 s1, s9, 8
	s_lshl_b32 s0, s0, 10
	s_sub_i32 s2, s1, s0
	v_mov_b32_e32 v184, v177
	s_addk_i32 s2, 0x800
	s_nop 0
	s_mov_b64 s[28:29], 0x1000
	v_ashrrev_i32_e32 v10, 2, v184
	v_lshrrev_b32_e32 v0, 4, v184
	v_sub_u32_e32 v11, 0, v0
	v_add_u32_e32 v2, s3, v10
	v_add_u32_e32 v6, s2, v10
	v_xor_b32_e32 v0, v184, v11
	v_ashrrev_i32_e32 v3, 31, v2
	v_ashrrev_i32_e32 v7, 31, v6
	v_lshlrev_b64 v[2:3], 6, v[2:3]
	v_lshlrev_b32_e32 v0, 4, v0
	v_lshlrev_b64 v[6:7], 6, v[6:7]
	v_lshl_add_u64 v[4:5], v[146:147], 0, v[2:3]
	v_and_b32_e32 v0, 48, v0
	v_lshl_add_u64 v[6:7], v[142:143], 0, v[6:7]
	v_lshlrev_b32_e32 v185, 4, v184
	v_lshl_add_u64 v[4:5], v[4:5], 0, v[0:1]
	v_lshl_add_u64 v[6:7], v[6:7], 0, v[0:1]
	v_readfirstlane_b32 s1, v185
	v_add_u32_e32 v0, 0x1000, v185
	s_mov_b32 m0, s1
	v_readfirstlane_b32 s1, v0
	v_add_u32_e32 v0, 0x2000, v185
	s_waitcnt lgkmcnt(0)
	s_barrier
	global_load_lds_dwordx4 v[4:5], off
	v_lshl_add_u64 v[8:9], v[4:5], 0, s[28:29]
	s_mov_b32 m0, s1
	v_readfirstlane_b32 s1, v0
	v_add_u32_e32 v0, 0x3000, v185
	global_load_lds_dwordx4 v[8:9], off
	s_mov_b32 m0, s1
	v_readfirstlane_b32 s1, v0
	v_add_u32_e32 v0, 0x4000, v185
	global_load_lds_dwordx4 v[6:7], off
	v_lshl_add_u64 v[8:9], v[6:7], 0, s[28:29]
	s_mov_b32 m0, s1
	s_mov_b64 s[28:29], 0x2000
	v_readfirstlane_b32 s1, v0
	v_add_u32_e32 v0, 0x5000, v185
	global_load_lds_dwordx4 v[8:9], off
	v_lshl_add_u64 v[8:9], v[6:7], 0, s[28:29]
	s_mov_b32 m0, s1
	s_mov_b64 s[28:29], 0x3000
	v_readfirstlane_b32 s1, v0
	v_add_u32_e32 v0, 0x6000, v185
	global_load_lds_dwordx4 v[8:9], off
	v_lshl_add_u64 v[8:9], v[6:7], 0, s[28:29]
	s_mov_b32 m0, s1
	v_readfirstlane_b32 s1, v0
	v_add_u32_e32 v0, 0x7000, v185
	global_load_lds_dwordx4 v[8:9], off
	v_lshl_add_u64 v[8:9], v[4:5], 0, s[94:95]
	s_mov_b32 m0, s1
	s_mov_b64 s[28:29], 0x30b000
	v_readfirstlane_b32 s1, v0
	v_add_u32_e32 v0, 0x8000, v185
	global_load_lds_dwordx4 v[8:9], off
	v_lshl_add_u64 v[4:5], v[4:5], 0, s[28:29]
	s_mov_b32 m0, s1
	v_readfirstlane_b32 s1, v0
	v_add_u32_e32 v0, 0x9000, v185
	global_load_lds_dwordx4 v[4:5], off
	v_lshl_add_u64 v[4:5], v[6:7], 0, s[4:5]
	s_mov_b32 m0, s1
	s_mov_b64 s[28:29], 0x31000
	v_readfirstlane_b32 s1, v0
	v_add_u32_e32 v0, 0xa000, v185
	global_load_lds_dwordx4 v[4:5], off
	v_lshl_add_u64 v[4:5], v[6:7], 0, s[28:29]
	s_mov_b32 m0, s1
	s_mov_b64 s[28:29], 0x32000
	v_readfirstlane_b32 s1, v0
	v_add_u32_e32 v0, 0xb000, v185
	global_load_lds_dwordx4 v[4:5], off
	v_lshl_add_u64 v[4:5], v[6:7], 0, s[28:29]
	s_mov_b32 m0, s1
	s_mov_b64 s[28:29], 0x33000
	v_readfirstlane_b32 s1, v0
	global_load_lds_dwordx4 v[4:5], off
	v_lshl_add_u64 v[4:5], v[6:7], 0, s[28:29]
	s_mov_b32 m0, s1
	v_and_b32_e32 v0, 15, v184
	global_load_lds_dwordx4 v[4:5], off
	v_lshlrev_b32_e32 v4, 2, v184
	v_and_b32_e32 v4, 48, v4
	v_ashrrev_i32_e32 v5, 1, v184
	v_sub_u32_e32 v4, 0, v4
	v_and_b32_e32 v187, 0xffffffc0, v5
	v_bitop3_b32 v4, v184, 48, v4 bitop3:0x48
	v_or_b32_e32 v5, v187, v0
	v_lshl_or_b32 v208, v5, 6, v4
	v_lshlrev_b32_e32 v5, 1, v184
	s_movk_i32 s1, 0x80
	v_and_or_b32 v186, v5, s1, v0
	v_lshl_or_b32 v0, v186, 6, v4
	v_add_u32_e32 v4, s8, v10
	v_subrev_u32_e32 v4, s0, v4
	v_ashrrev_i32_e32 v5, 31, v4
	v_add_u32_e32 v209, 0x2000, v0
	v_bitop3_b32 v0, v184, 3, v11 bitop3:0x48
	v_lshlrev_b64 v[4:5], 6, v[4:5]
	v_lshl_add_u64 v[182:183], v[130:131], 0, v[2:3]
	v_mov_b32_e32 v2, 0
	s_mov_b32 s42, 2
	s_mov_b32 s20, 0
	s_mov_b64 s[30:31], 0x1000
	v_lshlrev_b32_e32 v0, 4, v0
	v_lshl_add_u64 v[180:181], v[130:131], 0, v[4:5]
	s_mov_b32 s43, 0
	v_mov_b32_e32 v3, v2
	v_mov_b32_e32 v4, v2
	v_mov_b32_e32 v5, v2
	v_mov_b32_e32 v6, v2
	v_mov_b32_e32 v7, v2
	v_mov_b32_e32 v8, v2
	v_mov_b32_e32 v9, v2
	v_mov_b32_e32 v10, v2
	v_mov_b32_e32 v11, v2
	v_mov_b32_e32 v12, v2
	v_mov_b32_e32 v13, v2
	v_mov_b32_e32 v14, v2
	v_mov_b32_e32 v15, v2
	v_mov_b32_e32 v16, v2
	v_mov_b32_e32 v17, v2
	v_mov_b32_e32 v18, v2
	v_mov_b32_e32 v19, v2
	v_mov_b32_e32 v20, v2
	v_mov_b32_e32 v21, v2
	v_mov_b32_e32 v22, v2
	v_mov_b32_e32 v23, v2
; template <int EPI, int NB>
; DEVI void gemm_tile(const GemmJob& J, int m0, int n0, unsigned char* smem) {
;     ...
;   f32x4 acc[4][NB];
; #pragma unroll
;   for (int i = 0; i < 4; ++i)
; #pragma unroll
;     for (int j = 0; j < NB; ++j) acc[i][j] = (f32x4){0.f, 0.f, 0.f, 0.f};
;     ...
;     if (kt + S - 1 < nk) GEMM_ISSUE(kt + S - 1, is);
;     is = (is + 1 == S) ? 0 : is + 1;
;     const unsigned cur = lbase + cs * STG;
;     cs = (cs + 1 == S) ? 0 : cs + 1;
;     bf16x8 af[4], bfr[NB];
;     const unsigned aa = cur + aofs, ba = cur + bofs;
	v_mov_b32_e32 v24, v2
	v_mov_b32_e32 v25, v2
	v_mov_b32_e32 v26, v2
	v_mov_b32_e32 v27, v2
	v_mov_b32_e32 v28, v2
	v_mov_b32_e32 v29, v2
	v_mov_b32_e32 v30, v2
	v_mov_b32_e32 v31, v2
	v_mov_b32_e32 v32, v2
	v_mov_b32_e32 v33, v2
	v_mov_b32_e32 v34, v2
	v_mov_b32_e32 v35, v2
	v_mov_b32_e32 v36, v2
	v_mov_b32_e32 v37, v2
	v_mov_b32_e32 v38, v2
	v_mov_b32_e32 v39, v2
	v_mov_b32_e32 v40, v2
	v_mov_b32_e32 v41, v2
	v_mov_b32_e32 v42, v2
	v_mov_b32_e32 v43, v2
	v_mov_b32_e32 v44, v2
	v_mov_b32_e32 v45, v2
	v_mov_b32_e32 v46, v2
	v_mov_b32_e32 v47, v2
	v_mov_b32_e32 v48, v2
	v_mov_b32_e32 v49, v2
	v_mov_b32_e32 v50, v2
	v_mov_b32_e32 v51, v2
	v_mov_b32_e32 v52, v2
	v_mov_b32_e32 v53, v2
	v_mov_b32_e32 v54, v2
	v_mov_b32_e32 v55, v2
	v_mov_b32_e32 v56, v2
	v_mov_b32_e32 v57, v2
	v_mov_b32_e32 v58, v2
	v_mov_b32_e32 v59, v2
	v_mov_b32_e32 v60, v2
	v_mov_b32_e32 v61, v2
	v_mov_b32_e32 v62, v2
	v_mov_b32_e32 v63, v2
	v_mov_b32_e32 v64, v2
	v_mov_b32_e32 v65, v2
	v_mov_b32_e32 v66, v2
	v_mov_b32_e32 v67, v2
	v_mov_b32_e32 v68, v2
	v_mov_b32_e32 v69, v2
	v_mov_b32_e32 v70, v2
	v_mov_b32_e32 v71, v2
	v_mov_b32_e32 v72, v2
	v_mov_b32_e32 v73, v2
	v_mov_b32_e32 v74, v2
	v_mov_b32_e32 v75, v2
	v_mov_b32_e32 v76, v2
	v_mov_b32_e32 v77, v2
	v_mov_b32_e32 v78, v2
	v_mov_b32_e32 v79, v2
	v_mov_b32_e32 v80, v2
	v_mov_b32_e32 v81, v2
	v_mov_b32_e32 v82, v2
	v_mov_b32_e32 v83, v2
	v_mov_b32_e32 v84, v2
	v_mov_b32_e32 v85, v2
	v_mov_b32_e32 v86, v2
	v_mov_b32_e32 v87, v2
	v_mov_b32_e32 v88, v2
	v_mov_b32_e32 v89, v2
	v_mov_b32_e32 v90, v2
	v_mov_b32_e32 v91, v2
	v_mov_b32_e32 v92, v2
	v_mov_b32_e32 v93, v2
	v_mov_b32_e32 v94, v2
	v_mov_b32_e32 v95, v2
	v_mov_b32_e32 v96, v2
	v_mov_b32_e32 v97, v2
	v_mov_b32_e32 v98, v2
	v_mov_b32_e32 v99, v2
	v_mov_b32_e32 v100, v2
	v_mov_b32_e32 v101, v2
	v_mov_b32_e32 v102, v2
	v_mov_b32_e32 v103, v2
	v_mov_b32_e32 v104, v2
	v_mov_b32_e32 v105, v2
	v_mov_b32_e32 v106, v2
	v_mov_b32_e32 v107, v2
	v_mov_b32_e32 v108, v2
	v_mov_b32_e32 v109, v2
	v_mov_b32_e32 v110, v2
	v_mov_b32_e32 v111, v2
	v_mov_b32_e32 v112, v2
	v_mov_b32_e32 v113, v2
	v_mov_b32_e32 v114, v2
	v_mov_b32_e32 v115, v2
	v_mov_b32_e32 v116, v2
	v_mov_b32_e32 v117, v2
	v_mov_b32_e32 v118, v2
	v_mov_b32_e32 v119, v2
	v_mov_b32_e32 v120, v2
	v_mov_b32_e32 v121, v2
	v_mov_b32_e32 v122, v2
	v_mov_b32_e32 v123, v2
	v_mov_b32_e32 v124, v2
	v_mov_b32_e32 v125, v2
	v_mov_b32_e32 v126, v2
	v_mov_b32_e32 v127, v2
	v_mov_b32_e32 v128, v2
	v_mov_b32_e32 v129, v2
	s_mul_i32 s0, s42, 0x6000
	v_add_u32_e32 v214, s0, v185
	v_lshl_add_u64 v[210:211], v[182:183], 0, v[0:1]
	v_readfirstlane_b32 s0, v214
	v_lshl_add_u64 v[212:213], v[210:211], 0, s[84:85]
	s_mov_b32 m0, s0
	v_lshl_add_u64 v[210:211], v[210:211], 0, s[12:13]
	s_nop 0
	v_readfirstlane_b32 s100, v212
	v_readfirstlane_b32 s101, v213
	s_nop 1
	v_subrev_u32_e32 v226, s100, v212
	v_add_u32_e32 v212, 0x1000, v214
	v_add_u32_e32 v215, 0x2000, v214
	v_readfirstlane_b32 s0, v212
	s_mov_b32 m0, s0
	s_mov_b64 s[0:1], 0x49a6000
	v_subrev_u32_e32 v227, s100, v210
	v_lshl_add_u64 v[210:211], v[180:181], 0, v[0:1]
	v_lshl_add_u64 v[212:213], v[210:211], 0, s[0:1]
	v_readfirstlane_b32 s0, v215
	s_mov_b32 m0, s0
	s_mov_b64 s[0:1], 0x49a7000
	v_add_u32_e32 v215, 0x3000, v214
	s_nop 0
	v_readfirstlane_b32 vcc_lo, v212
	v_readfirstlane_b32 vcc_hi, v213
	s_nop 1
	v_subrev_u32_e32 v228, vcc_lo, v212
	v_lshl_add_u64 v[212:213], v[210:211], 0, s[0:1]
	v_readfirstlane_b32 s0, v215
	s_mov_b32 m0, s0
	s_mov_b64 s[0:1], 0x49a8000
	v_add_u32_e32 v215, 0x4000, v214
	v_subrev_u32_e32 v229, vcc_lo, v212
	v_lshl_add_u64 v[212:213], v[210:211], 0, s[0:1]
	v_readfirstlane_b32 s0, v215
	s_mov_b32 m0, s0
	s_mov_b64 s[0:1], 0x49a9000
	v_subrev_u32_e32 v230, vcc_lo, v212
	v_add_u32_e32 v212, 0x5000, v214
	v_lshl_add_u64 v[210:211], v[210:211], 0, s[0:1]
	v_readfirstlane_b32 s0, v212
	s_mov_b32 m0, s0
	s_nop 0
	v_subrev_u32_e32 v231, vcc_lo, v210
	v_mov_b32_e32 v182, v226
	v_mov_b32_e32 v183, v227
	v_mov_b32_e32 v180, v228
	v_mov_b32_e32 v181, v229
	v_mov_b32_e32 v253, v230
	v_mov_b32_e32 v254, v231
	v_readfirstlane_b32 s0, v185
	s_branch .LBB0_607
	.p2align	6

; #define RAW_BARRIER() do { asm volatile("s_waitcnt lgkmcnt(0)" ::: "memory"); __builtin_amdgcn_s_barrier(); } while (0)
; template <int EPI, int NB>
; DEVI void gemm_tile(const GemmJob& J, int m0, int n0, unsigned char* smem) {
;     ...
;   const int srow = tid >> 2, sch = tid & 3;
;   const int gch = sch ^ ((0 - (tid >> 4)) & 3);
;   const bf16_t* Ag = J.A + (size_t)(m0 + srow) * (J.ablk ? 32 : J.lda) + gch * 8;
;   const bf16_t* Bg = J.Bt + (size_t)(n0 + srow) * 32 + gch * 8;
;   const size_t Astep = (size_t)64 * (J.ablk ? 32 : J.lda), Ak = J.ablk ? (size_t)MROWS * 32 : (size_t)32, Bstep = (size_t)64 * 32, Bk = (size_t)J.NR * 32;
;   const int nk = J.K >> 5;
;   unsigned char* lds_t = smem + tid * 16;
;   const unsigned lbase = (unsigned)(uintptr_t)(__attribute__((address_space(3))) unsigned char*)smem;
;     ...
;   asm volatile("s_waitcnt vmcnt(0)" ::: "memory");
;   RAW_BARRIER();
; #pragma unroll
;   for (int st = 0; st < S - 1; ++st) GEMM_ISSUE(st, st);
;   const int fsl = (g ^ ((0 - (l16 >> 2)) & 3)) << 4;
;   const int aofs = (wm * 64 + l16) * 64 + fsl;
;   const int bofs = A_BYTES + (wn * NB * 16 + l16) * 64 + fsl;
; template <int EPI, int NB>
; DEVI void gemm_run(const GemmJob& J, unsigned char* smem, int rot) {
;     ...
;     for (int q0 = lb; q0 < ntot; q0 += nlb) {
;       const int q = J.rev ? ntot - 1 - q0 : q0;
;       int grp = q / gsz; const int qq = q - grp * gsz;
;       const int mg = min(8, mcnt - grp * 8);
;       const int nt = qq / mg, mi = qq - nt * mg;
;       gemm_tile<EPI, NB>(J, (mlo + grp * 8 + mi) * 128, (J.nt0 + nt) * BN, smem);
.LBB0_694:
	s_ashr_i32 s0, s9, 31
	s_lshr_b32 s0, s0, 26
	s_add_i32 s0, s9, s0
	s_ashr_i32 s1, s0, 6
	s_lshl_b32 s3, s1, 3
	v_readlane_b32 s2, v251, 48
	s_sub_i32 s2, s2, s3
	s_min_i32 s20, s2, 8
	s_abs_i32 s40, s20
	v_cvt_f32_u32_e32 v0, s40
	s_sub_i32 s43, 0, s40
	s_andn2_b32 s0, s0, 63
	s_sub_i32 s0, s9, s0
	v_rcp_iflag_f32_e32 v0, v0
	s_abs_i32 s41, s0
	s_xor_b32 s42, s0, s20
	s_ashr_i32 s42, s42, 31
	v_mul_f32_e32 v0, 0x4f7ffffe, v0
	v_cvt_u32_f32_e32 v0, v0
	v_mov_b32_e32 v184, v177
	s_nop 0
	v_readfirstlane_b32 s44, v0
	s_mul_i32 s43, s43, s44
	s_mul_hi_u32 s43, s44, s43
	s_add_i32 s44, s44, s43
	s_mul_hi_u32 s43, s41, s44
	s_mul_i32 s44, s43, s40
	s_sub_i32 s41, s41, s44
	s_add_i32 s45, s43, 1
	s_sub_i32 s44, s41, s40
	s_cmp_ge_u32 s41, s40
	s_cselect_b32 s43, s45, s43
	s_cselect_b32 s41, s44, s41
	s_add_i32 s44, s43, 1
	s_cmp_ge_u32 s41, s40
	s_cselect_b32 s40, s44, s43
	s_xor_b32 s40, s40, s42
	s_sub_i32 s40, s40, s42
	s_mul_i32 s41, s20, s40
	v_readlane_b32 s20, v250, 37
	s_add_i32 s3, s3, s20
	s_add_i32 s3, s3, s0
	s_sub_i32 s0, s3, s41
	s_lshl_b32 s20, s0, 7
	s_lshl_b32 s3, s40, 8
	v_ashrrev_i32_e32 v10, 2, v184
	v_lshrrev_b32_e32 v0, 4, v184
	v_sub_u32_e32 v11, 0, v0
	v_add_u32_e32 v2, s20, v10
	v_add_u32_e32 v4, s3, v10
	v_xor_b32_e32 v0, v184, v11
	v_ashrrev_i32_e32 v3, 31, v2
	v_ashrrev_i32_e32 v5, 31, v4
	v_lshlrev_b64 v[2:3], 6, v[2:3]
	v_lshlrev_b32_e32 v0, 4, v0
	v_lshlrev_b64 v[4:5], 6, v[4:5]
	v_lshl_add_u64 v[2:3], v[146:147], 0, v[2:3]
	v_and_b32_e32 v0, 48, v0
	v_lshl_add_u64 v[6:7], v[142:143], 0, v[4:5]
	v_lshlrev_b32_e32 v185, 4, v184
	v_lshl_add_u64 v[2:3], v[2:3], 0, v[0:1]
	v_lshl_add_u64 v[6:7], v[6:7], 0, v[0:1]
	v_readfirstlane_b32 s0, v185
	v_add_u32_e32 v0, 0x1000, v185
	s_mov_b32 m0, s0
	s_mov_b64 s[28:29], 0x1000
	v_readfirstlane_b32 s0, v0
	v_add_u32_e32 v0, 0x2000, v185
	s_waitcnt lgkmcnt(0)
	s_barrier
	global_load_lds_dwordx4 v[2:3], off
	v_lshl_add_u64 v[8:9], v[2:3], 0, s[28:29]
	s_mov_b32 m0, s0
	v_readfirstlane_b32 s0, v0
	v_add_u32_e32 v0, 0x3000, v185
	global_load_lds_dwordx4 v[8:9], off
	s_mov_b32 m0, s0
	v_readfirstlane_b32 s0, v0
	v_add_u32_e32 v0, 0x4000, v185
	global_load_lds_dwordx4 v[6:7], off
	v_lshl_add_u64 v[8:9], v[6:7], 0, s[28:29]
	s_mov_b32 m0, s0
	s_mov_b64 s[28:29], 0x2000
	v_readfirstlane_b32 s0, v0
	v_add_u32_e32 v0, 0x5000, v185
	global_load_lds_dwordx4 v[8:9], off
	v_lshl_add_u64 v[8:9], v[6:7], 0, s[28:29]
	s_mov_b32 m0, s0
	s_mov_b64 s[28:29], 0x3000
	v_readfirstlane_b32 s0, v0
	v_add_u32_e32 v0, 0x6000, v185
	global_load_lds_dwordx4 v[8:9], off
	v_lshl_add_u64 v[8:9], v[6:7], 0, s[28:29]
	s_mov_b32 m0, s0
	v_readfirstlane_b32 s0, v0
	v_add_u32_e32 v0, 0x7000, v185
	global_load_lds_dwordx4 v[8:9], off
	v_lshl_add_u64 v[8:9], v[2:3], 0, s[94:95]
	s_mov_b32 m0, s0
	s_mov_b64 s[28:29], 0x30b000
	v_readfirstlane_b32 s0, v0
	v_add_u32_e32 v0, 0x8000, v185
	global_load_lds_dwordx4 v[8:9], off
	v_lshl_add_u64 v[2:3], v[2:3], 0, s[28:29]
	s_mov_b32 m0, s0
	v_readfirstlane_b32 s0, v0
	v_add_u32_e32 v0, 0x9000, v185
	global_load_lds_dwordx4 v[2:3], off
	v_lshl_add_u64 v[2:3], v[6:7], 0, s[4:5]
	s_mov_b32 m0, s0
	s_mov_b64 s[28:29], 0x31000
	v_readfirstlane_b32 s0, v0
	v_add_u32_e32 v0, 0xa000, v185
	global_load_lds_dwordx4 v[2:3], off
	v_lshl_add_u64 v[2:3], v[6:7], 0, s[28:29]
	s_mov_b32 m0, s0
	s_mov_b64 s[28:29], 0x32000
	v_readfirstlane_b32 s0, v0
	v_add_u32_e32 v0, 0xb000, v185
	global_load_lds_dwordx4 v[2:3], off
	v_lshl_add_u64 v[2:3], v[6:7], 0, s[28:29]
	s_mov_b32 m0, s0
	s_mov_b64 s[28:29], 0x33000
	v_readfirstlane_b32 s0, v0
	global_load_lds_dwordx4 v[2:3], off
	v_lshl_add_u64 v[2:3], v[6:7], 0, s[28:29]
	s_mov_b32 m0, s0
	v_lshlrev_b32_e32 v0, 2, v184
	global_load_lds_dwordx4 v[2:3], off
	v_and_b32_e32 v0, 48, v0
	v_ashrrev_i32_e32 v2, 1, v184
	v_and_b32_e32 v186, 15, v184
	v_sub_u32_e32 v0, 0, v0
	v_and_b32_e32 v187, 0xffffffc0, v2
	v_bitop3_b32 v0, v184, 48, v0 bitop3:0x48
	v_or_b32_e32 v2, v187, v186
	v_lshl_or_b32 v209, v2, 6, v0
	v_lshlrev_b32_e32 v2, 1, v184
	v_and_b32_e32 v208, 0x80, v2
	s_sub_i32 s0, s8, s41
	s_mul_i32 s1, s1, 56
	v_or_b32_e32 v2, v208, v186
	s_sub_i32 s0, s0, s1
	v_lshl_or_b32 v0, v2, 6, v0
	v_lshl_add_u32 v2, s0, 7, v10
	v_ashrrev_i32_e32 v3, 31, v2
	v_lshlrev_b64 v[2:3], 6, v[2:3]
	v_add_u32_e32 v210, 0x2000, v0
	v_bitop3_b32 v0, v184, 3, v11 bitop3:0x48
	v_lshl_add_u64 v[182:183], v[130:131], 0, v[2:3]
	v_mov_b32_e32 v2, 0
	s_mov_b32 s2, 0
	s_mov_b32 s42, 2
	s_mov_b64 s[30:31], 0x1000
	v_lshlrev_b32_e32 v0, 4, v0
	v_lshl_add_u64 v[180:181], v[130:131], 0, v[4:5]
	s_mov_b32 s43, 0
	v_mov_b32_e32 v3, v2
; template <int EPI, int NB>
; DEVI void gemm_tile(const GemmJob& J, int m0, int n0, unsigned char* smem) {
;     ...
;   f32x4 acc[4][NB];
; #pragma unroll
;   for (int i = 0; i < 4; ++i)
; #pragma unroll
;     for (int j = 0; j < NB; ++j) acc[i][j] = (f32x4){0.f, 0.f, 0.f, 0.f};
;     ...
;     if (kt + S - 1 < nk) GEMM_ISSUE(kt + S - 1, is);
;     is = (is + 1 == S) ? 0 : is + 1;
;     const unsigned cur = lbase + cs * STG;
;     cs = (cs + 1 == S) ? 0 : cs + 1;
;     bf16x8 af[4], bfr[NB];
;     const unsigned aa = cur + aofs, ba = cur + bofs;
	v_mov_b32_e32 v4, v2
	v_mov_b32_e32 v5, v2
	v_mov_b32_e32 v6, v2
	v_mov_b32_e32 v7, v2
	v_mov_b32_e32 v8, v2
	v_mov_b32_e32 v9, v2
	v_mov_b32_e32 v10, v2
	v_mov_b32_e32 v11, v2
	v_mov_b32_e32 v12, v2
	v_mov_b32_e32 v13, v2
	v_mov_b32_e32 v14, v2
	v_mov_b32_e32 v15, v2
	v_mov_b32_e32 v16, v2
	v_mov_b32_e32 v17, v2
	v_mov_b32_e32 v18, v2
	v_mov_b32_e32 v19, v2
	v_mov_b32_e32 v20, v2
	v_mov_b32_e32 v21, v2
	v_mov_b32_e32 v22, v2
	v_mov_b32_e32 v23, v2
	v_mov_b32_e32 v24, v2
	v_mov_b32_e32 v25, v2
	v_mov_b32_e32 v26, v2
	v_mov_b32_e32 v27, v2
	v_mov_b32_e32 v28, v2
	v_mov_b32_e32 v29, v2
	v_mov_b32_e32 v30, v2
	v_mov_b32_e32 v31, v2
	v_mov_b32_e32 v32, v2
	v_mov_b32_e32 v33, v2
	v_mov_b32_e32 v34, v2
	v_mov_b32_e32 v35, v2
	v_mov_b32_e32 v36, v2
	v_mov_b32_e32 v37, v2
	v_mov_b32_e32 v38, v2
	v_mov_b32_e32 v39, v2
	v_mov_b32_e32 v40, v2
	v_mov_b32_e32 v41, v2
	v_mov_b32_e32 v42, v2
	v_mov_b32_e32 v43, v2
	v_mov_b32_e32 v44, v2
	v_mov_b32_e32 v45, v2
	v_mov_b32_e32 v46, v2
	v_mov_b32_e32 v47, v2
	v_mov_b32_e32 v48, v2
	v_mov_b32_e32 v49, v2
	v_mov_b32_e32 v50, v2
	v_mov_b32_e32 v51, v2
	v_mov_b32_e32 v52, v2
	v_mov_b32_e32 v53, v2
	v_mov_b32_e32 v54, v2
	v_mov_b32_e32 v55, v2
	v_mov_b32_e32 v56, v2
	v_mov_b32_e32 v57, v2
	v_mov_b32_e32 v58, v2
	v_mov_b32_e32 v59, v2
	v_mov_b32_e32 v60, v2
	v_mov_b32_e32 v61, v2
	v_mov_b32_e32 v62, v2
	v_mov_b32_e32 v63, v2
	v_mov_b32_e32 v64, v2
	v_mov_b32_e32 v65, v2
	v_mov_b32_e32 v66, v2
	v_mov_b32_e32 v67, v2
	v_mov_b32_e32 v68, v2
	v_mov_b32_e32 v69, v2
	v_mov_b32_e32 v70, v2
	v_mov_b32_e32 v71, v2
	v_mov_b32_e32 v72, v2
	v_mov_b32_e32 v73, v2
	v_mov_b32_e32 v74, v2
	v_mov_b32_e32 v75, v2
	v_mov_b32_e32 v76, v2
	v_mov_b32_e32 v77, v2
	v_mov_b32_e32 v78, v2
	v_mov_b32_e32 v79, v2
	v_mov_b32_e32 v80, v2
	v_mov_b32_e32 v81, v2
	v_mov_b32_e32 v82, v2
	v_mov_b32_e32 v83, v2
	v_mov_b32_e32 v84, v2
	v_mov_b32_e32 v85, v2
	v_mov_b32_e32 v86, v2
	v_mov_b32_e32 v87, v2
	v_mov_b32_e32 v88, v2
	v_mov_b32_e32 v89, v2
	v_mov_b32_e32 v90, v2
	v_mov_b32_e32 v91, v2
	v_mov_b32_e32 v92, v2
	v_mov_b32_e32 v93, v2
	v_mov_b32_e32 v94, v2
	v_mov_b32_e32 v95, v2
	v_mov_b32_e32 v96, v2
	v_mov_b32_e32 v97, v2
	v_mov_b32_e32 v98, v2
	v_mov_b32_e32 v99, v2
	v_mov_b32_e32 v100, v2
	v_mov_b32_e32 v101, v2
	v_mov_b32_e32 v102, v2
	v_mov_b32_e32 v103, v2
	v_mov_b32_e32 v104, v2
	v_mov_b32_e32 v105, v2
	v_mov_b32_e32 v106, v2
	v_mov_b32_e32 v107, v2
	v_mov_b32_e32 v108, v2
	v_mov_b32_e32 v109, v2
	v_mov_b32_e32 v110, v2
	v_mov_b32_e32 v111, v2
	v_mov_b32_e32 v112, v2
	v_mov_b32_e32 v113, v2
	v_mov_b32_e32 v114, v2
	v_mov_b32_e32 v115, v2
	v_mov_b32_e32 v116, v2
	v_mov_b32_e32 v117, v2
	v_mov_b32_e32 v118, v2
	v_mov_b32_e32 v119, v2
	v_mov_b32_e32 v120, v2
	v_mov_b32_e32 v121, v2
	v_mov_b32_e32 v122, v2
	v_mov_b32_e32 v123, v2
	v_mov_b32_e32 v124, v2
	v_mov_b32_e32 v125, v2
	v_mov_b32_e32 v126, v2
	v_mov_b32_e32 v127, v2
	v_mov_b32_e32 v128, v2
	v_mov_b32_e32 v129, v2
	s_mul_i32 s0, s42, 0x6000
	v_add_u32_e32 v211, s0, v185
	v_lshl_add_u64 v[212:213], v[182:183], 0, v[0:1]
	v_readfirstlane_b32 s0, v211
	v_lshl_add_u64 v[214:215], v[212:213], 0, s[84:85]
	s_mov_b32 m0, s0
	v_lshl_add_u64 v[212:213], v[212:213], 0, s[12:13]
	s_nop 0
	v_readfirstlane_b32 s100, v214
	v_readfirstlane_b32 s101, v215
	s_nop 1
	v_subrev_u32_e32 v228, s100, v214
	v_add_u32_e32 v214, 0x1000, v211
	v_add_u32_e32 v216, 0x2000, v211
	v_readfirstlane_b32 s0, v214
	s_mov_b32 m0, s0
	s_mov_b64 s[0:1], 0x49a6000
	v_subrev_u32_e32 v229, s100, v212
	v_lshl_add_u64 v[212:213], v[180:181], 0, v[0:1]
	v_lshl_add_u64 v[214:215], v[212:213], 0, s[0:1]
	v_readfirstlane_b32 s0, v216
	s_mov_b32 m0, s0
	s_mov_b64 s[0:1], 0x49a7000
	v_add_u32_e32 v216, 0x3000, v211
	s_nop 0
	v_readfirstlane_b32 vcc_lo, v214
	v_readfirstlane_b32 vcc_hi, v215
	s_nop 1
	v_subrev_u32_e32 v230, vcc_lo, v214
	v_lshl_add_u64 v[214:215], v[212:213], 0, s[0:1]
	v_readfirstlane_b32 s0, v216
	s_mov_b32 m0, s0
	s_mov_b64 s[0:1], 0x49a8000
	v_add_u32_e32 v216, 0x4000, v211
	v_subrev_u32_e32 v231, vcc_lo, v214
	v_lshl_add_u64 v[214:215], v[212:213], 0, s[0:1]
	v_readfirstlane_b32 s0, v216
	s_mov_b32 m0, s0
	s_mov_b64 s[0:1], 0x49a9000
	v_add_u32_e32 v211, 0x5000, v211
	v_lshl_add_u64 v[212:213], v[212:213], 0, s[0:1]
	v_readfirstlane_b32 s0, v211
	v_subrev_u32_e32 v232, vcc_lo, v214
	s_mov_b32 m0, s0
	s_nop 0
	v_subrev_u32_e32 v233, vcc_lo, v212
	v_mov_b32_e32 v182, v228
	v_mov_b32_e32 v183, v229
	v_mov_b32_e32 v180, v230
	v_mov_b32_e32 v181, v231
	v_mov_b32_e32 v253, v232
	v_mov_b32_e32 v254, v233
	v_readfirstlane_b32 s0, v185
	s_branch .LBB0_696
	.p2align	6

; #define RAW_BARRIER() do { asm volatile("s_waitcnt lgkmcnt(0)" ::: "memory"); __builtin_amdgcn_s_barrier(); } while (0)
; template <int EPI, int NB>
; DEVI void gemm_tile(const GemmJob& J, int m0, int n0, unsigned char* smem) {
;     ...
;   const int srow = tid >> 2, sch = tid & 3;
;   const int gch = sch ^ ((0 - (tid >> 4)) & 3);
;   const bf16_t* Ag = J.A + (size_t)(m0 + srow) * (J.ablk ? 32 : J.lda) + gch * 8;
;   const bf16_t* Bg = J.Bt + (size_t)(n0 + srow) * 32 + gch * 8;
;   const size_t Astep = (size_t)64 * (J.ablk ? 32 : J.lda), Ak = J.ablk ? (size_t)MROWS * 32 : (size_t)32, Bstep = (size_t)64 * 32, Bk = (size_t)J.NR * 32;
;   const int nk = J.K >> 5;
;   unsigned char* lds_t = smem + tid * 16;
;   const unsigned lbase = (unsigned)(uintptr_t)(__attribute__((address_space(3))) unsigned char*)smem;
;     ...
;   asm volatile("s_waitcnt vmcnt(0)" ::: "memory");
;   RAW_BARRIER();
; #pragma unroll
;   for (int st = 0; st < S - 1; ++st) GEMM_ISSUE(st, st);
;   const int fsl = (g ^ ((0 - (l16 >> 2)) & 3)) << 4;
;   const int aofs = (wm * 64 + l16) * 64 + fsl;
;   const int bofs = A_BYTES + (wn * NB * 16 + l16) * 64 + fsl;
; template <int EPI, int NB>
; DEVI void gemm_run(const GemmJob& J, unsigned char* smem, int rot) {
;     ...
;     for (int q0 = lb; q0 < ntot; q0 += nlb) {
;       const int q = J.rev ? ntot - 1 - q0 : q0;
;       int grp = q / gsz; const int qq = q - grp * gsz;
;       const int mg = min(8, mcnt - grp * 8);
;       const int nt = qq / mg, mi = qq - nt * mg;
;       gemm_tile<EPI, NB>(J, (mlo + grp * 8 + mi) * 128, (J.nt0 + nt) * BN, smem);
.LBB0_772:
	s_ashr_i32 s0, s9, 31
	s_lshr_b32 s0, s0, 27
	s_add_i32 s0, s9, s0
	s_ashr_i32 s1, s0, 5
	s_lshl_b32 s2, s1, 3
	v_readlane_b32 s3, v251, 48
	s_sub_i32 s3, s3, s2
	s_min_i32 s20, s3, 8
	s_abs_i32 s40, s20
	v_cvt_f32_u32_e32 v0, s40
	s_sub_i32 s43, 0, s40
	s_andn2_b32 s0, s0, 31
	s_sub_i32 s0, s9, s0
	v_rcp_iflag_f32_e32 v0, v0
	s_abs_i32 s41, s0
	s_xor_b32 s42, s0, s20
	s_ashr_i32 s42, s42, 31
	v_mul_f32_e32 v0, 0x4f7ffffe, v0
	v_cvt_u32_f32_e32 v0, v0
	v_mov_b32_e32 v184, v177
	s_nop 0
	v_readfirstlane_b32 s44, v0
	s_mul_i32 s43, s43, s44
	s_mul_hi_u32 s43, s44, s43
	s_add_i32 s44, s44, s43
	s_mul_hi_u32 s43, s41, s44
	s_mul_i32 s44, s43, s40
	s_sub_i32 s41, s41, s44
	s_add_i32 s45, s43, 1
	s_sub_i32 s44, s41, s40
	s_cmp_ge_u32 s41, s40
	s_cselect_b32 s43, s45, s43
	s_cselect_b32 s41, s44, s41
	s_add_i32 s44, s43, 1
	s_cmp_ge_u32 s41, s40
	s_cselect_b32 s40, s44, s43
	s_xor_b32 s40, s40, s42
	s_sub_i32 s40, s40, s42
	s_mul_i32 s41, s20, s40
	v_readlane_b32 s20, v250, 37
	s_add_i32 s2, s2, s20
	s_add_i32 s2, s2, s0
	s_sub_i32 s0, s2, s41
	s_lshl_b32 s2, s40, 8
	s_lshl_b32 s20, s0, 7
	s_addk_i32 s2, 0x800
	v_ashrrev_i32_e32 v10, 2, v184
	v_lshrrev_b32_e32 v0, 4, v184
	v_sub_u32_e32 v11, 0, v0
	v_add_u32_e32 v2, s20, v10
	v_add_u32_e32 v4, s2, v10
	v_xor_b32_e32 v0, v184, v11
	v_ashrrev_i32_e32 v3, 31, v2
	v_ashrrev_i32_e32 v5, 31, v4
	v_lshlrev_b64 v[2:3], 6, v[2:3]
	v_lshlrev_b32_e32 v0, 4, v0
	v_lshlrev_b64 v[4:5], 6, v[4:5]
	v_lshl_add_u64 v[2:3], v[146:147], 0, v[2:3]
	v_and_b32_e32 v0, 48, v0
	v_lshl_add_u64 v[6:7], v[142:143], 0, v[4:5]
	v_lshlrev_b32_e32 v185, 4, v184
	v_lshl_add_u64 v[2:3], v[2:3], 0, v[0:1]
	v_lshl_add_u64 v[6:7], v[6:7], 0, v[0:1]
	v_readfirstlane_b32 s0, v185
	v_add_u32_e32 v0, 0x1000, v185
	s_mov_b32 m0, s0
	s_mov_b64 s[28:29], 0x1000
	v_readfirstlane_b32 s0, v0
	v_add_u32_e32 v0, 0x2000, v185
	s_waitcnt lgkmcnt(0)
	s_barrier
	global_load_lds_dwordx4 v[2:3], off
	v_lshl_add_u64 v[8:9], v[2:3], 0, s[28:29]
	s_mov_b32 m0, s0
	v_readfirstlane_b32 s0, v0
	v_add_u32_e32 v0, 0x3000, v185
	global_load_lds_dwordx4 v[8:9], off
	s_mov_b32 m0, s0
	v_readfirstlane_b32 s0, v0
	v_add_u32_e32 v0, 0x4000, v185
	global_load_lds_dwordx4 v[6:7], off
	v_lshl_add_u64 v[8:9], v[6:7], 0, s[28:29]
	s_mov_b32 m0, s0
	s_mov_b64 s[28:29], 0x2000
	v_readfirstlane_b32 s0, v0
	v_add_u32_e32 v0, 0x5000, v185
	global_load_lds_dwordx4 v[8:9], off
	v_lshl_add_u64 v[8:9], v[6:7], 0, s[28:29]
	s_mov_b32 m0, s0
	s_mov_b64 s[28:29], 0x3000
	v_readfirstlane_b32 s0, v0
	v_add_u32_e32 v0, 0x6000, v185
	global_load_lds_dwordx4 v[8:9], off
	v_lshl_add_u64 v[8:9], v[6:7], 0, s[28:29]
	s_mov_b32 m0, s0
	v_readfirstlane_b32 s0, v0
	v_add_u32_e32 v0, 0x7000, v185
	global_load_lds_dwordx4 v[8:9], off
	v_lshl_add_u64 v[8:9], v[2:3], 0, s[94:95]
	s_mov_b32 m0, s0
	s_mov_b64 s[28:29], 0x30b000
	v_readfirstlane_b32 s0, v0
	v_add_u32_e32 v0, 0x8000, v185
	global_load_lds_dwordx4 v[8:9], off
	v_lshl_add_u64 v[2:3], v[2:3], 0, s[28:29]
	s_mov_b32 m0, s0
	v_readfirstlane_b32 s0, v0
	v_add_u32_e32 v0, 0x9000, v185
	global_load_lds_dwordx4 v[2:3], off
	v_lshl_add_u64 v[2:3], v[6:7], 0, s[4:5]
	s_mov_b32 m0, s0
	s_mov_b64 s[28:29], 0x31000
	v_readfirstlane_b32 s0, v0
	v_add_u32_e32 v0, 0xa000, v185
	global_load_lds_dwordx4 v[2:3], off
	v_lshl_add_u64 v[2:3], v[6:7], 0, s[28:29]
	s_mov_b32 m0, s0
	s_mov_b64 s[28:29], 0x32000
	v_readfirstlane_b32 s0, v0
	v_add_u32_e32 v0, 0xb000, v185
	global_load_lds_dwordx4 v[2:3], off
	v_lshl_add_u64 v[2:3], v[6:7], 0, s[28:29]
	s_mov_b32 m0, s0
	s_mov_b64 s[28:29], 0x33000
	v_readfirstlane_b32 s0, v0
	global_load_lds_dwordx4 v[2:3], off
	v_lshl_add_u64 v[2:3], v[6:7], 0, s[28:29]
	s_mov_b32 m0, s0
	v_and_b32_e32 v0, 15, v184
	global_load_lds_dwordx4 v[2:3], off
	v_lshlrev_b32_e32 v2, 2, v184
	v_and_b32_e32 v2, 48, v2
	v_ashrrev_i32_e32 v3, 1, v184
	v_sub_u32_e32 v2, 0, v2
	v_and_b32_e32 v187, 0xffffffc0, v3
	v_bitop3_b32 v2, v184, 48, v2 bitop3:0x48
	v_or_b32_e32 v3, v187, v0
	v_lshl_or_b32 v208, v3, 6, v2
	v_lshlrev_b32_e32 v3, 1, v184
	s_movk_i32 s0, 0x80
	v_and_or_b32 v186, v3, s0, v0
	s_sub_i32 s0, s8, s41
	s_mul_i32 s1, s1, 24
	s_sub_i32 s0, s0, s1
	v_lshl_or_b32 v0, v186, 6, v2
	v_lshl_add_u32 v2, s0, 7, v10
	v_ashrrev_i32_e32 v3, 31, v2
	v_lshlrev_b64 v[2:3], 6, v[2:3]
	v_add_u32_e32 v209, 0x2000, v0
	v_bitop3_b32 v0, v184, 3, v11 bitop3:0x48
	v_lshl_add_u64 v[182:183], v[130:131], 0, v[2:3]
	v_mov_b32_e32 v2, 0
	s_mov_b32 s3, 0
	s_mov_b32 s42, 2
	s_mov_b64 s[30:31], 0x1000
	v_lshlrev_b32_e32 v0, 4, v0
	v_lshl_add_u64 v[180:181], v[130:131], 0, v[4:5]
	s_mov_b32 s43, 0
; template <int EPI, int NB>
; DEVI void gemm_tile(const GemmJob& J, int m0, int n0, unsigned char* smem) {
;     ...
;   f32x4 acc[4][NB];
; #pragma unroll
;   for (int i = 0; i < 4; ++i)
; #pragma unroll
;     for (int j = 0; j < NB; ++j) acc[i][j] = (f32x4){0.f, 0.f, 0.f, 0.f};
;     ...
;     if (kt + S - 1 < nk) GEMM_ISSUE(kt + S - 1, is);
;     is = (is + 1 == S) ? 0 : is + 1;
;     const unsigned cur = lbase + cs * STG;
;     cs = (cs + 1 == S) ? 0 : cs + 1;
;     bf16x8 af[4], bfr[NB];
;     const unsigned aa = cur + aofs, ba = cur + bofs;
	v_mov_b32_e32 v3, v2
	v_mov_b32_e32 v4, v2
	v_mov_b32_e32 v5, v2
	v_mov_b32_e32 v6, v2
	v_mov_b32_e32 v7, v2
	v_mov_b32_e32 v8, v2
	v_mov_b32_e32 v9, v2
	v_mov_b32_e32 v10, v2
	v_mov_b32_e32 v11, v2
	v_mov_b32_e32 v12, v2
	v_mov_b32_e32 v13, v2
	v_mov_b32_e32 v14, v2
	v_mov_b32_e32 v15, v2
	v_mov_b32_e32 v16, v2
	v_mov_b32_e32 v17, v2
	v_mov_b32_e32 v18, v2
	v_mov_b32_e32 v19, v2
	v_mov_b32_e32 v20, v2
	v_mov_b32_e32 v21, v2
	v_mov_b32_e32 v22, v2
	v_mov_b32_e32 v23, v2
	v_mov_b32_e32 v24, v2
	v_mov_b32_e32 v25, v2
	v_mov_b32_e32 v26, v2
	v_mov_b32_e32 v27, v2
	v_mov_b32_e32 v28, v2
	v_mov_b32_e32 v29, v2
	v_mov_b32_e32 v30, v2
	v_mov_b32_e32 v31, v2
	v_mov_b32_e32 v32, v2
	v_mov_b32_e32 v33, v2
	v_mov_b32_e32 v34, v2
	v_mov_b32_e32 v35, v2
	v_mov_b32_e32 v36, v2
	v_mov_b32_e32 v37, v2
	v_mov_b32_e32 v38, v2
	v_mov_b32_e32 v39, v2
	v_mov_b32_e32 v40, v2
	v_mov_b32_e32 v41, v2
	v_mov_b32_e32 v42, v2
	v_mov_b32_e32 v43, v2
	v_mov_b32_e32 v44, v2
	v_mov_b32_e32 v45, v2
	v_mov_b32_e32 v46, v2
	v_mov_b32_e32 v47, v2
	v_mov_b32_e32 v48, v2
	v_mov_b32_e32 v49, v2
	v_mov_b32_e32 v50, v2
	v_mov_b32_e32 v51, v2
	v_mov_b32_e32 v52, v2
	v_mov_b32_e32 v53, v2
	v_mov_b32_e32 v54, v2
	v_mov_b32_e32 v55, v2
	v_mov_b32_e32 v56, v2
	v_mov_b32_e32 v57, v2
	v_mov_b32_e32 v58, v2
	v_mov_b32_e32 v59, v2
	v_mov_b32_e32 v60, v2
	v_mov_b32_e32 v61, v2
	v_mov_b32_e32 v62, v2
	v_mov_b32_e32 v63, v2
	v_mov_b32_e32 v64, v2
	v_mov_b32_e32 v65, v2
	v_mov_b32_e32 v66, v2
	v_mov_b32_e32 v67, v2
	v_mov_b32_e32 v68, v2
	v_mov_b32_e32 v69, v2
	v_mov_b32_e32 v70, v2
	v_mov_b32_e32 v71, v2
	v_mov_b32_e32 v72, v2
	v_mov_b32_e32 v73, v2
	v_mov_b32_e32 v74, v2
	v_mov_b32_e32 v75, v2
	v_mov_b32_e32 v76, v2
	v_mov_b32_e32 v77, v2
	v_mov_b32_e32 v78, v2
	v_mov_b32_e32 v79, v2
	v_mov_b32_e32 v80, v2
	v_mov_b32_e32 v81, v2
	v_mov_b32_e32 v82, v2
	v_mov_b32_e32 v83, v2
	v_mov_b32_e32 v84, v2
	v_mov_b32_e32 v85, v2
	v_mov_b32_e32 v86, v2
	v_mov_b32_e32 v87, v2
	v_mov_b32_e32 v88, v2
	v_mov_b32_e32 v89, v2
	v_mov_b32_e32 v90, v2
	v_mov_b32_e32 v91, v2
	v_mov_b32_e32 v92, v2
	v_mov_b32_e32 v93, v2
	v_mov_b32_e32 v94, v2
	v_mov_b32_e32 v95, v2
	v_mov_b32_e32 v96, v2
	v_mov_b32_e32 v97, v2
	v_mov_b32_e32 v98, v2
	v_mov_b32_e32 v99, v2
	v_mov_b32_e32 v100, v2
	v_mov_b32_e32 v101, v2
	v_mov_b32_e32 v102, v2
	v_mov_b32_e32 v103, v2
	v_mov_b32_e32 v104, v2
	v_mov_b32_e32 v105, v2
	v_mov_b32_e32 v106, v2
	v_mov_b32_e32 v107, v2
	v_mov_b32_e32 v108, v2
	v_mov_b32_e32 v109, v2
	v_mov_b32_e32 v110, v2
	v_mov_b32_e32 v111, v2
	v_mov_b32_e32 v112, v2
	v_mov_b32_e32 v113, v2
	v_mov_b32_e32 v114, v2
	v_mov_b32_e32 v115, v2
	v_mov_b32_e32 v116, v2
	v_mov_b32_e32 v117, v2
	v_mov_b32_e32 v118, v2
	v_mov_b32_e32 v119, v2
	v_mov_b32_e32 v120, v2
	v_mov_b32_e32 v121, v2
	v_mov_b32_e32 v122, v2
	v_mov_b32_e32 v123, v2
	v_mov_b32_e32 v124, v2
	v_mov_b32_e32 v125, v2
	v_mov_b32_e32 v126, v2
	v_mov_b32_e32 v127, v2
	v_mov_b32_e32 v128, v2
	v_mov_b32_e32 v129, v2
	s_mul_i32 s0, s42, 0x6000
	v_add_u32_e32 v214, s0, v185
	v_lshl_add_u64 v[210:211], v[182:183], 0, v[0:1]
	v_readfirstlane_b32 s0, v214
	v_lshl_add_u64 v[212:213], v[210:211], 0, s[84:85]
	s_mov_b32 m0, s0
	v_lshl_add_u64 v[210:211], v[210:211], 0, s[12:13]
	s_nop 0
	v_readfirstlane_b32 s100, v212
	v_readfirstlane_b32 s101, v213
	s_nop 1
	v_subrev_u32_e32 v226, s100, v212
	v_add_u32_e32 v212, 0x1000, v214
	v_add_u32_e32 v215, 0x2000, v214
	v_readfirstlane_b32 s0, v212
	s_mov_b32 m0, s0
	s_mov_b64 s[0:1], 0x49a6000
	v_subrev_u32_e32 v227, s100, v210
	v_lshl_add_u64 v[210:211], v[180:181], 0, v[0:1]
	v_lshl_add_u64 v[212:213], v[210:211], 0, s[0:1]
	v_readfirstlane_b32 s0, v215
	s_mov_b32 m0, s0
	s_mov_b64 s[0:1], 0x49a7000
	v_add_u32_e32 v215, 0x3000, v214
	s_nop 0
	v_readfirstlane_b32 vcc_lo, v212
	v_readfirstlane_b32 vcc_hi, v213
	s_nop 1
	v_subrev_u32_e32 v228, vcc_lo, v212
	v_lshl_add_u64 v[212:213], v[210:211], 0, s[0:1]
	v_readfirstlane_b32 s0, v215
	s_mov_b32 m0, s0
	s_mov_b64 s[0:1], 0x49a8000
	v_add_u32_e32 v215, 0x4000, v214
	v_subrev_u32_e32 v229, vcc_lo, v212
	v_lshl_add_u64 v[212:213], v[210:211], 0, s[0:1]
	v_readfirstlane_b32 s0, v215
	s_mov_b32 m0, s0
	s_mov_b64 s[0:1], 0x49a9000
	v_subrev_u32_e32 v230, vcc_lo, v212
	v_add_u32_e32 v212, 0x5000, v214
	v_lshl_add_u64 v[210:211], v[210:211], 0, s[0:1]
	v_readfirstlane_b32 s0, v212
	s_mov_b32 m0, s0
	s_nop 0
	v_subrev_u32_e32 v231, vcc_lo, v210
	v_mov_b32_e32 v182, v226
	v_mov_b32_e32 v183, v227
	v_mov_b32_e32 v180, v228
	v_mov_b32_e32 v181, v229
	v_mov_b32_e32 v253, v230
	v_mov_b32_e32 v254, v231
	v_readfirstlane_b32 s0, v185
	s_branch .LBB0_774
	.p2align	6

; #define RAW_BARRIER() do { asm volatile("s_waitcnt lgkmcnt(0)" ::: "memory"); __builtin_amdgcn_s_barrier(); } while (0)
; template <int EPI, int NB>
; DEVI void gemm_tile(const GemmJob& J, int m0, int n0, unsigned char* smem) {
;     ...
;   const int srow = tid >> 2, sch = tid & 3;
;   const int gch = sch ^ ((0 - (tid >> 4)) & 3);
;   const bf16_t* Ag = J.A + (size_t)(m0 + srow) * (J.ablk ? 32 : J.lda) + gch * 8;
;   const bf16_t* Bg = J.Bt + (size_t)(n0 + srow) * 32 + gch * 8;
;   const size_t Astep = (size_t)64 * (J.ablk ? 32 : J.lda), Ak = J.ablk ? (size_t)MROWS * 32 : (size_t)32, Bstep = (size_t)64 * 32, Bk = (size_t)J.NR * 32;
;   const int nk = J.K >> 5;
;   unsigned char* lds_t = smem + tid * 16;
;   const unsigned lbase = (unsigned)(uintptr_t)(__attribute__((address_space(3))) unsigned char*)smem;
;     ...
;   asm volatile("s_waitcnt vmcnt(0)" ::: "memory");
;   RAW_BARRIER();
; #pragma unroll
;   for (int st = 0; st < S - 1; ++st) GEMM_ISSUE(st, st);
;   const int fsl = (g ^ ((0 - (l16 >> 2)) & 3)) << 4;
;   const int aofs = (wm * 64 + l16) * 64 + fsl;
;   const int bofs = A_BYTES + (wn * NB * 16 + l16) * 64 + fsl;
; template <int EPI, int NB>
; DEVI void gemm_run(const GemmJob& J, unsigned char* smem, int rot) {
;     ...
;     for (int t = b; t < ntiles; t += G) {
;       const int mt = t / J.ntn, nt = J.nt0 + (t - mt * J.ntn);
;       gemm_tile<EPI, NB>(J, mt * 128, nt * BN, smem);
.LBB0_1010:
	s_ashr_i32 s0, s9, 31
	s_lshr_b32 s0, s0, 30
	s_add_i32 s0, s9, s0
	s_ashr_i32 s0, s0, 2
	s_lshl_b32 s3, s0, 7
	s_lshl_b32 s0, s0, 10
	s_lshl_b32 s1, s9, 8
	v_mov_b32_e32 v184, v177
	s_sub_i32 s2, s1, s0
	s_nop 0
	s_mov_b64 s[28:29], 0x1000
	v_ashrrev_i32_e32 v10, 2, v184
	v_lshrrev_b32_e32 v0, 4, v184
	v_sub_u32_e32 v11, 0, v0
	v_add_u32_e32 v2, s3, v10
	v_add_u32_e32 v6, s2, v10
	v_xor_b32_e32 v0, v184, v11
	v_ashrrev_i32_e32 v3, 31, v2
	v_ashrrev_i32_e32 v7, 31, v6
	v_lshlrev_b64 v[2:3], 6, v[2:3]
	v_lshlrev_b32_e32 v0, 4, v0
	v_lshlrev_b64 v[6:7], 6, v[6:7]
	v_lshl_add_u64 v[4:5], v[146:147], 0, v[2:3]
	v_and_b32_e32 v0, 48, v0
	v_lshl_add_u64 v[6:7], v[144:145], 0, v[6:7]
	v_lshlrev_b32_e32 v185, 4, v184
	v_lshl_add_u64 v[4:5], v[4:5], 0, v[0:1]
	v_lshl_add_u64 v[6:7], v[6:7], 0, v[0:1]
	v_readfirstlane_b32 s1, v185
	v_add_u32_e32 v0, 0x1000, v185
	s_mov_b32 m0, s1
	v_readfirstlane_b32 s1, v0
	v_add_u32_e32 v0, 0x2000, v185
	s_waitcnt lgkmcnt(0)
	s_barrier
	global_load_lds_dwordx4 v[4:5], off
	v_lshl_add_u64 v[8:9], v[4:5], 0, s[28:29]
	s_mov_b32 m0, s1
	v_readfirstlane_b32 s1, v0
	v_add_u32_e32 v0, 0x3000, v185
	global_load_lds_dwordx4 v[8:9], off
	s_mov_b32 m0, s1
	v_readfirstlane_b32 s1, v0
	v_add_u32_e32 v0, 0x4000, v185
	global_load_lds_dwordx4 v[6:7], off
	v_lshl_add_u64 v[8:9], v[6:7], 0, s[28:29]
	s_mov_b32 m0, s1
	s_mov_b64 s[28:29], 0x2000
	v_readfirstlane_b32 s1, v0
	v_add_u32_e32 v0, 0x5000, v185
	global_load_lds_dwordx4 v[8:9], off
	v_lshl_add_u64 v[8:9], v[6:7], 0, s[28:29]
	s_mov_b32 m0, s1
	s_mov_b64 s[28:29], 0x3000
	v_readfirstlane_b32 s1, v0
	v_add_u32_e32 v0, 0x6000, v185
	global_load_lds_dwordx4 v[8:9], off
	v_lshl_add_u64 v[8:9], v[6:7], 0, s[28:29]
	s_mov_b32 m0, s1
	v_readfirstlane_b32 s1, v0
	v_add_u32_e32 v0, 0x7000, v185
	global_load_lds_dwordx4 v[8:9], off
	v_lshl_add_u64 v[8:9], v[4:5], 0, s[94:95]
	s_mov_b32 m0, s1
	s_mov_b64 s[28:29], 0x30b000
	v_readfirstlane_b32 s1, v0
	v_add_u32_e32 v0, 0x8000, v185
	global_load_lds_dwordx4 v[8:9], off
	v_lshl_add_u64 v[4:5], v[4:5], 0, s[28:29]
	s_mov_b32 m0, s1
	v_readfirstlane_b32 s1, v0
	v_add_u32_e32 v0, 0x9000, v185
	global_load_lds_dwordx4 v[4:5], off
	v_lshl_add_u64 v[4:5], v[6:7], 0, s[22:23]
	s_mov_b32 m0, s1
	s_mov_b64 s[28:29], 0x11000
	v_readfirstlane_b32 s1, v0
	v_add_u32_e32 v0, 0xa000, v185
	global_load_lds_dwordx4 v[4:5], off
	v_lshl_add_u64 v[4:5], v[6:7], 0, s[28:29]
	s_mov_b32 m0, s1
	s_mov_b64 s[28:29], 0x12000
	v_readfirstlane_b32 s1, v0
	v_add_u32_e32 v0, 0xb000, v185
	global_load_lds_dwordx4 v[4:5], off
	v_lshl_add_u64 v[4:5], v[6:7], 0, s[28:29]
	s_mov_b32 m0, s1
	s_mov_b64 s[28:29], 0x13000
	v_readfirstlane_b32 s1, v0
	global_load_lds_dwordx4 v[4:5], off
	v_lshl_add_u64 v[4:5], v[6:7], 0, s[28:29]
	s_mov_b32 m0, s1
	v_lshlrev_b32_e32 v0, 2, v184
	global_load_lds_dwordx4 v[4:5], off
	v_and_b32_e32 v0, 48, v0
	v_ashrrev_i32_e32 v4, 1, v184
	v_and_b32_e32 v186, 15, v184
	v_sub_u32_e32 v0, 0, v0
	v_and_b32_e32 v187, 0xffffffc0, v4
	v_bitop3_b32 v0, v184, 48, v0 bitop3:0x48
	v_or_b32_e32 v4, v187, v186
	v_lshl_or_b32 v209, v4, 6, v0
	v_lshlrev_b32_e32 v4, 1, v184
	v_and_b32_e32 v208, 0x80, v4
	v_or_b32_e32 v4, v208, v186
	v_lshl_or_b32 v0, v4, 6, v0
	v_add_u32_e32 v4, s8, v10
	v_subrev_u32_e32 v4, s0, v4
	v_ashrrev_i32_e32 v5, 31, v4
	v_add_u32_e32 v210, 0x2000, v0
	v_bitop3_b32 v0, v184, 3, v11 bitop3:0x48
	v_lshlrev_b64 v[4:5], 6, v[4:5]
	v_lshl_add_u64 v[182:183], v[130:131], 0, v[2:3]
	v_mov_b32_e32 v2, 0
	s_mov_b32 s42, 2
	s_mov_b32 s20, 0
	s_mov_b64 s[30:31], 0x1000
	v_lshlrev_b32_e32 v0, 4, v0
	v_lshl_add_u64 v[180:181], v[130:131], 0, v[4:5]
	s_mov_b32 s43, 0
	v_mov_b32_e32 v3, v2
	v_mov_b32_e32 v4, v2
	v_mov_b32_e32 v5, v2
	v_mov_b32_e32 v6, v2
	v_mov_b32_e32 v7, v2
	v_mov_b32_e32 v8, v2
	v_mov_b32_e32 v9, v2
	v_mov_b32_e32 v10, v2
	v_mov_b32_e32 v11, v2
	v_mov_b32_e32 v12, v2
	v_mov_b32_e32 v13, v2
	v_mov_b32_e32 v14, v2
	v_mov_b32_e32 v15, v2
	v_mov_b32_e32 v16, v2
	v_mov_b32_e32 v17, v2
	v_mov_b32_e32 v18, v2
	v_mov_b32_e32 v19, v2
	v_mov_b32_e32 v20, v2
	v_mov_b32_e32 v21, v2
	v_mov_b32_e32 v22, v2
	v_mov_b32_e32 v23, v2
; template <int EPI, int NB>
; DEVI void gemm_tile(const GemmJob& J, int m0, int n0, unsigned char* smem) {
;     ...
;   f32x4 acc[4][NB];
; #pragma unroll
;   for (int i = 0; i < 4; ++i)
; #pragma unroll
;     for (int j = 0; j < NB; ++j) acc[i][j] = (f32x4){0.f, 0.f, 0.f, 0.f};
;     ...
;     if (kt + S - 1 < nk) GEMM_ISSUE(kt + S - 1, is);
;     is = (is + 1 == S) ? 0 : is + 1;
;     const unsigned cur = lbase + cs * STG;
;     cs = (cs + 1 == S) ? 0 : cs + 1;
;     bf16x8 af[4], bfr[NB];
;     const unsigned aa = cur + aofs, ba = cur + bofs;
	v_mov_b32_e32 v24, v2
	v_mov_b32_e32 v25, v2
	v_mov_b32_e32 v26, v2
	v_mov_b32_e32 v27, v2
	v_mov_b32_e32 v28, v2
	v_mov_b32_e32 v29, v2
	v_mov_b32_e32 v30, v2
	v_mov_b32_e32 v31, v2
	v_mov_b32_e32 v32, v2
	v_mov_b32_e32 v33, v2
	v_mov_b32_e32 v34, v2
	v_mov_b32_e32 v35, v2
	v_mov_b32_e32 v36, v2
	v_mov_b32_e32 v37, v2
	v_mov_b32_e32 v38, v2
	v_mov_b32_e32 v39, v2
	v_mov_b32_e32 v40, v2
	v_mov_b32_e32 v41, v2
	v_mov_b32_e32 v42, v2
	v_mov_b32_e32 v43, v2
	v_mov_b32_e32 v44, v2
	v_mov_b32_e32 v45, v2
	v_mov_b32_e32 v46, v2
	v_mov_b32_e32 v47, v2
	v_mov_b32_e32 v48, v2
	v_mov_b32_e32 v49, v2
	v_mov_b32_e32 v50, v2
	v_mov_b32_e32 v51, v2
	v_mov_b32_e32 v52, v2
	v_mov_b32_e32 v53, v2
	v_mov_b32_e32 v54, v2
	v_mov_b32_e32 v55, v2
	v_mov_b32_e32 v56, v2
	v_mov_b32_e32 v57, v2
	v_mov_b32_e32 v58, v2
	v_mov_b32_e32 v59, v2
	v_mov_b32_e32 v60, v2
	v_mov_b32_e32 v61, v2
	v_mov_b32_e32 v62, v2
	v_mov_b32_e32 v63, v2
	v_mov_b32_e32 v64, v2
	v_mov_b32_e32 v65, v2
	v_mov_b32_e32 v66, v2
	v_mov_b32_e32 v67, v2
	v_mov_b32_e32 v68, v2
	v_mov_b32_e32 v69, v2
	v_mov_b32_e32 v70, v2
	v_mov_b32_e32 v71, v2
	v_mov_b32_e32 v72, v2
	v_mov_b32_e32 v73, v2
	v_mov_b32_e32 v74, v2
	v_mov_b32_e32 v75, v2
	v_mov_b32_e32 v76, v2
	v_mov_b32_e32 v77, v2
	v_mov_b32_e32 v78, v2
	v_mov_b32_e32 v79, v2
	v_mov_b32_e32 v80, v2
	v_mov_b32_e32 v81, v2
	v_mov_b32_e32 v82, v2
	v_mov_b32_e32 v83, v2
	v_mov_b32_e32 v84, v2
	v_mov_b32_e32 v85, v2
	v_mov_b32_e32 v86, v2
	v_mov_b32_e32 v87, v2
	v_mov_b32_e32 v88, v2
	v_mov_b32_e32 v89, v2
	v_mov_b32_e32 v90, v2
	v_mov_b32_e32 v91, v2
	v_mov_b32_e32 v92, v2
	v_mov_b32_e32 v93, v2
	v_mov_b32_e32 v94, v2
	v_mov_b32_e32 v95, v2
	v_mov_b32_e32 v96, v2
	v_mov_b32_e32 v97, v2
	v_mov_b32_e32 v98, v2
	v_mov_b32_e32 v99, v2
	v_mov_b32_e32 v100, v2
	v_mov_b32_e32 v101, v2
	v_mov_b32_e32 v102, v2
	v_mov_b32_e32 v103, v2
	v_mov_b32_e32 v104, v2
	v_mov_b32_e32 v105, v2
	v_mov_b32_e32 v106, v2
	v_mov_b32_e32 v107, v2
	v_mov_b32_e32 v108, v2
	v_mov_b32_e32 v109, v2
	v_mov_b32_e32 v110, v2
	v_mov_b32_e32 v111, v2
	v_mov_b32_e32 v112, v2
	v_mov_b32_e32 v113, v2
	v_mov_b32_e32 v114, v2
	v_mov_b32_e32 v115, v2
	v_mov_b32_e32 v116, v2
	v_mov_b32_e32 v117, v2
	v_mov_b32_e32 v118, v2
	v_mov_b32_e32 v119, v2
	v_mov_b32_e32 v120, v2
	v_mov_b32_e32 v121, v2
	v_mov_b32_e32 v122, v2
	v_mov_b32_e32 v123, v2
	v_mov_b32_e32 v124, v2
	v_mov_b32_e32 v125, v2
	v_mov_b32_e32 v126, v2
	v_mov_b32_e32 v127, v2
	v_mov_b32_e32 v128, v2
	v_mov_b32_e32 v129, v2
	s_mul_i32 s0, s42, 0x6000
	v_add_u32_e32 v211, s0, v185
	v_lshl_add_u64 v[212:213], v[182:183], 0, v[0:1]
	v_readfirstlane_b32 s0, v211
	v_lshl_add_u64 v[214:215], v[212:213], 0, s[84:85]
	s_mov_b32 m0, s0
	v_lshl_add_u64 v[212:213], v[212:213], 0, s[12:13]
	s_nop 0
	v_readfirstlane_b32 s100, v214
	v_readfirstlane_b32 s101, v215
	s_nop 1
	v_subrev_u32_e32 v228, s100, v214
	v_add_u32_e32 v214, 0x1000, v211
	v_add_u32_e32 v216, 0x2000, v211
	v_readfirstlane_b32 s0, v214
	s_mov_b32 m0, s0
	s_mov_b64 s[0:1], 0x4f66000
	v_subrev_u32_e32 v229, s100, v212
	v_lshl_add_u64 v[212:213], v[180:181], 0, v[0:1]
	v_lshl_add_u64 v[214:215], v[212:213], 0, s[0:1]
	v_readfirstlane_b32 s0, v216
	s_mov_b32 m0, s0
	s_mov_b64 s[0:1], 0x4f67000
	v_add_u32_e32 v216, 0x3000, v211
	s_nop 0
	v_readfirstlane_b32 vcc_lo, v214
	v_readfirstlane_b32 vcc_hi, v215
	s_nop 1
	v_subrev_u32_e32 v230, vcc_lo, v214
	v_lshl_add_u64 v[214:215], v[212:213], 0, s[0:1]
	v_readfirstlane_b32 s0, v216
	s_mov_b32 m0, s0
	s_mov_b64 s[0:1], 0x4f68000
	v_add_u32_e32 v216, 0x4000, v211
	v_subrev_u32_e32 v231, vcc_lo, v214
	v_lshl_add_u64 v[214:215], v[212:213], 0, s[0:1]
	v_readfirstlane_b32 s0, v216
	s_mov_b32 m0, s0
	s_mov_b64 s[0:1], 0x4f69000
	v_add_u32_e32 v211, 0x5000, v211
	v_lshl_add_u64 v[212:213], v[212:213], 0, s[0:1]
	v_readfirstlane_b32 s0, v211
	v_subrev_u32_e32 v232, vcc_lo, v214
	s_mov_b32 m0, s0
	s_nop 0
	v_subrev_u32_e32 v233, vcc_lo, v212
	v_mov_b32_e32 v182, v228
	v_mov_b32_e32 v183, v229
	v_mov_b32_e32 v180, v230
	v_mov_b32_e32 v181, v231
	v_mov_b32_e32 v253, v232
	v_mov_b32_e32 v254, v233
	v_readfirstlane_b32 s0, v185
	s_branch .LBB0_1012
	.p2align	6

; #define RAW_BARRIER() do { asm volatile("s_waitcnt lgkmcnt(0)" ::: "memory"); __builtin_amdgcn_s_barrier(); } while (0)
; template <int EPI, int NB>
; DEVI void gemm_tile(const GemmJob& J, int m0, int n0, unsigned char* smem) {
;     ...
;   const int srow = tid >> 2, sch = tid & 3;
;   const int gch = sch ^ ((0 - (tid >> 4)) & 3);
;   const bf16_t* Ag = J.A + (size_t)(m0 + srow) * (J.ablk ? 32 : J.lda) + gch * 8;
;   const bf16_t* Bg = J.Bt + (size_t)(n0 + srow) * 32 + gch * 8;
;   const size_t Astep = (size_t)64 * (J.ablk ? 32 : J.lda), Ak = J.ablk ? (size_t)MROWS * 32 : (size_t)32, Bstep = (size_t)64 * 32, Bk = (size_t)J.NR * 32;
;   const int nk = J.K >> 5;
;   unsigned char* lds_t = smem + tid * 16;
;   const unsigned lbase = (unsigned)(uintptr_t)(__attribute__((address_space(3))) unsigned char*)smem;
;     ...
;   asm volatile("s_waitcnt vmcnt(0)" ::: "memory");
;   RAW_BARRIER();
; #pragma unroll
;   for (int st = 0; st < S - 1; ++st) GEMM_ISSUE(st, st);
;   const int fsl = (g ^ ((0 - (l16 >> 2)) & 3)) << 4;
;   const int aofs = (wm * 64 + l16) * 64 + fsl;
;   const int bofs = A_BYTES + (wn * NB * 16 + l16) * 64 + fsl;
; template <int EPI, int NB>
; DEVI void gemm_run(const GemmJob& J, unsigned char* smem, int rot) {
;     ...
;     for (int q0 = lb; q0 < ntot; q0 += nlb) {
;       const int q = J.rev ? ntot - 1 - q0 : q0;
;       int grp = q / gsz; const int qq = q - grp * gsz;
;       const int mg = min(8, mcnt - grp * 8);
;       const int nt = qq / mg, mi = qq - nt * mg;
;       gemm_tile<EPI, NB>(J, (mlo + grp * 8 + mi) * 128, (J.nt0 + nt) * BN, smem);
.LBB0_1088:
	s_ashr_i32 s0, s9, 31
	s_lshr_b32 s0, s0, 27
	s_add_i32 s0, s9, s0
	s_ashr_i32 s1, s0, 5
	s_lshl_b32 s3, s1, 3
	v_readlane_b32 s2, v251, 48
	s_sub_i32 s2, s2, s3
	s_min_i32 s20, s2, 8
	s_abs_i32 s40, s20
	v_cvt_f32_u32_e32 v0, s40
	s_sub_i32 s43, 0, s40
	s_andn2_b32 s0, s0, 31
	s_sub_i32 s0, s9, s0
	v_rcp_iflag_f32_e32 v0, v0
	s_abs_i32 s41, s0
	s_xor_b32 s42, s0, s20
	s_ashr_i32 s42, s42, 31
	v_mul_f32_e32 v0, 0x4f7ffffe, v0
	v_cvt_u32_f32_e32 v0, v0
	v_mov_b32_e32 v184, v177
	s_nop 0
	v_readfirstlane_b32 s44, v0
	s_mul_i32 s43, s43, s44
	s_mul_hi_u32 s43, s44, s43
	s_add_i32 s44, s44, s43
	s_mul_hi_u32 s43, s41, s44
	s_mul_i32 s44, s43, s40
	s_sub_i32 s41, s41, s44
	s_add_i32 s45, s43, 1
	s_sub_i32 s44, s41, s40
	s_cmp_ge_u32 s41, s40
	s_cselect_b32 s43, s45, s43
	s_cselect_b32 s41, s44, s41
	s_add_i32 s44, s43, 1
	s_cmp_ge_u32 s41, s40
	s_cselect_b32 s40, s44, s43
	s_xor_b32 s40, s40, s42
	s_sub_i32 s40, s40, s42
	s_mul_i32 s41, s20, s40
	v_readlane_b32 s20, v250, 37
	s_add_i32 s3, s3, s20
	s_add_i32 s3, s3, s0
	s_sub_i32 s0, s3, s41
	s_lshl_b32 s20, s0, 7
	s_lshl_b32 s3, s40, 8
	v_ashrrev_i32_e32 v10, 2, v184
	v_lshrrev_b32_e32 v0, 4, v184
	v_sub_u32_e32 v11, 0, v0
	v_add_u32_e32 v2, s20, v10
	v_add_u32_e32 v4, s3, v10
	v_xor_b32_e32 v0, v184, v11
	v_ashrrev_i32_e32 v3, 31, v2
	v_ashrrev_i32_e32 v5, 31, v4
	v_lshlrev_b64 v[2:3], 6, v[2:3]
	v_lshlrev_b32_e32 v0, 4, v0
	v_lshlrev_b64 v[4:5], 6, v[4:5]
	v_lshl_add_u64 v[2:3], v[146:147], 0, v[2:3]
	v_and_b32_e32 v0, 48, v0
	v_lshl_add_u64 v[6:7], v[144:145], 0, v[4:5]
	v_lshlrev_b32_e32 v185, 4, v184
	v_lshl_add_u64 v[2:3], v[2:3], 0, v[0:1]
	v_lshl_add_u64 v[6:7], v[6:7], 0, v[0:1]
	v_readfirstlane_b32 s0, v185
	v_add_u32_e32 v0, 0x1000, v185
	s_mov_b32 m0, s0
	s_mov_b64 s[28:29], 0x1000
	v_readfirstlane_b32 s0, v0
	v_add_u32_e32 v0, 0x2000, v185
	s_waitcnt lgkmcnt(0)
	s_barrier
	global_load_lds_dwordx4 v[2:3], off
	v_lshl_add_u64 v[8:9], v[2:3], 0, s[28:29]
	s_mov_b32 m0, s0
	v_readfirstlane_b32 s0, v0
	v_add_u32_e32 v0, 0x3000, v185
	global_load_lds_dwordx4 v[8:9], off
	s_mov_b32 m0, s0
	v_readfirstlane_b32 s0, v0
	v_add_u32_e32 v0, 0x4000, v185
	global_load_lds_dwordx4 v[6:7], off
	v_lshl_add_u64 v[8:9], v[6:7], 0, s[28:29]
	s_mov_b32 m0, s0
	s_mov_b64 s[28:29], 0x2000
	v_readfirstlane_b32 s0, v0
	v_add_u32_e32 v0, 0x5000, v185
	global_load_lds_dwordx4 v[8:9], off
	v_lshl_add_u64 v[8:9], v[6:7], 0, s[28:29]
	s_mov_b32 m0, s0
	s_mov_b64 s[28:29], 0x3000
	v_readfirstlane_b32 s0, v0
	v_add_u32_e32 v0, 0x6000, v185
	global_load_lds_dwordx4 v[8:9], off
	v_lshl_add_u64 v[8:9], v[6:7], 0, s[28:29]
	s_mov_b32 m0, s0
	v_readfirstlane_b32 s0, v0
	v_add_u32_e32 v0, 0x7000, v185
	global_load_lds_dwordx4 v[8:9], off
	v_lshl_add_u64 v[8:9], v[2:3], 0, s[94:95]
	s_mov_b32 m0, s0
	s_mov_b64 s[28:29], 0x30b000
	v_readfirstlane_b32 s0, v0
	v_add_u32_e32 v0, 0x8000, v185
	global_load_lds_dwordx4 v[8:9], off
	v_lshl_add_u64 v[2:3], v[2:3], 0, s[28:29]
	s_mov_b32 m0, s0
	v_readfirstlane_b32 s0, v0
	v_add_u32_e32 v0, 0x9000, v185
	global_load_lds_dwordx4 v[2:3], off
	v_lshl_add_u64 v[2:3], v[6:7], 0, s[22:23]
	s_mov_b32 m0, s0
	s_mov_b64 s[28:29], 0x11000
	v_readfirstlane_b32 s0, v0
	v_add_u32_e32 v0, 0xa000, v185
	global_load_lds_dwordx4 v[2:3], off
	v_lshl_add_u64 v[2:3], v[6:7], 0, s[28:29]
	s_mov_b32 m0, s0
	s_mov_b64 s[28:29], 0x12000
	v_readfirstlane_b32 s0, v0
	v_add_u32_e32 v0, 0xb000, v185
	global_load_lds_dwordx4 v[2:3], off
	v_lshl_add_u64 v[2:3], v[6:7], 0, s[28:29]
	s_mov_b32 m0, s0
	s_mov_b64 s[28:29], 0x13000
	v_readfirstlane_b32 s0, v0
	global_load_lds_dwordx4 v[2:3], off
	v_lshl_add_u64 v[2:3], v[6:7], 0, s[28:29]
	s_mov_b32 m0, s0
	v_lshlrev_b32_e32 v0, 2, v184
	global_load_lds_dwordx4 v[2:3], off
	v_and_b32_e32 v0, 48, v0
	v_ashrrev_i32_e32 v2, 1, v184
	v_and_b32_e32 v186, 15, v184
	v_sub_u32_e32 v0, 0, v0
	v_and_b32_e32 v187, 0xffffffc0, v2
	v_bitop3_b32 v0, v184, 48, v0 bitop3:0x48
	v_or_b32_e32 v2, v187, v186
	v_lshl_or_b32 v209, v2, 6, v0
	v_lshlrev_b32_e32 v2, 1, v184
	v_and_b32_e32 v208, 0x80, v2
	s_sub_i32 s0, s8, s41
	s_mul_i32 s1, s1, 24
	v_or_b32_e32 v2, v208, v186
	s_sub_i32 s0, s0, s1
	v_lshl_or_b32 v0, v2, 6, v0
	v_lshl_add_u32 v2, s0, 7, v10
	v_ashrrev_i32_e32 v3, 31, v2
	v_lshlrev_b64 v[2:3], 6, v[2:3]
	v_add_u32_e32 v210, 0x2000, v0
	v_bitop3_b32 v0, v184, 3, v11 bitop3:0x48
	v_lshl_add_u64 v[182:183], v[130:131], 0, v[2:3]
	v_mov_b32_e32 v2, 0
	s_mov_b32 s2, 0
	s_mov_b32 s42, 2
	s_mov_b64 s[30:31], 0x1000
	v_lshlrev_b32_e32 v0, 4, v0
	v_lshl_add_u64 v[180:181], v[130:131], 0, v[4:5]
	s_mov_b32 s43, 0
	v_mov_b32_e32 v3, v2
; template <int EPI, int NB>
; DEVI void gemm_tile(const GemmJob& J, int m0, int n0, unsigned char* smem) {
;     ...
;   f32x4 acc[4][NB];
; #pragma unroll
;   for (int i = 0; i < 4; ++i)
; #pragma unroll
;     for (int j = 0; j < NB; ++j) acc[i][j] = (f32x4){0.f, 0.f, 0.f, 0.f};
;     ...
;     if (kt + S - 1 < nk) GEMM_ISSUE(kt + S - 1, is);
;     is = (is + 1 == S) ? 0 : is + 1;
;     const unsigned cur = lbase + cs * STG;
;     cs = (cs + 1 == S) ? 0 : cs + 1;
;     bf16x8 af[4], bfr[NB];
;     const unsigned aa = cur + aofs, ba = cur + bofs;
	v_mov_b32_e32 v4, v2
	v_mov_b32_e32 v5, v2
	v_mov_b32_e32 v6, v2
	v_mov_b32_e32 v7, v2
	v_mov_b32_e32 v8, v2
	v_mov_b32_e32 v9, v2
	v_mov_b32_e32 v10, v2
	v_mov_b32_e32 v11, v2
	v_mov_b32_e32 v12, v2
	v_mov_b32_e32 v13, v2
	v_mov_b32_e32 v14, v2
	v_mov_b32_e32 v15, v2
	v_mov_b32_e32 v16, v2
	v_mov_b32_e32 v17, v2
	v_mov_b32_e32 v18, v2
	v_mov_b32_e32 v19, v2
	v_mov_b32_e32 v20, v2
	v_mov_b32_e32 v21, v2
	v_mov_b32_e32 v22, v2
	v_mov_b32_e32 v23, v2
	v_mov_b32_e32 v24, v2
	v_mov_b32_e32 v25, v2
	v_mov_b32_e32 v26, v2
	v_mov_b32_e32 v27, v2
	v_mov_b32_e32 v28, v2
	v_mov_b32_e32 v29, v2
	v_mov_b32_e32 v30, v2
	v_mov_b32_e32 v31, v2
	v_mov_b32_e32 v32, v2
	v_mov_b32_e32 v33, v2
	v_mov_b32_e32 v34, v2
	v_mov_b32_e32 v35, v2
	v_mov_b32_e32 v36, v2
	v_mov_b32_e32 v37, v2
	v_mov_b32_e32 v38, v2
	v_mov_b32_e32 v39, v2
	v_mov_b32_e32 v40, v2
	v_mov_b32_e32 v41, v2
	v_mov_b32_e32 v42, v2
	v_mov_b32_e32 v43, v2
	v_mov_b32_e32 v44, v2
	v_mov_b32_e32 v45, v2
	v_mov_b32_e32 v46, v2
	v_mov_b32_e32 v47, v2
	v_mov_b32_e32 v48, v2
	v_mov_b32_e32 v49, v2
	v_mov_b32_e32 v50, v2
	v_mov_b32_e32 v51, v2
	v_mov_b32_e32 v52, v2
	v_mov_b32_e32 v53, v2
	v_mov_b32_e32 v54, v2
	v_mov_b32_e32 v55, v2
	v_mov_b32_e32 v56, v2
	v_mov_b32_e32 v57, v2
	v_mov_b32_e32 v58, v2
	v_mov_b32_e32 v59, v2
	v_mov_b32_e32 v60, v2
	v_mov_b32_e32 v61, v2
	v_mov_b32_e32 v62, v2
	v_mov_b32_e32 v63, v2
	v_mov_b32_e32 v64, v2
	v_mov_b32_e32 v65, v2
	v_mov_b32_e32 v66, v2
	v_mov_b32_e32 v67, v2
	v_mov_b32_e32 v68, v2
	v_mov_b32_e32 v69, v2
	v_mov_b32_e32 v70, v2
	v_mov_b32_e32 v71, v2
	v_mov_b32_e32 v72, v2
	v_mov_b32_e32 v73, v2
	v_mov_b32_e32 v74, v2
	v_mov_b32_e32 v75, v2
	v_mov_b32_e32 v76, v2
	v_mov_b32_e32 v77, v2
	v_mov_b32_e32 v78, v2
	v_mov_b32_e32 v79, v2
	v_mov_b32_e32 v80, v2
	v_mov_b32_e32 v81, v2
	v_mov_b32_e32 v82, v2
	v_mov_b32_e32 v83, v2
	v_mov_b32_e32 v84, v2
	v_mov_b32_e32 v85, v2
	v_mov_b32_e32 v86, v2
	v_mov_b32_e32 v87, v2
	v_mov_b32_e32 v88, v2
	v_mov_b32_e32 v89, v2
	v_mov_b32_e32 v90, v2
	v_mov_b32_e32 v91, v2
	v_mov_b32_e32 v92, v2
	v_mov_b32_e32 v93, v2
	v_mov_b32_e32 v94, v2
	v_mov_b32_e32 v95, v2
	v_mov_b32_e32 v96, v2
	v_mov_b32_e32 v97, v2
	v_mov_b32_e32 v98, v2
	v_mov_b32_e32 v99, v2
	v_mov_b32_e32 v100, v2
	v_mov_b32_e32 v101, v2
	v_mov_b32_e32 v102, v2
	v_mov_b32_e32 v103, v2
	v_mov_b32_e32 v104, v2
	v_mov_b32_e32 v105, v2
	v_mov_b32_e32 v106, v2
	v_mov_b32_e32 v107, v2
	v_mov_b32_e32 v108, v2
	v_mov_b32_e32 v109, v2
	v_mov_b32_e32 v110, v2
	v_mov_b32_e32 v111, v2
	v_mov_b32_e32 v112, v2
	v_mov_b32_e32 v113, v2
	v_mov_b32_e32 v114, v2
	v_mov_b32_e32 v115, v2
	v_mov_b32_e32 v116, v2
	v_mov_b32_e32 v117, v2
	v_mov_b32_e32 v118, v2
	v_mov_b32_e32 v119, v2
	v_mov_b32_e32 v120, v2
	v_mov_b32_e32 v121, v2
	v_mov_b32_e32 v122, v2
	v_mov_b32_e32 v123, v2
	v_mov_b32_e32 v124, v2
	v_mov_b32_e32 v125, v2
	v_mov_b32_e32 v126, v2
	v_mov_b32_e32 v127, v2
	v_mov_b32_e32 v128, v2
	v_mov_b32_e32 v129, v2
	s_mul_i32 s0, s42, 0x6000
	v_add_u32_e32 v211, s0, v185
	v_lshl_add_u64 v[212:213], v[182:183], 0, v[0:1]
	v_readfirstlane_b32 s0, v211
	v_lshl_add_u64 v[214:215], v[212:213], 0, s[84:85]
	s_mov_b32 m0, s0
	v_lshl_add_u64 v[212:213], v[212:213], 0, s[12:13]
	s_nop 0
	v_readfirstlane_b32 s100, v214
	v_readfirstlane_b32 s101, v215
	s_nop 1
	v_subrev_u32_e32 v228, s100, v214
	v_add_u32_e32 v214, 0x1000, v211
	v_add_u32_e32 v216, 0x2000, v211
	v_readfirstlane_b32 s0, v214
	s_mov_b32 m0, s0
	s_mov_b64 s[0:1], 0x4f66000
	v_subrev_u32_e32 v229, s100, v212
	v_lshl_add_u64 v[212:213], v[180:181], 0, v[0:1]
	v_lshl_add_u64 v[214:215], v[212:213], 0, s[0:1]
	v_readfirstlane_b32 s0, v216
	s_mov_b32 m0, s0
	s_mov_b64 s[0:1], 0x4f67000
	v_add_u32_e32 v216, 0x3000, v211
	s_nop 0
	v_readfirstlane_b32 vcc_lo, v214
	v_readfirstlane_b32 vcc_hi, v215
	s_nop 1
	v_subrev_u32_e32 v230, vcc_lo, v214
	v_lshl_add_u64 v[214:215], v[212:213], 0, s[0:1]
	v_readfirstlane_b32 s0, v216
	s_mov_b32 m0, s0
	s_mov_b64 s[0:1], 0x4f68000
	v_add_u32_e32 v216, 0x4000, v211
	v_subrev_u32_e32 v231, vcc_lo, v214
	v_lshl_add_u64 v[214:215], v[212:213], 0, s[0:1]
	v_readfirstlane_b32 s0, v216
	s_mov_b32 m0, s0
	s_mov_b64 s[0:1], 0x4f69000
	v_add_u32_e32 v211, 0x5000, v211
	v_lshl_add_u64 v[212:213], v[212:213], 0, s[0:1]
	v_readfirstlane_b32 s0, v211
	v_subrev_u32_e32 v232, vcc_lo, v214
	s_mov_b32 m0, s0
	s_nop 0
	v_subrev_u32_e32 v233, vcc_lo, v212
	v_mov_b32_e32 v182, v228
	v_mov_b32_e32 v183, v229
	v_mov_b32_e32 v180, v230
	v_mov_b32_e32 v181, v231
	v_mov_b32_e32 v253, v232
	v_mov_b32_e32 v254, v233
	v_readfirstlane_b32 s0, v185
	s_branch .LBB0_1090
	.p2align	6

; #define RAW_BARRIER() do { asm volatile("s_waitcnt lgkmcnt(0)" ::: "memory"); __builtin_amdgcn_s_barrier(); } while (0)
; template <int EPI, int NB>
; DEVI void gemm_tile(const GemmJob& J, int m0, int n0, unsigned char* smem) {
;     ...
;   const int srow = tid >> 2, sch = tid & 3;
;   const int gch = sch ^ ((0 - (tid >> 4)) & 3);
;   const bf16_t* Ag = J.A + (size_t)(m0 + srow) * (J.ablk ? 32 : J.lda) + gch * 8;
;   const bf16_t* Bg = J.Bt + (size_t)(n0 + srow) * 32 + gch * 8;
;   const size_t Astep = (size_t)64 * (J.ablk ? 32 : J.lda), Ak = J.ablk ? (size_t)MROWS * 32 : (size_t)32, Bstep = (size_t)64 * 32, Bk = (size_t)J.NR * 32;
;   const int nk = J.K >> 5;
;   unsigned char* lds_t = smem + tid * 16;
;   const unsigned lbase = (unsigned)(uintptr_t)(__attribute__((address_space(3))) unsigned char*)smem;
;     ...
;   asm volatile("s_waitcnt vmcnt(0)" ::: "memory");
;   RAW_BARRIER();
; #pragma unroll
;   for (int st = 0; st < S - 1; ++st) GEMM_ISSUE(st, st);
;   const int fsl = (g ^ ((0 - (l16 >> 2)) & 3)) << 4;
;   const int aofs = (wm * 64 + l16) * 64 + fsl;
;   const int bofs = A_BYTES + (wn * NB * 16 + l16) * 64 + fsl;
; template <int EPI, int NB>
; DEVI void gemm_run(const GemmJob& J, unsigned char* smem, int rot) {
;     ...
;     for (int t = b; t < ntiles; t += G) {
;       const int mt = t / J.ntn, nt = J.nt0 + (t - mt * J.ntn);
;       gemm_tile<EPI, NB>(J, mt * 128, nt * BN, smem);
.LBB0_1215:
	s_mul_hi_i32 s0, s9, 0x66666667
	s_lshr_b32 s1, s0, 31
	s_ashr_i32 s0, s0, 1
	s_add_i32 s0, s0, s1
	s_mul_i32 s1, s0, -5
	s_add_i32 s1, s1, s9
	v_mov_b32_e32 v184, v177
	s_lshl_b32 s3, s0, 7
	s_lshl_b32 s2, s1, 8
	s_nop 0
	s_mov_b64 s[28:29], 0x1000
	v_ashrrev_i32_e32 v10, 2, v184
	v_lshrrev_b32_e32 v0, 4, v184
	v_sub_u32_e32 v11, 0, v0
	v_add_u32_e32 v2, s3, v10
	v_add_u32_e32 v6, s2, v10
	v_xor_b32_e32 v0, v184, v11
	v_ashrrev_i32_e32 v3, 31, v2
	v_ashrrev_i32_e32 v7, 31, v6
	v_lshlrev_b64 v[2:3], 6, v[2:3]
	v_lshlrev_b32_e32 v0, 4, v0
	v_lshlrev_b64 v[6:7], 6, v[6:7]
	v_lshl_add_u64 v[4:5], v[146:147], 0, v[2:3]
	v_and_b32_e32 v0, 48, v0
	v_lshl_add_u64 v[6:7], v[134:135], 0, v[6:7]
	v_lshlrev_b32_e32 v185, 4, v184
	v_lshl_add_u64 v[4:5], v[4:5], 0, v[0:1]
	v_lshl_add_u64 v[6:7], v[6:7], 0, v[0:1]
	v_readfirstlane_b32 s1, v185
	v_add_u32_e32 v0, 0x1000, v185
	s_mov_b32 m0, s1
	v_readfirstlane_b32 s1, v0
	v_add_u32_e32 v0, 0x2000, v185
	s_waitcnt lgkmcnt(0)
	s_barrier
	global_load_lds_dwordx4 v[4:5], off
	v_lshl_add_u64 v[8:9], v[4:5], 0, s[28:29]
	s_mov_b32 m0, s1
	v_readfirstlane_b32 s1, v0
	v_add_u32_e32 v0, 0x3000, v185
	global_load_lds_dwordx4 v[8:9], off
	s_mov_b32 m0, s1
	v_readfirstlane_b32 s1, v0
	v_add_u32_e32 v0, 0x4000, v185
	global_load_lds_dwordx4 v[6:7], off
	v_lshl_add_u64 v[8:9], v[6:7], 0, s[28:29]
	s_mov_b32 m0, s1
	s_mov_b64 s[28:29], 0x2000
	v_readfirstlane_b32 s1, v0
	v_add_u32_e32 v0, 0x5000, v185
	global_load_lds_dwordx4 v[8:9], off
	v_lshl_add_u64 v[8:9], v[6:7], 0, s[28:29]
	s_mov_b32 m0, s1
	s_mov_b64 s[28:29], 0x3000
	v_readfirstlane_b32 s1, v0
	v_add_u32_e32 v0, 0x6000, v185
	global_load_lds_dwordx4 v[8:9], off
	v_lshl_add_u64 v[8:9], v[6:7], 0, s[28:29]
	s_mov_b32 m0, s1
	v_readfirstlane_b32 s1, v0
	v_add_u32_e32 v0, 0x7000, v185
	global_load_lds_dwordx4 v[8:9], off
	v_lshl_add_u64 v[8:9], v[4:5], 0, s[94:95]
	s_mov_b32 m0, s1
	s_mov_b64 s[28:29], 0x30b000
	v_readfirstlane_b32 s1, v0
	v_add_u32_e32 v0, 0x8000, v185
	global_load_lds_dwordx4 v[8:9], off
	v_lshl_add_u64 v[4:5], v[4:5], 0, s[28:29]
	s_mov_b32 m0, s1
	v_readfirstlane_b32 s1, v0
	v_add_u32_e32 v0, 0x9000, v185
	global_load_lds_dwordx4 v[4:5], off
	v_lshl_add_u64 v[4:5], v[6:7], 0, s[38:39]
	s_mov_b32 m0, s1
	s_mov_b64 s[28:29], 0x19000
	v_readfirstlane_b32 s1, v0
	v_add_u32_e32 v0, 0xa000, v185
	global_load_lds_dwordx4 v[4:5], off
	v_lshl_add_u64 v[4:5], v[6:7], 0, s[28:29]
	s_mov_b32 m0, s1
	s_mov_b64 s[28:29], 0x1a000
	v_readfirstlane_b32 s1, v0
	v_add_u32_e32 v0, 0xb000, v185
	global_load_lds_dwordx4 v[4:5], off
	v_lshl_add_u64 v[4:5], v[6:7], 0, s[28:29]
	s_mov_b32 m0, s1
	s_mov_b64 s[28:29], 0x1b000
	v_readfirstlane_b32 s1, v0
	global_load_lds_dwordx4 v[4:5], off
	v_lshl_add_u64 v[4:5], v[6:7], 0, s[28:29]
	s_mov_b32 m0, s1
	v_lshlrev_b32_e32 v0, 2, v184
	global_load_lds_dwordx4 v[4:5], off
	v_and_b32_e32 v0, 48, v0
	v_ashrrev_i32_e32 v4, 1, v184
	v_and_b32_e32 v186, 15, v184
	v_sub_u32_e32 v0, 0, v0
	v_and_b32_e32 v187, 0xffffffc0, v4
	v_bitop3_b32 v0, v184, 48, v0 bitop3:0x48
	v_or_b32_e32 v4, v187, v186
	v_lshl_or_b32 v209, v4, 6, v0
	v_lshlrev_b32_e32 v4, 1, v184
	v_and_b32_e32 v208, 0x80, v4
	v_or_b32_e32 v4, v208, v186
	v_lshl_or_b32 v0, v4, 6, v0
	v_add_u32_e32 v4, s8, v10
	s_mulk_i32 s0, 0x500
	v_subrev_u32_e32 v4, s0, v4
	v_ashrrev_i32_e32 v5, 31, v4
	v_add_u32_e32 v210, 0x2000, v0
	v_bitop3_b32 v0, v184, 3, v11 bitop3:0x48
	v_lshlrev_b64 v[4:5], 6, v[4:5]
	v_lshl_add_u64 v[182:183], v[130:131], 0, v[2:3]
	v_mov_b32_e32 v2, 0
	s_mov_b32 s42, 2
	s_mov_b32 s20, 0
	s_mov_b64 s[30:31], 0x1000
	v_lshlrev_b32_e32 v0, 4, v0
	v_lshl_add_u64 v[180:181], v[130:131], 0, v[4:5]
	s_mov_b32 s43, 0
	v_mov_b32_e32 v3, v2
	v_mov_b32_e32 v4, v2
	v_mov_b32_e32 v5, v2
	v_mov_b32_e32 v6, v2
	v_mov_b32_e32 v7, v2
	v_mov_b32_e32 v8, v2
	v_mov_b32_e32 v9, v2
	v_mov_b32_e32 v10, v2
	v_mov_b32_e32 v11, v2
	v_mov_b32_e32 v12, v2
	v_mov_b32_e32 v13, v2
	v_mov_b32_e32 v14, v2
	v_mov_b32_e32 v15, v2
	v_mov_b32_e32 v16, v2
	v_mov_b32_e32 v17, v2
	v_mov_b32_e32 v18, v2
	v_mov_b32_e32 v19, v2
	v_mov_b32_e32 v20, v2
	v_mov_b32_e32 v21, v2
	v_mov_b32_e32 v22, v2
; template <int EPI, int NB>
; DEVI void gemm_tile(const GemmJob& J, int m0, int n0, unsigned char* smem) {
;     ...
;   f32x4 acc[4][NB];
; #pragma unroll
;   for (int i = 0; i < 4; ++i)
; #pragma unroll
;     for (int j = 0; j < NB; ++j) acc[i][j] = (f32x4){0.f, 0.f, 0.f, 0.f};
;     ...
;     if (kt + S - 1 < nk) GEMM_ISSUE(kt + S - 1, is);
;     is = (is + 1 == S) ? 0 : is + 1;
;     const unsigned cur = lbase + cs * STG;
;     cs = (cs + 1 == S) ? 0 : cs + 1;
;     bf16x8 af[4], bfr[NB];
;     const unsigned aa = cur + aofs, ba = cur + bofs;
	v_mov_b32_e32 v23, v2
	v_mov_b32_e32 v24, v2
	v_mov_b32_e32 v25, v2
	v_mov_b32_e32 v26, v2
	v_mov_b32_e32 v27, v2
	v_mov_b32_e32 v28, v2
	v_mov_b32_e32 v29, v2
	v_mov_b32_e32 v30, v2
	v_mov_b32_e32 v31, v2
	v_mov_b32_e32 v32, v2
	v_mov_b32_e32 v33, v2
	v_mov_b32_e32 v34, v2
	v_mov_b32_e32 v35, v2
	v_mov_b32_e32 v36, v2
	v_mov_b32_e32 v37, v2
	v_mov_b32_e32 v38, v2
	v_mov_b32_e32 v39, v2
	v_mov_b32_e32 v40, v2
	v_mov_b32_e32 v41, v2
	v_mov_b32_e32 v42, v2
	v_mov_b32_e32 v43, v2
	v_mov_b32_e32 v44, v2
	v_mov_b32_e32 v45, v2
	v_mov_b32_e32 v46, v2
	v_mov_b32_e32 v47, v2
	v_mov_b32_e32 v48, v2
	v_mov_b32_e32 v49, v2
	v_mov_b32_e32 v50, v2
	v_mov_b32_e32 v51, v2
	v_mov_b32_e32 v52, v2
	v_mov_b32_e32 v53, v2
	v_mov_b32_e32 v54, v2
	v_mov_b32_e32 v55, v2
	v_mov_b32_e32 v56, v2
	v_mov_b32_e32 v57, v2
	v_mov_b32_e32 v58, v2
	v_mov_b32_e32 v59, v2
	v_mov_b32_e32 v60, v2
	v_mov_b32_e32 v61, v2
	v_mov_b32_e32 v62, v2
	v_mov_b32_e32 v63, v2
	v_mov_b32_e32 v64, v2
	v_mov_b32_e32 v65, v2
	v_mov_b32_e32 v66, v2
	v_mov_b32_e32 v67, v2
	v_mov_b32_e32 v68, v2
	v_mov_b32_e32 v69, v2
	v_mov_b32_e32 v70, v2
	v_mov_b32_e32 v71, v2
	v_mov_b32_e32 v72, v2
	v_mov_b32_e32 v73, v2
	v_mov_b32_e32 v74, v2
	v_mov_b32_e32 v75, v2
	v_mov_b32_e32 v76, v2
	v_mov_b32_e32 v77, v2
	v_mov_b32_e32 v78, v2
	v_mov_b32_e32 v79, v2
	v_mov_b32_e32 v80, v2
	v_mov_b32_e32 v81, v2
	v_mov_b32_e32 v82, v2
	v_mov_b32_e32 v83, v2
	v_mov_b32_e32 v84, v2
	v_mov_b32_e32 v85, v2
	v_mov_b32_e32 v86, v2
	v_mov_b32_e32 v87, v2
	v_mov_b32_e32 v88, v2
	v_mov_b32_e32 v89, v2
	v_mov_b32_e32 v90, v2
	v_mov_b32_e32 v91, v2
	v_mov_b32_e32 v92, v2
	v_mov_b32_e32 v93, v2
	v_mov_b32_e32 v94, v2
	v_mov_b32_e32 v95, v2
	v_mov_b32_e32 v96, v2
	v_mov_b32_e32 v97, v2
	v_mov_b32_e32 v98, v2
	v_mov_b32_e32 v99, v2
	v_mov_b32_e32 v100, v2
	v_mov_b32_e32 v101, v2
	v_mov_b32_e32 v102, v2
	v_mov_b32_e32 v103, v2
	v_mov_b32_e32 v104, v2
	v_mov_b32_e32 v105, v2
	v_mov_b32_e32 v106, v2
	v_mov_b32_e32 v107, v2
	v_mov_b32_e32 v108, v2
	v_mov_b32_e32 v109, v2
	v_mov_b32_e32 v110, v2
	v_mov_b32_e32 v111, v2
	v_mov_b32_e32 v112, v2
	v_mov_b32_e32 v113, v2
	v_mov_b32_e32 v114, v2
	v_mov_b32_e32 v115, v2
	v_mov_b32_e32 v116, v2
	v_mov_b32_e32 v117, v2
	v_mov_b32_e32 v118, v2
	v_mov_b32_e32 v119, v2
	v_mov_b32_e32 v120, v2
	v_mov_b32_e32 v121, v2
	v_mov_b32_e32 v122, v2
	v_mov_b32_e32 v123, v2
	v_mov_b32_e32 v124, v2
	v_mov_b32_e32 v125, v2
	v_mov_b32_e32 v126, v2
	v_mov_b32_e32 v127, v2
	v_mov_b32_e32 v128, v2
	v_mov_b32_e32 v129, v2
	s_mul_i32 s0, s42, 0x6000
	v_add_u32_e32 v211, s0, v185
	v_lshl_add_u64 v[212:213], v[182:183], 0, v[0:1]
	v_readfirstlane_b32 s0, v211
	v_lshl_add_u64 v[214:215], v[212:213], 0, s[84:85]
	s_mov_b32 m0, s0
	v_lshl_add_u64 v[212:213], v[212:213], 0, s[12:13]
	s_nop 0
	v_readfirstlane_b32 s100, v214
	v_readfirstlane_b32 s101, v215
	s_nop 1
	v_subrev_u32_e32 v228, s100, v214
	v_add_u32_e32 v214, 0x1000, v211
	v_add_u32_e32 v216, 0x2000, v211
	v_readfirstlane_b32 s0, v214
	s_mov_b32 m0, s0
	s_mov_b64 s[0:1], 0x43d6000
	v_subrev_u32_e32 v229, s100, v212
	v_lshl_add_u64 v[212:213], v[180:181], 0, v[0:1]
	v_lshl_add_u64 v[214:215], v[212:213], 0, s[0:1]
	v_readfirstlane_b32 s0, v216
	s_mov_b32 m0, s0
	s_mov_b64 s[0:1], 0x43d7000
	v_add_u32_e32 v216, 0x3000, v211
	s_nop 0
	v_readfirstlane_b32 vcc_lo, v214
	v_readfirstlane_b32 vcc_hi, v215
	s_nop 1
	v_subrev_u32_e32 v230, vcc_lo, v214
	v_lshl_add_u64 v[214:215], v[212:213], 0, s[0:1]
	v_readfirstlane_b32 s0, v216
	s_mov_b32 m0, s0
	s_mov_b64 s[0:1], 0x43d8000
	v_add_u32_e32 v216, 0x4000, v211
	v_subrev_u32_e32 v231, vcc_lo, v214
	v_lshl_add_u64 v[214:215], v[212:213], 0, s[0:1]
	v_readfirstlane_b32 s0, v216
	s_mov_b32 m0, s0
	s_mov_b64 s[0:1], 0x43d9000
	v_add_u32_e32 v211, 0x5000, v211
	v_lshl_add_u64 v[212:213], v[212:213], 0, s[0:1]
	v_readfirstlane_b32 s0, v211
	v_subrev_u32_e32 v232, vcc_lo, v214
	s_mov_b32 m0, s0
	s_nop 0
	v_subrev_u32_e32 v233, vcc_lo, v212
	v_mov_b32_e32 v182, v228
	v_mov_b32_e32 v183, v229
	v_mov_b32_e32 v180, v230
	v_mov_b32_e32 v181, v231
	v_mov_b32_e32 v253, v232
	v_mov_b32_e32 v254, v233
	v_readfirstlane_b32 s0, v185
	s_branch .LBB0_1217
	.p2align	6

; #define RAW_BARRIER() do { asm volatile("s_waitcnt lgkmcnt(0)" ::: "memory"); __builtin_amdgcn_s_barrier(); } while (0)
; template <int EPI, int NB>
; DEVI void gemm_tile(const GemmJob& J, int m0, int n0, unsigned char* smem) {
;     ...
;   const int srow = tid >> 2, sch = tid & 3;
;   const int gch = sch ^ ((0 - (tid >> 4)) & 3);
;   const bf16_t* Ag = J.A + (size_t)(m0 + srow) * (J.ablk ? 32 : J.lda) + gch * 8;
;   const bf16_t* Bg = J.Bt + (size_t)(n0 + srow) * 32 + gch * 8;
;   const size_t Astep = (size_t)64 * (J.ablk ? 32 : J.lda), Ak = J.ablk ? (size_t)MROWS * 32 : (size_t)32, Bstep = (size_t)64 * 32, Bk = (size_t)J.NR * 32;
;   const int nk = J.K >> 5;
;   unsigned char* lds_t = smem + tid * 16;
;   const unsigned lbase = (unsigned)(uintptr_t)(__attribute__((address_space(3))) unsigned char*)smem;
;     ...
;   asm volatile("s_waitcnt vmcnt(0)" ::: "memory");
;   RAW_BARRIER();
; #pragma unroll
;   for (int st = 0; st < S - 1; ++st) GEMM_ISSUE(st, st);
;   const int fsl = (g ^ ((0 - (l16 >> 2)) & 3)) << 4;
;   const int aofs = (wm * 64 + l16) * 64 + fsl;
;   const int bofs = A_BYTES + (wn * NB * 16 + l16) * 64 + fsl;
; template <int EPI, int NB>
; DEVI void gemm_run(const GemmJob& J, unsigned char* smem, int rot) {
;     ...
;     for (int t = b; t < ntiles; t += G) {
;       const int mt = t / J.ntn, nt = J.nt0 + (t - mt * J.ntn);
;       gemm_tile<EPI, NB>(J, mt * 128, nt * BN, smem);
.LBB0_1293:
	v_mov_b32_e32 v185, v177
	s_lshl_b32 s8, s3, 7
	v_lshrrev_b32_e32 v0, 4, v185
	v_ashrrev_i32_e32 v2, 2, v185
	v_sub_u32_e32 v14, 0, v0
	v_xor_b32_e32 v0, v185, v14
	v_add_u32_e32 v4, s8, v2
	v_ashrrev_i32_e32 v3, 31, v2
	v_ashrrev_i32_e32 v5, 31, v4
	v_lshlrev_b32_e32 v0, 4, v0
	v_lshlrev_b64 v[6:7], 6, v[2:3]
	v_lshlrev_b64 v[4:5], 6, v[4:5]
	v_and_b32_e32 v0, 48, v0
	v_lshl_add_u64 v[8:9], v[134:135], 0, v[6:7]
	v_lshl_add_u64 v[4:5], v[146:147], 0, v[4:5]
	v_lshl_add_u64 v[8:9], v[8:9], 0, v[0:1]
	s_mov_b64 s[0:1], 0x14000
	v_lshlrev_b32_e32 v186, 4, v185
	v_lshl_add_u64 v[4:5], v[4:5], 0, v[0:1]
	v_lshl_add_u64 v[10:11], v[8:9], 0, s[0:1]
	v_readfirstlane_b32 s0, v186
	v_add_u32_e32 v0, 0x1000, v186
	s_nop 0
	s_mov_b32 m0, s0
	v_readfirstlane_b32 s0, v0
	v_add_u32_e32 v0, 0x2000, v186
	s_waitcnt lgkmcnt(0)
	s_barrier
	global_load_lds_dwordx4 v[4:5], off
	v_lshl_add_u64 v[12:13], v[4:5], 0, s[30:31]
	s_mov_b32 m0, s0
	v_readfirstlane_b32 s0, v0
	global_load_lds_dwordx4 v[12:13], off
	s_mov_b32 m0, s0
	s_mov_b64 s[0:1], 0x15000
	v_add_u32_e32 v0, 0x3000, v186
	global_load_lds_dwordx4 v[10:11], off
	v_lshl_add_u64 v[10:11], v[8:9], 0, s[0:1]
	v_readfirstlane_b32 s0, v0
	s_mov_b32 m0, s0
	s_mov_b64 s[0:1], 0x16000
	v_add_u32_e32 v0, 0x4000, v186
	global_load_lds_dwordx4 v[10:11], off
	v_lshl_add_u64 v[10:11], v[8:9], 0, s[0:1]
	v_readfirstlane_b32 s0, v0
	s_mov_b32 m0, s0
	s_mov_b64 s[0:1], 0x17000
	v_add_u32_e32 v0, 0x5000, v186
	global_load_lds_dwordx4 v[10:11], off
	v_lshl_add_u64 v[10:11], v[8:9], 0, s[0:1]
	v_readfirstlane_b32 s0, v0
	v_add_u32_e32 v0, 0x6000, v186
	s_mov_b32 m0, s0
	v_readfirstlane_b32 s0, v0
	global_load_lds_dwordx4 v[10:11], off
	s_mov_b32 m0, s0
	s_mov_b64 s[0:1], 0x30b000
	v_add_u32_e32 v0, 0x7000, v186
	v_lshl_add_u64 v[10:11], v[4:5], 0, s[94:95]
	v_lshl_add_u64 v[4:5], v[4:5], 0, s[0:1]
	v_readfirstlane_b32 s0, v0
	global_load_lds_dwordx4 v[10:11], off
	s_mov_b32 m0, s0
	s_mov_b64 s[0:1], 0x2c000
	v_add_u32_e32 v0, 0x8000, v186
	global_load_lds_dwordx4 v[4:5], off
	v_lshl_add_u64 v[4:5], v[8:9], 0, s[0:1]
	v_readfirstlane_b32 s0, v0
	s_mov_b32 m0, s0
	s_mov_b64 s[0:1], 0x2d000
	v_add_u32_e32 v0, 0x9000, v186
	global_load_lds_dwordx4 v[4:5], off
	v_lshl_add_u64 v[4:5], v[8:9], 0, s[0:1]
	v_readfirstlane_b32 s0, v0
	s_mov_b32 m0, s0
	s_mov_b64 s[0:1], 0x2e000
	v_add_u32_e32 v0, 0xa000, v186
	global_load_lds_dwordx4 v[4:5], off
	v_lshl_add_u64 v[4:5], v[8:9], 0, s[0:1]
	v_readfirstlane_b32 s0, v0
	s_mov_b32 m0, s0
	s_mov_b64 s[0:1], 0x2f000
	v_add_u32_e32 v0, 0xb000, v186
	global_load_lds_dwordx4 v[4:5], off
	v_lshl_add_u64 v[4:5], v[8:9], 0, s[0:1]
	v_readfirstlane_b32 s0, v0
	s_mov_b32 m0, s0
	v_lshlrev_b32_e32 v3, 2, v185
	global_load_lds_dwordx4 v[4:5], off
	v_and_b32_e32 v3, 48, v3
	v_ashrrev_i32_e32 v4, 1, v185
	v_and_b32_e32 v0, 15, v185
	v_sub_u32_e32 v3, 0, v3
	v_and_b32_e32 v208, 0xffffffc0, v4
	v_bitop3_b32 v3, v185, 48, v3 bitop3:0x48
	v_or_b32_e32 v4, v208, v0
	v_lshl_or_b32 v209, v4, 6, v3
	v_lshlrev_b32_e32 v4, 1, v185
	v_and_b32_e32 v187, 0x80, v4
	v_or_b32_e32 v184, v187, v0
	v_add_u32_e32 v2, s2, v2
	v_lshl_or_b32 v0, v184, 6, v3
	v_ashrrev_i32_e32 v3, 31, v2
	v_lshlrev_b64 v[2:3], 6, v[2:3]
	v_add_u32_e32 v210, 0x2000, v0
	v_bitop3_b32 v0, v185, 3, v14 bitop3:0x48
	v_lshl_add_u64 v[182:183], v[130:131], 0, v[2:3]
	v_mov_b32_e32 v2, 0
	s_mov_b32 s20, 2
	s_mov_b32 s9, 0
	v_lshlrev_b32_e32 v0, 4, v0
	v_lshl_add_u64 v[180:181], v[130:131], 0, v[6:7]
	s_mov_b32 s42, 0
	v_mov_b32_e32 v3, v2
	v_mov_b32_e32 v4, v2
	v_mov_b32_e32 v5, v2
	v_mov_b32_e32 v6, v2
	v_mov_b32_e32 v7, v2
	v_mov_b32_e32 v8, v2
	v_mov_b32_e32 v9, v2
	v_mov_b32_e32 v10, v2
	v_mov_b32_e32 v11, v2
	v_mov_b32_e32 v12, v2
	v_mov_b32_e32 v13, v2
	v_mov_b32_e32 v14, v2
	v_mov_b32_e32 v15, v2
	v_mov_b32_e32 v16, v2
	v_mov_b32_e32 v17, v2
	v_mov_b32_e32 v18, v2
	v_mov_b32_e32 v19, v2
	v_mov_b32_e32 v20, v2
	v_mov_b32_e32 v21, v2
	v_mov_b32_e32 v22, v2
	v_mov_b32_e32 v23, v2
	v_mov_b32_e32 v24, v2
	v_mov_b32_e32 v25, v2
	v_mov_b32_e32 v26, v2
; template <int EPI, int NB>
; DEVI void gemm_tile(const GemmJob& J, int m0, int n0, unsigned char* smem) {
;     ...
;   f32x4 acc[4][NB];
; #pragma unroll
;   for (int i = 0; i < 4; ++i)
; #pragma unroll
;     for (int j = 0; j < NB; ++j) acc[i][j] = (f32x4){0.f, 0.f, 0.f, 0.f};
;     ...
;     if (kt + S - 1 < nk) GEMM_ISSUE(kt + S - 1, is);
;     is = (is + 1 == S) ? 0 : is + 1;
;     const unsigned cur = lbase + cs * STG;
;     cs = (cs + 1 == S) ? 0 : cs + 1;
;     bf16x8 af[4], bfr[NB];
;     const unsigned aa = cur + aofs, ba = cur + bofs;
	v_mov_b32_e32 v27, v2
	v_mov_b32_e32 v28, v2
	v_mov_b32_e32 v29, v2
	v_mov_b32_e32 v30, v2
	v_mov_b32_e32 v31, v2
	v_mov_b32_e32 v32, v2
	v_mov_b32_e32 v33, v2
	v_mov_b32_e32 v34, v2
	v_mov_b32_e32 v35, v2
	v_mov_b32_e32 v36, v2
	v_mov_b32_e32 v37, v2
	v_mov_b32_e32 v38, v2
	v_mov_b32_e32 v39, v2
	v_mov_b32_e32 v40, v2
	v_mov_b32_e32 v41, v2
	v_mov_b32_e32 v42, v2
	v_mov_b32_e32 v43, v2
	v_mov_b32_e32 v44, v2
	v_mov_b32_e32 v45, v2
	v_mov_b32_e32 v46, v2
	v_mov_b32_e32 v47, v2
	v_mov_b32_e32 v48, v2
	v_mov_b32_e32 v49, v2
	v_mov_b32_e32 v50, v2
	v_mov_b32_e32 v51, v2
	v_mov_b32_e32 v52, v2
	v_mov_b32_e32 v53, v2
	v_mov_b32_e32 v54, v2
	v_mov_b32_e32 v55, v2
	v_mov_b32_e32 v56, v2
	v_mov_b32_e32 v57, v2
	v_mov_b32_e32 v58, v2
	v_mov_b32_e32 v59, v2
	v_mov_b32_e32 v60, v2
	v_mov_b32_e32 v61, v2
	v_mov_b32_e32 v62, v2
	v_mov_b32_e32 v63, v2
	v_mov_b32_e32 v64, v2
	v_mov_b32_e32 v65, v2
	v_mov_b32_e32 v66, v2
	v_mov_b32_e32 v67, v2
	v_mov_b32_e32 v68, v2
	v_mov_b32_e32 v69, v2
	v_mov_b32_e32 v70, v2
	v_mov_b32_e32 v71, v2
	v_mov_b32_e32 v72, v2
	v_mov_b32_e32 v73, v2
	v_mov_b32_e32 v74, v2
	v_mov_b32_e32 v75, v2
	v_mov_b32_e32 v76, v2
	v_mov_b32_e32 v77, v2
	v_mov_b32_e32 v78, v2
	v_mov_b32_e32 v79, v2
	v_mov_b32_e32 v80, v2
	v_mov_b32_e32 v81, v2
	v_mov_b32_e32 v82, v2
	v_mov_b32_e32 v83, v2
	v_mov_b32_e32 v84, v2
	v_mov_b32_e32 v85, v2
	v_mov_b32_e32 v86, v2
	v_mov_b32_e32 v87, v2
	v_mov_b32_e32 v88, v2
	v_mov_b32_e32 v89, v2
	v_mov_b32_e32 v90, v2
	v_mov_b32_e32 v91, v2
	v_mov_b32_e32 v92, v2
	v_mov_b32_e32 v93, v2
	v_mov_b32_e32 v94, v2
	v_mov_b32_e32 v95, v2
	v_mov_b32_e32 v96, v2
	v_mov_b32_e32 v97, v2
	v_mov_b32_e32 v98, v2
	v_mov_b32_e32 v99, v2
	v_mov_b32_e32 v100, v2
	v_mov_b32_e32 v101, v2
	v_mov_b32_e32 v102, v2
	v_mov_b32_e32 v103, v2
	v_mov_b32_e32 v104, v2
	v_mov_b32_e32 v105, v2
	v_mov_b32_e32 v106, v2
	v_mov_b32_e32 v107, v2
	v_mov_b32_e32 v108, v2
	v_mov_b32_e32 v109, v2
	v_mov_b32_e32 v110, v2
	v_mov_b32_e32 v111, v2
	v_mov_b32_e32 v112, v2
	v_mov_b32_e32 v113, v2
	v_mov_b32_e32 v114, v2
	v_mov_b32_e32 v115, v2
	v_mov_b32_e32 v116, v2
	v_mov_b32_e32 v117, v2
	v_mov_b32_e32 v118, v2
	v_mov_b32_e32 v119, v2
	v_mov_b32_e32 v120, v2
	v_mov_b32_e32 v121, v2
	v_mov_b32_e32 v122, v2
	v_mov_b32_e32 v123, v2
	v_mov_b32_e32 v124, v2
	v_mov_b32_e32 v125, v2
	v_mov_b32_e32 v126, v2
	v_mov_b32_e32 v127, v2
	v_mov_b32_e32 v128, v2
	v_mov_b32_e32 v129, v2
	s_mul_i32 s0, s20, 0x6000
	v_add_u32_e32 v211, s0, v186
	v_lshl_add_u64 v[212:213], v[182:183], 0, v[0:1]
	v_readfirstlane_b32 s0, v211
	v_lshl_add_u64 v[214:215], v[212:213], 0, s[84:85]
	s_mov_b32 m0, s0
	v_lshl_add_u64 v[212:213], v[212:213], 0, s[12:13]
	s_nop 0
	v_readfirstlane_b32 s100, v214
	v_readfirstlane_b32 s101, v215
	s_nop 1
	v_subrev_u32_e32 v228, s100, v214
	v_add_u32_e32 v214, 0x1000, v211
	v_add_u32_e32 v216, 0x2000, v211
	v_readfirstlane_b32 s0, v214
	s_mov_b32 m0, s0
	s_mov_b64 s[0:1], 0x43ea000
	v_subrev_u32_e32 v229, s100, v212
	v_lshl_add_u64 v[212:213], v[180:181], 0, v[0:1]
	v_lshl_add_u64 v[214:215], v[212:213], 0, s[0:1]
	v_readfirstlane_b32 s0, v216
	s_mov_b32 m0, s0
	s_mov_b64 s[0:1], 0x43eb000
	v_add_u32_e32 v216, 0x3000, v211
	s_nop 0
	v_readfirstlane_b32 vcc_lo, v214
	v_readfirstlane_b32 vcc_hi, v215
	s_nop 1
	v_subrev_u32_e32 v230, vcc_lo, v214
	v_lshl_add_u64 v[214:215], v[212:213], 0, s[0:1]
	v_readfirstlane_b32 s0, v216
	s_mov_b32 m0, s0
	s_mov_b64 s[0:1], 0x43ec000
	v_add_u32_e32 v216, 0x4000, v211
	v_subrev_u32_e32 v231, vcc_lo, v214
	v_lshl_add_u64 v[214:215], v[212:213], 0, s[0:1]
	v_readfirstlane_b32 s0, v216
	s_mov_b32 m0, s0
	s_mov_b64 s[0:1], 0x43ed000
	v_add_u32_e32 v211, 0x5000, v211
	v_lshl_add_u64 v[212:213], v[212:213], 0, s[0:1]
	v_readfirstlane_b32 s0, v211
	v_subrev_u32_e32 v232, vcc_lo, v214
	s_mov_b32 m0, s0
	s_nop 0
	v_subrev_u32_e32 v233, vcc_lo, v212
	v_mov_b32_e32 v182, v228
	v_mov_b32_e32 v183, v229
	v_mov_b32_e32 v180, v230
	v_mov_b32_e32 v181, v231
	v_mov_b32_e32 v253, v232
	v_mov_b32_e32 v254, v233
	v_readfirstlane_b32 s0, v186
	s_branch .LBB0_1295
	.p2align	6

; #define RAW_BARRIER() do { asm volatile("s_waitcnt lgkmcnt(0)" ::: "memory"); __builtin_amdgcn_s_barrier(); } while (0)
; template <int EPI, int NB>
; DEVI void gemm_tile(const GemmJob& J, int m0, int n0, unsigned char* smem) {
;     ...
;   const int srow = tid >> 2, sch = tid & 3;
;   const int gch = sch ^ ((0 - (tid >> 4)) & 3);
;   const bf16_t* Ag = J.A + (size_t)(m0 + srow) * (J.ablk ? 32 : J.lda) + gch * 8;
;   const bf16_t* Bg = J.Bt + (size_t)(n0 + srow) * 32 + gch * 8;
;   const size_t Astep = (size_t)64 * (J.ablk ? 32 : J.lda), Ak = J.ablk ? (size_t)MROWS * 32 : (size_t)32, Bstep = (size_t)64 * 32, Bk = (size_t)J.NR * 32;
;   const int nk = J.K >> 5;
;   unsigned char* lds_t = smem + tid * 16;
;   const unsigned lbase = (unsigned)(uintptr_t)(__attribute__((address_space(3))) unsigned char*)smem;
;     ...
;   asm volatile("s_waitcnt vmcnt(0)" ::: "memory");
;   RAW_BARRIER();
; #pragma unroll
;   for (int st = 0; st < S - 1; ++st) GEMM_ISSUE(st, st);
;   const int fsl = (g ^ ((0 - (l16 >> 2)) & 3)) << 4;
;   const int aofs = (wm * 64 + l16) * 64 + fsl;
;   const int bofs = A_BYTES + (wn * NB * 16 + l16) * 64 + fsl;
; template <int EPI, int NB>
; DEVI void gemm_run(const GemmJob& J, unsigned char* smem, int rot) {
;     ...
;     for (int q0 = lb; q0 < ntot; q0 += nlb) {
;       const int q = J.rev ? ntot - 1 - q0 : q0;
;       int grp = q / gsz; const int qq = q - grp * gsz;
;       const int mg = min(8, mcnt - grp * 8);
;       const int nt = qq / mg, mi = qq - nt * mg;
;       gemm_tile<EPI, NB>(J, (mlo + grp * 8 + mi) * 128, (J.nt0 + nt) * BN, smem);
.LBB0_1340:
	s_mul_hi_i32 s0, s9, 0x66666667
	s_lshr_b32 s1, s0, 31
	s_ashr_i32 s0, s0, 4
	s_add_i32 s0, s0, s1
	s_lshl_b32 s1, s0, 3
	v_readlane_b32 s2, v251, 48
	s_sub_i32 s2, s2, s1
	s_min_i32 s3, s2, 8
	s_abs_i32 s20, s3
	v_cvt_f32_u32_e32 v0, s20
	s_sub_i32 s43, 0, s20
	s_mul_i32 s40, s0, 0xffffffd8
	s_add_i32 s40, s40, s9
	v_rcp_iflag_f32_e32 v0, v0
	s_abs_i32 s41, s40
	s_xor_b32 s42, s40, s3
	s_ashr_i32 s42, s42, 31
	v_mul_f32_e32 v0, 0x4f7ffffe, v0
	v_cvt_u32_f32_e32 v0, v0
	v_mov_b32_e32 v184, v177
	s_nop 0
	v_readfirstlane_b32 s44, v0
	s_mul_i32 s43, s43, s44
	s_mul_hi_u32 s43, s44, s43
	s_add_i32 s44, s44, s43
	s_mul_hi_u32 s43, s41, s44
	s_mul_i32 s44, s43, s20
	s_sub_i32 s41, s41, s44
	s_add_i32 s45, s43, 1
	s_sub_i32 s44, s41, s20
	s_cmp_ge_u32 s41, s20
	s_cselect_b32 s43, s45, s43
	s_cselect_b32 s41, s44, s41
	s_add_i32 s44, s43, 1
	s_cmp_ge_u32 s41, s20
	s_cselect_b32 s20, s44, s43
	s_xor_b32 s20, s20, s42
	s_sub_i32 s41, s20, s42
	s_mul_i32 s43, s3, s41
	v_readlane_b32 s3, v250, 37
	s_add_i32 s1, s1, s3
	s_add_i32 s1, s1, s40
	s_sub_i32 s1, s1, s43
	s_lshl_b32 s20, s1, 7
	s_lshl_b32 s3, s41, 8
	v_ashrrev_i32_e32 v10, 2, v184
	v_lshrrev_b32_e32 v0, 4, v184
	v_sub_u32_e32 v11, 0, v0
	v_add_u32_e32 v2, s20, v10
	v_add_u32_e32 v4, s3, v10
	v_xor_b32_e32 v0, v184, v11
	v_ashrrev_i32_e32 v3, 31, v2
	v_ashrrev_i32_e32 v5, 31, v4
	v_lshlrev_b64 v[2:3], 6, v[2:3]
	v_lshlrev_b32_e32 v0, 4, v0
	v_lshlrev_b64 v[4:5], 6, v[4:5]
	v_lshl_add_u64 v[2:3], v[146:147], 0, v[2:3]
	v_and_b32_e32 v0, 48, v0
	v_lshl_add_u64 v[6:7], v[134:135], 0, v[4:5]
	v_lshlrev_b32_e32 v185, 4, v184
	v_lshl_add_u64 v[2:3], v[2:3], 0, v[0:1]
	v_lshl_add_u64 v[6:7], v[6:7], 0, v[0:1]
	v_readfirstlane_b32 s1, v185
	v_add_u32_e32 v0, 0x1000, v185
	s_mov_b32 m0, s1
	s_mov_b64 s[28:29], 0x1000
	v_readfirstlane_b32 s1, v0
	v_add_u32_e32 v0, 0x2000, v185
	s_waitcnt lgkmcnt(0)
	s_barrier
	global_load_lds_dwordx4 v[2:3], off
	v_lshl_add_u64 v[8:9], v[2:3], 0, s[28:29]
	s_mov_b32 m0, s1
	v_readfirstlane_b32 s1, v0
	v_add_u32_e32 v0, 0x3000, v185
	global_load_lds_dwordx4 v[8:9], off
	s_mov_b32 m0, s1
	v_readfirstlane_b32 s1, v0
	v_add_u32_e32 v0, 0x4000, v185
	global_load_lds_dwordx4 v[6:7], off
	v_lshl_add_u64 v[8:9], v[6:7], 0, s[28:29]
	s_mov_b32 m0, s1
	s_mov_b64 s[28:29], 0x2000
	v_readfirstlane_b32 s1, v0
	v_add_u32_e32 v0, 0x5000, v185
	global_load_lds_dwordx4 v[8:9], off
	v_lshl_add_u64 v[8:9], v[6:7], 0, s[28:29]
	s_mov_b32 m0, s1
	s_mov_b64 s[28:29], 0x3000
	v_readfirstlane_b32 s1, v0
	v_add_u32_e32 v0, 0x6000, v185
	global_load_lds_dwordx4 v[8:9], off
	v_lshl_add_u64 v[8:9], v[6:7], 0, s[28:29]
	s_mov_b32 m0, s1
	v_readfirstlane_b32 s1, v0
	v_add_u32_e32 v0, 0x7000, v185
	global_load_lds_dwordx4 v[8:9], off
	v_lshl_add_u64 v[8:9], v[2:3], 0, s[94:95]
	s_mov_b32 m0, s1
	s_mov_b64 s[28:29], 0x30b000
	v_readfirstlane_b32 s1, v0
	v_add_u32_e32 v0, 0x8000, v185
	global_load_lds_dwordx4 v[8:9], off
	v_lshl_add_u64 v[2:3], v[2:3], 0, s[28:29]
	s_mov_b32 m0, s1
	v_readfirstlane_b32 s1, v0
	v_add_u32_e32 v0, 0x9000, v185
	global_load_lds_dwordx4 v[2:3], off
	v_lshl_add_u64 v[2:3], v[6:7], 0, s[38:39]
	s_mov_b32 m0, s1
	s_mov_b64 s[28:29], 0x19000
	v_readfirstlane_b32 s1, v0
	v_add_u32_e32 v0, 0xa000, v185
	global_load_lds_dwordx4 v[2:3], off
	v_lshl_add_u64 v[2:3], v[6:7], 0, s[28:29]
	s_mov_b32 m0, s1
	s_mov_b64 s[28:29], 0x1a000
	v_readfirstlane_b32 s1, v0
	v_add_u32_e32 v0, 0xb000, v185
	global_load_lds_dwordx4 v[2:3], off
	v_lshl_add_u64 v[2:3], v[6:7], 0, s[28:29]
	s_mov_b32 m0, s1
	s_mov_b64 s[28:29], 0x1b000
	v_readfirstlane_b32 s1, v0
	global_load_lds_dwordx4 v[2:3], off
	v_lshl_add_u64 v[2:3], v[6:7], 0, s[28:29]
	s_mov_b32 m0, s1
	v_lshlrev_b32_e32 v0, 2, v184
	global_load_lds_dwordx4 v[2:3], off
	v_and_b32_e32 v0, 48, v0
	v_ashrrev_i32_e32 v2, 1, v184
	v_and_b32_e32 v186, 15, v184
	v_sub_u32_e32 v0, 0, v0
	v_and_b32_e32 v187, 0xffffffc0, v2
	v_bitop3_b32 v0, v184, 48, v0 bitop3:0x48
	v_or_b32_e32 v2, v187, v186
	v_lshl_or_b32 v209, v2, 6, v0
	v_lshlrev_b32_e32 v2, 1, v184
	v_and_b32_e32 v208, 0x80, v2
	s_sub_i32 s1, s8, s43
	s_lshl_b32 s0, s0, 5
	v_or_b32_e32 v2, v208, v186
	s_sub_i32 s0, s1, s0
	v_lshl_or_b32 v0, v2, 6, v0
	v_lshl_add_u32 v2, s0, 7, v10
	v_ashrrev_i32_e32 v3, 31, v2
	v_lshlrev_b64 v[2:3], 6, v[2:3]
	v_add_u32_e32 v210, 0x2000, v0
	v_bitop3_b32 v0, v184, 3, v11 bitop3:0x48
	v_lshl_add_u64 v[182:183], v[130:131], 0, v[2:3]
	v_mov_b32_e32 v2, 0
	s_mov_b32 s2, 0
	s_mov_b32 s42, 2
	s_mov_b64 s[30:31], 0x1000
	v_lshlrev_b32_e32 v0, 4, v0
	v_lshl_add_u64 v[180:181], v[130:131], 0, v[4:5]
	s_mov_b32 s43, 0
; template <int EPI, int NB>
; DEVI void gemm_tile(const GemmJob& J, int m0, int n0, unsigned char* smem) {
;     ...
;   f32x4 acc[4][NB];
; #pragma unroll
;   for (int i = 0; i < 4; ++i)
; #pragma unroll
;     for (int j = 0; j < NB; ++j) acc[i][j] = (f32x4){0.f, 0.f, 0.f, 0.f};
;     ...
;     if (kt + S - 1 < nk) GEMM_ISSUE(kt + S - 1, is);
;     is = (is + 1 == S) ? 0 : is + 1;
;     const unsigned cur = lbase + cs * STG;
;     cs = (cs + 1 == S) ? 0 : cs + 1;
;     bf16x8 af[4], bfr[NB];
;     const unsigned aa = cur + aofs, ba = cur + bofs;
	v_mov_b32_e32 v3, v2
	v_mov_b32_e32 v4, v2
	v_mov_b32_e32 v5, v2
	v_mov_b32_e32 v6, v2
	v_mov_b32_e32 v7, v2
	v_mov_b32_e32 v8, v2
	v_mov_b32_e32 v9, v2
	v_mov_b32_e32 v10, v2
	v_mov_b32_e32 v11, v2
	v_mov_b32_e32 v12, v2
	v_mov_b32_e32 v13, v2
	v_mov_b32_e32 v14, v2
	v_mov_b32_e32 v15, v2
	v_mov_b32_e32 v16, v2
	v_mov_b32_e32 v17, v2
	v_mov_b32_e32 v18, v2
	v_mov_b32_e32 v19, v2
	v_mov_b32_e32 v20, v2
	v_mov_b32_e32 v21, v2
	v_mov_b32_e32 v22, v2
	v_mov_b32_e32 v23, v2
	v_mov_b32_e32 v24, v2
	v_mov_b32_e32 v25, v2
	v_mov_b32_e32 v26, v2
	v_mov_b32_e32 v27, v2
	v_mov_b32_e32 v28, v2
	v_mov_b32_e32 v29, v2
	v_mov_b32_e32 v30, v2
	v_mov_b32_e32 v31, v2
	v_mov_b32_e32 v32, v2
	v_mov_b32_e32 v33, v2
	v_mov_b32_e32 v34, v2
	v_mov_b32_e32 v35, v2
	v_mov_b32_e32 v36, v2
	v_mov_b32_e32 v37, v2
	v_mov_b32_e32 v38, v2
	v_mov_b32_e32 v39, v2
	v_mov_b32_e32 v40, v2
	v_mov_b32_e32 v41, v2
	v_mov_b32_e32 v42, v2
	v_mov_b32_e32 v43, v2
	v_mov_b32_e32 v44, v2
	v_mov_b32_e32 v45, v2
	v_mov_b32_e32 v46, v2
	v_mov_b32_e32 v47, v2
	v_mov_b32_e32 v48, v2
	v_mov_b32_e32 v49, v2
	v_mov_b32_e32 v50, v2
	v_mov_b32_e32 v51, v2
	v_mov_b32_e32 v52, v2
	v_mov_b32_e32 v53, v2
	v_mov_b32_e32 v54, v2
	v_mov_b32_e32 v55, v2
	v_mov_b32_e32 v56, v2
	v_mov_b32_e32 v57, v2
	v_mov_b32_e32 v58, v2
	v_mov_b32_e32 v59, v2
	v_mov_b32_e32 v60, v2
	v_mov_b32_e32 v61, v2
	v_mov_b32_e32 v62, v2
	v_mov_b32_e32 v63, v2
	v_mov_b32_e32 v64, v2
	v_mov_b32_e32 v65, v2
	v_mov_b32_e32 v66, v2
	v_mov_b32_e32 v67, v2
	v_mov_b32_e32 v68, v2
	v_mov_b32_e32 v69, v2
	v_mov_b32_e32 v70, v2
	v_mov_b32_e32 v71, v2
	v_mov_b32_e32 v72, v2
	v_mov_b32_e32 v73, v2
	v_mov_b32_e32 v74, v2
	v_mov_b32_e32 v75, v2
	v_mov_b32_e32 v76, v2
	v_mov_b32_e32 v77, v2
	v_mov_b32_e32 v78, v2
	v_mov_b32_e32 v79, v2
	v_mov_b32_e32 v80, v2
	v_mov_b32_e32 v81, v2
	v_mov_b32_e32 v82, v2
	v_mov_b32_e32 v83, v2
	v_mov_b32_e32 v84, v2
	v_mov_b32_e32 v85, v2
	v_mov_b32_e32 v86, v2
	v_mov_b32_e32 v87, v2
	v_mov_b32_e32 v88, v2
	v_mov_b32_e32 v89, v2
	v_mov_b32_e32 v90, v2
	v_mov_b32_e32 v91, v2
	v_mov_b32_e32 v92, v2
	v_mov_b32_e32 v93, v2
	v_mov_b32_e32 v94, v2
	v_mov_b32_e32 v95, v2
	v_mov_b32_e32 v96, v2
	v_mov_b32_e32 v97, v2
	v_mov_b32_e32 v98, v2
	v_mov_b32_e32 v99, v2
	v_mov_b32_e32 v100, v2
	v_mov_b32_e32 v101, v2
	v_mov_b32_e32 v102, v2
	v_mov_b32_e32 v103, v2
	v_mov_b32_e32 v104, v2
	v_mov_b32_e32 v105, v2
	v_mov_b32_e32 v106, v2
	v_mov_b32_e32 v107, v2
	v_mov_b32_e32 v108, v2
	v_mov_b32_e32 v109, v2
	v_mov_b32_e32 v110, v2
	v_mov_b32_e32 v111, v2
	v_mov_b32_e32 v112, v2
	v_mov_b32_e32 v113, v2
	v_mov_b32_e32 v114, v2
	v_mov_b32_e32 v115, v2
	v_mov_b32_e32 v116, v2
	v_mov_b32_e32 v117, v2
	v_mov_b32_e32 v118, v2
	v_mov_b32_e32 v119, v2
	v_mov_b32_e32 v120, v2
	v_mov_b32_e32 v121, v2
	v_mov_b32_e32 v122, v2
	v_mov_b32_e32 v123, v2
	v_mov_b32_e32 v124, v2
	v_mov_b32_e32 v125, v2
	v_mov_b32_e32 v126, v2
	v_mov_b32_e32 v127, v2
	v_mov_b32_e32 v128, v2
	v_mov_b32_e32 v129, v2
	s_mul_i32 s0, s42, 0x6000
	v_add_u32_e32 v211, s0, v185
	v_lshl_add_u64 v[212:213], v[182:183], 0, v[0:1]
	v_readfirstlane_b32 s0, v211
	v_lshl_add_u64 v[214:215], v[212:213], 0, s[84:85]
	s_mov_b32 m0, s0
	v_lshl_add_u64 v[212:213], v[212:213], 0, s[12:13]
	s_nop 0
	v_readfirstlane_b32 s100, v214
	v_readfirstlane_b32 s101, v215
	s_nop 1
	v_subrev_u32_e32 v228, s100, v214
	v_add_u32_e32 v214, 0x1000, v211
	v_add_u32_e32 v216, 0x2000, v211
	v_readfirstlane_b32 s0, v214
	s_mov_b32 m0, s0
	s_mov_b64 s[0:1], 0x43d6000
	v_subrev_u32_e32 v229, s100, v212
	v_lshl_add_u64 v[212:213], v[180:181], 0, v[0:1]
	v_lshl_add_u64 v[214:215], v[212:213], 0, s[0:1]
	v_readfirstlane_b32 s0, v216
	s_mov_b32 m0, s0
	s_mov_b64 s[0:1], 0x43d7000
	v_add_u32_e32 v216, 0x3000, v211
	s_nop 0
	v_readfirstlane_b32 vcc_lo, v214
	v_readfirstlane_b32 vcc_hi, v215
	s_nop 1
	v_subrev_u32_e32 v230, vcc_lo, v214
	v_lshl_add_u64 v[214:215], v[212:213], 0, s[0:1]
	v_readfirstlane_b32 s0, v216
	s_mov_b32 m0, s0
	s_mov_b64 s[0:1], 0x43d8000
	v_add_u32_e32 v216, 0x4000, v211
	v_subrev_u32_e32 v231, vcc_lo, v214
	v_lshl_add_u64 v[214:215], v[212:213], 0, s[0:1]
	v_readfirstlane_b32 s0, v216
	s_mov_b32 m0, s0
	s_mov_b64 s[0:1], 0x43d9000
	v_add_u32_e32 v211, 0x5000, v211
	v_lshl_add_u64 v[212:213], v[212:213], 0, s[0:1]
	v_readfirstlane_b32 s0, v211
	v_subrev_u32_e32 v232, vcc_lo, v214
	s_mov_b32 m0, s0
	s_nop 0
	v_subrev_u32_e32 v233, vcc_lo, v212
	v_mov_b32_e32 v182, v228
	v_mov_b32_e32 v183, v229
	v_mov_b32_e32 v180, v230
	v_mov_b32_e32 v181, v231
	v_mov_b32_e32 v253, v232
	v_mov_b32_e32 v254, v233
	v_readfirstlane_b32 s0, v185
	s_branch .LBB0_1342
	.p2align	6

; #define RAW_BARRIER() do { asm volatile("s_waitcnt lgkmcnt(0)" ::: "memory"); __builtin_amdgcn_s_barrier(); } while (0)
; template <int EPI, int NB>
; DEVI void gemm_tile(const GemmJob& J, int m0, int n0, unsigned char* smem) {
;     ...
;   const int srow = tid >> 2, sch = tid & 3;
;   const int gch = sch ^ ((0 - (tid >> 4)) & 3);
;   const bf16_t* Ag = J.A + (size_t)(m0 + srow) * (J.ablk ? 32 : J.lda) + gch * 8;
;   const bf16_t* Bg = J.Bt + (size_t)(n0 + srow) * 32 + gch * 8;
;   const size_t Astep = (size_t)64 * (J.ablk ? 32 : J.lda), Ak = J.ablk ? (size_t)MROWS * 32 : (size_t)32, Bstep = (size_t)64 * 32, Bk = (size_t)J.NR * 32;
;   const int nk = J.K >> 5;
;   unsigned char* lds_t = smem + tid * 16;
;   const unsigned lbase = (unsigned)(uintptr_t)(__attribute__((address_space(3))) unsigned char*)smem;
;     ...
;   asm volatile("s_waitcnt vmcnt(0)" ::: "memory");
;   RAW_BARRIER();
; #pragma unroll
;   for (int st = 0; st < S - 1; ++st) GEMM_ISSUE(st, st);
;   const int fsl = (g ^ ((0 - (l16 >> 2)) & 3)) << 4;
;   const int aofs = (wm * 64 + l16) * 64 + fsl;
;   const int bofs = A_BYTES + (wn * NB * 16 + l16) * 64 + fsl;
; template <int EPI, int NB>
; DEVI void gemm_run(const GemmJob& J, unsigned char* smem, int rot) {
;     ...
;     for (int q0 = lb; q0 < ntot; q0 += nlb) {
;       const int q = J.rev ? ntot - 1 - q0 : q0;
;       int grp = q / gsz; const int qq = q - grp * gsz;
;       const int mg = min(8, mcnt - grp * 8);
;       const int nt = qq / mg, mi = qq - nt * mg;
;       gemm_tile<EPI, NB>(J, (mlo + grp * 8 + mi) * 128, (J.nt0 + nt) * BN, smem);
.LBB0_1419:
	s_ashr_i32 s0, s9, 31
	s_lshr_b32 s0, s0, 29
	s_add_i32 s0, s9, s0
	s_and_b32 s0, s0, -8
	s_sub_i32 s1, s1, s0
	s_min_i32 s1, s1, 8
	s_abs_i32 s2, s1
	v_cvt_f32_u32_e32 v0, s2
	s_sub_i32 s40, 0, s2
	s_sub_i32 s0, s9, s0
	s_abs_i32 s20, s0
	v_rcp_iflag_f32_e32 v0, v0
	s_xor_b32 s0, s0, s1
	s_ashr_i32 s0, s0, 31
	v_mov_b32_e32 v184, v177
	v_mul_f32_e32 v0, 0x4f7ffffe, v0
	v_cvt_u32_f32_e32 v0, v0
	s_nop 0
	s_mov_b64 s[28:29], 0x1000
	v_readfirstlane_b32 s41, v0
	s_mul_i32 s40, s40, s41
	s_mul_hi_u32 s40, s41, s40
	s_add_i32 s41, s41, s40
	s_mul_hi_u32 s40, s20, s41
	s_mul_i32 s41, s40, s2
	s_sub_i32 s20, s20, s41
	s_add_i32 s42, s40, 1
	s_sub_i32 s41, s20, s2
	s_cmp_ge_u32 s20, s2
	s_cselect_b32 s40, s42, s40
	s_cselect_b32 s20, s41, s20
	s_add_i32 s41, s40, 1
	s_cmp_ge_u32 s20, s2
	s_cselect_b32 s2, s41, s40
	s_xor_b32 s2, s2, s0
	v_readlane_b32 s20, v250, 53
	s_sub_i32 s0, s2, s0
	s_add_i32 s20, s9, s20
	s_mul_i32 s1, s1, s0
	s_sub_i32 s2, s20, s1
	s_lshl_b32 s20, s2, 7
	s_lshl_b32 s2, s0, 8
	s_addk_i32 s2, 0x500
	v_ashrrev_i32_e32 v10, 2, v184
	v_lshrrev_b32_e32 v0, 4, v184
	v_sub_u32_e32 v11, 0, v0
	v_add_u32_e32 v2, s20, v10
	v_add_u32_e32 v4, s2, v10
	v_xor_b32_e32 v0, v184, v11
	v_ashrrev_i32_e32 v3, 31, v2
	v_ashrrev_i32_e32 v5, 31, v4
	v_lshlrev_b64 v[2:3], 6, v[2:3]
	v_lshlrev_b32_e32 v0, 4, v0
	v_lshlrev_b64 v[4:5], 6, v[4:5]
	v_lshl_add_u64 v[2:3], v[146:147], 0, v[2:3]
	v_and_b32_e32 v0, 48, v0
	v_lshl_add_u64 v[6:7], v[134:135], 0, v[4:5]
	v_lshlrev_b32_e32 v185, 4, v184
	v_lshl_add_u64 v[2:3], v[2:3], 0, v[0:1]
	v_lshl_add_u64 v[6:7], v[6:7], 0, v[0:1]
	v_readfirstlane_b32 s0, v185
	v_add_u32_e32 v0, 0x1000, v185
	s_mov_b32 m0, s0
	v_readfirstlane_b32 s0, v0
	v_add_u32_e32 v0, 0x2000, v185
	s_waitcnt lgkmcnt(0)
	s_barrier
	global_load_lds_dwordx4 v[2:3], off
	v_lshl_add_u64 v[8:9], v[2:3], 0, s[28:29]
	s_mov_b32 m0, s0
	v_readfirstlane_b32 s0, v0
	v_add_u32_e32 v0, 0x3000, v185
	global_load_lds_dwordx4 v[8:9], off
	s_mov_b32 m0, s0
	v_readfirstlane_b32 s0, v0
	v_add_u32_e32 v0, 0x4000, v185
	global_load_lds_dwordx4 v[6:7], off
	v_lshl_add_u64 v[8:9], v[6:7], 0, s[28:29]
	s_mov_b32 m0, s0
	s_mov_b64 s[28:29], 0x2000
	v_readfirstlane_b32 s0, v0
	v_add_u32_e32 v0, 0x5000, v185
	global_load_lds_dwordx4 v[8:9], off
	v_lshl_add_u64 v[8:9], v[6:7], 0, s[28:29]
	s_mov_b32 m0, s0
	s_mov_b64 s[28:29], 0x3000
	v_readfirstlane_b32 s0, v0
	v_add_u32_e32 v0, 0x6000, v185
	global_load_lds_dwordx4 v[8:9], off
	v_lshl_add_u64 v[8:9], v[6:7], 0, s[28:29]
	s_mov_b32 m0, s0
	v_readfirstlane_b32 s0, v0
	v_add_u32_e32 v0, 0x7000, v185
	global_load_lds_dwordx4 v[8:9], off
	v_lshl_add_u64 v[8:9], v[2:3], 0, s[94:95]
	s_mov_b32 m0, s0
	s_mov_b64 s[28:29], 0x30b000
	v_readfirstlane_b32 s0, v0
	v_add_u32_e32 v0, 0x8000, v185
	global_load_lds_dwordx4 v[8:9], off
	v_lshl_add_u64 v[2:3], v[2:3], 0, s[28:29]
	s_mov_b32 m0, s0
	v_readfirstlane_b32 s0, v0
	v_add_u32_e32 v0, 0x9000, v185
	global_load_lds_dwordx4 v[2:3], off
	v_lshl_add_u64 v[2:3], v[6:7], 0, s[38:39]
	s_mov_b32 m0, s0
	s_mov_b64 s[28:29], 0x19000
	v_readfirstlane_b32 s0, v0
	v_add_u32_e32 v0, 0xa000, v185
	global_load_lds_dwordx4 v[2:3], off
	v_lshl_add_u64 v[2:3], v[6:7], 0, s[28:29]
	s_mov_b32 m0, s0
	s_mov_b64 s[28:29], 0x1a000
	v_readfirstlane_b32 s0, v0
	v_add_u32_e32 v0, 0xb000, v185
	global_load_lds_dwordx4 v[2:3], off
	v_lshl_add_u64 v[2:3], v[6:7], 0, s[28:29]
	s_mov_b32 m0, s0
	s_mov_b64 s[28:29], 0x1b000
	v_readfirstlane_b32 s0, v0
	global_load_lds_dwordx4 v[2:3], off
	v_lshl_add_u64 v[2:3], v[6:7], 0, s[28:29]
	s_mov_b32 m0, s0
	v_and_b32_e32 v0, 15, v184
	global_load_lds_dwordx4 v[2:3], off
	v_lshlrev_b32_e32 v2, 2, v184
	v_and_b32_e32 v2, 48, v2
	v_ashrrev_i32_e32 v3, 1, v184
	v_sub_u32_e32 v2, 0, v2
	v_and_b32_e32 v187, 0xffffffc0, v3
	v_bitop3_b32 v2, v184, 48, v2 bitop3:0x48
	v_or_b32_e32 v3, v187, v0
	v_lshl_or_b32 v208, v3, 6, v2
	v_lshlrev_b32_e32 v3, 1, v184
	s_movk_i32 s0, 0x80
	v_and_or_b32 v186, v3, s0, v0
	v_lshl_or_b32 v0, v186, 6, v2
	v_add_u32_e32 v2, s8, v10
	s_lshl_b32 s0, s1, 7
	v_subrev_u32_e32 v2, s0, v2
	v_ashrrev_i32_e32 v3, 31, v2
	v_lshlrev_b64 v[2:3], 6, v[2:3]
	v_add_u32_e32 v209, 0x2000, v0
	v_bitop3_b32 v0, v184, 3, v11 bitop3:0x48
	v_lshl_add_u64 v[182:183], v[130:131], 0, v[2:3]
	v_mov_b32_e32 v2, 0
	s_mov_b32 s3, 0
	s_mov_b32 s42, 2
	s_mov_b64 s[30:31], 0x1000
	v_lshlrev_b32_e32 v0, 4, v0
	v_lshl_add_u64 v[180:181], v[130:131], 0, v[4:5]
	s_mov_b32 s43, 0
	v_mov_b32_e32 v3, v2
	v_mov_b32_e32 v4, v2
	v_mov_b32_e32 v5, v2
; template <int EPI, int NB>
; DEVI void gemm_tile(const GemmJob& J, int m0, int n0, unsigned char* smem) {
;     ...
;   f32x4 acc[4][NB];
; #pragma unroll
;   for (int i = 0; i < 4; ++i)
; #pragma unroll
;     for (int j = 0; j < NB; ++j) acc[i][j] = (f32x4){0.f, 0.f, 0.f, 0.f};
;     ...
;     if (kt + S - 1 < nk) GEMM_ISSUE(kt + S - 1, is);
;     is = (is + 1 == S) ? 0 : is + 1;
;     const unsigned cur = lbase + cs * STG;
;     cs = (cs + 1 == S) ? 0 : cs + 1;
;     bf16x8 af[4], bfr[NB];
;     const unsigned aa = cur + aofs, ba = cur + bofs;
	v_mov_b32_e32 v6, v2
	v_mov_b32_e32 v7, v2
	v_mov_b32_e32 v8, v2
	v_mov_b32_e32 v9, v2
	v_mov_b32_e32 v10, v2
	v_mov_b32_e32 v11, v2
	v_mov_b32_e32 v12, v2
	v_mov_b32_e32 v13, v2
	v_mov_b32_e32 v14, v2
	v_mov_b32_e32 v15, v2
	v_mov_b32_e32 v16, v2
	v_mov_b32_e32 v17, v2
	v_mov_b32_e32 v18, v2
	v_mov_b32_e32 v19, v2
	v_mov_b32_e32 v20, v2
	v_mov_b32_e32 v21, v2
	v_mov_b32_e32 v22, v2
	v_mov_b32_e32 v23, v2
	v_mov_b32_e32 v24, v2
	v_mov_b32_e32 v25, v2
	v_mov_b32_e32 v26, v2
	v_mov_b32_e32 v27, v2
	v_mov_b32_e32 v28, v2
	v_mov_b32_e32 v29, v2
	v_mov_b32_e32 v30, v2
	v_mov_b32_e32 v31, v2
	v_mov_b32_e32 v32, v2
	v_mov_b32_e32 v33, v2
	v_mov_b32_e32 v34, v2
	v_mov_b32_e32 v35, v2
	v_mov_b32_e32 v36, v2
	v_mov_b32_e32 v37, v2
	v_mov_b32_e32 v38, v2
	v_mov_b32_e32 v39, v2
	v_mov_b32_e32 v40, v2
	v_mov_b32_e32 v41, v2
	v_mov_b32_e32 v42, v2
	v_mov_b32_e32 v43, v2
	v_mov_b32_e32 v44, v2
	v_mov_b32_e32 v45, v2
	v_mov_b32_e32 v46, v2
	v_mov_b32_e32 v47, v2
	v_mov_b32_e32 v48, v2
	v_mov_b32_e32 v49, v2
	v_mov_b32_e32 v50, v2
	v_mov_b32_e32 v51, v2
	v_mov_b32_e32 v52, v2
	v_mov_b32_e32 v53, v2
	v_mov_b32_e32 v54, v2
	v_mov_b32_e32 v55, v2
	v_mov_b32_e32 v56, v2
	v_mov_b32_e32 v57, v2
	v_mov_b32_e32 v58, v2
	v_mov_b32_e32 v59, v2
	v_mov_b32_e32 v60, v2
	v_mov_b32_e32 v61, v2
	v_mov_b32_e32 v62, v2
	v_mov_b32_e32 v63, v2
	v_mov_b32_e32 v64, v2
	v_mov_b32_e32 v65, v2
	v_mov_b32_e32 v66, v2
	v_mov_b32_e32 v67, v2
	v_mov_b32_e32 v68, v2
	v_mov_b32_e32 v69, v2
	v_mov_b32_e32 v70, v2
	v_mov_b32_e32 v71, v2
	v_mov_b32_e32 v72, v2
	v_mov_b32_e32 v73, v2
	v_mov_b32_e32 v74, v2
	v_mov_b32_e32 v75, v2
	v_mov_b32_e32 v76, v2
	v_mov_b32_e32 v77, v2
	v_mov_b32_e32 v78, v2
	v_mov_b32_e32 v79, v2
	v_mov_b32_e32 v80, v2
	v_mov_b32_e32 v81, v2
	v_mov_b32_e32 v82, v2
	v_mov_b32_e32 v83, v2
	v_mov_b32_e32 v84, v2
	v_mov_b32_e32 v85, v2
	v_mov_b32_e32 v86, v2
	v_mov_b32_e32 v87, v2
	v_mov_b32_e32 v88, v2
	v_mov_b32_e32 v89, v2
	v_mov_b32_e32 v90, v2
	v_mov_b32_e32 v91, v2
	v_mov_b32_e32 v92, v2
	v_mov_b32_e32 v93, v2
	v_mov_b32_e32 v94, v2
	v_mov_b32_e32 v95, v2
	v_mov_b32_e32 v96, v2
	v_mov_b32_e32 v97, v2
	v_mov_b32_e32 v98, v2
	v_mov_b32_e32 v99, v2
	v_mov_b32_e32 v100, v2
	v_mov_b32_e32 v101, v2
	v_mov_b32_e32 v102, v2
	v_mov_b32_e32 v103, v2
	v_mov_b32_e32 v104, v2
	v_mov_b32_e32 v105, v2
	v_mov_b32_e32 v106, v2
	v_mov_b32_e32 v107, v2
	v_mov_b32_e32 v108, v2
	v_mov_b32_e32 v109, v2
	v_mov_b32_e32 v110, v2
	v_mov_b32_e32 v111, v2
	v_mov_b32_e32 v112, v2
	v_mov_b32_e32 v113, v2
	v_mov_b32_e32 v114, v2
	v_mov_b32_e32 v115, v2
	v_mov_b32_e32 v116, v2
	v_mov_b32_e32 v117, v2
	v_mov_b32_e32 v118, v2
	v_mov_b32_e32 v119, v2
	v_mov_b32_e32 v120, v2
	v_mov_b32_e32 v121, v2
	v_mov_b32_e32 v122, v2
	v_mov_b32_e32 v123, v2
	v_mov_b32_e32 v124, v2
	v_mov_b32_e32 v125, v2
	v_mov_b32_e32 v126, v2
	v_mov_b32_e32 v127, v2
	v_mov_b32_e32 v128, v2
	v_mov_b32_e32 v129, v2
	s_mul_i32 s0, s42, 0x6000
	v_add_u32_e32 v214, s0, v185
	v_lshl_add_u64 v[210:211], v[182:183], 0, v[0:1]
	v_readfirstlane_b32 s0, v214
	v_lshl_add_u64 v[212:213], v[210:211], 0, s[84:85]
	s_mov_b32 m0, s0
	v_lshl_add_u64 v[210:211], v[210:211], 0, s[12:13]
	s_nop 0
	v_readfirstlane_b32 s100, v212
	v_readfirstlane_b32 s101, v213
	s_nop 1
	v_subrev_u32_e32 v226, s100, v212
	v_add_u32_e32 v212, 0x1000, v214
	v_add_u32_e32 v215, 0x2000, v214
	v_readfirstlane_b32 s0, v212
	s_mov_b32 m0, s0
	s_mov_b64 s[0:1], 0x43d6000
	v_subrev_u32_e32 v227, s100, v210
	v_lshl_add_u64 v[210:211], v[180:181], 0, v[0:1]
	v_lshl_add_u64 v[212:213], v[210:211], 0, s[0:1]
	v_readfirstlane_b32 s0, v215
	s_mov_b32 m0, s0
	s_mov_b64 s[0:1], 0x43d7000
	v_add_u32_e32 v215, 0x3000, v214
	s_nop 0
	v_readfirstlane_b32 vcc_lo, v212
	v_readfirstlane_b32 vcc_hi, v213
	s_nop 1
	v_subrev_u32_e32 v228, vcc_lo, v212
	v_lshl_add_u64 v[212:213], v[210:211], 0, s[0:1]
	v_readfirstlane_b32 s0, v215
	s_mov_b32 m0, s0
	s_mov_b64 s[0:1], 0x43d8000
	v_add_u32_e32 v215, 0x4000, v214
	v_subrev_u32_e32 v229, vcc_lo, v212
	v_lshl_add_u64 v[212:213], v[210:211], 0, s[0:1]
	v_readfirstlane_b32 s0, v215
	s_mov_b32 m0, s0
	s_mov_b64 s[0:1], 0x43d9000
	v_subrev_u32_e32 v230, vcc_lo, v212
	v_add_u32_e32 v212, 0x5000, v214
	v_lshl_add_u64 v[210:211], v[210:211], 0, s[0:1]
	v_readfirstlane_b32 s0, v212
	s_mov_b32 m0, s0
	s_nop 0
	v_subrev_u32_e32 v231, vcc_lo, v210
	v_mov_b32_e32 v182, v226
	v_mov_b32_e32 v183, v227
	v_mov_b32_e32 v180, v228
	v_mov_b32_e32 v181, v229
	v_mov_b32_e32 v253, v230
	v_mov_b32_e32 v254, v231
	v_readfirstlane_b32 s0, v185
	s_branch .LBB0_1421
	.p2align	6

; #define RAW_BARRIER() do { asm volatile("s_waitcnt lgkmcnt(0)" ::: "memory"); __builtin_amdgcn_s_barrier(); } while (0)
; template <int EPI, int NB>
; DEVI void gemm_tile(const GemmJob& J, int m0, int n0, unsigned char* smem) {
;     ...
;   const int srow = tid >> 2, sch = tid & 3;
;   const int gch = sch ^ ((0 - (tid >> 4)) & 3);
;   const bf16_t* Ag = J.A + (size_t)(m0 + srow) * (J.ablk ? 32 : J.lda) + gch * 8;
;   const bf16_t* Bg = J.Bt + (size_t)(n0 + srow) * 32 + gch * 8;
;   const size_t Astep = (size_t)64 * (J.ablk ? 32 : J.lda), Ak = J.ablk ? (size_t)MROWS * 32 : (size_t)32, Bstep = (size_t)64 * 32, Bk = (size_t)J.NR * 32;
;   const int nk = J.K >> 5;
;   unsigned char* lds_t = smem + tid * 16;
;   const unsigned lbase = (unsigned)(uintptr_t)(__attribute__((address_space(3))) unsigned char*)smem;
;     ...
;   asm volatile("s_waitcnt vmcnt(0)" ::: "memory");
;   RAW_BARRIER();
; #pragma unroll
;   for (int st = 0; st < S - 1; ++st) GEMM_ISSUE(st, st);
;   const int fsl = (g ^ ((0 - (l16 >> 2)) & 3)) << 4;
;   const int aofs = (wm * 64 + l16) * 64 + fsl;
;   const int bofs = A_BYTES + (wn * NB * 16 + l16) * 64 + fsl;
; template <int EPI, int NB>
; DEVI void gemm_run(const GemmJob& J, unsigned char* smem, int rot) {
;     ...
;     for (int t = b; t < ntiles; t += G) {
;       const int mt = t / J.ntn, nt = J.nt0 + (t - mt * J.ntn);
;       gemm_tile<EPI, NB>(J, mt * 128, nt * BN, smem);
.LBB0_1623:
	s_mul_hi_i32 s0, s9, 0x55555556
	s_lshr_b32 s1, s0, 31
	s_add_i32 s40, s0, s1
	s_mul_i32 s0, s40, -3
	s_add_i32 s0, s0, s9
	v_mov_b32_e32 v184, v177
	s_lshl_b32 s2, s0, 8
	s_lshl_b32 s3, s40, 7
	v_ashrrev_i32_e32 v8, 2, v184
	v_lshrrev_b32_e32 v0, 4, v184
	v_sub_u32_e32 v9, 0, v0
	v_add_u32_e32 v4, s2, v8
	v_xor_b32_e32 v0, v184, v9
	v_add_u32_e32 v10, s3, v8
	s_movk_i32 s28, 0x840
	v_ashrrev_i32_e32 v5, 31, v4
	v_mad_i64_i32 v[2:3], s[0:1], v10, s28, v[152:153]
	v_lshlrev_b32_e32 v0, 4, v0
	v_lshlrev_b64 v[4:5], 6, v[4:5]
	v_lshlrev_b32_e32 v185, 4, v184
	v_and_b32_e32 v0, 48, v0
	v_lshl_add_u64 v[4:5], v[136:137], 0, v[4:5]
	v_readfirstlane_b32 s0, v185
	v_lshl_add_u64 v[2:3], v[2:3], 0, v[0:1]
	v_lshl_add_u64 v[4:5], v[4:5], 0, v[0:1]
	s_mov_b32 m0, s0
	s_mov_b64 s[0:1], 0x21000
	v_add_u32_e32 v0, 0x1000, v185
	s_nop 0
	v_lshl_add_u64 v[6:7], v[2:3], 0, s[0:1]
	v_readfirstlane_b32 s0, v0
	v_add_u32_e32 v0, 0x2000, v185
	s_waitcnt lgkmcnt(0)
	s_barrier
	global_load_lds_dwordx4 v[2:3], off
	s_mov_b32 m0, s0
	v_readfirstlane_b32 s0, v0
	v_add_u32_e32 v0, 0x3000, v185
	global_load_lds_dwordx4 v[6:7], off
	s_mov_b32 m0, s0
	v_readfirstlane_b32 s0, v0
	global_load_lds_dwordx4 v[4:5], off
	v_lshl_add_u64 v[6:7], v[4:5], 0, s[30:31]
	s_mov_b32 m0, s0
	s_mov_b64 s[0:1], 0x2000
	v_add_u32_e32 v0, 0x4000, v185
	global_load_lds_dwordx4 v[6:7], off
	v_lshl_add_u64 v[6:7], v[4:5], 0, s[0:1]
	v_readfirstlane_b32 s0, v0
	s_mov_b32 m0, s0
	s_mov_b64 s[0:1], 0x3000
	v_add_u32_e32 v0, 0x5000, v185
	global_load_lds_dwordx4 v[6:7], off
	v_lshl_add_u64 v[6:7], v[4:5], 0, s[0:1]
	v_readfirstlane_b32 s0, v0
	v_add_u32_e32 v0, 0x6000, v185
	s_mov_b32 m0, s0
	v_readfirstlane_b32 s0, v0
	global_load_lds_dwordx4 v[6:7], off
	s_mov_b32 m0, s0
	s_mov_b64 s[0:1], 0x21040
	v_add_u32_e32 v0, 0x7000, v185
	v_lshl_add_u64 v[6:7], v[2:3], 0, 64
	v_lshl_add_u64 v[2:3], v[2:3], 0, s[0:1]
	v_readfirstlane_b32 s0, v0
	v_add_u32_e32 v0, 0x8000, v185
	global_load_lds_dwordx4 v[6:7], off
	s_mov_b32 m0, s0
	v_readfirstlane_b32 s0, v0
	global_load_lds_dwordx4 v[2:3], off
	v_lshl_add_u64 v[2:3], v[4:5], 0, s[86:87]
	s_mov_b32 m0, s0
	s_mov_b64 s[0:1], 0xd000
	v_add_u32_e32 v0, 0x9000, v185
	global_load_lds_dwordx4 v[2:3], off
	v_lshl_add_u64 v[2:3], v[4:5], 0, s[0:1]
	v_readfirstlane_b32 s0, v0
	s_mov_b32 m0, s0
	s_mov_b64 s[0:1], 0xe000
	v_add_u32_e32 v0, 0xa000, v185
	global_load_lds_dwordx4 v[2:3], off
	v_lshl_add_u64 v[2:3], v[4:5], 0, s[0:1]
	v_readfirstlane_b32 s0, v0
	s_mov_b32 m0, s0
	s_mov_b64 s[0:1], 0xf000
	v_add_u32_e32 v0, 0xb000, v185
	global_load_lds_dwordx4 v[2:3], off
	v_lshl_add_u64 v[2:3], v[4:5], 0, s[0:1]
	v_readfirstlane_b32 s0, v0
	s_mov_b32 m0, s0
	v_lshlrev_b32_e32 v0, 2, v184
	global_load_lds_dwordx4 v[2:3], off
	v_and_b32_e32 v0, 48, v0
	v_ashrrev_i32_e32 v2, 1, v184
	v_and_b32_e32 v187, 15, v184
	v_sub_u32_e32 v0, 0, v0
	v_and_b32_e32 v208, 0xffffffc0, v2
	v_bitop3_b32 v0, v184, 48, v0 bitop3:0x48
	v_or_b32_e32 v2, v208, v187
	v_lshl_or_b32 v209, v2, 6, v0
	v_lshlrev_b32_e32 v2, 1, v184
	v_and_b32_e32 v186, 0x80, v2
	v_or_b32_e32 v2, v186, v187
	v_lshl_or_b32 v0, v2, 6, v0
	v_add_u32_e32 v2, s8, v8
	s_mulk_i32 s40, 0x300
	v_subrev_u32_e32 v2, s40, v2
	v_ashrrev_i32_e32 v3, 31, v2
	v_lshlrev_b64 v[2:3], 6, v[2:3]
	v_add_u32_e32 v210, 0x2000, v0
	v_bitop3_b32 v0, v184, 3, v9 bitop3:0x48
	v_lshl_add_u64 v[180:181], v[130:131], 0, v[2:3]
	v_mov_b32_e32 v2, 0
	s_mov_b32 s42, 2
	s_mov_b32 s20, 0
	v_lshlrev_b32_e32 v0, 4, v0
	v_mad_i64_i32 v[182:183], s[0:1], v10, s28, v[130:131]
	s_mov_b32 s43, 0
	v_mov_b32_e32 v3, v2
	v_mov_b32_e32 v4, v2
	v_mov_b32_e32 v5, v2
	v_mov_b32_e32 v6, v2
	v_mov_b32_e32 v7, v2
	v_mov_b32_e32 v8, v2
	v_mov_b32_e32 v9, v2
	v_mov_b32_e32 v10, v2
	v_mov_b32_e32 v11, v2
	v_mov_b32_e32 v12, v2
	v_mov_b32_e32 v13, v2
	v_mov_b32_e32 v14, v2
	v_mov_b32_e32 v15, v2
	v_mov_b32_e32 v16, v2
	v_mov_b32_e32 v17, v2
	v_mov_b32_e32 v18, v2
	v_mov_b32_e32 v19, v2
	v_mov_b32_e32 v20, v2
	v_mov_b32_e32 v21, v2
	v_mov_b32_e32 v22, v2
	v_mov_b32_e32 v23, v2
	v_mov_b32_e32 v24, v2
	v_mov_b32_e32 v25, v2
	v_mov_b32_e32 v26, v2
; template <int EPI, int NB>
; DEVI void gemm_tile(const GemmJob& J, int m0, int n0, unsigned char* smem) {
;     ...
;   f32x4 acc[4][NB];
; #pragma unroll
;   for (int i = 0; i < 4; ++i)
; #pragma unroll
;     for (int j = 0; j < NB; ++j) acc[i][j] = (f32x4){0.f, 0.f, 0.f, 0.f};
;     ...
;     if (kt + S - 1 < nk) GEMM_ISSUE(kt + S - 1, is);
;     is = (is + 1 == S) ? 0 : is + 1;
;     const unsigned cur = lbase + cs * STG;
;     cs = (cs + 1 == S) ? 0 : cs + 1;
;     bf16x8 af[4], bfr[NB];
;     const unsigned aa = cur + aofs, ba = cur + bofs;
	v_mov_b32_e32 v27, v2
	v_mov_b32_e32 v28, v2
	v_mov_b32_e32 v29, v2
	v_mov_b32_e32 v30, v2
	v_mov_b32_e32 v31, v2
	v_mov_b32_e32 v32, v2
	v_mov_b32_e32 v33, v2
	v_mov_b32_e32 v34, v2
	v_mov_b32_e32 v35, v2
	v_mov_b32_e32 v36, v2
	v_mov_b32_e32 v37, v2
	v_mov_b32_e32 v38, v2
	v_mov_b32_e32 v39, v2
	v_mov_b32_e32 v40, v2
	v_mov_b32_e32 v41, v2
	v_mov_b32_e32 v42, v2
	v_mov_b32_e32 v43, v2
	v_mov_b32_e32 v44, v2
	v_mov_b32_e32 v45, v2
	v_mov_b32_e32 v46, v2
	v_mov_b32_e32 v47, v2
	v_mov_b32_e32 v48, v2
	v_mov_b32_e32 v49, v2
	v_mov_b32_e32 v50, v2
	v_mov_b32_e32 v51, v2
	v_mov_b32_e32 v52, v2
	v_mov_b32_e32 v53, v2
	v_mov_b32_e32 v54, v2
	v_mov_b32_e32 v55, v2
	v_mov_b32_e32 v56, v2
	v_mov_b32_e32 v57, v2
	v_mov_b32_e32 v58, v2
	v_mov_b32_e32 v59, v2
	v_mov_b32_e32 v60, v2
	v_mov_b32_e32 v61, v2
	v_mov_b32_e32 v62, v2
	v_mov_b32_e32 v63, v2
	v_mov_b32_e32 v64, v2
	v_mov_b32_e32 v65, v2
	v_mov_b32_e32 v66, v2
	v_mov_b32_e32 v67, v2
	v_mov_b32_e32 v68, v2
	v_mov_b32_e32 v69, v2
	v_mov_b32_e32 v70, v2
	v_mov_b32_e32 v71, v2
	v_mov_b32_e32 v72, v2
	v_mov_b32_e32 v73, v2
	v_mov_b32_e32 v74, v2
	v_mov_b32_e32 v75, v2
	v_mov_b32_e32 v76, v2
	v_mov_b32_e32 v77, v2
	v_mov_b32_e32 v78, v2
	v_mov_b32_e32 v79, v2
	v_mov_b32_e32 v80, v2
	v_mov_b32_e32 v81, v2
	v_mov_b32_e32 v82, v2
	v_mov_b32_e32 v83, v2
	v_mov_b32_e32 v84, v2
	v_mov_b32_e32 v85, v2
	v_mov_b32_e32 v86, v2
	v_mov_b32_e32 v87, v2
	v_mov_b32_e32 v88, v2
	v_mov_b32_e32 v89, v2
	v_mov_b32_e32 v90, v2
	v_mov_b32_e32 v91, v2
	v_mov_b32_e32 v92, v2
	v_mov_b32_e32 v93, v2
	v_mov_b32_e32 v94, v2
	v_mov_b32_e32 v95, v2
	v_mov_b32_e32 v96, v2
	v_mov_b32_e32 v97, v2
	v_mov_b32_e32 v98, v2
	v_mov_b32_e32 v99, v2
	v_mov_b32_e32 v100, v2
	v_mov_b32_e32 v101, v2
	v_mov_b32_e32 v102, v2
	v_mov_b32_e32 v103, v2
	v_mov_b32_e32 v104, v2
	v_mov_b32_e32 v105, v2
	v_mov_b32_e32 v106, v2
	v_mov_b32_e32 v107, v2
	v_mov_b32_e32 v108, v2
	v_mov_b32_e32 v109, v2
	v_mov_b32_e32 v110, v2
	v_mov_b32_e32 v111, v2
	v_mov_b32_e32 v112, v2
	v_mov_b32_e32 v113, v2
	v_mov_b32_e32 v114, v2
	v_mov_b32_e32 v115, v2
	v_mov_b32_e32 v116, v2
	v_mov_b32_e32 v117, v2
	v_mov_b32_e32 v118, v2
	v_mov_b32_e32 v119, v2
	v_mov_b32_e32 v120, v2
	v_mov_b32_e32 v121, v2
	v_mov_b32_e32 v122, v2
	v_mov_b32_e32 v123, v2
	v_mov_b32_e32 v124, v2
	v_mov_b32_e32 v125, v2
	v_mov_b32_e32 v126, v2
	v_mov_b32_e32 v127, v2
	v_mov_b32_e32 v128, v2
	v_mov_b32_e32 v129, v2
	s_mul_i32 s0, s42, 0x6000
	v_add_u32_e32 v211, s0, v185
	v_lshl_add_u64 v[212:213], v[182:183], 0, v[0:1]
	s_mov_b64 s[0:1], 0xb286080
	v_lshl_add_u64 v[214:215], v[212:213], 0, s[0:1]
	v_readfirstlane_b32 s0, v211
	s_mov_b32 m0, s0
	s_mov_b64 s[0:1], 0xb2a7080
	s_nop 0
	v_readfirstlane_b32 s100, v214
	v_readfirstlane_b32 s101, v215
	s_nop 1
	v_subrev_u32_e32 v228, s100, v214
	v_add_u32_e32 v214, 0x1000, v211
	v_lshl_add_u64 v[212:213], v[212:213], 0, s[0:1]
	v_readfirstlane_b32 s0, v214
	s_mov_b32 m0, s0
	s_mov_b64 s[0:1], 0x46be000
	v_subrev_u32_e32 v229, s100, v212
	v_lshl_add_u64 v[212:213], v[180:181], 0, v[0:1]
	v_add_u32_e32 v216, 0x2000, v211
	v_lshl_add_u64 v[214:215], v[212:213], 0, s[0:1]
	v_readfirstlane_b32 s0, v216
	s_mov_b32 m0, s0
	s_mov_b64 s[0:1], 0x46bf000
	v_add_u32_e32 v216, 0x3000, v211
	s_nop 0
	v_readfirstlane_b32 vcc_lo, v214
	v_readfirstlane_b32 vcc_hi, v215
	s_nop 1
	v_subrev_u32_e32 v230, vcc_lo, v214
	v_lshl_add_u64 v[214:215], v[212:213], 0, s[0:1]
	v_readfirstlane_b32 s0, v216
	s_mov_b32 m0, s0
	s_mov_b64 s[0:1], 0x46c0000
	v_add_u32_e32 v216, 0x4000, v211
	v_subrev_u32_e32 v231, vcc_lo, v214
	v_lshl_add_u64 v[214:215], v[212:213], 0, s[0:1]
	v_readfirstlane_b32 s0, v216
	s_mov_b32 m0, s0
	s_mov_b64 s[0:1], 0x46c1000
	v_add_u32_e32 v211, 0x5000, v211
	v_lshl_add_u64 v[212:213], v[212:213], 0, s[0:1]
	v_readfirstlane_b32 s0, v211
	v_subrev_u32_e32 v232, vcc_lo, v214
	s_mov_b32 m0, s0
	s_nop 0
	v_subrev_u32_e32 v233, vcc_lo, v212
	v_mov_b32_e32 v182, v228
	v_mov_b32_e32 v183, v229
	v_mov_b32_e32 v180, v230
	v_mov_b32_e32 v181, v231
	v_mov_b32_e32 v253, v232
	v_mov_b32_e32 v254, v233
	v_readfirstlane_b32 s0, v185
	s_branch .LBB0_1625
	.p2align	6

; #define RAW_BARRIER() do { asm volatile("s_waitcnt lgkmcnt(0)" ::: "memory"); __builtin_amdgcn_s_barrier(); } while (0)
; template <int EPI, int NB>
; DEVI void gemm_tile(const GemmJob& J, int m0, int n0, unsigned char* smem) {
;     ...
;   const int srow = tid >> 2, sch = tid & 3;
;   const int gch = sch ^ ((0 - (tid >> 4)) & 3);
;   const bf16_t* Ag = J.A + (size_t)(m0 + srow) * (J.ablk ? 32 : J.lda) + gch * 8;
;   const bf16_t* Bg = J.Bt + (size_t)(n0 + srow) * 32 + gch * 8;
;   const size_t Astep = (size_t)64 * (J.ablk ? 32 : J.lda), Ak = J.ablk ? (size_t)MROWS * 32 : (size_t)32, Bstep = (size_t)64 * 32, Bk = (size_t)J.NR * 32;
;   const int nk = J.K >> 5;
;   unsigned char* lds_t = smem + tid * 16;
;   const unsigned lbase = (unsigned)(uintptr_t)(__attribute__((address_space(3))) unsigned char*)smem;
;     ...
;   asm volatile("s_waitcnt vmcnt(0)" ::: "memory");
;   RAW_BARRIER();
; #pragma unroll
;   for (int st = 0; st < S - 1; ++st) GEMM_ISSUE(st, st);
;   const int fsl = (g ^ ((0 - (l16 >> 2)) & 3)) << 4;
;   const int aofs = (wm * 64 + l16) * 64 + fsl;
;   const int bofs = A_BYTES + (wn * NB * 16 + l16) * 64 + fsl;
; template <int EPI, int NB>
; DEVI void gemm_run(const GemmJob& J, unsigned char* smem, int rot) {
;     ...
;     for (int t = b; t < ntiles; t += G) {
;       const int mt = t / J.ntn, nt = J.nt0 + (t - mt * J.ntn);
;       gemm_tile<EPI, NB>(J, mt * 128, nt * BN, smem);
.LBB0_1749:
	s_lshr_b32 s0, s9, 31
	s_add_i32 s0, s9, s0
	s_ashr_i32 s0, s0, 1
	s_lshl_b32 s3, s0, 7
	s_lshl_b32 s40, s0, 9
	s_lshl_b32 s0, s9, 8
	v_mov_b32_e32 v184, v177
	s_sub_i32 s2, s0, s40
	s_movk_i32 s28, 0x840
	v_ashrrev_i32_e32 v8, 2, v184
	v_lshrrev_b32_e32 v0, 4, v184
	v_sub_u32_e32 v9, 0, v0
	v_add_u32_e32 v4, s2, v8
	v_xor_b32_e32 v0, v184, v9
	v_add_u32_e32 v10, s3, v8
	v_ashrrev_i32_e32 v5, 31, v4
	v_mad_i64_i32 v[2:3], s[0:1], v10, s28, v[170:171]
	v_lshlrev_b32_e32 v0, 4, v0
	v_lshlrev_b64 v[4:5], 6, v[4:5]
	v_lshlrev_b32_e32 v185, 4, v184
	v_and_b32_e32 v0, 48, v0
	v_lshl_add_u64 v[4:5], v[138:139], 0, v[4:5]
	v_readfirstlane_b32 s0, v185
	v_lshl_add_u64 v[2:3], v[2:3], 0, v[0:1]
	v_lshl_add_u64 v[4:5], v[4:5], 0, v[0:1]
	s_mov_b32 m0, s0
	s_mov_b64 s[0:1], 0x21000
	v_add_u32_e32 v0, 0x1000, v185
	s_nop 0
	v_lshl_add_u64 v[6:7], v[2:3], 0, s[0:1]
	v_readfirstlane_b32 s0, v0
	v_add_u32_e32 v0, 0x2000, v185
	s_waitcnt lgkmcnt(0)
	s_barrier
	global_load_lds_dwordx4 v[2:3], off
	s_mov_b32 m0, s0
	v_readfirstlane_b32 s0, v0
	v_add_u32_e32 v0, 0x3000, v185
	global_load_lds_dwordx4 v[6:7], off
	s_mov_b32 m0, s0
	v_readfirstlane_b32 s0, v0
	global_load_lds_dwordx4 v[4:5], off
	v_lshl_add_u64 v[6:7], v[4:5], 0, s[30:31]
	s_mov_b32 m0, s0
	s_mov_b64 s[0:1], 0x2000
	v_add_u32_e32 v0, 0x4000, v185
	global_load_lds_dwordx4 v[6:7], off
	v_lshl_add_u64 v[6:7], v[4:5], 0, s[0:1]
	v_readfirstlane_b32 s0, v0
	s_mov_b32 m0, s0
	s_mov_b64 s[0:1], 0x3000
	v_add_u32_e32 v0, 0x5000, v185
	global_load_lds_dwordx4 v[6:7], off
	v_lshl_add_u64 v[6:7], v[4:5], 0, s[0:1]
	v_readfirstlane_b32 s0, v0
	v_add_u32_e32 v0, 0x6000, v185
	s_mov_b32 m0, s0
	v_readfirstlane_b32 s0, v0
	global_load_lds_dwordx4 v[6:7], off
	s_mov_b32 m0, s0
	s_mov_b64 s[0:1], 0x21040
	v_add_u32_e32 v0, 0x7000, v185
	v_lshl_add_u64 v[6:7], v[2:3], 0, 64
	v_lshl_add_u64 v[2:3], v[2:3], 0, s[0:1]
	v_readfirstlane_b32 s0, v0
	v_add_u32_e32 v0, 0x8000, v185
	global_load_lds_dwordx4 v[6:7], off
	s_mov_b32 m0, s0
	v_readfirstlane_b32 s0, v0
	global_load_lds_dwordx4 v[2:3], off
	v_lshl_add_u64 v[2:3], v[4:5], 0, s[22:23]
	s_mov_b32 m0, s0
	s_mov_b64 s[0:1], 0x11000
	v_add_u32_e32 v0, 0x9000, v185
	global_load_lds_dwordx4 v[2:3], off
	v_lshl_add_u64 v[2:3], v[4:5], 0, s[0:1]
	v_readfirstlane_b32 s0, v0
	s_mov_b32 m0, s0
	s_mov_b64 s[0:1], 0x12000
	v_add_u32_e32 v0, 0xa000, v185
	global_load_lds_dwordx4 v[2:3], off
	v_lshl_add_u64 v[2:3], v[4:5], 0, s[0:1]
	v_readfirstlane_b32 s0, v0
	s_mov_b32 m0, s0
	s_mov_b64 s[0:1], 0x13000
	v_add_u32_e32 v0, 0xb000, v185
	global_load_lds_dwordx4 v[2:3], off
	v_lshl_add_u64 v[2:3], v[4:5], 0, s[0:1]
	v_readfirstlane_b32 s0, v0
	s_mov_b32 m0, s0
	v_lshlrev_b32_e32 v0, 2, v184
	global_load_lds_dwordx4 v[2:3], off
	v_and_b32_e32 v0, 48, v0
	v_ashrrev_i32_e32 v2, 1, v184
	v_and_b32_e32 v186, 15, v184
	v_sub_u32_e32 v0, 0, v0
	v_and_b32_e32 v187, 0xffffffc0, v2
	v_bitop3_b32 v0, v184, 48, v0 bitop3:0x48
	v_or_b32_e32 v2, v187, v186
	v_lshl_or_b32 v209, v2, 6, v0
	v_lshlrev_b32_e32 v2, 1, v184
	v_and_b32_e32 v208, 0x80, v2
	v_or_b32_e32 v2, v208, v186
	v_lshl_or_b32 v0, v2, 6, v0
	v_add_u32_e32 v2, s8, v8
	v_subrev_u32_e32 v2, s40, v2
	v_ashrrev_i32_e32 v3, 31, v2
	v_lshlrev_b64 v[2:3], 6, v[2:3]
	v_add_u32_e32 v210, 0x2000, v0
	v_bitop3_b32 v0, v184, 3, v9 bitop3:0x48
	v_lshl_add_u64 v[180:181], v[130:131], 0, v[2:3]
	v_mov_b32_e32 v2, 0
	s_mov_b32 s42, 2
	s_mov_b32 s20, 0
	v_lshlrev_b32_e32 v0, 4, v0
	v_mad_i64_i32 v[182:183], s[0:1], v10, s28, v[130:131]
	s_mov_b32 s43, 0
	v_mov_b32_e32 v3, v2
	v_mov_b32_e32 v4, v2
	v_mov_b32_e32 v5, v2
	v_mov_b32_e32 v6, v2
	v_mov_b32_e32 v7, v2
	v_mov_b32_e32 v8, v2
	v_mov_b32_e32 v9, v2
	v_mov_b32_e32 v10, v2
	v_mov_b32_e32 v11, v2
	v_mov_b32_e32 v12, v2
	v_mov_b32_e32 v13, v2
	v_mov_b32_e32 v14, v2
	v_mov_b32_e32 v15, v2
	v_mov_b32_e32 v16, v2
	v_mov_b32_e32 v17, v2
	v_mov_b32_e32 v18, v2
	v_mov_b32_e32 v19, v2
	v_mov_b32_e32 v20, v2
	v_mov_b32_e32 v21, v2
	v_mov_b32_e32 v22, v2
	v_mov_b32_e32 v23, v2
	v_mov_b32_e32 v24, v2
	v_mov_b32_e32 v25, v2
	v_mov_b32_e32 v26, v2
	v_mov_b32_e32 v27, v2
; template <int EPI, int NB>
; DEVI void gemm_tile(const GemmJob& J, int m0, int n0, unsigned char* smem) {
;     ...
;   f32x4 acc[4][NB];
; #pragma unroll
;   for (int i = 0; i < 4; ++i)
; #pragma unroll
;     for (int j = 0; j < NB; ++j) acc[i][j] = (f32x4){0.f, 0.f, 0.f, 0.f};
;     ...
;     if (kt + S - 1 < nk) GEMM_ISSUE(kt + S - 1, is);
;     is = (is + 1 == S) ? 0 : is + 1;
;     const unsigned cur = lbase + cs * STG;
;     cs = (cs + 1 == S) ? 0 : cs + 1;
;     bf16x8 af[4], bfr[NB];
;     const unsigned aa = cur + aofs, ba = cur + bofs;
	v_mov_b32_e32 v28, v2
	v_mov_b32_e32 v29, v2
	v_mov_b32_e32 v30, v2
	v_mov_b32_e32 v31, v2
	v_mov_b32_e32 v32, v2
	v_mov_b32_e32 v33, v2
	v_mov_b32_e32 v34, v2
	v_mov_b32_e32 v35, v2
	v_mov_b32_e32 v36, v2
	v_mov_b32_e32 v37, v2
	v_mov_b32_e32 v38, v2
	v_mov_b32_e32 v39, v2
	v_mov_b32_e32 v40, v2
	v_mov_b32_e32 v41, v2
	v_mov_b32_e32 v42, v2
	v_mov_b32_e32 v43, v2
	v_mov_b32_e32 v44, v2
	v_mov_b32_e32 v45, v2
	v_mov_b32_e32 v46, v2
	v_mov_b32_e32 v47, v2
	v_mov_b32_e32 v48, v2
	v_mov_b32_e32 v49, v2
	v_mov_b32_e32 v50, v2
	v_mov_b32_e32 v51, v2
	v_mov_b32_e32 v52, v2
	v_mov_b32_e32 v53, v2
	v_mov_b32_e32 v54, v2
	v_mov_b32_e32 v55, v2
	v_mov_b32_e32 v56, v2
	v_mov_b32_e32 v57, v2
	v_mov_b32_e32 v58, v2
	v_mov_b32_e32 v59, v2
	v_mov_b32_e32 v60, v2
	v_mov_b32_e32 v61, v2
	v_mov_b32_e32 v62, v2
	v_mov_b32_e32 v63, v2
	v_mov_b32_e32 v64, v2
	v_mov_b32_e32 v65, v2
	v_mov_b32_e32 v66, v2
	v_mov_b32_e32 v67, v2
	v_mov_b32_e32 v68, v2
	v_mov_b32_e32 v69, v2
	v_mov_b32_e32 v70, v2
	v_mov_b32_e32 v71, v2
	v_mov_b32_e32 v72, v2
	v_mov_b32_e32 v73, v2
	v_mov_b32_e32 v74, v2
	v_mov_b32_e32 v75, v2
	v_mov_b32_e32 v76, v2
	v_mov_b32_e32 v77, v2
	v_mov_b32_e32 v78, v2
	v_mov_b32_e32 v79, v2
	v_mov_b32_e32 v80, v2
	v_mov_b32_e32 v81, v2
	v_mov_b32_e32 v82, v2
	v_mov_b32_e32 v83, v2
	v_mov_b32_e32 v84, v2
	v_mov_b32_e32 v85, v2
	v_mov_b32_e32 v86, v2
	v_mov_b32_e32 v87, v2
	v_mov_b32_e32 v88, v2
	v_mov_b32_e32 v89, v2
	v_mov_b32_e32 v90, v2
	v_mov_b32_e32 v91, v2
	v_mov_b32_e32 v92, v2
	v_mov_b32_e32 v93, v2
	v_mov_b32_e32 v94, v2
	v_mov_b32_e32 v95, v2
	v_mov_b32_e32 v96, v2
	v_mov_b32_e32 v97, v2
	v_mov_b32_e32 v98, v2
	v_mov_b32_e32 v99, v2
	v_mov_b32_e32 v100, v2
	v_mov_b32_e32 v101, v2
	v_mov_b32_e32 v102, v2
	v_mov_b32_e32 v103, v2
	v_mov_b32_e32 v104, v2
	v_mov_b32_e32 v105, v2
	v_mov_b32_e32 v106, v2
	v_mov_b32_e32 v107, v2
	v_mov_b32_e32 v108, v2
	v_mov_b32_e32 v109, v2
	v_mov_b32_e32 v110, v2
	v_mov_b32_e32 v111, v2
	v_mov_b32_e32 v112, v2
	v_mov_b32_e32 v113, v2
	v_mov_b32_e32 v114, v2
	v_mov_b32_e32 v115, v2
	v_mov_b32_e32 v116, v2
	v_mov_b32_e32 v117, v2
	v_mov_b32_e32 v118, v2
	v_mov_b32_e32 v119, v2
	v_mov_b32_e32 v120, v2
	v_mov_b32_e32 v121, v2
	v_mov_b32_e32 v122, v2
	v_mov_b32_e32 v123, v2
	v_mov_b32_e32 v124, v2
	v_mov_b32_e32 v125, v2
	v_mov_b32_e32 v126, v2
	v_mov_b32_e32 v127, v2
	v_mov_b32_e32 v128, v2
	v_mov_b32_e32 v129, v2
	s_mul_i32 s0, s42, 0x6000
	v_add_u32_e32 v211, s0, v185
	v_lshl_add_u64 v[212:213], v[182:183], 0, v[0:1]
	s_mov_b64 s[0:1], 0xb286280
	v_lshl_add_u64 v[214:215], v[212:213], 0, s[0:1]
	v_readfirstlane_b32 s0, v211
	s_mov_b32 m0, s0
	s_mov_b64 s[0:1], 0xb2a7280
	s_nop 0
	v_readfirstlane_b32 s100, v214
	v_readfirstlane_b32 s101, v215
	s_nop 1
	v_subrev_u32_e32 v228, s100, v214
	v_add_u32_e32 v214, 0x1000, v211
	v_lshl_add_u64 v[212:213], v[212:213], 0, s[0:1]
	v_readfirstlane_b32 s0, v214
	s_mov_b32 m0, s0
	s_mov_b64 s[0:1], 0x4726000
	v_subrev_u32_e32 v229, s100, v212
	v_lshl_add_u64 v[212:213], v[180:181], 0, v[0:1]
	v_add_u32_e32 v216, 0x2000, v211
	v_lshl_add_u64 v[214:215], v[212:213], 0, s[0:1]
	v_readfirstlane_b32 s0, v216
	s_mov_b32 m0, s0
	s_mov_b64 s[0:1], 0x4727000
	v_add_u32_e32 v216, 0x3000, v211
	s_nop 0
	v_readfirstlane_b32 vcc_lo, v214
	v_readfirstlane_b32 vcc_hi, v215
	s_nop 1
	v_subrev_u32_e32 v230, vcc_lo, v214
	v_lshl_add_u64 v[214:215], v[212:213], 0, s[0:1]
	v_readfirstlane_b32 s0, v216
	s_mov_b32 m0, s0
	s_mov_b64 s[0:1], 0x4728000
	v_add_u32_e32 v216, 0x4000, v211
	v_subrev_u32_e32 v231, vcc_lo, v214
	v_lshl_add_u64 v[214:215], v[212:213], 0, s[0:1]
	v_readfirstlane_b32 s0, v216
	s_mov_b32 m0, s0
	s_mov_b64 s[0:1], 0x4729000
	v_add_u32_e32 v211, 0x5000, v211
	v_lshl_add_u64 v[212:213], v[212:213], 0, s[0:1]
	v_readfirstlane_b32 s0, v211
	v_subrev_u32_e32 v232, vcc_lo, v214
	s_mov_b32 m0, s0
	s_nop 0
	v_subrev_u32_e32 v233, vcc_lo, v212
	v_mov_b32_e32 v182, v228
	v_mov_b32_e32 v183, v229
	v_mov_b32_e32 v180, v230
	v_mov_b32_e32 v181, v231
	v_mov_b32_e32 v253, v232
	v_mov_b32_e32 v254, v233
	v_readfirstlane_b32 s0, v185
	s_branch .LBB0_1751
	.p2align	6

; #define RAW_BARRIER() do { asm volatile("s_waitcnt lgkmcnt(0)" ::: "memory"); __builtin_amdgcn_s_barrier(); } while (0)
; template <int EPI, int NB>
; DEVI void gemm_tile(const GemmJob& J, int m0, int n0, unsigned char* smem) {
;     ...
;   const int srow = tid >> 2, sch = tid & 3;
;   const int gch = sch ^ ((0 - (tid >> 4)) & 3);
;   const bf16_t* Ag = J.A + (size_t)(m0 + srow) * (J.ablk ? 32 : J.lda) + gch * 8;
;   const bf16_t* Bg = J.Bt + (size_t)(n0 + srow) * 32 + gch * 8;
;   const size_t Astep = (size_t)64 * (J.ablk ? 32 : J.lda), Ak = J.ablk ? (size_t)MROWS * 32 : (size_t)32, Bstep = (size_t)64 * 32, Bk = (size_t)J.NR * 32;
;   const int nk = J.K >> 5;
;   unsigned char* lds_t = smem + tid * 16;
;   const unsigned lbase = (unsigned)(uintptr_t)(__attribute__((address_space(3))) unsigned char*)smem;
;     ...
;   asm volatile("s_waitcnt vmcnt(0)" ::: "memory");
;   RAW_BARRIER();
; #pragma unroll
;   for (int st = 0; st < S - 1; ++st) GEMM_ISSUE(st, st);
;   const int fsl = (g ^ ((0 - (l16 >> 2)) & 3)) << 4;
;   const int aofs = (wm * 64 + l16) * 64 + fsl;
;   const int bofs = A_BYTES + (wn * NB * 16 + l16) * 64 + fsl;
; template <int EPI, int NB>
; DEVI void gemm_run(const GemmJob& J, unsigned char* smem, int rot) {
;     ...
;     for (int q0 = lb; q0 < ntot; q0 += nlb) {
;       const int q = J.rev ? ntot - 1 - q0 : q0;
;       int grp = q / gsz; const int qq = q - grp * gsz;
;       const int mg = min(8, mcnt - grp * 8);
;       const int nt = qq / mg, mi = qq - nt * mg;
;       gemm_tile<EPI, NB>(J, (mlo + grp * 8 + mi) * 128, (J.nt0 + nt) * BN, smem);
.LBB0_1822:
	s_mul_hi_i32 s0, s9, 0x2aaaaaab
	s_lshr_b32 s1, s0, 31
	s_ashr_i32 s0, s0, 2
	s_add_i32 s40, s0, s1
	s_lshl_b32 s0, s40, 3
	v_readlane_b32 s1, v251, 48
	s_sub_i32 s1, s1, s0
	s_min_i32 s1, s1, 8
	s_abs_i32 s2, s1
	v_cvt_f32_u32_e32 v0, s2
	s_sub_i32 s44, 0, s2
	s_mul_i32 s20, s40, 0xffffffe8
	s_add_i32 s20, s20, s9
	v_rcp_iflag_f32_e32 v0, v0
	s_abs_i32 s41, s20
	s_xor_b32 s43, s20, s1
	s_ashr_i32 s43, s43, 31
	v_mul_f32_e32 v0, 0x4f7ffffe, v0
	v_cvt_u32_f32_e32 v0, v0
	v_mov_b32_e32 v184, v177
	s_movk_i32 s28, 0x840
	v_readfirstlane_b32 s45, v0
	s_mul_i32 s44, s44, s45
	s_mul_hi_u32 s44, s45, s44
	s_add_i32 s45, s45, s44
	s_mul_hi_u32 s44, s41, s45
	s_mul_i32 s45, s44, s2
	s_sub_i32 s41, s41, s45
	s_add_i32 s45, s44, 1
	s_sub_i32 s46, s41, s2
	s_cmp_ge_u32 s41, s2
	s_cselect_b32 s44, s45, s44
	s_cselect_b32 s41, s46, s41
	s_add_i32 s45, s44, 1
	s_cmp_ge_u32 s41, s2
	s_cselect_b32 s2, s45, s44
	s_xor_b32 s2, s2, s43
	s_sub_i32 s2, s2, s43
	s_mul_i32 s41, s1, s2
	v_readlane_b32 s1, v250, 37
	s_add_i32 s0, s0, s1
	s_add_i32 s0, s0, s20
	s_sub_i32 s0, s0, s41
	s_lshl_b32 s2, s2, 8
	v_ashrrev_i32_e32 v10, 2, v184
	v_lshrrev_b32_e32 v0, 4, v184
	s_lshl_b32 s20, s0, 7
	v_sub_u32_e32 v11, 0, v0
	v_add_u32_e32 v4, s2, v10
	v_xor_b32_e32 v0, v184, v11
	v_add_u32_e32 v2, s20, v10
	v_ashrrev_i32_e32 v5, 31, v4
	v_mad_i64_i32 v[2:3], s[0:1], v2, s28, v[152:153]
	v_lshlrev_b32_e32 v0, 4, v0
	v_lshlrev_b64 v[4:5], 6, v[4:5]
	v_lshlrev_b32_e32 v185, 4, v184
	v_and_b32_e32 v0, 48, v0
	v_lshl_add_u64 v[6:7], v[136:137], 0, v[4:5]
	v_readfirstlane_b32 s0, v185
	v_lshl_add_u64 v[2:3], v[2:3], 0, v[0:1]
	v_lshl_add_u64 v[6:7], v[6:7], 0, v[0:1]
	s_mov_b32 m0, s0
	s_mov_b64 s[0:1], 0x21000
	v_add_u32_e32 v0, 0x1000, v185
	s_nop 0
	v_lshl_add_u64 v[8:9], v[2:3], 0, s[0:1]
	v_readfirstlane_b32 s0, v0
	v_add_u32_e32 v0, 0x2000, v185
	s_waitcnt lgkmcnt(0)
	s_barrier
	global_load_lds_dwordx4 v[2:3], off
	s_mov_b32 m0, s0
	v_readfirstlane_b32 s0, v0
	v_add_u32_e32 v0, 0x3000, v185
	global_load_lds_dwordx4 v[8:9], off
	s_mov_b32 m0, s0
	v_readfirstlane_b32 s0, v0
	global_load_lds_dwordx4 v[6:7], off
	v_lshl_add_u64 v[8:9], v[6:7], 0, s[30:31]
	s_mov_b32 m0, s0
	s_mov_b64 s[0:1], 0x2000
	v_add_u32_e32 v0, 0x4000, v185
	global_load_lds_dwordx4 v[8:9], off
	v_lshl_add_u64 v[8:9], v[6:7], 0, s[0:1]
	v_readfirstlane_b32 s0, v0
	s_mov_b32 m0, s0
	s_mov_b64 s[0:1], 0x3000
	v_add_u32_e32 v0, 0x5000, v185
	global_load_lds_dwordx4 v[8:9], off
	v_lshl_add_u64 v[8:9], v[6:7], 0, s[0:1]
	v_readfirstlane_b32 s0, v0
	v_add_u32_e32 v0, 0x6000, v185
	s_mov_b32 m0, s0
	v_readfirstlane_b32 s0, v0
	global_load_lds_dwordx4 v[8:9], off
	s_mov_b32 m0, s0
	s_mov_b64 s[0:1], 0x21040
	v_add_u32_e32 v0, 0x7000, v185
	v_lshl_add_u64 v[8:9], v[2:3], 0, 64
	v_lshl_add_u64 v[2:3], v[2:3], 0, s[0:1]
	v_readfirstlane_b32 s0, v0
	v_add_u32_e32 v0, 0x8000, v185
	global_load_lds_dwordx4 v[8:9], off
	s_mov_b32 m0, s0
	v_readfirstlane_b32 s0, v0
	global_load_lds_dwordx4 v[2:3], off
	v_lshl_add_u64 v[2:3], v[6:7], 0, s[86:87]
	s_mov_b32 m0, s0
	s_mov_b64 s[0:1], 0xd000
	v_add_u32_e32 v0, 0x9000, v185
	global_load_lds_dwordx4 v[2:3], off
	v_lshl_add_u64 v[2:3], v[6:7], 0, s[0:1]
	v_readfirstlane_b32 s0, v0
	s_mov_b32 m0, s0
	s_mov_b64 s[0:1], 0xe000
	v_add_u32_e32 v0, 0xa000, v185
	global_load_lds_dwordx4 v[2:3], off
	v_lshl_add_u64 v[2:3], v[6:7], 0, s[0:1]
	v_readfirstlane_b32 s0, v0
	s_mov_b32 m0, s0
	s_mov_b64 s[0:1], 0xf000
	v_add_u32_e32 v0, 0xb000, v185
	global_load_lds_dwordx4 v[2:3], off
	v_lshl_add_u64 v[2:3], v[6:7], 0, s[0:1]
	v_readfirstlane_b32 s0, v0
	s_mov_b32 m0, s0
	v_lshlrev_b32_e32 v0, 2, v184
	global_load_lds_dwordx4 v[2:3], off
	v_and_b32_e32 v0, 48, v0
	v_ashrrev_i32_e32 v2, 1, v184
	v_and_b32_e32 v187, 15, v184
	v_sub_u32_e32 v0, 0, v0
	v_and_b32_e32 v208, 0xffffffc0, v2
	v_bitop3_b32 v0, v184, 48, v0 bitop3:0x48
	v_or_b32_e32 v2, v208, v187
	v_lshl_or_b32 v209, v2, 6, v0
	v_lshlrev_b32_e32 v2, 1, v184
	v_and_b32_e32 v186, 0x80, v2
	s_sub_i32 s0, s8, s41
	s_lshl_b32 s1, s40, 4
	v_or_b32_e32 v2, v186, v187
	s_sub_i32 s0, s0, s1
	v_lshl_or_b32 v0, v2, 6, v0
	v_lshl_add_u32 v2, s0, 7, v10
	v_add_u32_e32 v210, 0x2000, v0
	v_bitop3_b32 v0, v184, 3, v11 bitop3:0x48
	v_mad_i64_i32 v[182:183], s[0:1], v2, s28, v[130:131]
	v_mov_b32_e32 v2, 0
	s_mov_b32 s42, 2
	s_mov_b32 s3, 0
	v_lshlrev_b32_e32 v0, 4, v0
	v_lshl_add_u64 v[180:181], v[130:131], 0, v[4:5]
	s_mov_b32 s43, 0
	v_mov_b32_e32 v3, v2
	v_mov_b32_e32 v4, v2
	v_mov_b32_e32 v5, v2
	v_mov_b32_e32 v6, v2
	v_mov_b32_e32 v7, v2
; template <int EPI, int NB>
; DEVI void gemm_tile(const GemmJob& J, int m0, int n0, unsigned char* smem) {
;     ...
;   f32x4 acc[4][NB];
; #pragma unroll
;   for (int i = 0; i < 4; ++i)
; #pragma unroll
;     for (int j = 0; j < NB; ++j) acc[i][j] = (f32x4){0.f, 0.f, 0.f, 0.f};
;     ...
;     if (kt + S - 1 < nk) GEMM_ISSUE(kt + S - 1, is);
;     is = (is + 1 == S) ? 0 : is + 1;
;     const unsigned cur = lbase + cs * STG;
;     cs = (cs + 1 == S) ? 0 : cs + 1;
;     bf16x8 af[4], bfr[NB];
;     const unsigned aa = cur + aofs, ba = cur + bofs;
	v_mov_b32_e32 v8, v2
	v_mov_b32_e32 v9, v2
	v_mov_b32_e32 v10, v2
	v_mov_b32_e32 v11, v2
	v_mov_b32_e32 v12, v2
	v_mov_b32_e32 v13, v2
	v_mov_b32_e32 v14, v2
	v_mov_b32_e32 v15, v2
	v_mov_b32_e32 v16, v2
	v_mov_b32_e32 v17, v2
	v_mov_b32_e32 v18, v2
	v_mov_b32_e32 v19, v2
	v_mov_b32_e32 v20, v2
	v_mov_b32_e32 v21, v2
	v_mov_b32_e32 v22, v2
	v_mov_b32_e32 v23, v2
	v_mov_b32_e32 v24, v2
	v_mov_b32_e32 v25, v2
	v_mov_b32_e32 v26, v2
	v_mov_b32_e32 v27, v2
	v_mov_b32_e32 v28, v2
	v_mov_b32_e32 v29, v2
	v_mov_b32_e32 v30, v2
	v_mov_b32_e32 v31, v2
	v_mov_b32_e32 v32, v2
	v_mov_b32_e32 v33, v2
	v_mov_b32_e32 v34, v2
	v_mov_b32_e32 v35, v2
	v_mov_b32_e32 v36, v2
	v_mov_b32_e32 v37, v2
	v_mov_b32_e32 v38, v2
	v_mov_b32_e32 v39, v2
	v_mov_b32_e32 v40, v2
	v_mov_b32_e32 v41, v2
	v_mov_b32_e32 v42, v2
	v_mov_b32_e32 v43, v2
	v_mov_b32_e32 v44, v2
	v_mov_b32_e32 v45, v2
	v_mov_b32_e32 v46, v2
	v_mov_b32_e32 v47, v2
	v_mov_b32_e32 v48, v2
	v_mov_b32_e32 v49, v2
	v_mov_b32_e32 v50, v2
	v_mov_b32_e32 v51, v2
	v_mov_b32_e32 v52, v2
	v_mov_b32_e32 v53, v2
	v_mov_b32_e32 v54, v2
	v_mov_b32_e32 v55, v2
	v_mov_b32_e32 v56, v2
	v_mov_b32_e32 v57, v2
	v_mov_b32_e32 v58, v2
	v_mov_b32_e32 v59, v2
	v_mov_b32_e32 v60, v2
	v_mov_b32_e32 v61, v2
	v_mov_b32_e32 v62, v2
	v_mov_b32_e32 v63, v2
	v_mov_b32_e32 v64, v2
	v_mov_b32_e32 v65, v2
	v_mov_b32_e32 v66, v2
	v_mov_b32_e32 v67, v2
	v_mov_b32_e32 v68, v2
	v_mov_b32_e32 v69, v2
	v_mov_b32_e32 v70, v2
	v_mov_b32_e32 v71, v2
	v_mov_b32_e32 v72, v2
	v_mov_b32_e32 v73, v2
	v_mov_b32_e32 v74, v2
	v_mov_b32_e32 v75, v2
	v_mov_b32_e32 v76, v2
	v_mov_b32_e32 v77, v2
	v_mov_b32_e32 v78, v2
	v_mov_b32_e32 v79, v2
	v_mov_b32_e32 v80, v2
	v_mov_b32_e32 v81, v2
	v_mov_b32_e32 v82, v2
	v_mov_b32_e32 v83, v2
	v_mov_b32_e32 v84, v2
	v_mov_b32_e32 v85, v2
	v_mov_b32_e32 v86, v2
	v_mov_b32_e32 v87, v2
	v_mov_b32_e32 v88, v2
	v_mov_b32_e32 v89, v2
	v_mov_b32_e32 v90, v2
	v_mov_b32_e32 v91, v2
	v_mov_b32_e32 v92, v2
	v_mov_b32_e32 v93, v2
	v_mov_b32_e32 v94, v2
	v_mov_b32_e32 v95, v2
	v_mov_b32_e32 v96, v2
	v_mov_b32_e32 v97, v2
	v_mov_b32_e32 v98, v2
	v_mov_b32_e32 v99, v2
	v_mov_b32_e32 v100, v2
	v_mov_b32_e32 v101, v2
	v_mov_b32_e32 v102, v2
	v_mov_b32_e32 v103, v2
	v_mov_b32_e32 v104, v2
	v_mov_b32_e32 v105, v2
	v_mov_b32_e32 v106, v2
	v_mov_b32_e32 v107, v2
	v_mov_b32_e32 v108, v2
	v_mov_b32_e32 v109, v2
	v_mov_b32_e32 v110, v2
	v_mov_b32_e32 v111, v2
	v_mov_b32_e32 v112, v2
	v_mov_b32_e32 v113, v2
	v_mov_b32_e32 v114, v2
	v_mov_b32_e32 v115, v2
	v_mov_b32_e32 v116, v2
	v_mov_b32_e32 v117, v2
	v_mov_b32_e32 v118, v2
	v_mov_b32_e32 v119, v2
	v_mov_b32_e32 v120, v2
	v_mov_b32_e32 v121, v2
	v_mov_b32_e32 v122, v2
	v_mov_b32_e32 v123, v2
	v_mov_b32_e32 v124, v2
	v_mov_b32_e32 v125, v2
	v_mov_b32_e32 v126, v2
	v_mov_b32_e32 v127, v2
	v_mov_b32_e32 v128, v2
	v_mov_b32_e32 v129, v2
	s_mul_i32 s0, s42, 0x6000
	v_add_u32_e32 v211, s0, v185
	v_lshl_add_u64 v[212:213], v[182:183], 0, v[0:1]
	s_mov_b64 s[0:1], 0xb286080
	v_lshl_add_u64 v[214:215], v[212:213], 0, s[0:1]
	v_readfirstlane_b32 s0, v211
	s_mov_b32 m0, s0
	s_mov_b64 s[0:1], 0xb2a7080
	s_nop 0
	v_readfirstlane_b32 s100, v214
	v_readfirstlane_b32 s101, v215
	s_nop 1
	v_subrev_u32_e32 v228, s100, v214
	v_add_u32_e32 v214, 0x1000, v211
	v_lshl_add_u64 v[212:213], v[212:213], 0, s[0:1]
	v_readfirstlane_b32 s0, v214
	s_mov_b32 m0, s0
	s_mov_b64 s[0:1], 0x46be000
	v_subrev_u32_e32 v229, s100, v212
	v_lshl_add_u64 v[212:213], v[180:181], 0, v[0:1]
	v_add_u32_e32 v216, 0x2000, v211
	v_lshl_add_u64 v[214:215], v[212:213], 0, s[0:1]
	v_readfirstlane_b32 s0, v216
	s_mov_b32 m0, s0
	s_mov_b64 s[0:1], 0x46bf000
	v_add_u32_e32 v216, 0x3000, v211
	s_nop 0
	v_readfirstlane_b32 vcc_lo, v214
	v_readfirstlane_b32 vcc_hi, v215
	s_nop 1
	v_subrev_u32_e32 v230, vcc_lo, v214
	v_lshl_add_u64 v[214:215], v[212:213], 0, s[0:1]
	v_readfirstlane_b32 s0, v216
	s_mov_b32 m0, s0
	s_mov_b64 s[0:1], 0x46c0000
	v_add_u32_e32 v216, 0x4000, v211
	v_subrev_u32_e32 v231, vcc_lo, v214
	v_lshl_add_u64 v[214:215], v[212:213], 0, s[0:1]
	v_readfirstlane_b32 s0, v216
	s_mov_b32 m0, s0
	s_mov_b64 s[0:1], 0x46c1000
	v_add_u32_e32 v211, 0x5000, v211
	v_lshl_add_u64 v[212:213], v[212:213], 0, s[0:1]
	v_readfirstlane_b32 s0, v211
	v_subrev_u32_e32 v232, vcc_lo, v214
	s_mov_b32 m0, s0
	s_nop 0
	v_subrev_u32_e32 v233, vcc_lo, v212
	v_mov_b32_e32 v182, v228
	v_mov_b32_e32 v183, v229
	v_mov_b32_e32 v180, v230
	v_mov_b32_e32 v181, v231
	v_mov_b32_e32 v253, v232
	v_mov_b32_e32 v254, v233
	v_readfirstlane_b32 s0, v185
	s_branch .LBB0_1824
	.p2align	6

; #define RAW_BARRIER() do { asm volatile("s_waitcnt lgkmcnt(0)" ::: "memory"); __builtin_amdgcn_s_barrier(); } while (0)
; template <int EPI, int NB>
; DEVI void gemm_tile(const GemmJob& J, int m0, int n0, unsigned char* smem) {
;     ...
;   const int srow = tid >> 2, sch = tid & 3;
;   const int gch = sch ^ ((0 - (tid >> 4)) & 3);
;   const bf16_t* Ag = J.A + (size_t)(m0 + srow) * (J.ablk ? 32 : J.lda) + gch * 8;
;   const bf16_t* Bg = J.Bt + (size_t)(n0 + srow) * 32 + gch * 8;
;   const size_t Astep = (size_t)64 * (J.ablk ? 32 : J.lda), Ak = J.ablk ? (size_t)MROWS * 32 : (size_t)32, Bstep = (size_t)64 * 32, Bk = (size_t)J.NR * 32;
;   const int nk = J.K >> 5;
;   unsigned char* lds_t = smem + tid * 16;
;   const unsigned lbase = (unsigned)(uintptr_t)(__attribute__((address_space(3))) unsigned char*)smem;
;     ...
;   asm volatile("s_waitcnt vmcnt(0)" ::: "memory");
;   RAW_BARRIER();
; #pragma unroll
;   for (int st = 0; st < S - 1; ++st) GEMM_ISSUE(st, st);
;   const int fsl = (g ^ ((0 - (l16 >> 2)) & 3)) << 4;
;   const int aofs = (wm * 64 + l16) * 64 + fsl;
;   const int bofs = A_BYTES + (wn * NB * 16 + l16) * 64 + fsl;
; template <int EPI, int NB>
; DEVI void gemm_run(const GemmJob& J, unsigned char* smem, int rot) {
;     ...
;     for (int t = b; t < ntiles; t += G) {
;       const int mt = t / J.ntn, nt = J.nt0 + (t - mt * J.ntn);
;       gemm_tile<EPI, NB>(J, mt * 128, nt * BN, smem);
.LBB0_1948:
	s_lshr_b32 s0, s9, 31
	s_add_i32 s0, s9, s0
	s_ashr_i32 s0, s0, 1
	s_lshl_b32 s1, s9, 8
	s_lshl_b32 s40, s0, 9
	s_sub_i32 s2, s1, s40
	v_mov_b32_e32 v184, v177
	s_addk_i32 s2, 0x200
	s_lshl_b32 s3, s0, 7
	v_ashrrev_i32_e32 v8, 2, v184
	v_lshrrev_b32_e32 v0, 4, v184
	v_sub_u32_e32 v9, 0, v0
	v_add_u32_e32 v4, s2, v8
	v_xor_b32_e32 v0, v184, v9
	v_add_u32_e32 v10, s3, v8
	s_movk_i32 s28, 0x840
	v_ashrrev_i32_e32 v5, 31, v4
	v_mad_i64_i32 v[2:3], s[0:1], v10, s28, v[170:171]
	v_lshlrev_b32_e32 v0, 4, v0
	v_lshlrev_b64 v[4:5], 6, v[4:5]
	v_lshlrev_b32_e32 v185, 4, v184
	v_and_b32_e32 v0, 48, v0
	v_lshl_add_u64 v[4:5], v[138:139], 0, v[4:5]
	v_readfirstlane_b32 s0, v185
	v_lshl_add_u64 v[2:3], v[2:3], 0, v[0:1]
	v_lshl_add_u64 v[4:5], v[4:5], 0, v[0:1]
	s_mov_b32 m0, s0
	s_mov_b64 s[0:1], 0x21000
	v_add_u32_e32 v0, 0x1000, v185
	s_nop 0
	v_lshl_add_u64 v[6:7], v[2:3], 0, s[0:1]
	v_readfirstlane_b32 s0, v0
	v_add_u32_e32 v0, 0x2000, v185
	s_waitcnt lgkmcnt(0)
	s_barrier
	global_load_lds_dwordx4 v[2:3], off
	s_mov_b32 m0, s0
	v_readfirstlane_b32 s0, v0
	v_add_u32_e32 v0, 0x3000, v185
	global_load_lds_dwordx4 v[6:7], off
	s_mov_b32 m0, s0
	v_readfirstlane_b32 s0, v0
	global_load_lds_dwordx4 v[4:5], off
	v_lshl_add_u64 v[6:7], v[4:5], 0, s[30:31]
	s_mov_b32 m0, s0
	s_mov_b64 s[0:1], 0x2000
	v_add_u32_e32 v0, 0x4000, v185
	global_load_lds_dwordx4 v[6:7], off
	v_lshl_add_u64 v[6:7], v[4:5], 0, s[0:1]
	v_readfirstlane_b32 s0, v0
	s_mov_b32 m0, s0
	s_mov_b64 s[0:1], 0x3000
	v_add_u32_e32 v0, 0x5000, v185
	global_load_lds_dwordx4 v[6:7], off
	v_lshl_add_u64 v[6:7], v[4:5], 0, s[0:1]
	v_readfirstlane_b32 s0, v0
	v_add_u32_e32 v0, 0x6000, v185
	s_mov_b32 m0, s0
	v_readfirstlane_b32 s0, v0
	global_load_lds_dwordx4 v[6:7], off
	s_mov_b32 m0, s0
	s_mov_b64 s[0:1], 0x21040
	v_add_u32_e32 v0, 0x7000, v185
	v_lshl_add_u64 v[6:7], v[2:3], 0, 64
	v_lshl_add_u64 v[2:3], v[2:3], 0, s[0:1]
	v_readfirstlane_b32 s0, v0
	v_add_u32_e32 v0, 0x8000, v185
	global_load_lds_dwordx4 v[6:7], off
	s_mov_b32 m0, s0
	v_readfirstlane_b32 s0, v0
	global_load_lds_dwordx4 v[2:3], off
	v_lshl_add_u64 v[2:3], v[4:5], 0, s[22:23]
	s_mov_b32 m0, s0
	s_mov_b64 s[0:1], 0x11000
	v_add_u32_e32 v0, 0x9000, v185
	global_load_lds_dwordx4 v[2:3], off
	v_lshl_add_u64 v[2:3], v[4:5], 0, s[0:1]
	v_readfirstlane_b32 s0, v0
	s_mov_b32 m0, s0
	s_mov_b64 s[0:1], 0x12000
	v_add_u32_e32 v0, 0xa000, v185
	global_load_lds_dwordx4 v[2:3], off
	v_lshl_add_u64 v[2:3], v[4:5], 0, s[0:1]
	v_readfirstlane_b32 s0, v0
	s_mov_b32 m0, s0
	s_mov_b64 s[0:1], 0x13000
	v_add_u32_e32 v0, 0xb000, v185
	global_load_lds_dwordx4 v[2:3], off
	v_lshl_add_u64 v[2:3], v[4:5], 0, s[0:1]
	v_readfirstlane_b32 s0, v0
	s_mov_b32 m0, s0
	v_and_b32_e32 v0, 15, v184
	global_load_lds_dwordx4 v[2:3], off
	v_lshlrev_b32_e32 v2, 2, v184
	v_and_b32_e32 v2, 48, v2
	v_ashrrev_i32_e32 v3, 1, v184
	v_sub_u32_e32 v2, 0, v2
	v_and_b32_e32 v187, 0xffffffc0, v3
	v_bitop3_b32 v2, v184, 48, v2 bitop3:0x48
	v_or_b32_e32 v3, v187, v0
	v_lshl_or_b32 v208, v3, 6, v2
	v_lshlrev_b32_e32 v3, 1, v184
	s_movk_i32 s0, 0x80
	v_and_or_b32 v186, v3, s0, v0
	v_lshl_or_b32 v0, v186, 6, v2
	v_add_u32_e32 v2, s8, v8
	v_subrev_u32_e32 v2, s40, v2
	v_ashrrev_i32_e32 v3, 31, v2
	v_lshlrev_b64 v[2:3], 6, v[2:3]
	v_add_u32_e32 v209, 0x2000, v0
	v_bitop3_b32 v0, v184, 3, v9 bitop3:0x48
	v_lshl_add_u64 v[180:181], v[130:131], 0, v[2:3]
	v_mov_b32_e32 v2, 0
	s_mov_b32 s42, 2
	s_mov_b32 s20, 0
	v_lshlrev_b32_e32 v0, 4, v0
	v_mad_i64_i32 v[182:183], s[0:1], v10, s28, v[130:131]
	s_mov_b32 s43, 0
	v_mov_b32_e32 v3, v2
	v_mov_b32_e32 v4, v2
	v_mov_b32_e32 v5, v2
	v_mov_b32_e32 v6, v2
	v_mov_b32_e32 v7, v2
	v_mov_b32_e32 v8, v2
	v_mov_b32_e32 v9, v2
	v_mov_b32_e32 v10, v2
	v_mov_b32_e32 v11, v2
	v_mov_b32_e32 v12, v2
	v_mov_b32_e32 v13, v2
	v_mov_b32_e32 v14, v2
	v_mov_b32_e32 v15, v2
	v_mov_b32_e32 v16, v2
	v_mov_b32_e32 v17, v2
	v_mov_b32_e32 v18, v2
	v_mov_b32_e32 v19, v2
	v_mov_b32_e32 v20, v2
	v_mov_b32_e32 v21, v2
	v_mov_b32_e32 v22, v2
	v_mov_b32_e32 v23, v2
	v_mov_b32_e32 v24, v2
	v_mov_b32_e32 v25, v2
	v_mov_b32_e32 v26, v2
; template <int EPI, int NB>
; DEVI void gemm_tile(const GemmJob& J, int m0, int n0, unsigned char* smem) {
;     ...
;   f32x4 acc[4][NB];
; #pragma unroll
;   for (int i = 0; i < 4; ++i)
; #pragma unroll
;     for (int j = 0; j < NB; ++j) acc[i][j] = (f32x4){0.f, 0.f, 0.f, 0.f};
;     ...
;     if (kt + S - 1 < nk) GEMM_ISSUE(kt + S - 1, is);
;     is = (is + 1 == S) ? 0 : is + 1;
;     const unsigned cur = lbase + cs * STG;
;     cs = (cs + 1 == S) ? 0 : cs + 1;
;     bf16x8 af[4], bfr[NB];
;     const unsigned aa = cur + aofs, ba = cur + bofs;
	v_mov_b32_e32 v27, v2
	v_mov_b32_e32 v28, v2
	v_mov_b32_e32 v29, v2
	v_mov_b32_e32 v30, v2
	v_mov_b32_e32 v31, v2
	v_mov_b32_e32 v32, v2
	v_mov_b32_e32 v33, v2
	v_mov_b32_e32 v34, v2
	v_mov_b32_e32 v35, v2
	v_mov_b32_e32 v36, v2
	v_mov_b32_e32 v37, v2
	v_mov_b32_e32 v38, v2
	v_mov_b32_e32 v39, v2
	v_mov_b32_e32 v40, v2
	v_mov_b32_e32 v41, v2
	v_mov_b32_e32 v42, v2
	v_mov_b32_e32 v43, v2
	v_mov_b32_e32 v44, v2
	v_mov_b32_e32 v45, v2
	v_mov_b32_e32 v46, v2
	v_mov_b32_e32 v47, v2
	v_mov_b32_e32 v48, v2
	v_mov_b32_e32 v49, v2
	v_mov_b32_e32 v50, v2
	v_mov_b32_e32 v51, v2
	v_mov_b32_e32 v52, v2
	v_mov_b32_e32 v53, v2
	v_mov_b32_e32 v54, v2
	v_mov_b32_e32 v55, v2
	v_mov_b32_e32 v56, v2
	v_mov_b32_e32 v57, v2
	v_mov_b32_e32 v58, v2
	v_mov_b32_e32 v59, v2
	v_mov_b32_e32 v60, v2
	v_mov_b32_e32 v61, v2
	v_mov_b32_e32 v62, v2
	v_mov_b32_e32 v63, v2
	v_mov_b32_e32 v64, v2
	v_mov_b32_e32 v65, v2
	v_mov_b32_e32 v66, v2
	v_mov_b32_e32 v67, v2
	v_mov_b32_e32 v68, v2
	v_mov_b32_e32 v69, v2
	v_mov_b32_e32 v70, v2
	v_mov_b32_e32 v71, v2
	v_mov_b32_e32 v72, v2
	v_mov_b32_e32 v73, v2
	v_mov_b32_e32 v74, v2
	v_mov_b32_e32 v75, v2
	v_mov_b32_e32 v76, v2
	v_mov_b32_e32 v77, v2
	v_mov_b32_e32 v78, v2
	v_mov_b32_e32 v79, v2
	v_mov_b32_e32 v80, v2
	v_mov_b32_e32 v81, v2
	v_mov_b32_e32 v82, v2
	v_mov_b32_e32 v83, v2
	v_mov_b32_e32 v84, v2
	v_mov_b32_e32 v85, v2
	v_mov_b32_e32 v86, v2
	v_mov_b32_e32 v87, v2
	v_mov_b32_e32 v88, v2
	v_mov_b32_e32 v89, v2
	v_mov_b32_e32 v90, v2
	v_mov_b32_e32 v91, v2
	v_mov_b32_e32 v92, v2
	v_mov_b32_e32 v93, v2
	v_mov_b32_e32 v94, v2
	v_mov_b32_e32 v95, v2
	v_mov_b32_e32 v96, v2
	v_mov_b32_e32 v97, v2
	v_mov_b32_e32 v98, v2
	v_mov_b32_e32 v99, v2
	v_mov_b32_e32 v100, v2
	v_mov_b32_e32 v101, v2
	v_mov_b32_e32 v102, v2
	v_mov_b32_e32 v103, v2
	v_mov_b32_e32 v104, v2
	v_mov_b32_e32 v105, v2
	v_mov_b32_e32 v106, v2
	v_mov_b32_e32 v107, v2
	v_mov_b32_e32 v108, v2
	v_mov_b32_e32 v109, v2
	v_mov_b32_e32 v110, v2
	v_mov_b32_e32 v111, v2
	v_mov_b32_e32 v112, v2
	v_mov_b32_e32 v113, v2
	v_mov_b32_e32 v114, v2
	v_mov_b32_e32 v115, v2
	v_mov_b32_e32 v116, v2
	v_mov_b32_e32 v117, v2
	v_mov_b32_e32 v118, v2
	v_mov_b32_e32 v119, v2
	v_mov_b32_e32 v120, v2
	v_mov_b32_e32 v121, v2
	v_mov_b32_e32 v122, v2
	v_mov_b32_e32 v123, v2
	v_mov_b32_e32 v124, v2
	v_mov_b32_e32 v125, v2
	v_mov_b32_e32 v126, v2
	v_mov_b32_e32 v127, v2
	v_mov_b32_e32 v128, v2
	v_mov_b32_e32 v129, v2
	s_mul_i32 s0, s42, 0x6000
	v_add_u32_e32 v214, s0, v185
	v_lshl_add_u64 v[210:211], v[182:183], 0, v[0:1]
	s_mov_b64 s[0:1], 0xb286280
	v_lshl_add_u64 v[212:213], v[210:211], 0, s[0:1]
	v_readfirstlane_b32 s0, v214
	s_mov_b32 m0, s0
	s_mov_b64 s[0:1], 0xb2a7280
	s_nop 0
	v_readfirstlane_b32 s100, v212
	v_readfirstlane_b32 s101, v213
	s_nop 1
	v_subrev_u32_e32 v226, s100, v212
	v_add_u32_e32 v212, 0x1000, v214
	v_lshl_add_u64 v[210:211], v[210:211], 0, s[0:1]
	v_readfirstlane_b32 s0, v212
	s_mov_b32 m0, s0
	s_mov_b64 s[0:1], 0x4726000
	v_subrev_u32_e32 v227, s100, v210
	v_lshl_add_u64 v[210:211], v[180:181], 0, v[0:1]
	v_add_u32_e32 v215, 0x2000, v214
	v_lshl_add_u64 v[212:213], v[210:211], 0, s[0:1]
	v_readfirstlane_b32 s0, v215
	s_mov_b32 m0, s0
	s_mov_b64 s[0:1], 0x4727000
	v_add_u32_e32 v215, 0x3000, v214
	s_nop 0
	v_readfirstlane_b32 vcc_lo, v212
	v_readfirstlane_b32 vcc_hi, v213
	s_nop 1
	v_subrev_u32_e32 v228, vcc_lo, v212
	v_lshl_add_u64 v[212:213], v[210:211], 0, s[0:1]
	v_readfirstlane_b32 s0, v215
	s_mov_b32 m0, s0
	s_mov_b64 s[0:1], 0x4728000
	v_add_u32_e32 v215, 0x4000, v214
	v_subrev_u32_e32 v229, vcc_lo, v212
	v_lshl_add_u64 v[212:213], v[210:211], 0, s[0:1]
	v_readfirstlane_b32 s0, v215
	s_mov_b32 m0, s0
	s_mov_b64 s[0:1], 0x4729000
	v_subrev_u32_e32 v230, vcc_lo, v212
	v_add_u32_e32 v212, 0x5000, v214
	v_lshl_add_u64 v[210:211], v[210:211], 0, s[0:1]
	v_readfirstlane_b32 s0, v212
	s_mov_b32 m0, s0
	s_nop 0
	v_subrev_u32_e32 v231, vcc_lo, v210
	v_mov_b32_e32 v182, v226
	v_mov_b32_e32 v183, v227
	v_mov_b32_e32 v180, v228
	v_mov_b32_e32 v181, v229
	v_mov_b32_e32 v253, v230
	v_mov_b32_e32 v254, v231
	v_readfirstlane_b32 s0, v185
	s_branch .LBB0_1950
	.p2align	6

; #define RAW_BARRIER() do { asm volatile("s_waitcnt lgkmcnt(0)" ::: "memory"); __builtin_amdgcn_s_barrier(); } while (0)
; template <int EPI, int NB>
; DEVI void gemm_tile(const GemmJob& J, int m0, int n0, unsigned char* smem) {
;     ...
;   const int srow = tid >> 2, sch = tid & 3;
;   const int gch = sch ^ ((0 - (tid >> 4)) & 3);
;   const bf16_t* Ag = J.A + (size_t)(m0 + srow) * (J.ablk ? 32 : J.lda) + gch * 8;
;   const bf16_t* Bg = J.Bt + (size_t)(n0 + srow) * 32 + gch * 8;
;   const size_t Astep = (size_t)64 * (J.ablk ? 32 : J.lda), Ak = J.ablk ? (size_t)MROWS * 32 : (size_t)32, Bstep = (size_t)64 * 32, Bk = (size_t)J.NR * 32;
;   const int nk = J.K >> 5;
;   unsigned char* lds_t = smem + tid * 16;
;   const unsigned lbase = (unsigned)(uintptr_t)(__attribute__((address_space(3))) unsigned char*)smem;
;     ...
;   asm volatile("s_waitcnt vmcnt(0)" ::: "memory");
;   RAW_BARRIER();
; #pragma unroll
;   for (int st = 0; st < S - 1; ++st) GEMM_ISSUE(st, st);
;   const int fsl = (g ^ ((0 - (l16 >> 2)) & 3)) << 4;
;   const int aofs = (wm * 64 + l16) * 64 + fsl;
;   const int bofs = A_BYTES + (wn * NB * 16 + l16) * 64 + fsl;
; template <int EPI, int NB>
; DEVI void gemm_run(const GemmJob& J, unsigned char* smem, int rot) {
;     ...
;     for (int q0 = lb; q0 < ntot; q0 += nlb) {
;       const int q = J.rev ? ntot - 1 - q0 : q0;
;       int grp = q / gsz; const int qq = q - grp * gsz;
;       const int mg = min(8, mcnt - grp * 8);
;       const int nt = qq / mg, mi = qq - nt * mg;
;       gemm_tile<EPI, NB>(J, (mlo + grp * 8 + mi) * 128, (J.nt0 + nt) * BN, smem);
.LBB0_2037:
	s_ashr_i32 s0, s9, 31
	s_lshr_b32 s0, s0, 28
	s_add_i32 s0, s9, s0
	s_ashr_i32 s1, s0, 4
	s_lshl_b32 s40, s1, 3
	v_readlane_b32 s1, v250, 16
	s_sub_i32 s1, s1, s40
	s_min_i32 s1, s1, 8
	s_abs_i32 s3, s1
	v_cvt_f32_u32_e32 v0, s3
	s_sub_i32 s42, 0, s3
	s_and_b32 s0, s0, -16
	s_sub_i32 s0, s9, s0
	v_rcp_iflag_f32_e32 v0, v0
	s_abs_i32 s20, s0
	s_xor_b32 s41, s0, s1
	s_ashr_i32 s41, s41, 31
	v_mul_f32_e32 v0, 0x4f7ffffe, v0
	v_cvt_u32_f32_e32 v0, v0
	v_mov_b32_e32 v184, v177
	s_movk_i32 s28, 0x840
	v_readfirstlane_b32 s43, v0
	s_mul_i32 s42, s42, s43
	s_mul_hi_u32 s42, s43, s42
	s_add_i32 s43, s43, s42
	s_mul_hi_u32 s42, s20, s43
	s_mul_i32 s43, s42, s3
	s_sub_i32 s20, s20, s43
	s_add_i32 s44, s42, 1
	s_sub_i32 s43, s20, s3
	s_cmp_ge_u32 s20, s3
	s_cselect_b32 s42, s44, s42
	s_cselect_b32 s20, s43, s20
	s_add_i32 s43, s42, 1
	s_cmp_ge_u32 s20, s3
	s_cselect_b32 s3, s43, s42
	s_xor_b32 s3, s3, s41
	s_sub_i32 s3, s3, s41
	s_mul_i32 s41, s1, s3
	v_readlane_b32 s1, v250, 48
	s_add_i32 s1, s40, s1
	s_add_i32 s1, s1, s0
	s_sub_i32 s0, s1, s41
	s_lshl_b32 s3, s3, 8
	v_ashrrev_i32_e32 v10, 2, v184
	v_lshrrev_b32_e32 v0, 4, v184
	s_lshl_b32 s20, s0, 7
	v_sub_u32_e32 v11, 0, v0
	v_add_u32_e32 v4, s3, v10
	v_xor_b32_e32 v0, v184, v11
	v_add_u32_e32 v2, s20, v10
	v_ashrrev_i32_e32 v5, 31, v4
	v_mad_i64_i32 v[2:3], s[0:1], v2, s28, v[170:171]
	v_lshlrev_b32_e32 v0, 4, v0
	v_lshlrev_b64 v[4:5], 6, v[4:5]
	v_lshlrev_b32_e32 v185, 4, v184
	v_and_b32_e32 v0, 48, v0
	v_lshl_add_u64 v[6:7], v[138:139], 0, v[4:5]
	v_readfirstlane_b32 s0, v185
	v_lshl_add_u64 v[2:3], v[2:3], 0, v[0:1]
	v_lshl_add_u64 v[6:7], v[6:7], 0, v[0:1]
	s_mov_b32 m0, s0
	s_mov_b64 s[0:1], 0x21000
	v_add_u32_e32 v0, 0x1000, v185
	s_nop 0
	v_lshl_add_u64 v[8:9], v[2:3], 0, s[0:1]
	v_readfirstlane_b32 s0, v0
	v_add_u32_e32 v0, 0x2000, v185
	s_waitcnt lgkmcnt(0)
	s_barrier
	global_load_lds_dwordx4 v[2:3], off
	s_mov_b32 m0, s0
	v_readfirstlane_b32 s0, v0
	v_add_u32_e32 v0, 0x3000, v185
	global_load_lds_dwordx4 v[8:9], off
	s_mov_b32 m0, s0
	v_readfirstlane_b32 s0, v0
	global_load_lds_dwordx4 v[6:7], off
	v_lshl_add_u64 v[8:9], v[6:7], 0, s[30:31]
	s_mov_b32 m0, s0
	s_mov_b64 s[0:1], 0x2000
	v_add_u32_e32 v0, 0x4000, v185
	global_load_lds_dwordx4 v[8:9], off
	v_lshl_add_u64 v[8:9], v[6:7], 0, s[0:1]
	v_readfirstlane_b32 s0, v0
	s_mov_b32 m0, s0
	s_mov_b64 s[0:1], 0x3000
	v_add_u32_e32 v0, 0x5000, v185
	global_load_lds_dwordx4 v[8:9], off
	v_lshl_add_u64 v[8:9], v[6:7], 0, s[0:1]
	v_readfirstlane_b32 s0, v0
	v_add_u32_e32 v0, 0x6000, v185
	s_mov_b32 m0, s0
	v_readfirstlane_b32 s0, v0
	global_load_lds_dwordx4 v[8:9], off
	s_mov_b32 m0, s0
	s_mov_b64 s[0:1], 0x21040
	v_add_u32_e32 v0, 0x7000, v185
	v_lshl_add_u64 v[8:9], v[2:3], 0, 64
	v_lshl_add_u64 v[2:3], v[2:3], 0, s[0:1]
	v_readfirstlane_b32 s0, v0
	v_add_u32_e32 v0, 0x8000, v185
	global_load_lds_dwordx4 v[8:9], off
	s_mov_b32 m0, s0
	v_readfirstlane_b32 s0, v0
	global_load_lds_dwordx4 v[2:3], off
	v_lshl_add_u64 v[2:3], v[6:7], 0, s[22:23]
	s_mov_b32 m0, s0
	s_mov_b64 s[0:1], 0x11000
	v_add_u32_e32 v0, 0x9000, v185
	global_load_lds_dwordx4 v[2:3], off
	v_lshl_add_u64 v[2:3], v[6:7], 0, s[0:1]
	v_readfirstlane_b32 s0, v0
	s_mov_b32 m0, s0
	s_mov_b64 s[0:1], 0x12000
	v_add_u32_e32 v0, 0xa000, v185
	global_load_lds_dwordx4 v[2:3], off
	v_lshl_add_u64 v[2:3], v[6:7], 0, s[0:1]
	v_readfirstlane_b32 s0, v0
	s_mov_b32 m0, s0
	s_mov_b64 s[0:1], 0x13000
	v_add_u32_e32 v0, 0xb000, v185
	global_load_lds_dwordx4 v[2:3], off
	v_lshl_add_u64 v[2:3], v[6:7], 0, s[0:1]
	v_readfirstlane_b32 s0, v0
	s_mov_b32 m0, s0
	v_lshlrev_b32_e32 v0, 2, v184
	global_load_lds_dwordx4 v[2:3], off
	v_and_b32_e32 v0, 48, v0
	v_ashrrev_i32_e32 v2, 1, v184
	v_and_b32_e32 v186, 15, v184
	v_sub_u32_e32 v0, 0, v0
	v_and_b32_e32 v187, 0xffffffc0, v2
	v_bitop3_b32 v0, v184, 48, v0 bitop3:0x48
	v_or_b32_e32 v2, v187, v186
	v_lshl_or_b32 v209, v2, 6, v0
	v_lshlrev_b32_e32 v2, 1, v184
	v_and_b32_e32 v208, 0x80, v2
	s_sub_i32 s0, s8, s41
	v_or_b32_e32 v2, v208, v186
	s_sub_i32 s0, s0, s40
	v_lshl_or_b32 v0, v2, 6, v0
	v_lshl_add_u32 v2, s0, 7, v10
	v_add_u32_e32 v210, 0x2000, v0
	v_bitop3_b32 v0, v184, 3, v11 bitop3:0x48
	v_mad_i64_i32 v[182:183], s[0:1], v2, s28, v[130:131]
	v_mov_b32_e32 v2, 0
	s_mov_b32 s2, 0
	s_mov_b32 s42, 2
	v_lshlrev_b32_e32 v0, 4, v0
	v_lshl_add_u64 v[180:181], v[130:131], 0, v[4:5]
	s_mov_b32 s43, 0
	v_mov_b32_e32 v3, v2
	v_mov_b32_e32 v4, v2
	v_mov_b32_e32 v5, v2
	v_mov_b32_e32 v6, v2
	v_mov_b32_e32 v7, v2
	v_mov_b32_e32 v8, v2
; template <int EPI, int NB>
; DEVI void gemm_tile(const GemmJob& J, int m0, int n0, unsigned char* smem) {
;     ...
;   f32x4 acc[4][NB];
; #pragma unroll
;   for (int i = 0; i < 4; ++i)
; #pragma unroll
;     for (int j = 0; j < NB; ++j) acc[i][j] = (f32x4){0.f, 0.f, 0.f, 0.f};
;     ...
;     if (kt + S - 1 < nk) GEMM_ISSUE(kt + S - 1, is);
;     is = (is + 1 == S) ? 0 : is + 1;
;     const unsigned cur = lbase + cs * STG;
;     cs = (cs + 1 == S) ? 0 : cs + 1;
;     bf16x8 af[4], bfr[NB];
;     const unsigned aa = cur + aofs, ba = cur + bofs;
	v_mov_b32_e32 v9, v2
	v_mov_b32_e32 v10, v2
	v_mov_b32_e32 v11, v2
	v_mov_b32_e32 v12, v2
	v_mov_b32_e32 v13, v2
	v_mov_b32_e32 v14, v2
	v_mov_b32_e32 v15, v2
	v_mov_b32_e32 v16, v2
	v_mov_b32_e32 v17, v2
	v_mov_b32_e32 v18, v2
	v_mov_b32_e32 v19, v2
	v_mov_b32_e32 v20, v2
	v_mov_b32_e32 v21, v2
	v_mov_b32_e32 v22, v2
	v_mov_b32_e32 v23, v2
	v_mov_b32_e32 v24, v2
	v_mov_b32_e32 v25, v2
	v_mov_b32_e32 v26, v2
	v_mov_b32_e32 v27, v2
	v_mov_b32_e32 v28, v2
	v_mov_b32_e32 v29, v2
	v_mov_b32_e32 v30, v2
	v_mov_b32_e32 v31, v2
	v_mov_b32_e32 v32, v2
	v_mov_b32_e32 v33, v2
	v_mov_b32_e32 v34, v2
	v_mov_b32_e32 v35, v2
	v_mov_b32_e32 v36, v2
	v_mov_b32_e32 v37, v2
	v_mov_b32_e32 v38, v2
	v_mov_b32_e32 v39, v2
	v_mov_b32_e32 v40, v2
	v_mov_b32_e32 v41, v2
	v_mov_b32_e32 v42, v2
	v_mov_b32_e32 v43, v2
	v_mov_b32_e32 v44, v2
	v_mov_b32_e32 v45, v2
	v_mov_b32_e32 v46, v2
	v_mov_b32_e32 v47, v2
	v_mov_b32_e32 v48, v2
	v_mov_b32_e32 v49, v2
	v_mov_b32_e32 v50, v2
	v_mov_b32_e32 v51, v2
	v_mov_b32_e32 v52, v2
	v_mov_b32_e32 v53, v2
	v_mov_b32_e32 v54, v2
	v_mov_b32_e32 v55, v2
	v_mov_b32_e32 v56, v2
	v_mov_b32_e32 v57, v2
	v_mov_b32_e32 v58, v2
	v_mov_b32_e32 v59, v2
	v_mov_b32_e32 v60, v2
	v_mov_b32_e32 v61, v2
	v_mov_b32_e32 v62, v2
	v_mov_b32_e32 v63, v2
	v_mov_b32_e32 v64, v2
	v_mov_b32_e32 v65, v2
	v_mov_b32_e32 v66, v2
	v_mov_b32_e32 v67, v2
	v_mov_b32_e32 v68, v2
	v_mov_b32_e32 v69, v2
	v_mov_b32_e32 v70, v2
	v_mov_b32_e32 v71, v2
	v_mov_b32_e32 v72, v2
	v_mov_b32_e32 v73, v2
	v_mov_b32_e32 v74, v2
	v_mov_b32_e32 v75, v2
	v_mov_b32_e32 v76, v2
	v_mov_b32_e32 v77, v2
	v_mov_b32_e32 v78, v2
	v_mov_b32_e32 v79, v2
	v_mov_b32_e32 v80, v2
	v_mov_b32_e32 v81, v2
	v_mov_b32_e32 v82, v2
	v_mov_b32_e32 v83, v2
	v_mov_b32_e32 v84, v2
	v_mov_b32_e32 v85, v2
	v_mov_b32_e32 v86, v2
	v_mov_b32_e32 v87, v2
	v_mov_b32_e32 v88, v2
	v_mov_b32_e32 v89, v2
	v_mov_b32_e32 v90, v2
	v_mov_b32_e32 v91, v2
	v_mov_b32_e32 v92, v2
	v_mov_b32_e32 v93, v2
	v_mov_b32_e32 v94, v2
	v_mov_b32_e32 v95, v2
	v_mov_b32_e32 v96, v2
	v_mov_b32_e32 v97, v2
	v_mov_b32_e32 v98, v2
	v_mov_b32_e32 v99, v2
	v_mov_b32_e32 v100, v2
	v_mov_b32_e32 v101, v2
	v_mov_b32_e32 v102, v2
	v_mov_b32_e32 v103, v2
	v_mov_b32_e32 v104, v2
	v_mov_b32_e32 v105, v2
	v_mov_b32_e32 v106, v2
	v_mov_b32_e32 v107, v2
	v_mov_b32_e32 v108, v2
	v_mov_b32_e32 v109, v2
	v_mov_b32_e32 v110, v2
	v_mov_b32_e32 v111, v2
	v_mov_b32_e32 v112, v2
	v_mov_b32_e32 v113, v2
	v_mov_b32_e32 v114, v2
	v_mov_b32_e32 v115, v2
	v_mov_b32_e32 v116, v2
	v_mov_b32_e32 v117, v2
	v_mov_b32_e32 v118, v2
	v_mov_b32_e32 v119, v2
	v_mov_b32_e32 v120, v2
	v_mov_b32_e32 v121, v2
	v_mov_b32_e32 v122, v2
	v_mov_b32_e32 v123, v2
	v_mov_b32_e32 v124, v2
	v_mov_b32_e32 v125, v2
	v_mov_b32_e32 v126, v2
	v_mov_b32_e32 v127, v2
	v_mov_b32_e32 v128, v2
	v_mov_b32_e32 v129, v2
	s_mul_i32 s0, s42, 0x6000
	v_add_u32_e32 v211, s0, v185
	v_lshl_add_u64 v[212:213], v[182:183], 0, v[0:1]
	s_mov_b64 s[0:1], 0xb286280
	v_lshl_add_u64 v[214:215], v[212:213], 0, s[0:1]
	v_readfirstlane_b32 s0, v211
	s_mov_b32 m0, s0
	s_mov_b64 s[0:1], 0xb2a7280
	s_nop 0
	v_readfirstlane_b32 s100, v214
	v_readfirstlane_b32 s101, v215
	s_nop 1
	v_subrev_u32_e32 v228, s100, v214
	v_add_u32_e32 v214, 0x1000, v211
	v_lshl_add_u64 v[212:213], v[212:213], 0, s[0:1]
	v_readfirstlane_b32 s0, v214
	s_mov_b32 m0, s0
	s_mov_b64 s[0:1], 0x4726000
	v_subrev_u32_e32 v229, s100, v212
	v_lshl_add_u64 v[212:213], v[180:181], 0, v[0:1]
	v_add_u32_e32 v216, 0x2000, v211
	v_lshl_add_u64 v[214:215], v[212:213], 0, s[0:1]
	v_readfirstlane_b32 s0, v216
	s_mov_b32 m0, s0
	s_mov_b64 s[0:1], 0x4727000
	v_add_u32_e32 v216, 0x3000, v211
	s_nop 0
	v_readfirstlane_b32 vcc_lo, v214
	v_readfirstlane_b32 vcc_hi, v215
	s_nop 1
	v_subrev_u32_e32 v230, vcc_lo, v214
	v_lshl_add_u64 v[214:215], v[212:213], 0, s[0:1]
	v_readfirstlane_b32 s0, v216
	s_mov_b32 m0, s0
	s_mov_b64 s[0:1], 0x4728000
	v_add_u32_e32 v216, 0x4000, v211
	v_subrev_u32_e32 v231, vcc_lo, v214
	v_lshl_add_u64 v[214:215], v[212:213], 0, s[0:1]
	v_readfirstlane_b32 s0, v216
	s_mov_b32 m0, s0
	s_mov_b64 s[0:1], 0x4729000
	v_add_u32_e32 v211, 0x5000, v211
	v_lshl_add_u64 v[212:213], v[212:213], 0, s[0:1]
	v_readfirstlane_b32 s0, v211
	v_subrev_u32_e32 v232, vcc_lo, v214
	s_mov_b32 m0, s0
	s_nop 0
	v_subrev_u32_e32 v233, vcc_lo, v212
	v_mov_b32_e32 v182, v228
	v_mov_b32_e32 v183, v229
	v_mov_b32_e32 v180, v230
	v_mov_b32_e32 v181, v231
	v_mov_b32_e32 v253, v232
	v_mov_b32_e32 v254, v233
	v_readfirstlane_b32 s0, v185
	s_branch .LBB0_2039
	.p2align	6

; #define RAW_BARRIER() do { asm volatile("s_waitcnt lgkmcnt(0)" ::: "memory"); __builtin_amdgcn_s_barrier(); } while (0)
; template <int EPI, int NB>
; DEVI void gemm_tile(const GemmJob& J, int m0, int n0, unsigned char* smem) {
;     ...
;   const int srow = tid >> 2, sch = tid & 3;
;   const int gch = sch ^ ((0 - (tid >> 4)) & 3);
;   const bf16_t* Ag = J.A + (size_t)(m0 + srow) * (J.ablk ? 32 : J.lda) + gch * 8;
;   const bf16_t* Bg = J.Bt + (size_t)(n0 + srow) * 32 + gch * 8;
;   const size_t Astep = (size_t)64 * (J.ablk ? 32 : J.lda), Ak = J.ablk ? (size_t)MROWS * 32 : (size_t)32, Bstep = (size_t)64 * 32, Bk = (size_t)J.NR * 32;
;   const int nk = J.K >> 5;
;   unsigned char* lds_t = smem + tid * 16;
;   const unsigned lbase = (unsigned)(uintptr_t)(__attribute__((address_space(3))) unsigned char*)smem;
;     ...
;   asm volatile("s_waitcnt vmcnt(0)" ::: "memory");
;   RAW_BARRIER();
; #pragma unroll
;   for (int st = 0; st < S - 1; ++st) GEMM_ISSUE(st, st);
;   const int fsl = (g ^ ((0 - (l16 >> 2)) & 3)) << 4;
;   const int aofs = (wm * 64 + l16) * 64 + fsl;
;   const int bofs = A_BYTES + (wn * NB * 16 + l16) * 64 + fsl;
; template <int EPI, int NB>
; DEVI void gemm_run(const GemmJob& J, unsigned char* smem, int rot) {
;     ...
;     for (int q0 = lb; q0 < ntot; q0 += nlb) {
;       const int q = J.rev ? ntot - 1 - q0 : q0;
;       int grp = q / gsz; const int qq = q - grp * gsz;
;       const int mg = min(8, mcnt - grp * 8);
;       const int nt = qq / mg, mi = qq - nt * mg;
;       gemm_tile<EPI, NB>(J, (mlo + grp * 8 + mi) * 128, (J.nt0 + nt) * BN, smem);
.LBB0_2115:
	s_ashr_i32 s0, s9, 31
	s_lshr_b32 s0, s0, 28
	s_add_i32 s0, s9, s0
	s_ashr_i32 s1, s0, 4
	s_lshl_b32 s40, s1, 3
	v_readlane_b32 s1, v250, 22
	s_sub_i32 s1, s1, s40
	s_min_i32 s1, s1, 8
	s_abs_i32 s2, s1
	v_cvt_f32_u32_e32 v0, s2
	s_sub_i32 s42, 0, s2
	s_and_b32 s0, s0, -16
	s_sub_i32 s0, s9, s0
	v_rcp_iflag_f32_e32 v0, v0
	s_abs_i32 s20, s0
	s_xor_b32 s41, s0, s1
	s_ashr_i32 s41, s41, 31
	v_mul_f32_e32 v0, 0x4f7ffffe, v0
	v_cvt_u32_f32_e32 v0, v0
	v_mov_b32_e32 v184, v177
	s_movk_i32 s28, 0x840
	v_readfirstlane_b32 s43, v0
	s_mul_i32 s42, s42, s43
	s_mul_hi_u32 s42, s43, s42
	s_add_i32 s43, s43, s42
	s_mul_hi_u32 s42, s20, s43
	s_mul_i32 s43, s42, s2
	s_sub_i32 s20, s20, s43
	s_add_i32 s44, s42, 1
	s_sub_i32 s43, s20, s2
	s_cmp_ge_u32 s20, s2
	s_cselect_b32 s42, s44, s42
	s_cselect_b32 s20, s43, s20
	s_add_i32 s43, s42, 1
	s_cmp_ge_u32 s20, s2
	s_cselect_b32 s2, s43, s42
	s_xor_b32 s2, s2, s41
	s_sub_i32 s2, s2, s41
	s_mul_i32 s41, s1, s2
	v_readlane_b32 s1, v250, 53
	s_add_i32 s1, s40, s1
	s_add_i32 s1, s1, s0
	s_lshl_b32 s2, s2, 8
	s_sub_i32 s0, s1, s41
	s_addk_i32 s2, 0x200
	v_ashrrev_i32_e32 v10, 2, v184
	v_lshrrev_b32_e32 v0, 4, v184
	s_lshl_b32 s20, s0, 7
	v_sub_u32_e32 v11, 0, v0
	v_add_u32_e32 v4, s2, v10
	v_xor_b32_e32 v0, v184, v11
	v_add_u32_e32 v2, s20, v10
	v_ashrrev_i32_e32 v5, 31, v4
	v_mad_i64_i32 v[2:3], s[0:1], v2, s28, v[170:171]
	v_lshlrev_b32_e32 v0, 4, v0
	v_lshlrev_b64 v[4:5], 6, v[4:5]
	v_lshlrev_b32_e32 v185, 4, v184
	v_and_b32_e32 v0, 48, v0
	v_lshl_add_u64 v[6:7], v[138:139], 0, v[4:5]
	v_readfirstlane_b32 s0, v185
	v_lshl_add_u64 v[2:3], v[2:3], 0, v[0:1]
	v_lshl_add_u64 v[6:7], v[6:7], 0, v[0:1]
	s_mov_b32 m0, s0
	s_mov_b64 s[0:1], 0x21000
	v_add_u32_e32 v0, 0x1000, v185
	s_nop 0
	v_lshl_add_u64 v[8:9], v[2:3], 0, s[0:1]
	v_readfirstlane_b32 s0, v0
	v_add_u32_e32 v0, 0x2000, v185
	s_waitcnt lgkmcnt(0)
	s_barrier
	global_load_lds_dwordx4 v[2:3], off
	s_mov_b32 m0, s0
	v_readfirstlane_b32 s0, v0
	v_add_u32_e32 v0, 0x3000, v185
	global_load_lds_dwordx4 v[8:9], off
	s_mov_b32 m0, s0
	v_readfirstlane_b32 s0, v0
	global_load_lds_dwordx4 v[6:7], off
	v_lshl_add_u64 v[8:9], v[6:7], 0, s[30:31]
	s_mov_b32 m0, s0
	s_mov_b64 s[0:1], 0x2000
	v_add_u32_e32 v0, 0x4000, v185
	global_load_lds_dwordx4 v[8:9], off
	v_lshl_add_u64 v[8:9], v[6:7], 0, s[0:1]
	v_readfirstlane_b32 s0, v0
	s_mov_b32 m0, s0
	s_mov_b64 s[0:1], 0x3000
	v_add_u32_e32 v0, 0x5000, v185
	global_load_lds_dwordx4 v[8:9], off
	v_lshl_add_u64 v[8:9], v[6:7], 0, s[0:1]
	v_readfirstlane_b32 s0, v0
	v_add_u32_e32 v0, 0x6000, v185
	s_mov_b32 m0, s0
	v_readfirstlane_b32 s0, v0
	global_load_lds_dwordx4 v[8:9], off
	s_mov_b32 m0, s0
	s_mov_b64 s[0:1], 0x21040
	v_add_u32_e32 v0, 0x7000, v185
	v_lshl_add_u64 v[8:9], v[2:3], 0, 64
	v_lshl_add_u64 v[2:3], v[2:3], 0, s[0:1]
	v_readfirstlane_b32 s0, v0
	v_add_u32_e32 v0, 0x8000, v185
	global_load_lds_dwordx4 v[8:9], off
	s_mov_b32 m0, s0
	v_readfirstlane_b32 s0, v0
	global_load_lds_dwordx4 v[2:3], off
	v_lshl_add_u64 v[2:3], v[6:7], 0, s[22:23]
	s_mov_b32 m0, s0
	s_mov_b64 s[0:1], 0x11000
	v_add_u32_e32 v0, 0x9000, v185
	global_load_lds_dwordx4 v[2:3], off
	v_lshl_add_u64 v[2:3], v[6:7], 0, s[0:1]
	v_readfirstlane_b32 s0, v0
	s_mov_b32 m0, s0
	s_mov_b64 s[0:1], 0x12000
	v_add_u32_e32 v0, 0xa000, v185
	global_load_lds_dwordx4 v[2:3], off
	v_lshl_add_u64 v[2:3], v[6:7], 0, s[0:1]
	v_readfirstlane_b32 s0, v0
	s_mov_b32 m0, s0
	s_mov_b64 s[0:1], 0x13000
	v_add_u32_e32 v0, 0xb000, v185
	global_load_lds_dwordx4 v[2:3], off
	v_lshl_add_u64 v[2:3], v[6:7], 0, s[0:1]
	v_readfirstlane_b32 s0, v0
	s_mov_b32 m0, s0
	v_and_b32_e32 v0, 15, v184
	global_load_lds_dwordx4 v[2:3], off
	v_lshlrev_b32_e32 v2, 2, v184
	v_and_b32_e32 v2, 48, v2
	v_ashrrev_i32_e32 v3, 1, v184
	v_sub_u32_e32 v2, 0, v2
	v_and_b32_e32 v187, 0xffffffc0, v3
	v_bitop3_b32 v2, v184, 48, v2 bitop3:0x48
	v_or_b32_e32 v3, v187, v0
	v_lshl_or_b32 v208, v3, 6, v2
	v_lshlrev_b32_e32 v3, 1, v184
	s_movk_i32 s0, 0x80
	v_and_or_b32 v186, v3, s0, v0
	s_sub_i32 s0, s8, s41
	s_sub_i32 s0, s0, s40
	v_lshl_or_b32 v0, v186, 6, v2
	v_lshl_add_u32 v2, s0, 7, v10
	v_add_u32_e32 v209, 0x2000, v0
	v_bitop3_b32 v0, v184, 3, v11 bitop3:0x48
	v_mad_i64_i32 v[182:183], s[0:1], v2, s28, v[130:131]
	v_mov_b32_e32 v2, 0
	s_mov_b32 s3, 0
	s_mov_b32 s42, 2
	v_lshlrev_b32_e32 v0, 4, v0
	v_lshl_add_u64 v[180:181], v[130:131], 0, v[4:5]
	s_mov_b32 s43, 0
	v_mov_b32_e32 v3, v2
	v_mov_b32_e32 v4, v2
	v_mov_b32_e32 v5, v2
	v_mov_b32_e32 v6, v2
	v_mov_b32_e32 v7, v2
	v_mov_b32_e32 v8, v2
; #define RAW_BARRIER() do { asm volatile("s_waitcnt lgkmcnt(0)" ::: "memory"); __builtin_amdgcn_s_barrier(); } while (0)
; template <int EPI, int NB>
; DEVI void gemm_tile(const GemmJob& J, int m0, int n0, unsigned char* smem) {
;     ...
;   f32x4 acc[4][NB];
; #pragma unroll
;   for (int i = 0; i < 4; ++i)
; #pragma unroll
;     for (int j = 0; j < NB; ++j) acc[i][j] = (f32x4){0.f, 0.f, 0.f, 0.f};
;   const int srow = tid >> 2, sch = tid & 3;
;   const int gch = sch ^ ((0 - (tid >> 4)) & 3);
;   const bf16_t* Ag = J.A + (size_t)(m0 + srow) * (J.ablk ? 32 : J.lda) + gch * 8;
;   const bf16_t* Bg = J.Bt + (size_t)(n0 + srow) * 32 + gch * 8;
;   const size_t Astep = (size_t)64 * (J.ablk ? 32 : J.lda), Ak = J.ablk ? (size_t)MROWS * 32 : (size_t)32, Bstep = (size_t)64 * 32, Bk = (size_t)J.NR * 32;
;   const int nk = J.K >> 5;
;   unsigned char* lds_t = smem + tid * 16;
;   const unsigned lbase = (unsigned)(uintptr_t)(__attribute__((address_space(3))) unsigned char*)smem;
;     ...
;   asm volatile("s_waitcnt vmcnt(0)" ::: "memory");
;   RAW_BARRIER();
; #pragma unroll
;   for (int st = 0; st < S - 1; ++st) GEMM_ISSUE(st, st);
;   const int fsl = (g ^ ((0 - (l16 >> 2)) & 3)) << 4;
;   const int aofs = (wm * 64 + l16) * 64 + fsl;
;   const int bofs = A_BYTES + (wn * NB * 16 + l16) * 64 + fsl;
;   int cs = 0, is = S - 1;
; #pragma clang loop unroll(disable)
;   for (int kt = 0; kt < nk; ++kt) {
;     if (nk - 1 - kt >= S - 2) {
;       if constexpr (NB == 8) asm volatile("s_waitcnt vmcnt(6)" ::: "memory");
;       else                   asm volatile("s_waitcnt vmcnt(8)" ::: "memory");
;     } else {
;       asm volatile("s_waitcnt vmcnt(0)" ::: "memory");
;     }
;     RAW_BARRIER();
;     if (kt + S - 1 < nk) GEMM_ISSUE(kt + S - 1, is);
	v_mov_b32_e32 v9, v2
	v_mov_b32_e32 v10, v2
	v_mov_b32_e32 v11, v2
	v_mov_b32_e32 v12, v2
	v_mov_b32_e32 v13, v2
	v_mov_b32_e32 v14, v2
	v_mov_b32_e32 v15, v2
	v_mov_b32_e32 v16, v2
	v_mov_b32_e32 v17, v2
	v_mov_b32_e32 v18, v2
	v_mov_b32_e32 v19, v2
	v_mov_b32_e32 v20, v2
	v_mov_b32_e32 v21, v2
	v_mov_b32_e32 v22, v2
	v_mov_b32_e32 v23, v2
	v_mov_b32_e32 v24, v2
	v_mov_b32_e32 v25, v2
	v_mov_b32_e32 v26, v2
	v_mov_b32_e32 v27, v2
	v_mov_b32_e32 v28, v2
	v_mov_b32_e32 v29, v2
	v_mov_b32_e32 v30, v2
	v_mov_b32_e32 v31, v2
	v_mov_b32_e32 v32, v2
	v_mov_b32_e32 v33, v2
	v_mov_b32_e32 v34, v2
	v_mov_b32_e32 v35, v2
	v_mov_b32_e32 v36, v2
	v_mov_b32_e32 v37, v2
	v_mov_b32_e32 v38, v2
	v_mov_b32_e32 v39, v2
	v_mov_b32_e32 v40, v2
	v_mov_b32_e32 v41, v2
	v_mov_b32_e32 v42, v2
	v_mov_b32_e32 v43, v2
	v_mov_b32_e32 v44, v2
	v_mov_b32_e32 v45, v2
	v_mov_b32_e32 v46, v2
	v_mov_b32_e32 v47, v2
	v_mov_b32_e32 v48, v2
	v_mov_b32_e32 v49, v2
	v_mov_b32_e32 v50, v2
	v_mov_b32_e32 v51, v2
	v_mov_b32_e32 v52, v2
	v_mov_b32_e32 v53, v2
	v_mov_b32_e32 v54, v2
	v_mov_b32_e32 v55, v2
	v_mov_b32_e32 v56, v2
	v_mov_b32_e32 v57, v2
	v_mov_b32_e32 v58, v2
	v_mov_b32_e32 v59, v2
	v_mov_b32_e32 v60, v2
	v_mov_b32_e32 v61, v2
	v_mov_b32_e32 v62, v2
	v_mov_b32_e32 v63, v2
	v_mov_b32_e32 v64, v2
	v_mov_b32_e32 v65, v2
	v_mov_b32_e32 v66, v2
	v_mov_b32_e32 v67, v2
	v_mov_b32_e32 v68, v2
	v_mov_b32_e32 v69, v2
	v_mov_b32_e32 v70, v2
	v_mov_b32_e32 v71, v2
	v_mov_b32_e32 v72, v2
	v_mov_b32_e32 v73, v2
	v_mov_b32_e32 v74, v2
	v_mov_b32_e32 v75, v2
	v_mov_b32_e32 v76, v2
	v_mov_b32_e32 v77, v2
	v_mov_b32_e32 v78, v2
	v_mov_b32_e32 v79, v2
	v_mov_b32_e32 v80, v2
	v_mov_b32_e32 v81, v2
	v_mov_b32_e32 v82, v2
	v_mov_b32_e32 v83, v2
	v_mov_b32_e32 v84, v2
	v_mov_b32_e32 v85, v2
	v_mov_b32_e32 v86, v2
	v_mov_b32_e32 v87, v2
	v_mov_b32_e32 v88, v2
	v_mov_b32_e32 v89, v2
	v_mov_b32_e32 v90, v2
	v_mov_b32_e32 v91, v2
	v_mov_b32_e32 v92, v2
	v_mov_b32_e32 v93, v2
	v_mov_b32_e32 v94, v2
	v_mov_b32_e32 v95, v2
	v_mov_b32_e32 v96, v2
	v_mov_b32_e32 v97, v2
	v_mov_b32_e32 v98, v2
	v_mov_b32_e32 v99, v2
	v_mov_b32_e32 v100, v2
	v_mov_b32_e32 v101, v2
	v_mov_b32_e32 v102, v2
	v_mov_b32_e32 v103, v2
	v_mov_b32_e32 v104, v2
	v_mov_b32_e32 v105, v2
	v_mov_b32_e32 v106, v2
	v_mov_b32_e32 v107, v2
	v_mov_b32_e32 v108, v2
	v_mov_b32_e32 v109, v2
	v_mov_b32_e32 v110, v2
	v_mov_b32_e32 v111, v2
	v_mov_b32_e32 v112, v2
	v_mov_b32_e32 v113, v2
	v_mov_b32_e32 v114, v2
	v_mov_b32_e32 v115, v2
	v_mov_b32_e32 v116, v2
	v_mov_b32_e32 v117, v2
	v_mov_b32_e32 v118, v2
	v_mov_b32_e32 v119, v2
	v_mov_b32_e32 v120, v2
	v_mov_b32_e32 v121, v2
	v_mov_b32_e32 v122, v2
	v_mov_b32_e32 v123, v2
	v_mov_b32_e32 v124, v2
	v_mov_b32_e32 v125, v2
	v_mov_b32_e32 v126, v2
	v_mov_b32_e32 v127, v2
	v_mov_b32_e32 v128, v2
	v_mov_b32_e32 v129, v2
	s_mul_i32 s0, s42, 0x6000
	v_add_u32_e32 v214, s0, v185
	v_lshl_add_u64 v[210:211], v[182:183], 0, v[0:1]
	s_mov_b64 s[0:1], 0xb286280
	v_lshl_add_u64 v[212:213], v[210:211], 0, s[0:1]
	v_readfirstlane_b32 s0, v214
	s_mov_b32 m0, s0
	s_mov_b64 s[0:1], 0xb2a7280
	s_nop 0
	v_readfirstlane_b32 s100, v212
	v_readfirstlane_b32 s101, v213
	s_nop 1
	v_subrev_u32_e32 v226, s100, v212
	v_add_u32_e32 v212, 0x1000, v214
	v_lshl_add_u64 v[210:211], v[210:211], 0, s[0:1]
	v_readfirstlane_b32 s0, v212
	s_mov_b32 m0, s0
	s_mov_b64 s[0:1], 0x4726000
	v_subrev_u32_e32 v227, s100, v210
	v_lshl_add_u64 v[210:211], v[180:181], 0, v[0:1]
	v_add_u32_e32 v215, 0x2000, v214
	v_lshl_add_u64 v[212:213], v[210:211], 0, s[0:1]
	v_readfirstlane_b32 s0, v215
	s_mov_b32 m0, s0
	s_mov_b64 s[0:1], 0x4727000
	v_add_u32_e32 v215, 0x3000, v214
	s_nop 0
	v_readfirstlane_b32 vcc_lo, v212
	v_readfirstlane_b32 vcc_hi, v213
	s_nop 1
	v_subrev_u32_e32 v228, vcc_lo, v212
	v_lshl_add_u64 v[212:213], v[210:211], 0, s[0:1]
	v_readfirstlane_b32 s0, v215
	s_mov_b32 m0, s0
	s_mov_b64 s[0:1], 0x4728000
	v_add_u32_e32 v215, 0x4000, v214
	v_subrev_u32_e32 v229, vcc_lo, v212
	v_lshl_add_u64 v[212:213], v[210:211], 0, s[0:1]
	v_readfirstlane_b32 s0, v215
	s_mov_b32 m0, s0
	s_mov_b64 s[0:1], 0x4729000
	v_subrev_u32_e32 v230, vcc_lo, v212
	v_add_u32_e32 v212, 0x5000, v214
	v_lshl_add_u64 v[210:211], v[210:211], 0, s[0:1]
	v_readfirstlane_b32 s0, v212
	s_mov_b32 m0, s0
	s_nop 0
	v_subrev_u32_e32 v231, vcc_lo, v210
	v_mov_b32_e32 v182, v226
	v_mov_b32_e32 v183, v227
	v_mov_b32_e32 v180, v228
	v_mov_b32_e32 v181, v229
	v_mov_b32_e32 v253, v230
	v_mov_b32_e32 v254, v231
	v_readfirstlane_b32 s0, v185
	s_branch .LBB0_2117
	.p2align	6

; #define RAW_BARRIER() do { asm volatile("s_waitcnt lgkmcnt(0)" ::: "memory"); __builtin_amdgcn_s_barrier(); } while (0)
; template <int EPI, int NB>
; DEVI void gemm_tile(const GemmJob& J, int m0, int n0, unsigned char* smem) {
;     ...
;   const int srow = tid >> 2, sch = tid & 3;
;   const int gch = sch ^ ((0 - (tid >> 4)) & 3);
;   const bf16_t* Ag = J.A + (size_t)(m0 + srow) * (J.ablk ? 32 : J.lda) + gch * 8;
;   const bf16_t* Bg = J.Bt + (size_t)(n0 + srow) * 32 + gch * 8;
;   const size_t Astep = (size_t)64 * (J.ablk ? 32 : J.lda), Ak = J.ablk ? (size_t)MROWS * 32 : (size_t)32, Bstep = (size_t)64 * 32, Bk = (size_t)J.NR * 32;
;   const int nk = J.K >> 5;
;   unsigned char* lds_t = smem + tid * 16;
;   const unsigned lbase = (unsigned)(uintptr_t)(__attribute__((address_space(3))) unsigned char*)smem;
;     ...
;   asm volatile("s_waitcnt vmcnt(0)" ::: "memory");
;   RAW_BARRIER();
; #pragma unroll
;   for (int st = 0; st < S - 1; ++st) GEMM_ISSUE(st, st);
; template <int EPI, int NB>
; DEVI void gemm_run(const GemmJob& J, unsigned char* smem, int rot) {
;     ...
;     for (int t = b; t < ntiles; t += G) {
;       const int mt = t / J.ntn, nt = J.nt0 + (t - mt * J.ntn);
;       gemm_tile<EPI, NB>(J, mt * 128, nt * BN, smem);
.LBB0_2396:
	s_ashr_i32 s0, s9, 31
	s_lshr_b32 s0, s0, 30
	s_add_i32 s0, s9, s0
	s_ashr_i32 s0, s0, 2
	s_lshl_b32 s3, s0, 7
	s_lshl_b32 s0, s0, 10
	s_lshl_b32 s1, s9, 8
	v_mov_b32_e32 v184, v177
	s_sub_i32 s2, s1, s0
	s_nop 0
	s_mov_b64 s[28:29], 0x1000
	v_ashrrev_i32_e32 v10, 2, v184
	v_lshrrev_b32_e32 v0, 4, v184
	v_sub_u32_e32 v11, 0, v0
	v_add_u32_e32 v2, s3, v10
	v_add_u32_e32 v6, s2, v10
	v_xor_b32_e32 v0, v184, v11
	v_ashrrev_i32_e32 v3, 31, v2
	v_ashrrev_i32_e32 v7, 31, v6
	v_lshlrev_b64 v[2:3], 6, v[2:3]
	v_lshlrev_b32_e32 v0, 4, v0
	v_lshlrev_b64 v[6:7], 6, v[6:7]
	v_lshl_add_u64 v[4:5], v[146:147], 0, v[2:3]
	v_and_b32_e32 v0, 48, v0
	v_lshl_add_u64 v[6:7], v[140:141], 0, v[6:7]
	v_lshlrev_b32_e32 v185, 4, v184
	v_lshl_add_u64 v[4:5], v[4:5], 0, v[0:1]
	v_lshl_add_u64 v[6:7], v[6:7], 0, v[0:1]
	v_readfirstlane_b32 s1, v185
	v_add_u32_e32 v0, 0x1000, v185
	s_mov_b32 m0, s1
	v_readfirstlane_b32 s1, v0
	v_add_u32_e32 v0, 0x2000, v185
	s_waitcnt lgkmcnt(0)
	s_barrier
	global_load_lds_dwordx4 v[4:5], off
	v_lshl_add_u64 v[8:9], v[4:5], 0, s[28:29]
	s_mov_b32 m0, s1
	v_readfirstlane_b32 s1, v0
	v_add_u32_e32 v0, 0x3000, v185
	global_load_lds_dwordx4 v[8:9], off
	s_mov_b32 m0, s1
	v_readfirstlane_b32 s1, v0
	v_add_u32_e32 v0, 0x4000, v185
	global_load_lds_dwordx4 v[6:7], off
	v_lshl_add_u64 v[8:9], v[6:7], 0, s[28:29]
	s_mov_b32 m0, s1
	s_mov_b64 s[28:29], 0x2000
	v_readfirstlane_b32 s1, v0
	v_add_u32_e32 v0, 0x5000, v185
	global_load_lds_dwordx4 v[8:9], off
	v_lshl_add_u64 v[8:9], v[6:7], 0, s[28:29]
	s_mov_b32 m0, s1
	s_mov_b64 s[28:29], 0x3000
	v_readfirstlane_b32 s1, v0
	v_add_u32_e32 v0, 0x6000, v185
	global_load_lds_dwordx4 v[8:9], off
	v_lshl_add_u64 v[8:9], v[6:7], 0, s[28:29]
	s_mov_b32 m0, s1
	v_readfirstlane_b32 s1, v0
	v_add_u32_e32 v0, 0x7000, v185
	global_load_lds_dwordx4 v[8:9], off
	v_lshl_add_u64 v[8:9], v[4:5], 0, s[94:95]
	s_mov_b32 m0, s1
	s_mov_b64 s[28:29], 0x30b000
	v_readfirstlane_b32 s1, v0
	v_add_u32_e32 v0, 0x8000, v185
	global_load_lds_dwordx4 v[8:9], off
	v_lshl_add_u64 v[4:5], v[4:5], 0, s[28:29]
	s_mov_b32 m0, s1
	v_readfirstlane_b32 s1, v0
	v_add_u32_e32 v0, 0x9000, v185
	global_load_lds_dwordx4 v[4:5], off
	v_lshl_add_u64 v[4:5], v[6:7], 0, s[22:23]
	s_mov_b32 m0, s1
	s_mov_b64 s[28:29], 0x11000
	v_readfirstlane_b32 s1, v0
	v_add_u32_e32 v0, 0xa000, v185
	global_load_lds_dwordx4 v[4:5], off
	v_lshl_add_u64 v[4:5], v[6:7], 0, s[28:29]
	s_mov_b32 m0, s1
	s_mov_b64 s[28:29], 0x12000
	v_readfirstlane_b32 s1, v0
	v_add_u32_e32 v0, 0xb000, v185
	global_load_lds_dwordx4 v[4:5], off
	v_lshl_add_u64 v[4:5], v[6:7], 0, s[28:29]
	s_mov_b32 m0, s1
	s_mov_b64 s[28:29], 0x13000
	v_readfirstlane_b32 s1, v0
	global_load_lds_dwordx4 v[4:5], off
	v_lshl_add_u64 v[4:5], v[6:7], 0, s[28:29]
	s_mov_b32 m0, s1
	v_lshlrev_b32_e32 v0, 2, v184
	global_load_lds_dwordx4 v[4:5], off
	v_and_b32_e32 v0, 48, v0
	v_ashrrev_i32_e32 v4, 1, v184
	v_and_b32_e32 v186, 15, v184
	v_sub_u32_e32 v0, 0, v0
	v_and_b32_e32 v187, 0xffffffc0, v4
	v_bitop3_b32 v0, v184, 48, v0 bitop3:0x48
	v_or_b32_e32 v4, v187, v186
	v_lshl_or_b32 v209, v4, 6, v0
	v_lshlrev_b32_e32 v4, 1, v184
	v_and_b32_e32 v208, 0x80, v4
	v_or_b32_e32 v4, v208, v186
	v_lshl_or_b32 v0, v4, 6, v0
	v_add_u32_e32 v4, s8, v10
	v_subrev_u32_e32 v4, s0, v4
	v_ashrrev_i32_e32 v5, 31, v4
	v_add_u32_e32 v210, 0x2000, v0
	v_bitop3_b32 v0, v184, 3, v11 bitop3:0x48
	v_lshlrev_b64 v[4:5], 6, v[4:5]
	v_lshl_add_u64 v[182:183], v[130:131], 0, v[2:3]
	v_mov_b32_e32 v2, 0
	s_mov_b32 s42, 2
	s_mov_b32 s20, 0
	s_mov_b64 s[30:31], 0x1000
	v_lshlrev_b32_e32 v0, 4, v0
	v_lshl_add_u64 v[180:181], v[130:131], 0, v[4:5]
	s_mov_b32 s43, 0
	v_mov_b32_e32 v3, v2
	v_mov_b32_e32 v4, v2
	v_mov_b32_e32 v5, v2
	v_mov_b32_e32 v6, v2
	v_mov_b32_e32 v7, v2
	v_mov_b32_e32 v8, v2
	v_mov_b32_e32 v9, v2
	v_mov_b32_e32 v10, v2
	v_mov_b32_e32 v11, v2
	v_mov_b32_e32 v12, v2
	v_mov_b32_e32 v13, v2
	v_mov_b32_e32 v14, v2
	v_mov_b32_e32 v15, v2
	v_mov_b32_e32 v16, v2
	v_mov_b32_e32 v17, v2
	v_mov_b32_e32 v18, v2
	v_mov_b32_e32 v19, v2
	v_mov_b32_e32 v20, v2
	v_mov_b32_e32 v21, v2
	v_mov_b32_e32 v22, v2
	v_mov_b32_e32 v23, v2
; #define RAW_BARRIER() do { asm volatile("s_waitcnt lgkmcnt(0)" ::: "memory"); __builtin_amdgcn_s_barrier(); } while (0)
; template <int EPI, int NB>
; DEVI void gemm_tile(const GemmJob& J, int m0, int n0, unsigned char* smem) {
;     ...
;   f32x4 acc[4][NB];
; #pragma unroll
;   for (int i = 0; i < 4; ++i)
; #pragma unroll
;     for (int j = 0; j < NB; ++j) acc[i][j] = (f32x4){0.f, 0.f, 0.f, 0.f};
;   const int srow = tid >> 2, sch = tid & 3;
;   const int gch = sch ^ ((0 - (tid >> 4)) & 3);
;   const bf16_t* Ag = J.A + (size_t)(m0 + srow) * (J.ablk ? 32 : J.lda) + gch * 8;
;   const bf16_t* Bg = J.Bt + (size_t)(n0 + srow) * 32 + gch * 8;
;   const size_t Astep = (size_t)64 * (J.ablk ? 32 : J.lda), Ak = J.ablk ? (size_t)MROWS * 32 : (size_t)32, Bstep = (size_t)64 * 32, Bk = (size_t)J.NR * 32;
;   const int nk = J.K >> 5;
;   unsigned char* lds_t = smem + tid * 16;
;   const unsigned lbase = (unsigned)(uintptr_t)(__attribute__((address_space(3))) unsigned char*)smem;
;     ...
;   asm volatile("s_waitcnt vmcnt(0)" ::: "memory");
;   RAW_BARRIER();
; #pragma unroll
;   for (int st = 0; st < S - 1; ++st) GEMM_ISSUE(st, st);
;   const int fsl = (g ^ ((0 - (l16 >> 2)) & 3)) << 4;
;   const int aofs = (wm * 64 + l16) * 64 + fsl;
;   const int bofs = A_BYTES + (wn * NB * 16 + l16) * 64 + fsl;
;   int cs = 0, is = S - 1;
; #pragma clang loop unroll(disable)
;   for (int kt = 0; kt < nk; ++kt) {
;     if (nk - 1 - kt >= S - 2) {
;       if constexpr (NB == 8) asm volatile("s_waitcnt vmcnt(6)" ::: "memory");
;       else                   asm volatile("s_waitcnt vmcnt(8)" ::: "memory");
;     } else {
;       asm volatile("s_waitcnt vmcnt(0)" ::: "memory");
;     }
;     RAW_BARRIER();
;     if (kt + S - 1 < nk) GEMM_ISSUE(kt + S - 1, is);
	v_mov_b32_e32 v24, v2
	v_mov_b32_e32 v25, v2
	v_mov_b32_e32 v26, v2
	v_mov_b32_e32 v27, v2
	v_mov_b32_e32 v28, v2
	v_mov_b32_e32 v29, v2
	v_mov_b32_e32 v30, v2
	v_mov_b32_e32 v31, v2
	v_mov_b32_e32 v32, v2
	v_mov_b32_e32 v33, v2
	v_mov_b32_e32 v34, v2
	v_mov_b32_e32 v35, v2
	v_mov_b32_e32 v36, v2
	v_mov_b32_e32 v37, v2
	v_mov_b32_e32 v38, v2
	v_mov_b32_e32 v39, v2
	v_mov_b32_e32 v40, v2
	v_mov_b32_e32 v41, v2
	v_mov_b32_e32 v42, v2
	v_mov_b32_e32 v43, v2
	v_mov_b32_e32 v44, v2
	v_mov_b32_e32 v45, v2
	v_mov_b32_e32 v46, v2
	v_mov_b32_e32 v47, v2
	v_mov_b32_e32 v48, v2
	v_mov_b32_e32 v49, v2
	v_mov_b32_e32 v50, v2
	v_mov_b32_e32 v51, v2
	v_mov_b32_e32 v52, v2
	v_mov_b32_e32 v53, v2
	v_mov_b32_e32 v54, v2
	v_mov_b32_e32 v55, v2
	v_mov_b32_e32 v56, v2
	v_mov_b32_e32 v57, v2
	v_mov_b32_e32 v58, v2
	v_mov_b32_e32 v59, v2
	v_mov_b32_e32 v60, v2
	v_mov_b32_e32 v61, v2
	v_mov_b32_e32 v62, v2
	v_mov_b32_e32 v63, v2
	v_mov_b32_e32 v64, v2
	v_mov_b32_e32 v65, v2
	v_mov_b32_e32 v66, v2
	v_mov_b32_e32 v67, v2
	v_mov_b32_e32 v68, v2
	v_mov_b32_e32 v69, v2
	v_mov_b32_e32 v70, v2
	v_mov_b32_e32 v71, v2
	v_mov_b32_e32 v72, v2
	v_mov_b32_e32 v73, v2
	v_mov_b32_e32 v74, v2
	v_mov_b32_e32 v75, v2
	v_mov_b32_e32 v76, v2
	v_mov_b32_e32 v77, v2
	v_mov_b32_e32 v78, v2
	v_mov_b32_e32 v79, v2
	v_mov_b32_e32 v80, v2
	v_mov_b32_e32 v81, v2
	v_mov_b32_e32 v82, v2
	v_mov_b32_e32 v83, v2
	v_mov_b32_e32 v84, v2
	v_mov_b32_e32 v85, v2
	v_mov_b32_e32 v86, v2
	v_mov_b32_e32 v87, v2
	v_mov_b32_e32 v88, v2
	v_mov_b32_e32 v89, v2
	v_mov_b32_e32 v90, v2
	v_mov_b32_e32 v91, v2
	v_mov_b32_e32 v92, v2
	v_mov_b32_e32 v93, v2
	v_mov_b32_e32 v94, v2
	v_mov_b32_e32 v95, v2
	v_mov_b32_e32 v96, v2
	v_mov_b32_e32 v97, v2
	v_mov_b32_e32 v98, v2
	v_mov_b32_e32 v99, v2
	v_mov_b32_e32 v100, v2
	v_mov_b32_e32 v101, v2
	v_mov_b32_e32 v102, v2
	v_mov_b32_e32 v103, v2
	v_mov_b32_e32 v104, v2
	v_mov_b32_e32 v105, v2
	v_mov_b32_e32 v106, v2
	v_mov_b32_e32 v107, v2
	v_mov_b32_e32 v108, v2
	v_mov_b32_e32 v109, v2
	v_mov_b32_e32 v110, v2
	v_mov_b32_e32 v111, v2
	v_mov_b32_e32 v112, v2
	v_mov_b32_e32 v113, v2
	v_mov_b32_e32 v114, v2
	v_mov_b32_e32 v115, v2
	v_mov_b32_e32 v116, v2
	v_mov_b32_e32 v117, v2
	v_mov_b32_e32 v118, v2
	v_mov_b32_e32 v119, v2
	v_mov_b32_e32 v120, v2
	v_mov_b32_e32 v121, v2
	v_mov_b32_e32 v122, v2
	v_mov_b32_e32 v123, v2
	v_mov_b32_e32 v124, v2
	v_mov_b32_e32 v125, v2
	v_mov_b32_e32 v126, v2
	v_mov_b32_e32 v127, v2
	v_mov_b32_e32 v128, v2
	v_mov_b32_e32 v129, v2
	s_mul_i32 s0, s42, 0x6000
	v_add_u32_e32 v211, s0, v185
	v_lshl_add_u64 v[212:213], v[182:183], 0, v[0:1]
	v_readfirstlane_b32 s0, v211
	v_lshl_add_u64 v[214:215], v[212:213], 0, s[84:85]
	s_mov_b32 m0, s0
	v_lshl_add_u64 v[212:213], v[212:213], 0, s[12:13]
	s_nop 0
	v_readfirstlane_b32 s100, v214
	v_readfirstlane_b32 s101, v215
	s_nop 1
	v_subrev_u32_e32 v228, s100, v214
	v_add_u32_e32 v214, 0x1000, v211
	v_add_u32_e32 v216, 0x2000, v211
	v_readfirstlane_b32 s0, v214
	s_mov_b32 m0, s0
	s_mov_b64 s[0:1], 0x4766000
	v_subrev_u32_e32 v229, s100, v212
	v_lshl_add_u64 v[212:213], v[180:181], 0, v[0:1]
	v_lshl_add_u64 v[214:215], v[212:213], 0, s[0:1]
	v_readfirstlane_b32 s0, v216
	s_mov_b32 m0, s0
	s_mov_b64 s[0:1], 0x4767000
	v_add_u32_e32 v216, 0x3000, v211
	s_nop 0
	v_readfirstlane_b32 vcc_lo, v214
	v_readfirstlane_b32 vcc_hi, v215
	s_nop 1
	v_subrev_u32_e32 v230, vcc_lo, v214
	v_lshl_add_u64 v[214:215], v[212:213], 0, s[0:1]
	v_readfirstlane_b32 s0, v216
	s_mov_b32 m0, s0
	s_mov_b64 s[0:1], 0x4768000
	v_add_u32_e32 v216, 0x4000, v211
	v_subrev_u32_e32 v231, vcc_lo, v214
	v_lshl_add_u64 v[214:215], v[212:213], 0, s[0:1]
	v_readfirstlane_b32 s0, v216
	s_mov_b32 m0, s0
	s_mov_b64 s[0:1], 0x4769000
	v_add_u32_e32 v211, 0x5000, v211
	v_lshl_add_u64 v[212:213], v[212:213], 0, s[0:1]
	v_readfirstlane_b32 s0, v211
	v_subrev_u32_e32 v232, vcc_lo, v214
	s_mov_b32 m0, s0
	s_nop 0
	v_subrev_u32_e32 v233, vcc_lo, v212
	v_mov_b32_e32 v182, v228
	v_mov_b32_e32 v183, v229
	v_mov_b32_e32 v180, v230
	v_mov_b32_e32 v181, v231
	v_mov_b32_e32 v253, v232
	v_mov_b32_e32 v254, v233
	v_readfirstlane_b32 s0, v185
	s_branch .LBB0_2398
	.p2align	6

; #define RAW_BARRIER() do { asm volatile("s_waitcnt lgkmcnt(0)" ::: "memory"); __builtin_amdgcn_s_barrier(); } while (0)
; template <int EPI, int NB>
; DEVI void gemm_tile(const GemmJob& J, int m0, int n0, unsigned char* smem) {
;     ...
;   const int srow = tid >> 2, sch = tid & 3;
;   const int gch = sch ^ ((0 - (tid >> 4)) & 3);
;   const bf16_t* Ag = J.A + (size_t)(m0 + srow) * (J.ablk ? 32 : J.lda) + gch * 8;
;   const bf16_t* Bg = J.Bt + (size_t)(n0 + srow) * 32 + gch * 8;
;   const size_t Astep = (size_t)64 * (J.ablk ? 32 : J.lda), Ak = J.ablk ? (size_t)MROWS * 32 : (size_t)32, Bstep = (size_t)64 * 32, Bk = (size_t)J.NR * 32;
;   const int nk = J.K >> 5;
;   unsigned char* lds_t = smem + tid * 16;
;   const unsigned lbase = (unsigned)(uintptr_t)(__attribute__((address_space(3))) unsigned char*)smem;
;     ...
;   asm volatile("s_waitcnt vmcnt(0)" ::: "memory");
;   RAW_BARRIER();
; #pragma unroll
;   for (int st = 0; st < S - 1; ++st) GEMM_ISSUE(st, st);
; template <int EPI, int NB>
; DEVI void gemm_run(const GemmJob& J, unsigned char* smem, int rot) {
;     ...
;     const int x = b & 7, lb = b >> 3, nlb = G >> 3;
;     const int mlo = x * 49;
;     const int mcnt = min(49, MT128 - mlo);
;     const int ntot = mcnt * J.ntn, gsz = 8 * J.ntn;
;     const int ngrp = (mcnt + 7) >> 3;
;     for (int q0 = lb; q0 < ntot; q0 += nlb) {
;       const int q = J.rev ? ntot - 1 - q0 : q0;
;       int grp = q / gsz; const int qq = q - grp * gsz;
;       const int mg = min(8, mcnt - grp * 8);
;       const int nt = qq / mg, mi = qq - nt * mg;
;       gemm_tile<EPI, NB>(J, (mlo + grp * 8 + mi) * 128, (J.nt0 + nt) * BN, smem);
.LBB0_2474:
	s_ashr_i32 s0, s9, 31
	s_lshr_b32 s0, s0, 27
	s_add_i32 s0, s9, s0
	s_ashr_i32 s1, s0, 5
	s_lshl_b32 s3, s1, 3
	v_readlane_b32 s2, v251, 48
	s_sub_i32 s2, s2, s3
	s_min_i32 s20, s2, 8
	s_abs_i32 s40, s20
	v_cvt_f32_u32_e32 v0, s40
	s_sub_i32 s43, 0, s40
	s_andn2_b32 s0, s0, 31
	s_sub_i32 s0, s9, s0
	v_rcp_iflag_f32_e32 v0, v0
	s_abs_i32 s41, s0
	s_xor_b32 s42, s0, s20
	s_ashr_i32 s42, s42, 31
	v_mul_f32_e32 v0, 0x4f7ffffe, v0
	v_cvt_u32_f32_e32 v0, v0
	v_mov_b32_e32 v184, v177
	s_nop 0
	v_readfirstlane_b32 s44, v0
	s_mul_i32 s43, s43, s44
	s_mul_hi_u32 s43, s44, s43
	s_add_i32 s44, s44, s43
	s_mul_hi_u32 s43, s41, s44
	s_mul_i32 s44, s43, s40
	s_sub_i32 s41, s41, s44
	s_add_i32 s45, s43, 1
	s_sub_i32 s44, s41, s40
	s_cmp_ge_u32 s41, s40
	s_cselect_b32 s43, s45, s43
	s_cselect_b32 s41, s44, s41
	s_add_i32 s44, s43, 1
	s_cmp_ge_u32 s41, s40
	s_cselect_b32 s40, s44, s43
	s_xor_b32 s40, s40, s42
	s_sub_i32 s40, s40, s42
	s_mul_i32 s41, s20, s40
	v_readlane_b32 s20, v250, 37
	s_add_i32 s3, s3, s20
	s_add_i32 s3, s3, s0
	s_sub_i32 s0, s3, s41
	s_lshl_b32 s20, s0, 7
	s_lshl_b32 s3, s40, 8
	v_ashrrev_i32_e32 v10, 2, v184
	v_lshrrev_b32_e32 v0, 4, v184
	v_sub_u32_e32 v11, 0, v0
	v_add_u32_e32 v2, s20, v10
	v_add_u32_e32 v4, s3, v10
	v_xor_b32_e32 v0, v184, v11
	v_ashrrev_i32_e32 v3, 31, v2
	v_ashrrev_i32_e32 v5, 31, v4
	v_lshlrev_b64 v[2:3], 6, v[2:3]
	v_lshlrev_b32_e32 v0, 4, v0
	v_lshlrev_b64 v[4:5], 6, v[4:5]
	v_lshl_add_u64 v[2:3], v[146:147], 0, v[2:3]
	v_and_b32_e32 v0, 48, v0
	v_lshl_add_u64 v[6:7], v[140:141], 0, v[4:5]
	v_lshlrev_b32_e32 v185, 4, v184
	v_lshl_add_u64 v[2:3], v[2:3], 0, v[0:1]
	v_lshl_add_u64 v[6:7], v[6:7], 0, v[0:1]
	v_readfirstlane_b32 s0, v185
	v_add_u32_e32 v0, 0x1000, v185
	s_mov_b32 m0, s0
	s_mov_b64 s[28:29], 0x1000
	v_readfirstlane_b32 s0, v0
	v_add_u32_e32 v0, 0x2000, v185
	s_waitcnt lgkmcnt(0)
	s_barrier
	global_load_lds_dwordx4 v[2:3], off
	v_lshl_add_u64 v[8:9], v[2:3], 0, s[28:29]
	s_mov_b32 m0, s0
	v_readfirstlane_b32 s0, v0
	v_add_u32_e32 v0, 0x3000, v185
	global_load_lds_dwordx4 v[8:9], off
	s_mov_b32 m0, s0
	v_readfirstlane_b32 s0, v0
	v_add_u32_e32 v0, 0x4000, v185
	global_load_lds_dwordx4 v[6:7], off
	v_lshl_add_u64 v[8:9], v[6:7], 0, s[28:29]
	s_mov_b32 m0, s0
	s_mov_b64 s[28:29], 0x2000
	v_readfirstlane_b32 s0, v0
	v_add_u32_e32 v0, 0x5000, v185
	global_load_lds_dwordx4 v[8:9], off
	v_lshl_add_u64 v[8:9], v[6:7], 0, s[28:29]
	s_mov_b32 m0, s0
	s_mov_b64 s[28:29], 0x3000
	v_readfirstlane_b32 s0, v0
	v_add_u32_e32 v0, 0x6000, v185
	global_load_lds_dwordx4 v[8:9], off
	v_lshl_add_u64 v[8:9], v[6:7], 0, s[28:29]
	s_mov_b32 m0, s0
	v_readfirstlane_b32 s0, v0
	v_add_u32_e32 v0, 0x7000, v185
	global_load_lds_dwordx4 v[8:9], off
	v_lshl_add_u64 v[8:9], v[2:3], 0, s[94:95]
	s_mov_b32 m0, s0
	s_mov_b64 s[28:29], 0x30b000
	v_readfirstlane_b32 s0, v0
	v_add_u32_e32 v0, 0x8000, v185
	global_load_lds_dwordx4 v[8:9], off
	v_lshl_add_u64 v[2:3], v[2:3], 0, s[28:29]
	s_mov_b32 m0, s0
	v_readfirstlane_b32 s0, v0
	v_add_u32_e32 v0, 0x9000, v185
	global_load_lds_dwordx4 v[2:3], off
	v_lshl_add_u64 v[2:3], v[6:7], 0, s[22:23]
	s_mov_b32 m0, s0
	s_mov_b64 s[28:29], 0x11000
	v_readfirstlane_b32 s0, v0
	v_add_u32_e32 v0, 0xa000, v185
	global_load_lds_dwordx4 v[2:3], off
	v_lshl_add_u64 v[2:3], v[6:7], 0, s[28:29]
	s_mov_b32 m0, s0
	s_mov_b64 s[28:29], 0x12000
	v_readfirstlane_b32 s0, v0
	v_add_u32_e32 v0, 0xb000, v185
	global_load_lds_dwordx4 v[2:3], off
	v_lshl_add_u64 v[2:3], v[6:7], 0, s[28:29]
	s_mov_b32 m0, s0
	s_mov_b64 s[28:29], 0x13000
	v_readfirstlane_b32 s0, v0
	global_load_lds_dwordx4 v[2:3], off
	v_lshl_add_u64 v[2:3], v[6:7], 0, s[28:29]
	s_mov_b32 m0, s0
	v_lshlrev_b32_e32 v0, 2, v184
	global_load_lds_dwordx4 v[2:3], off
	v_and_b32_e32 v0, 48, v0
	v_ashrrev_i32_e32 v2, 1, v184
	v_and_b32_e32 v186, 15, v184
	v_sub_u32_e32 v0, 0, v0
	v_and_b32_e32 v187, 0xffffffc0, v2
	v_bitop3_b32 v0, v184, 48, v0 bitop3:0x48
	v_or_b32_e32 v2, v187, v186
	v_lshl_or_b32 v209, v2, 6, v0
	v_lshlrev_b32_e32 v2, 1, v184
	v_and_b32_e32 v208, 0x80, v2
	s_sub_i32 s0, s8, s41
	s_mul_i32 s1, s1, 24
	v_or_b32_e32 v2, v208, v186
	s_sub_i32 s0, s0, s1
	v_lshl_or_b32 v0, v2, 6, v0
	v_lshl_add_u32 v2, s0, 7, v10
	v_ashrrev_i32_e32 v3, 31, v2
	v_lshlrev_b64 v[2:3], 6, v[2:3]
	v_add_u32_e32 v210, 0x2000, v0
	v_bitop3_b32 v0, v184, 3, v11 bitop3:0x48
	v_lshl_add_u64 v[182:183], v[130:131], 0, v[2:3]
	v_mov_b32_e32 v2, 0
	s_mov_b32 s2, 0
	s_mov_b32 s42, 2
	s_mov_b64 s[30:31], 0x1000
	v_lshlrev_b32_e32 v0, 4, v0
	v_lshl_add_u64 v[180:181], v[130:131], 0, v[4:5]
	s_mov_b32 s43, 0
	v_mov_b32_e32 v3, v2
; #define RAW_BARRIER() do { asm volatile("s_waitcnt lgkmcnt(0)" ::: "memory"); __builtin_amdgcn_s_barrier(); } while (0)
; template <int EPI, int NB>
; DEVI void gemm_tile(const GemmJob& J, int m0, int n0, unsigned char* smem) {
;     ...
;   f32x4 acc[4][NB];
; #pragma unroll
;   for (int i = 0; i < 4; ++i)
; #pragma unroll
;     for (int j = 0; j < NB; ++j) acc[i][j] = (f32x4){0.f, 0.f, 0.f, 0.f};
;   const int srow = tid >> 2, sch = tid & 3;
;   const int gch = sch ^ ((0 - (tid >> 4)) & 3);
;   const bf16_t* Ag = J.A + (size_t)(m0 + srow) * (J.ablk ? 32 : J.lda) + gch * 8;
;   const bf16_t* Bg = J.Bt + (size_t)(n0 + srow) * 32 + gch * 8;
;   const size_t Astep = (size_t)64 * (J.ablk ? 32 : J.lda), Ak = J.ablk ? (size_t)MROWS * 32 : (size_t)32, Bstep = (size_t)64 * 32, Bk = (size_t)J.NR * 32;
;   const int nk = J.K >> 5;
;   unsigned char* lds_t = smem + tid * 16;
;   const unsigned lbase = (unsigned)(uintptr_t)(__attribute__((address_space(3))) unsigned char*)smem;
;     ...
;   asm volatile("s_waitcnt vmcnt(0)" ::: "memory");
;   RAW_BARRIER();
; #pragma unroll
;   for (int st = 0; st < S - 1; ++st) GEMM_ISSUE(st, st);
;   const int fsl = (g ^ ((0 - (l16 >> 2)) & 3)) << 4;
;   const int aofs = (wm * 64 + l16) * 64 + fsl;
;   const int bofs = A_BYTES + (wn * NB * 16 + l16) * 64 + fsl;
;   int cs = 0, is = S - 1;
; #pragma clang loop unroll(disable)
;   for (int kt = 0; kt < nk; ++kt) {
;     if (nk - 1 - kt >= S - 2) {
;       if constexpr (NB == 8) asm volatile("s_waitcnt vmcnt(6)" ::: "memory");
;       else                   asm volatile("s_waitcnt vmcnt(8)" ::: "memory");
;     } else {
;       asm volatile("s_waitcnt vmcnt(0)" ::: "memory");
;     }
;     RAW_BARRIER();
;     if (kt + S - 1 < nk) GEMM_ISSUE(kt + S - 1, is);
	v_mov_b32_e32 v4, v2
	v_mov_b32_e32 v5, v2
	v_mov_b32_e32 v6, v2
	v_mov_b32_e32 v7, v2
	v_mov_b32_e32 v8, v2
	v_mov_b32_e32 v9, v2
	v_mov_b32_e32 v10, v2
	v_mov_b32_e32 v11, v2
	v_mov_b32_e32 v12, v2
	v_mov_b32_e32 v13, v2
	v_mov_b32_e32 v14, v2
	v_mov_b32_e32 v15, v2
	v_mov_b32_e32 v16, v2
	v_mov_b32_e32 v17, v2
	v_mov_b32_e32 v18, v2
	v_mov_b32_e32 v19, v2
	v_mov_b32_e32 v20, v2
	v_mov_b32_e32 v21, v2
	v_mov_b32_e32 v22, v2
	v_mov_b32_e32 v23, v2
	v_mov_b32_e32 v24, v2
	v_mov_b32_e32 v25, v2
	v_mov_b32_e32 v26, v2
	v_mov_b32_e32 v27, v2
	v_mov_b32_e32 v28, v2
	v_mov_b32_e32 v29, v2
	v_mov_b32_e32 v30, v2
	v_mov_b32_e32 v31, v2
	v_mov_b32_e32 v32, v2
	v_mov_b32_e32 v33, v2
	v_mov_b32_e32 v34, v2
	v_mov_b32_e32 v35, v2
	v_mov_b32_e32 v36, v2
	v_mov_b32_e32 v37, v2
	v_mov_b32_e32 v38, v2
	v_mov_b32_e32 v39, v2
	v_mov_b32_e32 v40, v2
	v_mov_b32_e32 v41, v2
	v_mov_b32_e32 v42, v2
	v_mov_b32_e32 v43, v2
	v_mov_b32_e32 v44, v2
	v_mov_b32_e32 v45, v2
	v_mov_b32_e32 v46, v2
	v_mov_b32_e32 v47, v2
	v_mov_b32_e32 v48, v2
	v_mov_b32_e32 v49, v2
	v_mov_b32_e32 v50, v2
	v_mov_b32_e32 v51, v2
	v_mov_b32_e32 v52, v2
	v_mov_b32_e32 v53, v2
	v_mov_b32_e32 v54, v2
	v_mov_b32_e32 v55, v2
	v_mov_b32_e32 v56, v2
	v_mov_b32_e32 v57, v2
	v_mov_b32_e32 v58, v2
	v_mov_b32_e32 v59, v2
	v_mov_b32_e32 v60, v2
	v_mov_b32_e32 v61, v2
	v_mov_b32_e32 v62, v2
	v_mov_b32_e32 v63, v2
	v_mov_b32_e32 v64, v2
	v_mov_b32_e32 v65, v2
	v_mov_b32_e32 v66, v2
	v_mov_b32_e32 v67, v2
	v_mov_b32_e32 v68, v2
	v_mov_b32_e32 v69, v2
	v_mov_b32_e32 v70, v2
	v_mov_b32_e32 v71, v2
	v_mov_b32_e32 v72, v2
	v_mov_b32_e32 v73, v2
	v_mov_b32_e32 v74, v2
	v_mov_b32_e32 v75, v2
	v_mov_b32_e32 v76, v2
	v_mov_b32_e32 v77, v2
	v_mov_b32_e32 v78, v2
	v_mov_b32_e32 v79, v2
	v_mov_b32_e32 v80, v2
	v_mov_b32_e32 v81, v2
	v_mov_b32_e32 v82, v2
	v_mov_b32_e32 v83, v2
	v_mov_b32_e32 v84, v2
	v_mov_b32_e32 v85, v2
	v_mov_b32_e32 v86, v2
	v_mov_b32_e32 v87, v2
	v_mov_b32_e32 v88, v2
	v_mov_b32_e32 v89, v2
	v_mov_b32_e32 v90, v2
	v_mov_b32_e32 v91, v2
	v_mov_b32_e32 v92, v2
	v_mov_b32_e32 v93, v2
	v_mov_b32_e32 v94, v2
	v_mov_b32_e32 v95, v2
	v_mov_b32_e32 v96, v2
	v_mov_b32_e32 v97, v2
	v_mov_b32_e32 v98, v2
	v_mov_b32_e32 v99, v2
	v_mov_b32_e32 v100, v2
	v_mov_b32_e32 v101, v2
	v_mov_b32_e32 v102, v2
	v_mov_b32_e32 v103, v2
	v_mov_b32_e32 v104, v2
	v_mov_b32_e32 v105, v2
	v_mov_b32_e32 v106, v2
	v_mov_b32_e32 v107, v2
	v_mov_b32_e32 v108, v2
	v_mov_b32_e32 v109, v2
	v_mov_b32_e32 v110, v2
	v_mov_b32_e32 v111, v2
	v_mov_b32_e32 v112, v2
	v_mov_b32_e32 v113, v2
	v_mov_b32_e32 v114, v2
	v_mov_b32_e32 v115, v2
	v_mov_b32_e32 v116, v2
	v_mov_b32_e32 v117, v2
	v_mov_b32_e32 v118, v2
	v_mov_b32_e32 v119, v2
	v_mov_b32_e32 v120, v2
	v_mov_b32_e32 v121, v2
	v_mov_b32_e32 v122, v2
	v_mov_b32_e32 v123, v2
	v_mov_b32_e32 v124, v2
	v_mov_b32_e32 v125, v2
	v_mov_b32_e32 v126, v2
	v_mov_b32_e32 v127, v2
	v_mov_b32_e32 v128, v2
	v_mov_b32_e32 v129, v2
	s_mul_i32 s0, s42, 0x6000
	v_add_u32_e32 v211, s0, v185
	v_lshl_add_u64 v[212:213], v[182:183], 0, v[0:1]
	v_readfirstlane_b32 s0, v211
	v_lshl_add_u64 v[214:215], v[212:213], 0, s[84:85]
	s_mov_b32 m0, s0
	v_lshl_add_u64 v[212:213], v[212:213], 0, s[12:13]
	s_nop 0
	v_readfirstlane_b32 s100, v214
	v_readfirstlane_b32 s101, v215
	s_nop 1
	v_subrev_u32_e32 v228, s100, v214
	v_add_u32_e32 v214, 0x1000, v211
	v_add_u32_e32 v216, 0x2000, v211
	v_readfirstlane_b32 s0, v214
	s_mov_b32 m0, s0
	s_mov_b64 s[0:1], 0x4766000
	v_subrev_u32_e32 v229, s100, v212
	v_lshl_add_u64 v[212:213], v[180:181], 0, v[0:1]
	v_lshl_add_u64 v[214:215], v[212:213], 0, s[0:1]
	v_readfirstlane_b32 s0, v216
	s_mov_b32 m0, s0
	s_mov_b64 s[0:1], 0x4767000
	v_add_u32_e32 v216, 0x3000, v211
	s_nop 0
	v_readfirstlane_b32 vcc_lo, v214
	v_readfirstlane_b32 vcc_hi, v215
	s_nop 1
	v_subrev_u32_e32 v230, vcc_lo, v214
	v_lshl_add_u64 v[214:215], v[212:213], 0, s[0:1]
	v_readfirstlane_b32 s0, v216
	s_mov_b32 m0, s0
	s_mov_b64 s[0:1], 0x4768000
	v_add_u32_e32 v216, 0x4000, v211
	v_subrev_u32_e32 v231, vcc_lo, v214
	v_lshl_add_u64 v[214:215], v[212:213], 0, s[0:1]
	v_readfirstlane_b32 s0, v216
	s_mov_b32 m0, s0
	s_mov_b64 s[0:1], 0x4769000
	v_add_u32_e32 v211, 0x5000, v211
	v_lshl_add_u64 v[212:213], v[212:213], 0, s[0:1]
	v_readfirstlane_b32 s0, v211
	v_subrev_u32_e32 v232, vcc_lo, v214
	s_mov_b32 m0, s0
	s_nop 0
	v_subrev_u32_e32 v233, vcc_lo, v212
	v_mov_b32_e32 v182, v228
	v_mov_b32_e32 v183, v229
	v_mov_b32_e32 v180, v230
	v_mov_b32_e32 v181, v231
	v_mov_b32_e32 v253, v232
	v_mov_b32_e32 v254, v233
	v_readfirstlane_b32 s0, v185
	s_branch .LBB0_2476
	.p2align	6

; #define RAW_BARRIER() do { asm volatile("s_waitcnt lgkmcnt(0)" ::: "memory"); __builtin_amdgcn_s_barrier(); } while (0)
; template <int EPI, int NB>
; DEVI void gemm_tile(const GemmJob& J, int m0, int n0, unsigned char* smem) {
;     ...
;   const int srow = tid >> 2, sch = tid & 3;
;   const int gch = sch ^ ((0 - (tid >> 4)) & 3);
;   const bf16_t* Ag = J.A + (size_t)(m0 + srow) * (J.ablk ? 32 : J.lda) + gch * 8;
;   const bf16_t* Bg = J.Bt + (size_t)(n0 + srow) * 32 + gch * 8;
;   const size_t Astep = (size_t)64 * (J.ablk ? 32 : J.lda), Ak = J.ablk ? (size_t)MROWS * 32 : (size_t)32, Bstep = (size_t)64 * 32, Bk = (size_t)J.NR * 32;
;   const int nk = J.K >> 5;
;   unsigned char* lds_t = smem + tid * 16;
;   const unsigned lbase = (unsigned)(uintptr_t)(__attribute__((address_space(3))) unsigned char*)smem;
;     ...
;   asm volatile("s_waitcnt vmcnt(0)" ::: "memory");
;   RAW_BARRIER();
; #pragma unroll
;   for (int st = 0; st < S - 1; ++st) GEMM_ISSUE(st, st);
; template <int EPI, int NB>
; DEVI void gemm_run(const GemmJob& J, unsigned char* smem, int rot) {
;     ...
;     for (int t = b; t < ntiles; t += G) {
;       const int mt = t / J.ntn, nt = J.nt0 + (t - mt * J.ntn);
;       gemm_tile<EPI, NB>(J, mt * 128, nt * BN, smem);
.LBB0_2663:
	s_mul_hi_i32 s0, s3, 0x2e8ba2e9
	s_lshr_b32 s1, s0, 31
	s_ashr_i32 s0, s0, 2
	s_add_i32 s0, s0, s1
	s_mul_i32 s1, s0, 0xffffffea
	s_add_i32 s1, s1, s3
	v_mov_b32_e32 v208, v177
	s_lshl_b32 s8, s0, 7
	s_lshl_b32 s9, s1, 8
	s_nop 0
	s_mov_b64 s[28:29], 0x1000
	v_ashrrev_i32_e32 v10, 2, v208
	v_lshrrev_b32_e32 v0, 4, v208
	v_sub_u32_e32 v11, 0, v0
	v_add_u32_e32 v2, s8, v10
	v_add_u32_e32 v6, s9, v10
	v_xor_b32_e32 v0, v208, v11
	v_ashrrev_i32_e32 v3, 31, v2
	v_ashrrev_i32_e32 v7, 31, v6
	v_lshlrev_b64 v[2:3], 6, v[2:3]
	v_lshlrev_b32_e32 v0, 4, v0
	v_lshlrev_b64 v[6:7], 6, v[6:7]
	v_lshl_add_u64 v[4:5], v[146:147], 0, v[2:3]
	v_and_b32_e32 v0, 48, v0
	v_lshl_add_u64 v[6:7], v[180:181], 0, v[6:7]
	v_lshlrev_b32_e32 v209, 4, v208
	v_lshl_add_u64 v[4:5], v[4:5], 0, v[0:1]
	v_lshl_add_u64 v[6:7], v[6:7], 0, v[0:1]
	v_readfirstlane_b32 s1, v209
	v_add_u32_e32 v0, 0x1000, v209
	s_mov_b32 m0, s1
	v_readfirstlane_b32 s1, v0
	v_add_u32_e32 v0, 0x2000, v209
	s_waitcnt lgkmcnt(0)
	s_barrier
	global_load_lds_dwordx4 v[4:5], off
	v_lshl_add_u64 v[8:9], v[4:5], 0, s[28:29]
	s_mov_b32 m0, s1
	v_readfirstlane_b32 s1, v0
	v_add_u32_e32 v0, 0x3000, v209
	global_load_lds_dwordx4 v[8:9], off
	s_mov_b32 m0, s1
	v_readfirstlane_b32 s1, v0
	v_add_u32_e32 v0, 0x4000, v209
	global_load_lds_dwordx4 v[6:7], off
	v_lshl_add_u64 v[8:9], v[6:7], 0, s[28:29]
	s_mov_b32 m0, s1
	s_mov_b64 s[28:29], 0x2000
	v_readfirstlane_b32 s1, v0
	v_add_u32_e32 v0, 0x5000, v209
	global_load_lds_dwordx4 v[8:9], off
	v_lshl_add_u64 v[8:9], v[6:7], 0, s[28:29]
	s_mov_b32 m0, s1
	s_mov_b64 s[28:29], 0x3000
	v_readfirstlane_b32 s1, v0
	v_add_u32_e32 v0, 0x6000, v209
	global_load_lds_dwordx4 v[8:9], off
	v_lshl_add_u64 v[8:9], v[6:7], 0, s[28:29]
	s_mov_b32 m0, s1
	v_readfirstlane_b32 s1, v0
	v_add_u32_e32 v0, 0x7000, v209
	global_load_lds_dwordx4 v[8:9], off
	v_lshl_add_u64 v[8:9], v[4:5], 0, s[94:95]
	s_mov_b32 m0, s1
	s_mov_b64 s[28:29], 0x30b000
	v_readfirstlane_b32 s1, v0
	v_add_u32_e32 v0, 0x8000, v209
	global_load_lds_dwordx4 v[8:9], off
	v_lshl_add_u64 v[4:5], v[4:5], 0, s[28:29]
	s_mov_b32 m0, s1
	v_readfirstlane_b32 s1, v0
	v_add_u32_e32 v0, 0x9000, v209
	global_load_lds_dwordx4 v[4:5], off
	v_lshl_add_u64 v[4:5], v[6:7], 0, s[50:51]
	s_mov_b32 m0, s1
	s_mov_b64 s[28:29], 0x59000
	v_readfirstlane_b32 s1, v0
	v_add_u32_e32 v0, 0xa000, v209
	global_load_lds_dwordx4 v[4:5], off
	v_lshl_add_u64 v[4:5], v[6:7], 0, s[28:29]
	s_mov_b32 m0, s1
	s_mov_b64 s[28:29], 0x5a000
	v_readfirstlane_b32 s1, v0
	v_add_u32_e32 v0, 0xb000, v209
	global_load_lds_dwordx4 v[4:5], off
	v_lshl_add_u64 v[4:5], v[6:7], 0, s[28:29]
	s_mov_b32 m0, s1
	s_mov_b64 s[28:29], 0x5b000
	v_readfirstlane_b32 s1, v0
	global_load_lds_dwordx4 v[4:5], off
	v_lshl_add_u64 v[4:5], v[6:7], 0, s[28:29]
	s_mov_b32 m0, s1
	v_lshlrev_b32_e32 v0, 2, v208
	global_load_lds_dwordx4 v[4:5], off
	v_and_b32_e32 v0, 48, v0
	v_ashrrev_i32_e32 v4, 1, v208
	v_and_b32_e32 v210, 15, v208
	v_sub_u32_e32 v0, 0, v0
	v_and_b32_e32 v211, 0xffffffc0, v4
	v_bitop3_b32 v0, v208, 48, v0 bitop3:0x48
	v_or_b32_e32 v4, v211, v210
	v_lshl_or_b32 v212, v4, 6, v0
	v_lshlrev_b32_e32 v4, 1, v208
	v_and_b32_e32 v213, 0x80, v4
	v_or_b32_e32 v4, v213, v210
	v_lshl_or_b32 v0, v4, 6, v0
	v_add_u32_e32 v4, s2, v10
	s_mulk_i32 s0, 0x1600
	v_subrev_u32_e32 v4, s0, v4
	v_ashrrev_i32_e32 v5, 31, v4
	v_add_u32_e32 v214, 0x2000, v0
	v_bitop3_b32 v0, v208, 3, v11 bitop3:0x48
	v_lshlrev_b64 v[4:5], 6, v[4:5]
	v_mov_b32_e32 v6, 0
	s_mov_b32 s42, 2
	s_mov_b32 s20, 0
	s_mov_b64 s[30:31], 0x1000
	v_lshlrev_b32_e32 v0, 4, v0
	v_lshl_add_u64 v[184:185], v[182:183], 0, v[4:5]
	v_lshl_add_u64 v[186:187], v[130:131], 0, v[2:3]
	s_mov_b32 s43, 0
	v_mov_b32_e32 v7, v6
	v_mov_b32_e32 v8, v6
	v_mov_b32_e32 v9, v6
	v_mov_b32_e32 v14, v6
	v_mov_b32_e32 v15, v6
	v_mov_b32_e32 v16, v6
	v_mov_b32_e32 v17, v6
	v_mov_b32_e32 v2, v6
	v_mov_b32_e32 v3, v6
	v_mov_b32_e32 v4, v6
	v_mov_b32_e32 v5, v6
	v_mov_b32_e32 v10, v6
	v_mov_b32_e32 v11, v6
	v_mov_b32_e32 v12, v6
	v_mov_b32_e32 v13, v6
	v_mov_b32_e32 v22, v6
	v_mov_b32_e32 v23, v6
	v_mov_b32_e32 v24, v6
; #define RAW_BARRIER() do { asm volatile("s_waitcnt lgkmcnt(0)" ::: "memory"); __builtin_amdgcn_s_barrier(); } while (0)
; template <int EPI, int NB>
; DEVI void gemm_tile(const GemmJob& J, int m0, int n0, unsigned char* smem) {
;     ...
;   f32x4 acc[4][NB];
; #pragma unroll
;   for (int i = 0; i < 4; ++i)
; #pragma unroll
;     for (int j = 0; j < NB; ++j) acc[i][j] = (f32x4){0.f, 0.f, 0.f, 0.f};
;   const int srow = tid >> 2, sch = tid & 3;
;   const int gch = sch ^ ((0 - (tid >> 4)) & 3);
;   const bf16_t* Ag = J.A + (size_t)(m0 + srow) * (J.ablk ? 32 : J.lda) + gch * 8;
;   const bf16_t* Bg = J.Bt + (size_t)(n0 + srow) * 32 + gch * 8;
;   const size_t Astep = (size_t)64 * (J.ablk ? 32 : J.lda), Ak = J.ablk ? (size_t)MROWS * 32 : (size_t)32, Bstep = (size_t)64 * 32, Bk = (size_t)J.NR * 32;
;   const int nk = J.K >> 5;
;   unsigned char* lds_t = smem + tid * 16;
;   const unsigned lbase = (unsigned)(uintptr_t)(__attribute__((address_space(3))) unsigned char*)smem;
;     ...
;   asm volatile("s_waitcnt vmcnt(0)" ::: "memory");
;   RAW_BARRIER();
; #pragma unroll
;   for (int st = 0; st < S - 1; ++st) GEMM_ISSUE(st, st);
;   const int fsl = (g ^ ((0 - (l16 >> 2)) & 3)) << 4;
;   const int aofs = (wm * 64 + l16) * 64 + fsl;
;   const int bofs = A_BYTES + (wn * NB * 16 + l16) * 64 + fsl;
;   int cs = 0, is = S - 1;
; #pragma clang loop unroll(disable)
;   for (int kt = 0; kt < nk; ++kt) {
;     if (nk - 1 - kt >= S - 2) {
;       if constexpr (NB == 8) asm volatile("s_waitcnt vmcnt(6)" ::: "memory");
;       else                   asm volatile("s_waitcnt vmcnt(8)" ::: "memory");
;     } else {
;       asm volatile("s_waitcnt vmcnt(0)" ::: "memory");
;     }
;     RAW_BARRIER();
;     if (kt + S - 1 < nk) GEMM_ISSUE(kt + S - 1, is);
	v_mov_b32_e32 v25, v6
	v_mov_b32_e32 v30, v6
	v_mov_b32_e32 v31, v6
	v_mov_b32_e32 v32, v6
	v_mov_b32_e32 v33, v6
	v_mov_b32_e32 v18, v6
	v_mov_b32_e32 v19, v6
	v_mov_b32_e32 v20, v6
	v_mov_b32_e32 v21, v6
	v_mov_b32_e32 v26, v6
	v_mov_b32_e32 v27, v6
	v_mov_b32_e32 v28, v6
	v_mov_b32_e32 v29, v6
	v_mov_b32_e32 v38, v6
	v_mov_b32_e32 v39, v6
	v_mov_b32_e32 v40, v6
	v_mov_b32_e32 v41, v6
	v_mov_b32_e32 v46, v6
	v_mov_b32_e32 v47, v6
	v_mov_b32_e32 v48, v6
	v_mov_b32_e32 v49, v6
	v_mov_b32_e32 v34, v6
	v_mov_b32_e32 v35, v6
	v_mov_b32_e32 v36, v6
	v_mov_b32_e32 v37, v6
	v_mov_b32_e32 v42, v6
	v_mov_b32_e32 v43, v6
	v_mov_b32_e32 v44, v6
	v_mov_b32_e32 v45, v6
	v_mov_b32_e32 v54, v6
	v_mov_b32_e32 v55, v6
	v_mov_b32_e32 v56, v6
	v_mov_b32_e32 v57, v6
	v_mov_b32_e32 v62, v6
	v_mov_b32_e32 v63, v6
	v_mov_b32_e32 v64, v6
	v_mov_b32_e32 v65, v6
	v_mov_b32_e32 v50, v6
	v_mov_b32_e32 v51, v6
	v_mov_b32_e32 v52, v6
	v_mov_b32_e32 v53, v6
	v_mov_b32_e32 v58, v6
	v_mov_b32_e32 v59, v6
	v_mov_b32_e32 v60, v6
	v_mov_b32_e32 v61, v6
	v_mov_b32_e32 v70, v6
	v_mov_b32_e32 v71, v6
	v_mov_b32_e32 v72, v6
	v_mov_b32_e32 v73, v6
	v_mov_b32_e32 v78, v6
	v_mov_b32_e32 v79, v6
	v_mov_b32_e32 v80, v6
	v_mov_b32_e32 v81, v6
	v_mov_b32_e32 v66, v6
	v_mov_b32_e32 v67, v6
	v_mov_b32_e32 v68, v6
	v_mov_b32_e32 v69, v6
	v_mov_b32_e32 v74, v6
	v_mov_b32_e32 v75, v6
	v_mov_b32_e32 v76, v6
	v_mov_b32_e32 v77, v6
	v_mov_b32_e32 v86, v6
	v_mov_b32_e32 v87, v6
	v_mov_b32_e32 v88, v6
	v_mov_b32_e32 v89, v6
	v_mov_b32_e32 v94, v6
	v_mov_b32_e32 v95, v6
	v_mov_b32_e32 v96, v6
	v_mov_b32_e32 v97, v6
	v_mov_b32_e32 v82, v6
	v_mov_b32_e32 v83, v6
	v_mov_b32_e32 v84, v6
	v_mov_b32_e32 v85, v6
	v_mov_b32_e32 v90, v6
	v_mov_b32_e32 v91, v6
	v_mov_b32_e32 v92, v6
	v_mov_b32_e32 v93, v6
	v_mov_b32_e32 v102, v6
	v_mov_b32_e32 v103, v6
	v_mov_b32_e32 v104, v6
	v_mov_b32_e32 v105, v6
	v_mov_b32_e32 v110, v6
	v_mov_b32_e32 v111, v6
	v_mov_b32_e32 v112, v6
	v_mov_b32_e32 v113, v6
	v_mov_b32_e32 v98, v6
	v_mov_b32_e32 v99, v6
	v_mov_b32_e32 v100, v6
	v_mov_b32_e32 v101, v6
	v_mov_b32_e32 v106, v6
	v_mov_b32_e32 v107, v6
	v_mov_b32_e32 v108, v6
	v_mov_b32_e32 v109, v6
	v_mov_b32_e32 v118, v6
	v_mov_b32_e32 v119, v6
	v_mov_b32_e32 v120, v6
	v_mov_b32_e32 v121, v6
	v_mov_b32_e32 v126, v6
	v_mov_b32_e32 v127, v6
	v_mov_b32_e32 v128, v6
	v_mov_b32_e32 v129, v6
	v_mov_b32_e32 v114, v6
	v_mov_b32_e32 v115, v6
	v_mov_b32_e32 v116, v6
	v_mov_b32_e32 v117, v6
	v_mov_b32_e32 v122, v6
	v_mov_b32_e32 v123, v6
	v_mov_b32_e32 v124, v6
	v_mov_b32_e32 v125, v6
	s_mul_i32 s0, s42, 0x6000
	v_add_u32_e32 v215, s0, v209
	v_lshl_add_u64 v[216:217], v[186:187], 0, v[0:1]
	v_readfirstlane_b32 s0, v215
	v_lshl_add_u64 v[218:219], v[216:217], 0, s[84:85]
	s_mov_b32 m0, s0
	v_lshl_add_u64 v[216:217], v[216:217], 0, s[12:13]
	s_nop 0
	v_readfirstlane_b32 s100, v218
	v_readfirstlane_b32 s101, v219
	s_nop 1
	v_subrev_u32_e32 v232, s100, v218
	v_add_u32_e32 v218, 0x1000, v215
	v_add_u32_e32 v220, 0x2000, v215
	v_readfirstlane_b32 s0, v218
	s_mov_b32 m0, s0
	v_readfirstlane_b32 s0, v220
	v_subrev_u32_e32 v233, s100, v216
	v_lshl_add_u64 v[216:217], v[184:185], 0, v[0:1]
	v_add_u32_e32 v220, 0x3000, v215
	v_lshl_add_u64 v[218:219], v[216:217], 0, s[36:37]
	s_mov_b32 m0, s0
	v_readfirstlane_b32 s0, v220
	v_add_u32_e32 v220, 0x4000, v215
	s_nop 0
	v_readfirstlane_b32 vcc_lo, v218
	v_readfirstlane_b32 vcc_hi, v219
	s_nop 1
	v_subrev_u32_e32 v234, vcc_lo, v218
	v_lshl_add_u64 v[218:219], v[216:217], 0, s[6:7]
	s_mov_b32 m0, s0
	v_readfirstlane_b32 s0, v220
	v_add_u32_e32 v215, 0x5000, v215
	v_subrev_u32_e32 v235, vcc_lo, v218
	v_lshl_add_u64 v[218:219], v[216:217], 0, s[88:89]
	s_mov_b32 m0, s0
	v_readfirstlane_b32 s0, v215
	v_subrev_u32_e32 v236, vcc_lo, v218
	v_lshl_add_u64 v[216:217], v[216:217], 0, s[90:91]
	s_mov_b32 m0, s0
	s_nop 0
	v_subrev_u32_e32 v237, vcc_lo, v216
	v_mov_b32_e32 v186, v232
	v_mov_b32_e32 v187, v233
	v_mov_b32_e32 v184, v234
	v_mov_b32_e32 v185, v235
	v_mov_b32_e32 v253, v236
	v_mov_b32_e32 v254, v237
	v_readfirstlane_b32 s0, v209
	s_branch .LBB0_2665
	.p2align	6

; #define RAW_BARRIER() do { asm volatile("s_waitcnt lgkmcnt(0)" ::: "memory"); __builtin_amdgcn_s_barrier(); } while (0)
; template <int EPI, int NB>
; DEVI void gemm_tile(const GemmJob& J, int m0, int n0, unsigned char* smem) {
;     ...
;   const int srow = tid >> 2, sch = tid & 3;
;   const int gch = sch ^ ((0 - (tid >> 4)) & 3);
;   const bf16_t* Ag = J.A + (size_t)(m0 + srow) * (J.ablk ? 32 : J.lda) + gch * 8;
;   const bf16_t* Bg = J.Bt + (size_t)(n0 + srow) * 32 + gch * 8;
;   const size_t Astep = (size_t)64 * (J.ablk ? 32 : J.lda), Ak = J.ablk ? (size_t)MROWS * 32 : (size_t)32, Bstep = (size_t)64 * 32, Bk = (size_t)J.NR * 32;
;   const int nk = J.K >> 5;
;   unsigned char* lds_t = smem + tid * 16;
;   const unsigned lbase = (unsigned)(uintptr_t)(__attribute__((address_space(3))) unsigned char*)smem;
;     ...
;   asm volatile("s_waitcnt vmcnt(0)" ::: "memory");
;   RAW_BARRIER();
; #pragma unroll
;   for (int st = 0; st < S - 1; ++st) GEMM_ISSUE(st, st);
; template <int EPI, int NB>
; DEVI void gemm_run(const GemmJob& J, unsigned char* smem, int rot) {
;     ...
;     const int x = b & 7, lb = b >> 3, nlb = G >> 3;
;     const int mlo = x * 49;
;     const int mcnt = min(49, MT128 - mlo);
;     const int ntot = mcnt * J.ntn, gsz = 8 * J.ntn;
;     const int ngrp = (mcnt + 7) >> 3;
;     for (int q0 = lb; q0 < ntot; q0 += nlb) {
;       const int q = J.rev ? ntot - 1 - q0 : q0;
;       int grp = q / gsz; const int qq = q - grp * gsz;
;       const int mg = min(8, mcnt - grp * 8);
;       const int nt = qq / mg, mi = qq - nt * mg;
;       gemm_tile<EPI, NB>(J, (mlo + grp * 8 + mi) * 128, (J.nt0 + nt) * BN, smem);
.LBB0_2677:
	s_mul_hi_i32 s0, s3, 0x2e8ba2e9
	s_lshr_b32 s1, s0, 31
	s_ashr_i32 s0, s0, 5
	s_add_i32 s0, s0, s1
	s_lshl_b32 s1, s0, 3
	v_readlane_b32 s8, v251, 48
	s_sub_i32 s8, s8, s1
	s_min_i32 s9, s8, 8
	s_abs_i32 s20, s9
	v_cvt_f32_u32_e32 v0, s20
	s_sub_i32 s43, 0, s20
	s_mul_i32 s40, s0, 0xffffff50
	s_add_i32 s40, s40, s3
	v_rcp_iflag_f32_e32 v0, v0
	s_abs_i32 s41, s40
	s_xor_b32 s42, s40, s9
	s_ashr_i32 s42, s42, 31
	v_mul_f32_e32 v0, 0x4f7ffffe, v0
	v_cvt_u32_f32_e32 v0, v0
	v_mov_b32_e32 v208, v177
	s_nop 0
	v_readfirstlane_b32 s44, v0
	s_mul_i32 s43, s43, s44
	s_mul_hi_u32 s43, s44, s43
	s_add_i32 s44, s44, s43
	s_mul_hi_u32 s43, s41, s44
	s_mul_i32 s44, s43, s20
	s_sub_i32 s41, s41, s44
	s_add_i32 s45, s43, 1
	s_sub_i32 s44, s41, s20
	s_cmp_ge_u32 s41, s20
	s_cselect_b32 s43, s45, s43
	s_cselect_b32 s41, s44, s41
	s_add_i32 s44, s43, 1
	s_cmp_ge_u32 s41, s20
	s_cselect_b32 s20, s44, s43
	s_xor_b32 s20, s20, s42
	s_sub_i32 s20, s20, s42
	s_mul_i32 s41, s9, s20
	v_readlane_b32 s9, v250, 37
	s_add_i32 s1, s1, s9
	s_add_i32 s1, s1, s40
	s_sub_i32 s1, s1, s41
	s_lshl_b32 s9, s1, 7
	s_lshl_b32 s20, s20, 8
	v_ashrrev_i32_e32 v10, 2, v208
	v_lshrrev_b32_e32 v0, 4, v208
	v_sub_u32_e32 v11, 0, v0
	v_add_u32_e32 v2, s9, v10
	v_add_u32_e32 v4, s20, v10
	v_xor_b32_e32 v0, v208, v11
	v_ashrrev_i32_e32 v3, 31, v2
	v_ashrrev_i32_e32 v5, 31, v4
	v_lshlrev_b64 v[2:3], 6, v[2:3]
	v_lshlrev_b32_e32 v0, 4, v0
	v_lshlrev_b64 v[4:5], 6, v[4:5]
	v_lshl_add_u64 v[2:3], v[146:147], 0, v[2:3]
	v_and_b32_e32 v0, 48, v0
	v_lshl_add_u64 v[6:7], v[180:181], 0, v[4:5]
	v_lshlrev_b32_e32 v209, 4, v208
	v_lshl_add_u64 v[2:3], v[2:3], 0, v[0:1]
	v_lshl_add_u64 v[6:7], v[6:7], 0, v[0:1]
	v_readfirstlane_b32 s1, v209
	v_add_u32_e32 v0, 0x1000, v209
	s_mov_b32 m0, s1
	s_mov_b64 s[28:29], 0x1000
	v_readfirstlane_b32 s1, v0
	v_add_u32_e32 v0, 0x2000, v209
	s_waitcnt lgkmcnt(0)
	s_barrier
	global_load_lds_dwordx4 v[2:3], off
	v_lshl_add_u64 v[8:9], v[2:3], 0, s[28:29]
	s_mov_b32 m0, s1
	v_readfirstlane_b32 s1, v0
	v_add_u32_e32 v0, 0x3000, v209
	global_load_lds_dwordx4 v[8:9], off
	s_mov_b32 m0, s1
	v_readfirstlane_b32 s1, v0
	v_add_u32_e32 v0, 0x4000, v209
	global_load_lds_dwordx4 v[6:7], off
	v_lshl_add_u64 v[8:9], v[6:7], 0, s[28:29]
	s_mov_b32 m0, s1
	s_mov_b64 s[28:29], 0x2000
	v_readfirstlane_b32 s1, v0
	v_add_u32_e32 v0, 0x5000, v209
	global_load_lds_dwordx4 v[8:9], off
	v_lshl_add_u64 v[8:9], v[6:7], 0, s[28:29]
	s_mov_b32 m0, s1
	s_mov_b64 s[28:29], 0x3000
	v_readfirstlane_b32 s1, v0
	v_add_u32_e32 v0, 0x6000, v209
	global_load_lds_dwordx4 v[8:9], off
	v_lshl_add_u64 v[8:9], v[6:7], 0, s[28:29]
	s_mov_b32 m0, s1
	v_readfirstlane_b32 s1, v0
	v_add_u32_e32 v0, 0x7000, v209
	global_load_lds_dwordx4 v[8:9], off
	v_lshl_add_u64 v[8:9], v[2:3], 0, s[94:95]
	s_mov_b32 m0, s1
	s_mov_b64 s[28:29], 0x30b000
	v_readfirstlane_b32 s1, v0
	v_add_u32_e32 v0, 0x8000, v209
	global_load_lds_dwordx4 v[8:9], off
	v_lshl_add_u64 v[2:3], v[2:3], 0, s[28:29]
	s_mov_b32 m0, s1
	v_readfirstlane_b32 s1, v0
	v_add_u32_e32 v0, 0x9000, v209
	global_load_lds_dwordx4 v[2:3], off
	v_lshl_add_u64 v[2:3], v[6:7], 0, s[50:51]
	s_mov_b32 m0, s1
	s_mov_b64 s[28:29], 0x59000
	v_readfirstlane_b32 s1, v0
	v_add_u32_e32 v0, 0xa000, v209
	global_load_lds_dwordx4 v[2:3], off
	v_lshl_add_u64 v[2:3], v[6:7], 0, s[28:29]
	s_mov_b32 m0, s1
	s_mov_b64 s[28:29], 0x5a000
	v_readfirstlane_b32 s1, v0
	v_add_u32_e32 v0, 0xb000, v209
	global_load_lds_dwordx4 v[2:3], off
	v_lshl_add_u64 v[2:3], v[6:7], 0, s[28:29]
	s_mov_b32 m0, s1
	s_mov_b64 s[28:29], 0x5b000
	v_readfirstlane_b32 s1, v0
	global_load_lds_dwordx4 v[2:3], off
	v_lshl_add_u64 v[2:3], v[6:7], 0, s[28:29]
	s_mov_b32 m0, s1
	v_lshlrev_b32_e32 v0, 2, v208
	global_load_lds_dwordx4 v[2:3], off
	v_and_b32_e32 v0, 48, v0
	v_ashrrev_i32_e32 v2, 1, v208
	v_and_b32_e32 v210, 15, v208
	v_sub_u32_e32 v0, 0, v0
	v_and_b32_e32 v211, 0xffffffc0, v2
	v_bitop3_b32 v0, v208, 48, v0 bitop3:0x48
	v_or_b32_e32 v2, v211, v210
	v_lshl_or_b32 v212, v2, 6, v0
	v_lshlrev_b32_e32 v2, 1, v208
	v_and_b32_e32 v213, 0x80, v2
	s_sub_i32 s1, s2, s41
	s_mulk_i32 s0, 0xa8
	v_or_b32_e32 v2, v213, v210
	s_sub_i32 s0, s1, s0
	v_lshl_or_b32 v0, v2, 6, v0
	v_lshl_add_u32 v2, s0, 7, v10
	v_ashrrev_i32_e32 v3, 31, v2
	v_add_u32_e32 v214, 0x2000, v0
	v_bitop3_b32 v0, v208, 3, v11 bitop3:0x48
	v_lshlrev_b64 v[2:3], 6, v[2:3]
	v_mov_b32_e32 v6, 0
	s_mov_b32 s8, 0
	s_mov_b32 s42, 2
	s_mov_b64 s[30:31], 0x1000
	v_lshlrev_b32_e32 v0, 4, v0
	v_lshl_add_u64 v[184:185], v[182:183], 0, v[4:5]
; #define RAW_BARRIER() do { asm volatile("s_waitcnt lgkmcnt(0)" ::: "memory"); __builtin_amdgcn_s_barrier(); } while (0)
; template <int EPI, int NB>
; DEVI void gemm_tile(const GemmJob& J, int m0, int n0, unsigned char* smem) {
;     ...
;   f32x4 acc[4][NB];
; #pragma unroll
;   for (int i = 0; i < 4; ++i)
; #pragma unroll
;     for (int j = 0; j < NB; ++j) acc[i][j] = (f32x4){0.f, 0.f, 0.f, 0.f};
;   const int srow = tid >> 2, sch = tid & 3;
;   const int gch = sch ^ ((0 - (tid >> 4)) & 3);
;   const bf16_t* Ag = J.A + (size_t)(m0 + srow) * (J.ablk ? 32 : J.lda) + gch * 8;
;   const bf16_t* Bg = J.Bt + (size_t)(n0 + srow) * 32 + gch * 8;
;   const size_t Astep = (size_t)64 * (J.ablk ? 32 : J.lda), Ak = J.ablk ? (size_t)MROWS * 32 : (size_t)32, Bstep = (size_t)64 * 32, Bk = (size_t)J.NR * 32;
;   const int nk = J.K >> 5;
;   unsigned char* lds_t = smem + tid * 16;
;   const unsigned lbase = (unsigned)(uintptr_t)(__attribute__((address_space(3))) unsigned char*)smem;
;     ...
;   asm volatile("s_waitcnt vmcnt(0)" ::: "memory");
;   RAW_BARRIER();
; #pragma unroll
;   for (int st = 0; st < S - 1; ++st) GEMM_ISSUE(st, st);
;   const int fsl = (g ^ ((0 - (l16 >> 2)) & 3)) << 4;
;   const int aofs = (wm * 64 + l16) * 64 + fsl;
;   const int bofs = A_BYTES + (wn * NB * 16 + l16) * 64 + fsl;
;   int cs = 0, is = S - 1;
; #pragma clang loop unroll(disable)
;   for (int kt = 0; kt < nk; ++kt) {
;     if (nk - 1 - kt >= S - 2) {
;       if constexpr (NB == 8) asm volatile("s_waitcnt vmcnt(6)" ::: "memory");
;       else                   asm volatile("s_waitcnt vmcnt(8)" ::: "memory");
;     } else {
;       asm volatile("s_waitcnt vmcnt(0)" ::: "memory");
;     }
;     RAW_BARRIER();
;     if (kt + S - 1 < nk) GEMM_ISSUE(kt + S - 1, is);
	v_lshl_add_u64 v[186:187], v[130:131], 0, v[2:3]
	s_mov_b32 s43, 0
	v_mov_b32_e32 v7, v6
	v_mov_b32_e32 v8, v6
	v_mov_b32_e32 v9, v6
	v_mov_b32_e32 v14, v6
	v_mov_b32_e32 v15, v6
	v_mov_b32_e32 v16, v6
	v_mov_b32_e32 v17, v6
	v_mov_b32_e32 v2, v6
	v_mov_b32_e32 v3, v6
	v_mov_b32_e32 v4, v6
	v_mov_b32_e32 v5, v6
	v_mov_b32_e32 v10, v6
	v_mov_b32_e32 v11, v6
	v_mov_b32_e32 v12, v6
	v_mov_b32_e32 v13, v6
	v_mov_b32_e32 v22, v6
	v_mov_b32_e32 v23, v6
	v_mov_b32_e32 v24, v6
	v_mov_b32_e32 v25, v6
	v_mov_b32_e32 v30, v6
	v_mov_b32_e32 v31, v6
	v_mov_b32_e32 v32, v6
	v_mov_b32_e32 v33, v6
	v_mov_b32_e32 v18, v6
	v_mov_b32_e32 v19, v6
	v_mov_b32_e32 v20, v6
	v_mov_b32_e32 v21, v6
	v_mov_b32_e32 v26, v6
	v_mov_b32_e32 v27, v6
	v_mov_b32_e32 v28, v6
	v_mov_b32_e32 v29, v6
	v_mov_b32_e32 v38, v6
	v_mov_b32_e32 v39, v6
	v_mov_b32_e32 v40, v6
	v_mov_b32_e32 v41, v6
	v_mov_b32_e32 v46, v6
	v_mov_b32_e32 v47, v6
	v_mov_b32_e32 v48, v6
	v_mov_b32_e32 v49, v6
	v_mov_b32_e32 v34, v6
	v_mov_b32_e32 v35, v6
	v_mov_b32_e32 v36, v6
	v_mov_b32_e32 v37, v6
	v_mov_b32_e32 v42, v6
	v_mov_b32_e32 v43, v6
	v_mov_b32_e32 v44, v6
	v_mov_b32_e32 v45, v6
	v_mov_b32_e32 v54, v6
	v_mov_b32_e32 v55, v6
	v_mov_b32_e32 v56, v6
	v_mov_b32_e32 v57, v6
	v_mov_b32_e32 v62, v6
	v_mov_b32_e32 v63, v6
	v_mov_b32_e32 v64, v6
	v_mov_b32_e32 v65, v6
	v_mov_b32_e32 v50, v6
	v_mov_b32_e32 v51, v6
	v_mov_b32_e32 v52, v6
	v_mov_b32_e32 v53, v6
	v_mov_b32_e32 v58, v6
	v_mov_b32_e32 v59, v6
	v_mov_b32_e32 v60, v6
	v_mov_b32_e32 v61, v6
	v_mov_b32_e32 v70, v6
	v_mov_b32_e32 v71, v6
	v_mov_b32_e32 v72, v6
	v_mov_b32_e32 v73, v6
	v_mov_b32_e32 v78, v6
	v_mov_b32_e32 v79, v6
	v_mov_b32_e32 v80, v6
	v_mov_b32_e32 v81, v6
	v_mov_b32_e32 v66, v6
	v_mov_b32_e32 v67, v6
	v_mov_b32_e32 v68, v6
	v_mov_b32_e32 v69, v6
	v_mov_b32_e32 v74, v6
	v_mov_b32_e32 v75, v6
	v_mov_b32_e32 v76, v6
	v_mov_b32_e32 v77, v6
	v_mov_b32_e32 v86, v6
	v_mov_b32_e32 v87, v6
	v_mov_b32_e32 v88, v6
	v_mov_b32_e32 v89, v6
	v_mov_b32_e32 v94, v6
	v_mov_b32_e32 v95, v6
	v_mov_b32_e32 v96, v6
	v_mov_b32_e32 v97, v6
	v_mov_b32_e32 v82, v6
	v_mov_b32_e32 v83, v6
	v_mov_b32_e32 v84, v6
	v_mov_b32_e32 v85, v6
	v_mov_b32_e32 v90, v6
	v_mov_b32_e32 v91, v6
	v_mov_b32_e32 v92, v6
	v_mov_b32_e32 v93, v6
	v_mov_b32_e32 v102, v6
	v_mov_b32_e32 v103, v6
	v_mov_b32_e32 v104, v6
	v_mov_b32_e32 v105, v6
	v_mov_b32_e32 v110, v6
	v_mov_b32_e32 v111, v6
	v_mov_b32_e32 v112, v6
	v_mov_b32_e32 v113, v6
	v_mov_b32_e32 v98, v6
	v_mov_b32_e32 v99, v6
	v_mov_b32_e32 v100, v6
	v_mov_b32_e32 v101, v6
	v_mov_b32_e32 v106, v6
	v_mov_b32_e32 v107, v6
	v_mov_b32_e32 v108, v6
	v_mov_b32_e32 v109, v6
	v_mov_b32_e32 v118, v6
	v_mov_b32_e32 v119, v6
	v_mov_b32_e32 v120, v6
	v_mov_b32_e32 v121, v6
	v_mov_b32_e32 v126, v6
	v_mov_b32_e32 v127, v6
	v_mov_b32_e32 v128, v6
	v_mov_b32_e32 v129, v6
	v_mov_b32_e32 v114, v6
	v_mov_b32_e32 v115, v6
	v_mov_b32_e32 v116, v6
	v_mov_b32_e32 v117, v6
	v_mov_b32_e32 v122, v6
	v_mov_b32_e32 v123, v6
	v_mov_b32_e32 v124, v6
	v_mov_b32_e32 v125, v6
	s_mul_i32 s0, s42, 0x6000
	v_add_u32_e32 v215, s0, v209
	v_lshl_add_u64 v[216:217], v[186:187], 0, v[0:1]
	v_readfirstlane_b32 s0, v215
	v_lshl_add_u64 v[218:219], v[216:217], 0, s[84:85]
	s_mov_b32 m0, s0
	v_lshl_add_u64 v[216:217], v[216:217], 0, s[12:13]
	s_nop 0
	v_readfirstlane_b32 s100, v218
	v_readfirstlane_b32 s101, v219
	s_nop 1
	v_subrev_u32_e32 v232, s100, v218
	v_add_u32_e32 v218, 0x1000, v215
	v_add_u32_e32 v220, 0x2000, v215
	v_readfirstlane_b32 s0, v218
	s_mov_b32 m0, s0
	v_readfirstlane_b32 s0, v220
	v_subrev_u32_e32 v233, s100, v216
	v_lshl_add_u64 v[216:217], v[184:185], 0, v[0:1]
	v_add_u32_e32 v220, 0x3000, v215
	v_lshl_add_u64 v[218:219], v[216:217], 0, s[36:37]
	s_mov_b32 m0, s0
	v_readfirstlane_b32 s0, v220
	v_add_u32_e32 v220, 0x4000, v215
	s_nop 0
	v_readfirstlane_b32 vcc_lo, v218
	v_readfirstlane_b32 vcc_hi, v219
	s_nop 1
	v_subrev_u32_e32 v234, vcc_lo, v218
	v_lshl_add_u64 v[218:219], v[216:217], 0, s[6:7]
	s_mov_b32 m0, s0
	v_readfirstlane_b32 s0, v220
	v_add_u32_e32 v215, 0x5000, v215
	v_subrev_u32_e32 v235, vcc_lo, v218
	v_lshl_add_u64 v[218:219], v[216:217], 0, s[88:89]
	s_mov_b32 m0, s0
	v_readfirstlane_b32 s0, v215
	v_subrev_u32_e32 v236, vcc_lo, v218
	v_lshl_add_u64 v[216:217], v[216:217], 0, s[90:91]
	s_mov_b32 m0, s0
	s_nop 0
	v_subrev_u32_e32 v237, vcc_lo, v216
	v_mov_b32_e32 v186, v232
	v_mov_b32_e32 v187, v233
	v_mov_b32_e32 v184, v234
	v_mov_b32_e32 v185, v235
	v_mov_b32_e32 v253, v236
	v_mov_b32_e32 v254, v237
	v_readfirstlane_b32 s0, v209
	s_branch .LBB0_2679
	.p2align	6

; #define RAW_BARRIER() do { asm volatile("s_waitcnt lgkmcnt(0)" ::: "memory"); __builtin_amdgcn_s_barrier(); } while (0)
; template <int EPI, int NB>
; DEVI void gemm_tile(const GemmJob& J, int m0, int n0, unsigned char* smem) {
;     ...
;   const int srow = tid >> 2, sch = tid & 3;
;   const int gch = sch ^ ((0 - (tid >> 4)) & 3);
;   const bf16_t* Ag = J.A + (size_t)(m0 + srow) * (J.ablk ? 32 : J.lda) + gch * 8;
;   const bf16_t* Bg = J.Bt + (size_t)(n0 + srow) * 32 + gch * 8;
;   const size_t Astep = (size_t)64 * (J.ablk ? 32 : J.lda), Ak = J.ablk ? (size_t)MROWS * 32 : (size_t)32, Bstep = (size_t)64 * 32, Bk = (size_t)J.NR * 32;
;   const int nk = J.K >> 5;
;   unsigned char* lds_t = smem + tid * 16;
;   const unsigned lbase = (unsigned)(uintptr_t)(__attribute__((address_space(3))) unsigned char*)smem;
;     ...
;   asm volatile("s_waitcnt vmcnt(0)" ::: "memory");
;   RAW_BARRIER();
; #pragma unroll
;   for (int st = 0; st < S - 1; ++st) GEMM_ISSUE(st, st);
; template <int EPI, int NB>
; DEVI void gemm_run(const GemmJob& J, unsigned char* smem, int rot) {
;     ...
;     for (int t = b; t < ntiles; t += G) {
;       const int mt = t / J.ntn, nt = J.nt0 + (t - mt * J.ntn);
;       gemm_tile<EPI, NB>(J, mt * 128, nt * BN, smem);
.LBB0_2742:
	s_ashr_i32 s0, s9, 31
	s_lshr_b32 s0, s0, 30
	s_add_i32 s0, s9, s0
	s_ashr_i32 s0, s0, 2
	s_lshl_b32 s3, s0, 7
	s_lshl_b32 s0, s0, 10
	s_lshl_b32 s1, s9, 8
	v_mov_b32_e32 v186, v177
	s_sub_i32 s2, s1, s0
	s_nop 0
	s_mov_b64 s[28:29], 0x1000
	v_ashrrev_i32_e32 v10, 2, v186
	v_lshrrev_b32_e32 v0, 4, v186
	v_sub_u32_e32 v11, 0, v0
	v_add_u32_e32 v2, s3, v10
	v_add_u32_e32 v6, s2, v10
	v_xor_b32_e32 v0, v186, v11
	v_ashrrev_i32_e32 v3, 31, v2
	v_ashrrev_i32_e32 v7, 31, v6
	v_lshlrev_b64 v[2:3], 6, v[2:3]
	v_lshlrev_b32_e32 v0, 4, v0
	v_lshlrev_b64 v[6:7], 6, v[6:7]
	v_lshl_add_u64 v[4:5], v[152:153], 0, v[2:3]
	v_and_b32_e32 v0, 48, v0
	v_lshl_add_u64 v[6:7], v[178:179], 0, v[6:7]
	v_lshlrev_b32_e32 v187, 4, v186
	v_lshl_add_u64 v[4:5], v[4:5], 0, v[0:1]
	v_lshl_add_u64 v[6:7], v[6:7], 0, v[0:1]
	v_readfirstlane_b32 s1, v187
	v_add_u32_e32 v0, 0x1000, v187
	s_mov_b32 m0, s1
	v_readfirstlane_b32 s1, v0
	v_add_u32_e32 v0, 0x2000, v187
	s_waitcnt lgkmcnt(0)
	s_barrier
	global_load_lds_dwordx4 v[4:5], off
	v_lshl_add_u64 v[8:9], v[4:5], 0, s[28:29]
	s_mov_b32 m0, s1
	v_readfirstlane_b32 s1, v0
	v_add_u32_e32 v0, 0x3000, v187
	global_load_lds_dwordx4 v[8:9], off
	s_mov_b32 m0, s1
	v_readfirstlane_b32 s1, v0
	v_add_u32_e32 v0, 0x4000, v187
	global_load_lds_dwordx4 v[6:7], off
	v_lshl_add_u64 v[8:9], v[6:7], 0, s[28:29]
	s_mov_b32 m0, s1
	s_mov_b64 s[28:29], 0x2000
	v_readfirstlane_b32 s1, v0
	v_add_u32_e32 v0, 0x5000, v187
	global_load_lds_dwordx4 v[8:9], off
	v_lshl_add_u64 v[8:9], v[6:7], 0, s[28:29]
	s_mov_b32 m0, s1
	s_mov_b64 s[28:29], 0x3000
	v_readfirstlane_b32 s1, v0
	v_add_u32_e32 v0, 0x6000, v187
	global_load_lds_dwordx4 v[8:9], off
	v_lshl_add_u64 v[8:9], v[6:7], 0, s[28:29]
	s_mov_b32 m0, s1
	v_readfirstlane_b32 s1, v0
	v_add_u32_e32 v0, 0x7000, v187
	global_load_lds_dwordx4 v[8:9], off
	v_lshl_add_u64 v[8:9], v[4:5], 0, s[94:95]
	s_mov_b32 m0, s1
	s_mov_b64 s[28:29], 0x30b000
	v_readfirstlane_b32 s1, v0
	v_add_u32_e32 v0, 0x8000, v187
	global_load_lds_dwordx4 v[8:9], off
	v_lshl_add_u64 v[4:5], v[4:5], 0, s[28:29]
	s_mov_b32 m0, s1
	v_readfirstlane_b32 s1, v0
	v_add_u32_e32 v0, 0x9000, v187
	global_load_lds_dwordx4 v[4:5], off
	v_lshl_add_u64 v[4:5], v[6:7], 0, s[22:23]
	s_mov_b32 m0, s1
	s_mov_b64 s[28:29], 0x11000
	v_readfirstlane_b32 s1, v0
	v_add_u32_e32 v0, 0xa000, v187
	global_load_lds_dwordx4 v[4:5], off
	v_lshl_add_u64 v[4:5], v[6:7], 0, s[28:29]
	s_mov_b32 m0, s1
	s_mov_b64 s[28:29], 0x12000
	v_readfirstlane_b32 s1, v0
	v_add_u32_e32 v0, 0xb000, v187
	global_load_lds_dwordx4 v[4:5], off
	v_lshl_add_u64 v[4:5], v[6:7], 0, s[28:29]
	s_mov_b32 m0, s1
	s_mov_b64 s[28:29], 0x13000
	v_readfirstlane_b32 s1, v0
	global_load_lds_dwordx4 v[4:5], off
	v_lshl_add_u64 v[4:5], v[6:7], 0, s[28:29]
	s_mov_b32 m0, s1
	v_lshlrev_b32_e32 v0, 2, v186
	global_load_lds_dwordx4 v[4:5], off
	v_and_b32_e32 v0, 48, v0
	v_ashrrev_i32_e32 v4, 1, v186
	v_and_b32_e32 v208, 15, v186
	v_sub_u32_e32 v0, 0, v0
	v_and_b32_e32 v209, 0xffffffc0, v4
	v_bitop3_b32 v0, v186, 48, v0 bitop3:0x48
	v_or_b32_e32 v4, v209, v208
	v_lshl_or_b32 v211, v4, 6, v0
	v_lshlrev_b32_e32 v4, 1, v186
	v_and_b32_e32 v210, 0x80, v4
	v_or_b32_e32 v4, v210, v208
	v_lshl_or_b32 v0, v4, 6, v0
	v_add_u32_e32 v4, s8, v10
	v_subrev_u32_e32 v4, s0, v4
	v_ashrrev_i32_e32 v5, 31, v4
	v_add_u32_e32 v212, 0x2000, v0
	v_bitop3_b32 v0, v186, 3, v11 bitop3:0x48
	v_lshlrev_b64 v[4:5], 6, v[4:5]
	v_lshl_add_u64 v[184:185], v[130:131], 0, v[2:3]
	v_mov_b32_e32 v2, 0
	s_mov_b32 s40, 2
	s_mov_b32 s20, 0
	s_mov_b64 s[30:31], 0x1000
	v_lshlrev_b32_e32 v0, 4, v0
	v_lshl_add_u64 v[182:183], v[180:181], 0, v[4:5]
	s_mov_b32 s41, 0
	v_mov_b32_e32 v3, v2
	v_mov_b32_e32 v4, v2
	v_mov_b32_e32 v5, v2
	v_mov_b32_e32 v6, v2
	v_mov_b32_e32 v7, v2
	v_mov_b32_e32 v8, v2
	v_mov_b32_e32 v9, v2
	v_mov_b32_e32 v10, v2
	v_mov_b32_e32 v11, v2
	v_mov_b32_e32 v12, v2
	v_mov_b32_e32 v13, v2
	v_mov_b32_e32 v14, v2
	v_mov_b32_e32 v15, v2
	v_mov_b32_e32 v16, v2
	v_mov_b32_e32 v17, v2
	v_mov_b32_e32 v18, v2
	v_mov_b32_e32 v19, v2
	v_mov_b32_e32 v20, v2
	v_mov_b32_e32 v21, v2
; #define RAW_BARRIER() do { asm volatile("s_waitcnt lgkmcnt(0)" ::: "memory"); __builtin_amdgcn_s_barrier(); } while (0)
; template <int EPI, int NB>
; DEVI void gemm_tile(const GemmJob& J, int m0, int n0, unsigned char* smem) {
;     ...
;   f32x4 acc[4][NB];
; #pragma unroll
;   for (int i = 0; i < 4; ++i)
; #pragma unroll
;     for (int j = 0; j < NB; ++j) acc[i][j] = (f32x4){0.f, 0.f, 0.f, 0.f};
;   const int srow = tid >> 2, sch = tid & 3;
;   const int gch = sch ^ ((0 - (tid >> 4)) & 3);
;   const bf16_t* Ag = J.A + (size_t)(m0 + srow) * (J.ablk ? 32 : J.lda) + gch * 8;
;   const bf16_t* Bg = J.Bt + (size_t)(n0 + srow) * 32 + gch * 8;
;   const size_t Astep = (size_t)64 * (J.ablk ? 32 : J.lda), Ak = J.ablk ? (size_t)MROWS * 32 : (size_t)32, Bstep = (size_t)64 * 32, Bk = (size_t)J.NR * 32;
;   const int nk = J.K >> 5;
;   unsigned char* lds_t = smem + tid * 16;
;   const unsigned lbase = (unsigned)(uintptr_t)(__attribute__((address_space(3))) unsigned char*)smem;
;     ...
;   asm volatile("s_waitcnt vmcnt(0)" ::: "memory");
;   RAW_BARRIER();
; #pragma unroll
;   for (int st = 0; st < S - 1; ++st) GEMM_ISSUE(st, st);
;   const int fsl = (g ^ ((0 - (l16 >> 2)) & 3)) << 4;
;   const int aofs = (wm * 64 + l16) * 64 + fsl;
;   const int bofs = A_BYTES + (wn * NB * 16 + l16) * 64 + fsl;
;   int cs = 0, is = S - 1;
; #pragma clang loop unroll(disable)
;   for (int kt = 0; kt < nk; ++kt) {
;     if (nk - 1 - kt >= S - 2) {
;       if constexpr (NB == 8) asm volatile("s_waitcnt vmcnt(6)" ::: "memory");
;       else                   asm volatile("s_waitcnt vmcnt(8)" ::: "memory");
;     } else {
;       asm volatile("s_waitcnt vmcnt(0)" ::: "memory");
;     }
;     RAW_BARRIER();
;     if (kt + S - 1 < nk) GEMM_ISSUE(kt + S - 1, is);
	v_mov_b32_e32 v22, v2
	v_mov_b32_e32 v23, v2
	v_mov_b32_e32 v24, v2
	v_mov_b32_e32 v25, v2
	v_mov_b32_e32 v26, v2
	v_mov_b32_e32 v27, v2
	v_mov_b32_e32 v28, v2
	v_mov_b32_e32 v29, v2
	v_mov_b32_e32 v30, v2
	v_mov_b32_e32 v31, v2
	v_mov_b32_e32 v32, v2
	v_mov_b32_e32 v33, v2
	v_mov_b32_e32 v34, v2
	v_mov_b32_e32 v35, v2
	v_mov_b32_e32 v36, v2
	v_mov_b32_e32 v37, v2
	v_mov_b32_e32 v38, v2
	v_mov_b32_e32 v39, v2
	v_mov_b32_e32 v40, v2
	v_mov_b32_e32 v41, v2
	v_mov_b32_e32 v42, v2
	v_mov_b32_e32 v43, v2
	v_mov_b32_e32 v44, v2
	v_mov_b32_e32 v45, v2
	v_mov_b32_e32 v46, v2
	v_mov_b32_e32 v47, v2
	v_mov_b32_e32 v48, v2
	v_mov_b32_e32 v49, v2
	v_mov_b32_e32 v50, v2
	v_mov_b32_e32 v51, v2
	v_mov_b32_e32 v52, v2
	v_mov_b32_e32 v53, v2
	v_mov_b32_e32 v54, v2
	v_mov_b32_e32 v55, v2
	v_mov_b32_e32 v56, v2
	v_mov_b32_e32 v57, v2
	v_mov_b32_e32 v58, v2
	v_mov_b32_e32 v59, v2
	v_mov_b32_e32 v60, v2
	v_mov_b32_e32 v61, v2
	v_mov_b32_e32 v62, v2
	v_mov_b32_e32 v63, v2
	v_mov_b32_e32 v64, v2
	v_mov_b32_e32 v65, v2
	v_mov_b32_e32 v66, v2
	v_mov_b32_e32 v67, v2
	v_mov_b32_e32 v68, v2
	v_mov_b32_e32 v69, v2
	v_mov_b32_e32 v70, v2
	v_mov_b32_e32 v71, v2
	v_mov_b32_e32 v72, v2
	v_mov_b32_e32 v73, v2
	v_mov_b32_e32 v74, v2
	v_mov_b32_e32 v75, v2
	v_mov_b32_e32 v76, v2
	v_mov_b32_e32 v77, v2
	v_mov_b32_e32 v78, v2
	v_mov_b32_e32 v79, v2
	v_mov_b32_e32 v80, v2
	v_mov_b32_e32 v81, v2
	v_mov_b32_e32 v82, v2
	v_mov_b32_e32 v83, v2
	v_mov_b32_e32 v84, v2
	v_mov_b32_e32 v85, v2
	v_mov_b32_e32 v86, v2
	v_mov_b32_e32 v87, v2
	v_mov_b32_e32 v88, v2
	v_mov_b32_e32 v89, v2
	v_mov_b32_e32 v90, v2
	v_mov_b32_e32 v91, v2
	v_mov_b32_e32 v92, v2
	v_mov_b32_e32 v93, v2
	v_mov_b32_e32 v94, v2
	v_mov_b32_e32 v95, v2
	v_mov_b32_e32 v96, v2
	v_mov_b32_e32 v97, v2
	v_mov_b32_e32 v98, v2
	v_mov_b32_e32 v99, v2
	v_mov_b32_e32 v100, v2
	v_mov_b32_e32 v101, v2
	v_mov_b32_e32 v102, v2
	v_mov_b32_e32 v103, v2
	v_mov_b32_e32 v104, v2
	v_mov_b32_e32 v105, v2
	v_mov_b32_e32 v106, v2
	v_mov_b32_e32 v107, v2
	v_mov_b32_e32 v108, v2
	v_mov_b32_e32 v109, v2
	v_mov_b32_e32 v110, v2
	v_mov_b32_e32 v111, v2
	v_mov_b32_e32 v112, v2
	v_mov_b32_e32 v113, v2
	v_mov_b32_e32 v114, v2
	v_mov_b32_e32 v115, v2
	v_mov_b32_e32 v116, v2
	v_mov_b32_e32 v117, v2
	v_mov_b32_e32 v118, v2
	v_mov_b32_e32 v119, v2
	v_mov_b32_e32 v120, v2
	v_mov_b32_e32 v121, v2
	v_mov_b32_e32 v122, v2
	v_mov_b32_e32 v123, v2
	v_mov_b32_e32 v124, v2
	v_mov_b32_e32 v125, v2
	v_mov_b32_e32 v126, v2
	v_mov_b32_e32 v127, v2
	v_mov_b32_e32 v128, v2
	v_mov_b32_e32 v129, v2
	s_mul_i32 s0, s40, 0x6000
	v_add_u32_e32 v213, s0, v187
	v_lshl_add_u64 v[214:215], v[184:185], 0, v[0:1]
	v_readfirstlane_b32 s0, v213
	v_lshl_add_u64 v[216:217], v[214:215], 0, s[24:25]
	s_mov_b32 m0, s0
	v_lshl_add_u64 v[214:215], v[214:215], 0, s[26:27]
	s_nop 0
	v_readfirstlane_b32 s100, v216
	v_readfirstlane_b32 s101, v217
	s_nop 1
	v_subrev_u32_e32 v230, s100, v216
	v_add_u32_e32 v216, 0x1000, v213
	v_add_u32_e32 v218, 0x2000, v213
	v_readfirstlane_b32 s0, v216
	s_mov_b32 m0, s0
	v_readfirstlane_b32 s0, v218
	v_subrev_u32_e32 v231, s100, v214
	v_lshl_add_u64 v[214:215], v[182:183], 0, v[0:1]
	v_add_u32_e32 v218, 0x3000, v213
	v_lshl_add_u64 v[216:217], v[214:215], 0, s[10:11]
	s_mov_b32 m0, s0
	v_readfirstlane_b32 s0, v218
	v_add_u32_e32 v218, 0x4000, v213
	s_nop 0
	v_readfirstlane_b32 vcc_lo, v216
	v_readfirstlane_b32 vcc_hi, v217
	s_nop 1
	v_subrev_u32_e32 v232, vcc_lo, v216
	v_lshl_add_u64 v[216:217], v[214:215], 0, s[14:15]
	s_mov_b32 m0, s0
	v_readfirstlane_b32 s0, v218
	v_add_u32_e32 v213, 0x5000, v213
	v_subrev_u32_e32 v233, vcc_lo, v216
	v_lshl_add_u64 v[216:217], v[214:215], 0, s[16:17]
	s_mov_b32 m0, s0
	v_readfirstlane_b32 s0, v213
	v_subrev_u32_e32 v234, vcc_lo, v216
	v_lshl_add_u64 v[214:215], v[214:215], 0, s[18:19]
	s_mov_b32 m0, s0
	s_nop 0
	v_subrev_u32_e32 v235, vcc_lo, v214
	v_mov_b32_e32 v184, v230
	v_mov_b32_e32 v185, v231
	v_mov_b32_e32 v182, v232
	v_mov_b32_e32 v183, v233
	v_mov_b32_e32 v253, v234
	v_mov_b32_e32 v254, v235
	v_readfirstlane_b32 s0, v187
	s_branch .LBB0_2744
	.p2align	6

; #define RAW_BARRIER() do { asm volatile("s_waitcnt lgkmcnt(0)" ::: "memory"); __builtin_amdgcn_s_barrier(); } while (0)
; template <int EPI, int NB>
; DEVI void gemm_tile(const GemmJob& J, int m0, int n0, unsigned char* smem) {
;     ...
;   const int srow = tid >> 2, sch = tid & 3;
;   const int gch = sch ^ ((0 - (tid >> 4)) & 3);
;   const bf16_t* Ag = J.A + (size_t)(m0 + srow) * (J.ablk ? 32 : J.lda) + gch * 8;
;   const bf16_t* Bg = J.Bt + (size_t)(n0 + srow) * 32 + gch * 8;
;   const size_t Astep = (size_t)64 * (J.ablk ? 32 : J.lda), Ak = J.ablk ? (size_t)MROWS * 32 : (size_t)32, Bstep = (size_t)64 * 32, Bk = (size_t)J.NR * 32;
;   const int nk = J.K >> 5;
;   unsigned char* lds_t = smem + tid * 16;
;   const unsigned lbase = (unsigned)(uintptr_t)(__attribute__((address_space(3))) unsigned char*)smem;
;     ...
;   asm volatile("s_waitcnt vmcnt(0)" ::: "memory");
;   RAW_BARRIER();
; #pragma unroll
;   for (int st = 0; st < S - 1; ++st) GEMM_ISSUE(st, st);
; template <int EPI, int NB>
; DEVI void gemm_run(const GemmJob& J, unsigned char* smem, int rot) {
;     ...
;     const int x = b & 7, lb = b >> 3, nlb = G >> 3;
;     const int mlo = x * 49;
;     const int mcnt = min(49, MT128 - mlo);
;     const int ntot = mcnt * J.ntn, gsz = 8 * J.ntn;
;     const int ngrp = (mcnt + 7) >> 3;
;     for (int q0 = lb; q0 < ntot; q0 += nlb) {
;       const int q = J.rev ? ntot - 1 - q0 : q0;
;       int grp = q / gsz; const int qq = q - grp * gsz;
;       const int mg = min(8, mcnt - grp * 8);
;       const int nt = qq / mg, mi = qq - nt * mg;
;       gemm_tile<EPI, NB>(J, (mlo + grp * 8 + mi) * 128, (J.nt0 + nt) * BN, smem);
.LBB0_2819:
	s_not_b32 s0, s9
	s_add_i32 s0, s1, s0
	s_ashr_i32 s1, s0, 31
	s_lshr_b32 s1, s1, 27
	s_add_i32 s1, s0, s1
	s_ashr_i32 s41, s1, 5
	s_lshl_b32 s3, s41, 3
	v_readlane_b32 s2, v251, 48
	s_sub_i32 s2, s2, s3
	s_min_i32 s20, s2, 8
	s_abs_i32 s40, s20
	v_cvt_f32_u32_e32 v0, s40
	s_sub_i32 s43, 0, s40
	s_andn2_b32 s1, s1, 31
	s_sub_i32 s0, s0, s1
	v_rcp_iflag_f32_e32 v0, v0
	s_abs_i32 s1, s0
	s_xor_b32 s42, s0, s20
	s_ashr_i32 s42, s42, 31
	v_mul_f32_e32 v0, 0x4f7ffffe, v0
	v_cvt_u32_f32_e32 v0, v0
	v_mov_b32_e32 v186, v177
	s_nop 0
	v_readfirstlane_b32 s44, v0
	s_mul_i32 s43, s43, s44
	s_mul_hi_u32 s43, s44, s43
	s_add_i32 s44, s44, s43
	s_mul_hi_u32 s43, s1, s44
	s_mul_i32 s44, s43, s40
	s_sub_i32 s1, s1, s44
	s_add_i32 s45, s43, 1
	s_sub_i32 s44, s1, s40
	s_cmp_ge_u32 s1, s40
	s_cselect_b32 s43, s45, s43
	s_cselect_b32 s1, s44, s1
	s_add_i32 s44, s43, 1
	s_cmp_ge_u32 s1, s40
	s_cselect_b32 s1, s44, s43
	s_xor_b32 s1, s1, s42
	s_sub_i32 s1, s1, s42
	s_mul_i32 s42, s20, s1
	v_readlane_b32 s20, v250, 37
	s_add_i32 s3, s3, s20
	s_add_i32 s3, s3, s0
	s_sub_i32 s0, s3, s42
	s_lshl_b32 s20, s0, 7
	s_lshl_b32 s3, s1, 8
	v_ashrrev_i32_e32 v10, 2, v186
	v_lshrrev_b32_e32 v0, 4, v186
	v_sub_u32_e32 v11, 0, v0
	v_add_u32_e32 v2, s20, v10
	v_add_u32_e32 v4, s3, v10
	v_xor_b32_e32 v0, v186, v11
	v_ashrrev_i32_e32 v3, 31, v2
	v_ashrrev_i32_e32 v5, 31, v4
	v_lshlrev_b64 v[2:3], 6, v[2:3]
	v_lshlrev_b32_e32 v0, 4, v0
	v_lshlrev_b64 v[4:5], 6, v[4:5]
	v_lshl_add_u64 v[2:3], v[152:153], 0, v[2:3]
	v_and_b32_e32 v0, 48, v0
	v_lshl_add_u64 v[6:7], v[178:179], 0, v[4:5]
	v_lshlrev_b32_e32 v187, 4, v186
	v_lshl_add_u64 v[2:3], v[2:3], 0, v[0:1]
	v_lshl_add_u64 v[6:7], v[6:7], 0, v[0:1]
	v_readfirstlane_b32 s0, v187
	v_add_u32_e32 v0, 0x1000, v187
	s_mov_b32 m0, s0
	s_mov_b64 s[28:29], 0x1000
	v_readfirstlane_b32 s0, v0
	v_add_u32_e32 v0, 0x2000, v187
	s_waitcnt lgkmcnt(0)
	s_barrier
	global_load_lds_dwordx4 v[2:3], off
	v_lshl_add_u64 v[8:9], v[2:3], 0, s[28:29]
	s_mov_b32 m0, s0
	v_readfirstlane_b32 s0, v0
	v_add_u32_e32 v0, 0x3000, v187
	global_load_lds_dwordx4 v[8:9], off
	s_mov_b32 m0, s0
	v_readfirstlane_b32 s0, v0
	global_load_lds_dwordx4 v[6:7], off
	v_lshl_add_u64 v[8:9], v[6:7], 0, s[28:29]
	s_mov_b32 m0, s0
	s_mov_b64 s[0:1], 0x2000
	v_add_u32_e32 v0, 0x4000, v187
	global_load_lds_dwordx4 v[8:9], off
	v_lshl_add_u64 v[8:9], v[6:7], 0, s[0:1]
	v_readfirstlane_b32 s0, v0
	s_mov_b32 m0, s0
	s_mov_b64 s[0:1], 0x3000
	v_add_u32_e32 v0, 0x5000, v187
	global_load_lds_dwordx4 v[8:9], off
	v_lshl_add_u64 v[8:9], v[6:7], 0, s[0:1]
	v_readfirstlane_b32 s0, v0
	v_add_u32_e32 v0, 0x6000, v187
	s_mov_b32 m0, s0
	v_readfirstlane_b32 s0, v0
	global_load_lds_dwordx4 v[8:9], off
	s_mov_b32 m0, s0
	s_mov_b64 s[0:1], 0x30b000
	v_add_u32_e32 v0, 0x7000, v187
	v_lshl_add_u64 v[8:9], v[2:3], 0, s[94:95]
	v_lshl_add_u64 v[2:3], v[2:3], 0, s[0:1]
	v_readfirstlane_b32 s0, v0
	v_add_u32_e32 v0, 0x8000, v187
	global_load_lds_dwordx4 v[8:9], off
	s_mov_b32 m0, s0
	v_readfirstlane_b32 s0, v0
	global_load_lds_dwordx4 v[2:3], off
	v_lshl_add_u64 v[2:3], v[6:7], 0, s[22:23]
	s_mov_b32 m0, s0
	s_mov_b64 s[0:1], 0x11000
	v_add_u32_e32 v0, 0x9000, v187
	global_load_lds_dwordx4 v[2:3], off
	v_lshl_add_u64 v[2:3], v[6:7], 0, s[0:1]
	v_readfirstlane_b32 s0, v0
	s_mov_b32 m0, s0
	s_mov_b64 s[0:1], 0x12000
	v_add_u32_e32 v0, 0xa000, v187
	global_load_lds_dwordx4 v[2:3], off
	v_lshl_add_u64 v[2:3], v[6:7], 0, s[0:1]
	v_readfirstlane_b32 s0, v0
	s_mov_b32 m0, s0
	s_mov_b64 s[0:1], 0x13000
	v_add_u32_e32 v0, 0xb000, v187
	global_load_lds_dwordx4 v[2:3], off
	v_lshl_add_u64 v[2:3], v[6:7], 0, s[0:1]
	v_readfirstlane_b32 s0, v0
	s_mov_b32 m0, s0
	v_lshlrev_b32_e32 v0, 2, v186
	global_load_lds_dwordx4 v[2:3], off
	v_and_b32_e32 v0, 48, v0
	v_ashrrev_i32_e32 v2, 1, v186
	v_and_b32_e32 v208, 15, v186
	v_sub_u32_e32 v0, 0, v0
	v_and_b32_e32 v209, 0xffffffc0, v2
	v_bitop3_b32 v0, v186, 48, v0 bitop3:0x48
	v_or_b32_e32 v2, v209, v208
	v_lshl_or_b32 v211, v2, 6, v0
	v_lshlrev_b32_e32 v2, 1, v186
	v_and_b32_e32 v210, 0x80, v2
	s_sub_i32 s0, s8, s42
	s_mul_i32 s41, s41, 24
	v_or_b32_e32 v2, v210, v208
	s_sub_i32 s0, s0, s41
	v_lshl_or_b32 v0, v2, 6, v0
	v_lshl_add_u32 v2, s0, 7, v10
	v_ashrrev_i32_e32 v3, 31, v2
	v_lshlrev_b64 v[2:3], 6, v[2:3]
	v_add_u32_e32 v212, 0x2000, v0
	v_bitop3_b32 v0, v186, 3, v11 bitop3:0x48
	v_lshl_add_u64 v[184:185], v[130:131], 0, v[2:3]
	v_mov_b32_e32 v2, 0
	s_mov_b32 s2, 0
	s_mov_b32 s40, 2
	s_mov_b64 s[30:31], 0x1000
	v_lshlrev_b32_e32 v0, 4, v0
; #define RAW_BARRIER() do { asm volatile("s_waitcnt lgkmcnt(0)" ::: "memory"); __builtin_amdgcn_s_barrier(); } while (0)
; template <int EPI, int NB>
; DEVI void gemm_tile(const GemmJob& J, int m0, int n0, unsigned char* smem) {
;     ...
;   f32x4 acc[4][NB];
; #pragma unroll
;   for (int i = 0; i < 4; ++i)
; #pragma unroll
;     for (int j = 0; j < NB; ++j) acc[i][j] = (f32x4){0.f, 0.f, 0.f, 0.f};
;   const int srow = tid >> 2, sch = tid & 3;
;   const int gch = sch ^ ((0 - (tid >> 4)) & 3);
;   const bf16_t* Ag = J.A + (size_t)(m0 + srow) * (J.ablk ? 32 : J.lda) + gch * 8;
;   const bf16_t* Bg = J.Bt + (size_t)(n0 + srow) * 32 + gch * 8;
;   const size_t Astep = (size_t)64 * (J.ablk ? 32 : J.lda), Ak = J.ablk ? (size_t)MROWS * 32 : (size_t)32, Bstep = (size_t)64 * 32, Bk = (size_t)J.NR * 32;
;   const int nk = J.K >> 5;
;   unsigned char* lds_t = smem + tid * 16;
;   const unsigned lbase = (unsigned)(uintptr_t)(__attribute__((address_space(3))) unsigned char*)smem;
;     ...
;   asm volatile("s_waitcnt vmcnt(0)" ::: "memory");
;   RAW_BARRIER();
; #pragma unroll
;   for (int st = 0; st < S - 1; ++st) GEMM_ISSUE(st, st);
;   const int fsl = (g ^ ((0 - (l16 >> 2)) & 3)) << 4;
;   const int aofs = (wm * 64 + l16) * 64 + fsl;
;   const int bofs = A_BYTES + (wn * NB * 16 + l16) * 64 + fsl;
;   int cs = 0, is = S - 1;
; #pragma clang loop unroll(disable)
;   for (int kt = 0; kt < nk; ++kt) {
;     if (nk - 1 - kt >= S - 2) {
;       if constexpr (NB == 8) asm volatile("s_waitcnt vmcnt(6)" ::: "memory");
;       else                   asm volatile("s_waitcnt vmcnt(8)" ::: "memory");
;     } else {
;       asm volatile("s_waitcnt vmcnt(0)" ::: "memory");
;     }
;     RAW_BARRIER();
;     if (kt + S - 1 < nk) GEMM_ISSUE(kt + S - 1, is);
	v_lshl_add_u64 v[182:183], v[180:181], 0, v[4:5]
	s_mov_b32 s41, 0
	v_mov_b32_e32 v3, v2
	v_mov_b32_e32 v4, v2
	v_mov_b32_e32 v5, v2
	v_mov_b32_e32 v6, v2
	v_mov_b32_e32 v7, v2
	v_mov_b32_e32 v8, v2
	v_mov_b32_e32 v9, v2
	v_mov_b32_e32 v10, v2
	v_mov_b32_e32 v11, v2
	v_mov_b32_e32 v12, v2
	v_mov_b32_e32 v13, v2
	v_mov_b32_e32 v14, v2
	v_mov_b32_e32 v15, v2
	v_mov_b32_e32 v16, v2
	v_mov_b32_e32 v17, v2
	v_mov_b32_e32 v18, v2
	v_mov_b32_e32 v19, v2
	v_mov_b32_e32 v20, v2
	v_mov_b32_e32 v21, v2
	v_mov_b32_e32 v22, v2
	v_mov_b32_e32 v23, v2
	v_mov_b32_e32 v24, v2
	v_mov_b32_e32 v25, v2
	v_mov_b32_e32 v26, v2
	v_mov_b32_e32 v27, v2
	v_mov_b32_e32 v28, v2
	v_mov_b32_e32 v29, v2
	v_mov_b32_e32 v30, v2
	v_mov_b32_e32 v31, v2
	v_mov_b32_e32 v32, v2
	v_mov_b32_e32 v33, v2
	v_mov_b32_e32 v34, v2
	v_mov_b32_e32 v35, v2
	v_mov_b32_e32 v36, v2
	v_mov_b32_e32 v37, v2
	v_mov_b32_e32 v38, v2
	v_mov_b32_e32 v39, v2
	v_mov_b32_e32 v40, v2
	v_mov_b32_e32 v41, v2
	v_mov_b32_e32 v42, v2
	v_mov_b32_e32 v43, v2
	v_mov_b32_e32 v44, v2
	v_mov_b32_e32 v45, v2
	v_mov_b32_e32 v46, v2
	v_mov_b32_e32 v47, v2
	v_mov_b32_e32 v48, v2
	v_mov_b32_e32 v49, v2
	v_mov_b32_e32 v50, v2
	v_mov_b32_e32 v51, v2
	v_mov_b32_e32 v52, v2
	v_mov_b32_e32 v53, v2
	v_mov_b32_e32 v54, v2
	v_mov_b32_e32 v55, v2
	v_mov_b32_e32 v56, v2
	v_mov_b32_e32 v57, v2
	v_mov_b32_e32 v58, v2
	v_mov_b32_e32 v59, v2
	v_mov_b32_e32 v60, v2
	v_mov_b32_e32 v61, v2
	v_mov_b32_e32 v62, v2
	v_mov_b32_e32 v63, v2
	v_mov_b32_e32 v64, v2
	v_mov_b32_e32 v65, v2
	v_mov_b32_e32 v66, v2
	v_mov_b32_e32 v67, v2
	v_mov_b32_e32 v68, v2
	v_mov_b32_e32 v69, v2
	v_mov_b32_e32 v70, v2
	v_mov_b32_e32 v71, v2
	v_mov_b32_e32 v72, v2
	v_mov_b32_e32 v73, v2
	v_mov_b32_e32 v74, v2
	v_mov_b32_e32 v75, v2
	v_mov_b32_e32 v76, v2
	v_mov_b32_e32 v77, v2
	v_mov_b32_e32 v78, v2
	v_mov_b32_e32 v79, v2
	v_mov_b32_e32 v80, v2
	v_mov_b32_e32 v81, v2
	v_mov_b32_e32 v82, v2
	v_mov_b32_e32 v83, v2
	v_mov_b32_e32 v84, v2
	v_mov_b32_e32 v85, v2
	v_mov_b32_e32 v86, v2
	v_mov_b32_e32 v87, v2
	v_mov_b32_e32 v88, v2
	v_mov_b32_e32 v89, v2
	v_mov_b32_e32 v90, v2
	v_mov_b32_e32 v91, v2
	v_mov_b32_e32 v92, v2
	v_mov_b32_e32 v93, v2
	v_mov_b32_e32 v94, v2
	v_mov_b32_e32 v95, v2
	v_mov_b32_e32 v96, v2
	v_mov_b32_e32 v97, v2
	v_mov_b32_e32 v98, v2
	v_mov_b32_e32 v99, v2
	v_mov_b32_e32 v100, v2
	v_mov_b32_e32 v101, v2
	v_mov_b32_e32 v102, v2
	v_mov_b32_e32 v103, v2
	v_mov_b32_e32 v104, v2
	v_mov_b32_e32 v105, v2
	v_mov_b32_e32 v106, v2
	v_mov_b32_e32 v107, v2
	v_mov_b32_e32 v108, v2
	v_mov_b32_e32 v109, v2
	v_mov_b32_e32 v110, v2
	v_mov_b32_e32 v111, v2
	v_mov_b32_e32 v112, v2
	v_mov_b32_e32 v113, v2
	v_mov_b32_e32 v114, v2
	v_mov_b32_e32 v115, v2
	v_mov_b32_e32 v116, v2
	v_mov_b32_e32 v117, v2
	v_mov_b32_e32 v118, v2
	v_mov_b32_e32 v119, v2
	v_mov_b32_e32 v120, v2
	v_mov_b32_e32 v121, v2
	v_mov_b32_e32 v122, v2
	v_mov_b32_e32 v123, v2
	v_mov_b32_e32 v124, v2
	v_mov_b32_e32 v125, v2
	v_mov_b32_e32 v126, v2
	v_mov_b32_e32 v127, v2
	v_mov_b32_e32 v128, v2
	v_mov_b32_e32 v129, v2
	s_mul_i32 s0, s40, 0x6000
	v_add_u32_e32 v213, s0, v187
	v_lshl_add_u64 v[214:215], v[184:185], 0, v[0:1]
	v_readfirstlane_b32 s0, v213
	v_lshl_add_u64 v[216:217], v[214:215], 0, s[24:25]
	s_mov_b32 m0, s0
	v_lshl_add_u64 v[214:215], v[214:215], 0, s[26:27]
	s_nop 0
	v_readfirstlane_b32 s100, v216
	v_readfirstlane_b32 s101, v217
	s_nop 1
	v_subrev_u32_e32 v230, s100, v216
	v_add_u32_e32 v216, 0x1000, v213
	v_add_u32_e32 v218, 0x2000, v213
	v_readfirstlane_b32 s0, v216
	s_mov_b32 m0, s0
	v_readfirstlane_b32 s0, v218
	v_subrev_u32_e32 v231, s100, v214
	v_lshl_add_u64 v[214:215], v[182:183], 0, v[0:1]
	v_add_u32_e32 v218, 0x3000, v213
	v_lshl_add_u64 v[216:217], v[214:215], 0, s[10:11]
	s_mov_b32 m0, s0
	v_readfirstlane_b32 s0, v218
	v_add_u32_e32 v218, 0x4000, v213
	s_nop 0
	v_readfirstlane_b32 vcc_lo, v216
	v_readfirstlane_b32 vcc_hi, v217
	s_nop 1
	v_subrev_u32_e32 v232, vcc_lo, v216
	v_lshl_add_u64 v[216:217], v[214:215], 0, s[14:15]
	s_mov_b32 m0, s0
	v_readfirstlane_b32 s0, v218
	v_add_u32_e32 v213, 0x5000, v213
	v_subrev_u32_e32 v233, vcc_lo, v216
	v_lshl_add_u64 v[216:217], v[214:215], 0, s[16:17]
	s_mov_b32 m0, s0
	v_readfirstlane_b32 s0, v213
	v_subrev_u32_e32 v234, vcc_lo, v216
	v_lshl_add_u64 v[214:215], v[214:215], 0, s[18:19]
	s_mov_b32 m0, s0
	s_nop 0
	v_subrev_u32_e32 v235, vcc_lo, v214
	v_mov_b32_e32 v184, v230
	v_mov_b32_e32 v185, v231
	v_mov_b32_e32 v182, v232
	v_mov_b32_e32 v183, v233
	v_mov_b32_e32 v253, v234
	v_mov_b32_e32 v254, v235
	v_readfirstlane_b32 s0, v187
	s_branch .LBB0_2821
	.p2align	6
